# speedup vs baseline: 1.0110x; 1.0110x over previous
; #define PG8_STAGE(bufoff, gbase, voff) do { _Pragma("unroll") for (int _i = 0; _i < 2; ++_i) \
;         __builtin_amdgcn_global_load_lds((const unsigned*)((const char*)(gbase) + (voff)[_i]), (LAS unsigned*)(lds + (bufoff) + ldsw + _i * 8192), 16, 0, 0); } while (0)
; #define PG8_LDA(dst, b, h) do { _Pragma("unroll") for (int m = 0; m < 4; ++m) _Pragma("unroll") for (int k = 0; k < 2; ++k) dst[m][k] = *(const LAS bf16x8*)(lds + PG8_SA(b, h) + aoff + m * 2048 + k * 1024); } while (0)
; #define PG8_LDB(dst, b, h) do { _Pragma("unroll") for (int n = 0; n < 2; ++n) _Pragma("unroll") for (int k = 0; k < 2; ++k) dst[n][k] = *(const LAS bf16x8*)(lds + PG8_SB(b, h) + boff + n * 2048 + k * 1024); } while (0)
; #define PG8_WAIT_V(n) asm volatile("s_waitcnt vmcnt(" #n ")" ::: "memory")
; #define PG8_WAIT_L(n) asm volatile("s_waitcnt lgkmcnt(" #n ")" ::: "memory")
; #define PG8_BAR __builtin_amdgcn_s_barrier()
; template <class Epi>
; DEV void gemm_phase(LAS unsigned char* lds, const Gemm g, const StaticOrder& S, const Epi& E) {
;     ...
;         for (int t = 0; t < nt; t += 2) {
;             const bool last = (t == nt - 2);
;             const char* a1 = cA + (size_t)(t + 1) * kstep;
;             const char* a2 = last ? nA : cA + (size_t)(t + 2) * kstep; const char* b2 = last ? nB : cB + (size_t)(t + 2) * kstep;
;             const char* a3 = a2 + kstep; const char* b3 = b2 + kstep;
;             PG8_LDB(B0, 0, 0); PG8_SCHED; PG8_LDA(At, 0, 0); PG8_STAGE(PG8_SA(1, 1), a1 + hstep, voffA);
;             PG8_WAIT_L(8); PG8_BAR; PG8_WAIT_L(0); PG8_MMA(0, 0, At, B0); PG8_BAR; PG8_SCHED;
;             PG8_LDB(B1, 0, 1); PG8_STAGE(PG8_SB(0, 0), b2, voffB);
;             PG8_BAR; PG8_WAIT_L(0); PG8_MMA(0, 1, At, B1); PG8_BAR;
;             PG8_LDA(At, 0, 1); PG8_STAGE(PG8_SA(0, 0), a2, voffA);
;             PG8_BAR; PG8_WAIT_L(0); PG8_MMA(1, 0, At, B0); PG8_BAR; PG8_SCHED;
;             PG8_STAGE(PG8_SB(0, 1), b2 + hstep, voffB);
;             PG8_WAIT_V(6); PG8_BAR; PG8_MMA(1, 1, At, B1); PG8_BAR;
;             PG8_LDB(B0, 1, 0); PG8_SCHED; PG8_LDA(At, 1, 0); PG8_STAGE(PG8_SA(0, 1), a2 + hstep, voffA);
;             PG8_WAIT_L(8); PG8_BAR; PG8_WAIT_L(0); PG8_MMA(0, 0, At, B0); PG8_BAR; PG8_SCHED;
;             PG8_LDB(B1, 1, 1); PG8_STAGE(PG8_SB(1, 0), b3, voffB);
;             PG8_BAR; PG8_WAIT_L(0); PG8_MMA(0, 1, At, B1); PG8_BAR;
.LBB0_61:
	s_add_u32 s28, s26, 0xfff80080
	s_addc_u32 s29, s27, -1
	s_add_i32 s49, 0, 0x10000
	v_add_u32_e32 v140, s49, v178
	ds_read_b128 v[128:131], v140
	ds_read_b128 v[132:135], v140 offset:1024
	ds_read_b128 v[136:139], v140 offset:2048
	ds_read_b128 v[140:143], v140 offset:3072
	s_cmp_eq_u32 s48, 28
	s_cselect_b32 s31, s15, s29
	s_cselect_b32 s30, s19, s28
	s_cselect_b32 s29, s17, s47
	s_cselect_b32 s28, s25, s46
	s_add_i32 m0, s37, 0xc000
	ds_read_b128 v[154:157], v181
	ds_read_b128 v[174:177], v181 offset:1024
	ds_read_b128 v[182:185], v181 offset:2048
	ds_read_b128 v[186:189], v181 offset:3072
	ds_read_b128 v[190:193], v181 offset:4096
	ds_read_b128 v[194:197], v181 offset:5120
	ds_read_b128 v[214:217], v181 offset:6144
	ds_read_b128 v[218:221], v181 offset:7168
	global_load_lds_dwordx4 v150, s[26:27]
	s_add_i32 m0, s37, 0xe000
	s_nop 0
	global_load_lds_dwordx4 v152, s[26:27]
	s_waitcnt lgkmcnt(8)
	s_barrier
	s_waitcnt lgkmcnt(0)
	v_mfma_f32_16x16x32_bf16 v[124:127], v[128:131], v[154:157], v[124:127]
	v_mfma_f32_16x16x32_bf16 v[120:123], v[136:139], v[154:157], v[120:123]
	v_mfma_f32_16x16x32_bf16 v[108:111], v[128:131], v[182:185], v[108:111]
	v_mfma_f32_16x16x32_bf16 v[104:107], v[136:139], v[182:185], v[104:107]
	v_mfma_f32_16x16x32_bf16 v[92:95], v[128:131], v[190:193], v[92:95]
	v_mfma_f32_16x16x32_bf16 v[88:91], v[136:139], v[190:193], v[88:91]
	v_mfma_f32_16x16x32_bf16 v[76:79], v[128:131], v[214:217], v[76:79]
	v_mfma_f32_16x16x32_bf16 v[72:75], v[136:139], v[214:217], v[72:75]
	v_mfma_f32_16x16x32_bf16 v[124:127], v[132:135], v[174:177], v[124:127]
	v_mfma_f32_16x16x32_bf16 v[120:123], v[140:143], v[174:177], v[120:123]
	v_mfma_f32_16x16x32_bf16 v[108:111], v[132:135], v[186:189], v[108:111]
	v_mfma_f32_16x16x32_bf16 v[104:107], v[140:143], v[186:189], v[104:107]
	v_mfma_f32_16x16x32_bf16 v[92:95], v[132:135], v[194:197], v[92:95]
	v_mfma_f32_16x16x32_bf16 v[88:91], v[140:143], v[194:197], v[88:91]
	v_mfma_f32_16x16x32_bf16 v[76:79], v[132:135], v[218:221], v[76:79]
	v_mfma_f32_16x16x32_bf16 v[72:75], v[140:143], v[218:221], v[72:75]
	s_barrier
	s_add_i32 s52, 0, 0x14000
	v_add_u32_e32 v158, s52, v178
	s_add_i32 s49, s49, s36
	ds_read_b128 v[222:225], v158
	ds_read_b128 v[226:229], v158 offset:1024
	ds_read_b128 v[230:233], v158 offset:2048
	ds_read_b128 v[234:237], v158 offset:3072
	v_lshl_add_u64 v[158:159], s[28:29], 0, v[160:161]
	s_mov_b32 m0, s49
	v_lshl_add_u64 v[238:239], s[28:29], 0, v[148:149]
	global_load_lds_dwordx4 v160, s[28:29]
	s_add_i32 m0, s49, 0x2000
	s_nop 0
	global_load_lds_dwordx4 v148, s[28:29]
	s_barrier
	s_waitcnt lgkmcnt(0)
	v_mfma_f32_16x16x32_bf16 v[116:119], v[222:225], v[154:157], v[116:119]
	v_mfma_f32_16x16x32_bf16 v[112:115], v[230:233], v[154:157], v[112:115]
	v_mfma_f32_16x16x32_bf16 v[100:103], v[222:225], v[182:185], v[100:103]
	v_mfma_f32_16x16x32_bf16 v[96:99], v[230:233], v[182:185], v[96:99]
	v_mfma_f32_16x16x32_bf16 v[84:87], v[222:225], v[190:193], v[84:87]
	v_mfma_f32_16x16x32_bf16 v[80:83], v[230:233], v[190:193], v[80:83]
	v_mfma_f32_16x16x32_bf16 v[68:71], v[222:225], v[214:217], v[68:71]
	v_mfma_f32_16x16x32_bf16 v[64:67], v[230:233], v[214:217], v[64:67]
	v_mfma_f32_16x16x32_bf16 v[116:119], v[226:229], v[174:177], v[116:119]
	v_mfma_f32_16x16x32_bf16 v[112:115], v[234:237], v[174:177], v[112:115]
	v_mfma_f32_16x16x32_bf16 v[100:103], v[226:229], v[186:189], v[100:103]
	v_mfma_f32_16x16x32_bf16 v[96:99], v[234:237], v[186:189], v[96:99]
	v_mfma_f32_16x16x32_bf16 v[84:87], v[226:229], v[194:197], v[84:87]
	v_mfma_f32_16x16x32_bf16 v[80:83], v[234:237], v[194:197], v[80:83]
	v_mfma_f32_16x16x32_bf16 v[68:71], v[226:229], v[218:221], v[68:71]
	v_mfma_f32_16x16x32_bf16 v[64:67], v[234:237], v[218:221], v[64:67]
	s_mov_b32 m0, s37
	v_lshl_add_u64 v[240:241], s[30:31], 0, v[144:145]
	s_barrier
	ds_read_b128 v[154:157], v181 offset:16384
	ds_read_b128 v[174:177], v181 offset:17408
	ds_read_b128 v[182:185], v181 offset:18432
	ds_read_b128 v[186:189], v181 offset:19456
	ds_read_b128 v[190:193], v181 offset:20480
	ds_read_b128 v[194:197], v181 offset:21504
	ds_read_b128 v[214:217], v181 offset:22528
	ds_read_b128 v[218:221], v181 offset:23552
	global_load_lds_dwordx4 v144, s[30:31]
	v_lshl_add_u64 v[242:243], s[30:31], 0, v[146:147]
	s_mov_b32 m0, s38
	s_nop 0
	global_load_lds_dwordx4 v146, s[30:31]
	s_barrier
	s_waitcnt lgkmcnt(0)
	v_mfma_f32_16x16x32_bf16 v[60:63], v[128:131], v[154:157], v[60:63]
	v_mfma_f32_16x16x32_bf16 v[56:59], v[136:139], v[154:157], v[56:59]
	v_mfma_f32_16x16x32_bf16 v[44:47], v[128:131], v[182:185], v[44:47]
	v_mfma_f32_16x16x32_bf16 v[40:43], v[136:139], v[182:185], v[40:43]
	v_mfma_f32_16x16x32_bf16 v[28:31], v[128:131], v[190:193], v[28:31]
	v_mfma_f32_16x16x32_bf16 v[24:27], v[136:139], v[190:193], v[24:27]
	v_mfma_f32_16x16x32_bf16 v[12:15], v[128:131], v[214:217], v[12:15]
	v_mfma_f32_16x16x32_bf16 v[8:11], v[136:139], v[214:217], v[8:11]
	v_mfma_f32_16x16x32_bf16 v[60:63], v[132:135], v[174:177], v[60:63]
	v_mfma_f32_16x16x32_bf16 v[56:59], v[140:143], v[174:177], v[56:59]
	v_mfma_f32_16x16x32_bf16 v[44:47], v[132:135], v[186:189], v[44:47]
	v_mfma_f32_16x16x32_bf16 v[40:43], v[140:143], v[186:189], v[40:43]
	v_mfma_f32_16x16x32_bf16 v[28:31], v[132:135], v[194:197], v[28:31]
	v_mfma_f32_16x16x32_bf16 v[24:27], v[140:143], v[194:197], v[24:27]
	v_mfma_f32_16x16x32_bf16 v[12:15], v[132:135], v[218:221], v[12:15]
	v_mfma_f32_16x16x32_bf16 v[8:11], v[140:143], v[218:221], v[8:11]
	s_barrier
	s_add_u32 s50, s28, 0x80000
	s_addc_u32 s51, s29, 0
	s_add_i32 s49, s52, s36
	s_mov_b32 m0, s49
	s_nop 0
	global_load_lds_dwordx4 v160, s[50:51]
	s_add_i32 m0, s49, 0x2000
	s_nop 0
	global_load_lds_dwordx4 v148, s[50:51]
	s_waitcnt vmcnt(6)
	s_barrier
; #define PG8_STAGE(bufoff, gbase, voff) do { _Pragma("unroll") for (int _i = 0; _i < 2; ++_i) \
;         __builtin_amdgcn_global_load_lds((const unsigned*)((const char*)(gbase) + (voff)[_i]), (LAS unsigned*)(lds + (bufoff) + ldsw + _i * 8192), 16, 0, 0); } while (0)
; #define PG8_LDA(dst, b, h) do { _Pragma("unroll") for (int m = 0; m < 4; ++m) _Pragma("unroll") for (int k = 0; k < 2; ++k) dst[m][k] = *(const LAS bf16x8*)(lds + PG8_SA(b, h) + aoff + m * 2048 + k * 1024); } while (0)
; #define PG8_LDB(dst, b, h) do { _Pragma("unroll") for (int n = 0; n < 2; ++n) _Pragma("unroll") for (int k = 0; k < 2; ++k) dst[n][k] = *(const LAS bf16x8*)(lds + PG8_SB(b, h) + boff + n * 2048 + k * 1024); } while (0)
; #define PG8_MMA(ai, bj, At, Bt) do { __builtin_amdgcn_s_setprio(1); _Pragma("unroll") for (int m = 0; m < 4; ++m) _Pragma("unroll") for (int n = 0; n < 2; ++n) _Pragma("unroll") for (int k = 0; k < 2; ++k) \
;         acc[ai][bj][m][n] = __builtin_amdgcn_mfma_f32_16x16x32_bf16(Bt[n][k], At[m][k], acc[ai][bj][m][n], 0, 0, 0); __builtin_amdgcn_s_setprio(0); } while (0)
; #define PG8_WAIT_V(n) asm volatile("s_waitcnt vmcnt(" #n ")" ::: "memory")
; #define PG8_WAIT_L(n) asm volatile("s_waitcnt lgkmcnt(" #n ")" ::: "memory")
; #define PG8_BAR __builtin_amdgcn_s_barrier()
; #define PG8_SCHED __builtin_amdgcn_sched_barrier(0)
; template <class Epi>
; DEV void gemm_phase(LAS unsigned char* lds, const Gemm g, const StaticOrder& S, const Epi& E) {
;     ...
;             PG8_WAIT_V(6); PG8_BAR; PG8_MMA(1, 1, At, B1); PG8_BAR;
;             PG8_LDB(B0, 1, 0); PG8_SCHED; PG8_LDA(At, 1, 0); PG8_STAGE(PG8_SA(0, 1), a2 + hstep, voffA);
;             PG8_WAIT_L(8); PG8_BAR; PG8_WAIT_L(0); PG8_MMA(0, 0, At, B0); PG8_BAR; PG8_SCHED;
;             PG8_LDB(B1, 1, 1); PG8_STAGE(PG8_SB(1, 0), b3, voffB);
;             PG8_BAR; PG8_WAIT_L(0); PG8_MMA(0, 1, At, B1); PG8_BAR;
;             PG8_LDA(At, 1, 1); PG8_STAGE(PG8_SA(1, 0), a3, voffA);
;             PG8_BAR; PG8_WAIT_L(0); PG8_MMA(1, 0, At, B0); PG8_BAR; PG8_SCHED;
;             PG8_STAGE(PG8_SB(1, 1), b3 + hstep, voffB);
	v_mfma_f32_16x16x32_bf16 v[52:55], v[222:225], v[154:157], v[52:55]
	v_mfma_f32_16x16x32_bf16 v[48:51], v[230:233], v[154:157], v[48:51]
	v_mfma_f32_16x16x32_bf16 v[36:39], v[222:225], v[182:185], v[36:39]
	v_mfma_f32_16x16x32_bf16 v[32:35], v[230:233], v[182:185], v[32:35]
	v_mfma_f32_16x16x32_bf16 v[20:23], v[222:225], v[190:193], v[20:23]
	v_mfma_f32_16x16x32_bf16 v[16:19], v[230:233], v[190:193], v[16:19]
	v_mfma_f32_16x16x32_bf16 v[4:7], v[222:225], v[214:217], v[4:7]
	v_mfma_f32_16x16x32_bf16 v[0:3], v[230:233], v[214:217], v[0:3]
	v_mfma_f32_16x16x32_bf16 v[52:55], v[226:229], v[174:177], v[52:55]
	v_mfma_f32_16x16x32_bf16 v[48:51], v[234:237], v[174:177], v[48:51]
	v_mfma_f32_16x16x32_bf16 v[36:39], v[226:229], v[186:189], v[36:39]
	v_mfma_f32_16x16x32_bf16 v[32:35], v[234:237], v[186:189], v[32:35]
	v_mfma_f32_16x16x32_bf16 v[20:23], v[226:229], v[194:197], v[20:23]
	v_mfma_f32_16x16x32_bf16 v[16:19], v[234:237], v[194:197], v[16:19]
	v_mfma_f32_16x16x32_bf16 v[4:7], v[226:229], v[218:221], v[4:7]
	v_mfma_f32_16x16x32_bf16 v[0:3], v[234:237], v[218:221], v[0:3]
	s_add_i32 s49, 0, 0x18000
	v_add_u32_e32 v140, s49, v178
	s_barrier
	ds_read_b128 v[128:131], v140
	ds_read_b128 v[132:135], v140 offset:1024
	ds_read_b128 v[136:139], v140 offset:2048
	ds_read_b128 v[140:143], v140 offset:3072
	s_add_u32 s30, s30, 0x80000
	s_addc_u32 s31, s31, 0
	s_mov_b32 m0, s39
	ds_read_b128 v[154:157], v181 offset:32768
	ds_read_b128 v[174:177], v181 offset:33792
	ds_read_b128 v[182:185], v181 offset:34816
	ds_read_b128 v[186:189], v181 offset:35840
	ds_read_b128 v[190:193], v181 offset:36864
	ds_read_b128 v[194:197], v181 offset:37888
	ds_read_b128 v[214:217], v181 offset:38912
	ds_read_b128 v[218:221], v181 offset:39936
	global_load_lds_dwordx4 v144, s[30:31]
	s_mov_b32 m0, s40
	s_nop 0
	global_load_lds_dwordx4 v146, s[30:31]
	s_waitcnt lgkmcnt(8)
	s_barrier
	s_waitcnt lgkmcnt(0)
	v_mfma_f32_16x16x32_bf16 v[124:127], v[128:131], v[154:157], v[124:127]
	v_mfma_f32_16x16x32_bf16 v[120:123], v[136:139], v[154:157], v[120:123]
	v_mfma_f32_16x16x32_bf16 v[108:111], v[128:131], v[182:185], v[108:111]
	v_mfma_f32_16x16x32_bf16 v[104:107], v[136:139], v[182:185], v[104:107]
	v_mfma_f32_16x16x32_bf16 v[92:95], v[128:131], v[190:193], v[92:95]
	v_mfma_f32_16x16x32_bf16 v[88:91], v[136:139], v[190:193], v[88:91]
	v_mfma_f32_16x16x32_bf16 v[76:79], v[128:131], v[214:217], v[76:79]
	v_mfma_f32_16x16x32_bf16 v[72:75], v[136:139], v[214:217], v[72:75]
	v_mfma_f32_16x16x32_bf16 v[124:127], v[132:135], v[174:177], v[124:127]
	v_mfma_f32_16x16x32_bf16 v[120:123], v[140:143], v[174:177], v[120:123]
	v_mfma_f32_16x16x32_bf16 v[108:111], v[132:135], v[186:189], v[108:111]
	v_mfma_f32_16x16x32_bf16 v[104:107], v[140:143], v[186:189], v[104:107]
	v_mfma_f32_16x16x32_bf16 v[92:95], v[132:135], v[194:197], v[92:95]
	v_mfma_f32_16x16x32_bf16 v[88:91], v[140:143], v[194:197], v[88:91]
	v_mfma_f32_16x16x32_bf16 v[76:79], v[132:135], v[218:221], v[76:79]
	v_mfma_f32_16x16x32_bf16 v[72:75], v[140:143], v[218:221], v[72:75]
	s_barrier
	s_add_i32 s30, 0, 0x1c000
	s_add_i32 s31, s49, s36
	v_add_u32_e32 v234, s30, v178
	v_lshl_add_u64 v[158:159], v[158:159], 0, s[2:3]
	s_mov_b32 m0, s31
	ds_read_b128 v[222:225], v234
	ds_read_b128 v[226:229], v234 offset:1024
	ds_read_b128 v[230:233], v234 offset:2048
	ds_read_b128 v[234:237], v234 offset:3072
	global_load_lds_dwordx4 v[158:159], off
	v_lshl_add_u64 v[158:159], v[238:239], 0, s[2:3]
	s_add_i32 m0, s31, 0x2000
	s_nop 0
	global_load_lds_dwordx4 v[158:159], off
	s_barrier
	s_waitcnt lgkmcnt(0)
	v_mfma_f32_16x16x32_bf16 v[116:119], v[222:225], v[154:157], v[116:119]
	v_mfma_f32_16x16x32_bf16 v[112:115], v[230:233], v[154:157], v[112:115]
	v_mfma_f32_16x16x32_bf16 v[100:103], v[222:225], v[182:185], v[100:103]
	v_mfma_f32_16x16x32_bf16 v[96:99], v[230:233], v[182:185], v[96:99]
	v_mfma_f32_16x16x32_bf16 v[84:87], v[222:225], v[190:193], v[84:87]
	v_mfma_f32_16x16x32_bf16 v[80:83], v[230:233], v[190:193], v[80:83]
	v_mfma_f32_16x16x32_bf16 v[68:71], v[222:225], v[214:217], v[68:71]
	v_mfma_f32_16x16x32_bf16 v[64:67], v[230:233], v[214:217], v[64:67]
	v_mfma_f32_16x16x32_bf16 v[116:119], v[226:229], v[174:177], v[116:119]
	v_mfma_f32_16x16x32_bf16 v[112:115], v[234:237], v[174:177], v[112:115]
	v_mfma_f32_16x16x32_bf16 v[100:103], v[226:229], v[186:189], v[100:103]
	v_mfma_f32_16x16x32_bf16 v[96:99], v[234:237], v[186:189], v[96:99]
	v_mfma_f32_16x16x32_bf16 v[84:87], v[226:229], v[194:197], v[84:87]
	v_mfma_f32_16x16x32_bf16 v[80:83], v[234:237], v[194:197], v[80:83]
	v_mfma_f32_16x16x32_bf16 v[68:71], v[226:229], v[218:221], v[68:71]
	v_mfma_f32_16x16x32_bf16 v[64:67], v[234:237], v[218:221], v[64:67]
	s_mov_b32 m0, s41
	v_lshl_add_u64 v[158:159], v[240:241], 0, s[2:3]
	s_barrier
	ds_read_b128 v[154:157], v181 offset:49152
	ds_read_b128 v[174:177], v181 offset:50176
	ds_read_b128 v[182:185], v181 offset:51200
	ds_read_b128 v[186:189], v181 offset:52224
	ds_read_b128 v[190:193], v181 offset:53248
	ds_read_b128 v[194:197], v181 offset:54272
	ds_read_b128 v[214:217], v181 offset:55296
	ds_read_b128 v[218:221], v181 offset:56320
	global_load_lds_dwordx4 v[158:159], off
	v_lshl_add_u64 v[158:159], v[242:243], 0, s[2:3]
	s_mov_b32 m0, s42
	s_nop 0
	global_load_lds_dwordx4 v[158:159], off
	s_barrier
; DEV bf16x8 pack8(f32x4 a, f32x4 b) { u32x4 w; w.x = cvt_pk_bf16(a[0], a[1]); w.y = cvt_pk_bf16(a[2], a[3]); w.z = cvt_pk_bf16(b[0], b[1]); w.w = cvt_pk_bf16(b[2], b[3]); return __builtin_bit_cast(bf16x8, w); }
; #define PG8_WAIT_V(n) asm volatile("s_waitcnt vmcnt(" #n ")" ::: "memory")
; #define PG8_WAIT_L(n) asm volatile("s_waitcnt lgkmcnt(" #n ")" ::: "memory")
; #define PG8_BAR __builtin_amdgcn_s_barrier()
; template <class Epi>
; DEV void gemm_phase(LAS unsigned char* lds, const Gemm g, const StaticOrder& S, const Epi& E) {
;     ...
;             PG8_BAR; PG8_WAIT_L(0); PG8_MMA(1, 0, At, B0); PG8_BAR; PG8_SCHED;
;             PG8_STAGE(PG8_SB(1, 1), b3 + hstep, voffB);
;             PG8_WAIT_V(6); PG8_BAR; PG8_MMA(1, 1, At, B1); PG8_BAR;
;         }
;     DEV void operator()(AccRef acc, const pg8::Unit& u, int wr, int wc, int fr, int fq) const {
;         const int row0 = u.pm * 256 + wr * 64 + fr, col0 = u.pn * 256 + wc * 32 + 8 * fq;
; #pragma unroll
;         for (int am = 0; am < 4; ++am) { const int ai = am >> 1, m0 = (am & 1) * 2;
;             f32x4 bv[4][2][2];
; #pragma unroll
;             for (int m = m0; m < m0 + 2; ++m)
; #pragma unroll
;                 for (int bj = 0; bj < 2; ++bj)
; #pragma unroll
;                     for (int n = 0; n < 2; ++n) bv[m][bj][n] = *(const f32x4*)(base + (size_t)(row0 + ai * 128 + m * 16) * 2048 + col0 + bj * 128 + n * 4);
; #pragma unroll
;             for (int m = m0; m < m0 + 2; ++m) { const size_t off = (size_t)(row0 + ai * 128 + m * 16) * 2048 + col0; float sq = 0.f;
; #pragma unroll
;                 for (int bj = 0; bj < 2; ++bj) { const f32x4 o0 = bv[m][bj][0] + scale * acc[ai][bj][m][0], o1 = bv[m][bj][1] + scale * acc[ai][bj][m][1];
;                     *(f32x4*)(out + off + bj * 128) = o0; *(f32x4*)(out + off + bj * 128 + 4) = o1;
;                     if (xb) { *(u32x4*)(xb + off + bj * 128) = __builtin_bit_cast(u32x4, pack8(o0, o1));
;                         sq += (o0[0] * o0[0] + o0[1] * o0[1] + o0[2] * o0[2] + o0[3] * o0[3]) + (o1[0] * o1[0] + o1[1] * o1[1] + o1[2] * o1[2] + o1[3] * o1[3]); } }
;                 if (ssout) { sq += __shfl_xor(sq, 16); sq += __shfl_xor(sq, 32);
;                     if (fq == 0) { if (red) red[(ai * 128 + wr * 64 + m * 16 + fr) * 4 + wc] = sq; else atomicAdd(ssout + (size_t)(row0 + ai * 128 + m * 16) * 8 + u.pn, sq); } } }
	s_waitcnt lgkmcnt(0)
	v_mfma_f32_16x16x32_bf16 v[60:63], v[128:131], v[154:157], v[60:63]
	v_mfma_f32_16x16x32_bf16 v[56:59], v[136:139], v[154:157], v[56:59]
	v_mfma_f32_16x16x32_bf16 v[44:47], v[128:131], v[182:185], v[44:47]
	v_mfma_f32_16x16x32_bf16 v[40:43], v[136:139], v[182:185], v[40:43]
	v_mfma_f32_16x16x32_bf16 v[28:31], v[128:131], v[190:193], v[28:31]
	v_mfma_f32_16x16x32_bf16 v[24:27], v[136:139], v[190:193], v[24:27]
	v_mfma_f32_16x16x32_bf16 v[12:15], v[128:131], v[214:217], v[12:15]
	v_mfma_f32_16x16x32_bf16 v[8:11], v[136:139], v[214:217], v[8:11]
	v_mfma_f32_16x16x32_bf16 v[60:63], v[132:135], v[174:177], v[60:63]
	v_mfma_f32_16x16x32_bf16 v[56:59], v[140:143], v[174:177], v[56:59]
	v_mfma_f32_16x16x32_bf16 v[44:47], v[132:135], v[186:189], v[44:47]
	v_mfma_f32_16x16x32_bf16 v[40:43], v[140:143], v[186:189], v[40:43]
	v_mfma_f32_16x16x32_bf16 v[28:31], v[132:135], v[194:197], v[28:31]
	v_mfma_f32_16x16x32_bf16 v[24:27], v[140:143], v[194:197], v[24:27]
	v_mfma_f32_16x16x32_bf16 v[12:15], v[132:135], v[218:221], v[12:15]
	v_mfma_f32_16x16x32_bf16 v[8:11], v[140:143], v[218:221], v[8:11]
	s_barrier
	s_add_u32 s28, s28, 0x80080
	s_addc_u32 s29, s29, 0
	s_add_i32 s30, s30, s36
	s_mov_b32 m0, s30
	s_nop 0
	global_load_lds_dwordx4 v160, s[28:29]
	s_add_i32 m0, s30, 0x2000
	s_nop 0
	global_load_lds_dwordx4 v148, s[28:29]
	s_waitcnt vmcnt(6)
	s_barrier
	v_mfma_f32_16x16x32_bf16 v[52:55], v[222:225], v[154:157], v[52:55]
	v_mfma_f32_16x16x32_bf16 v[48:51], v[230:233], v[154:157], v[48:51]
	v_mfma_f32_16x16x32_bf16 v[36:39], v[222:225], v[182:185], v[36:39]
	v_mfma_f32_16x16x32_bf16 v[32:35], v[230:233], v[182:185], v[32:35]
	v_mfma_f32_16x16x32_bf16 v[20:23], v[222:225], v[190:193], v[20:23]
	v_mfma_f32_16x16x32_bf16 v[16:19], v[230:233], v[190:193], v[16:19]
	v_mfma_f32_16x16x32_bf16 v[4:7], v[222:225], v[214:217], v[4:7]
	v_mfma_f32_16x16x32_bf16 v[0:3], v[230:233], v[214:217], v[0:3]
	v_mfma_f32_16x16x32_bf16 v[52:55], v[226:229], v[174:177], v[52:55]
	v_mfma_f32_16x16x32_bf16 v[48:51], v[234:237], v[174:177], v[48:51]
	v_mfma_f32_16x16x32_bf16 v[36:39], v[226:229], v[186:189], v[36:39]
	v_mfma_f32_16x16x32_bf16 v[32:35], v[234:237], v[186:189], v[32:35]
	v_mfma_f32_16x16x32_bf16 v[20:23], v[226:229], v[194:197], v[20:23]
	v_mfma_f32_16x16x32_bf16 v[16:19], v[234:237], v[194:197], v[16:19]
	v_mfma_f32_16x16x32_bf16 v[4:7], v[226:229], v[218:221], v[4:7]
	v_mfma_f32_16x16x32_bf16 v[0:3], v[234:237], v[218:221], v[0:3]
	s_add_i32 s48, s48, 2
	s_add_u32 s26, s26, 0x100
	s_addc_u32 s27, s27, 0
	s_add_u32 s46, s46, 0x100
	s_addc_u32 s47, s47, 0
	s_cmp_gt_u32 s48, 29
	s_barrier
	s_cbranch_scc0 .LBB0_61
	v_lshl_add_u32 v156, s24, 8, v167
	v_lshl_or_b32 v154, s14, 8, v179
	v_readlane_b32 s24, v254, 16
	v_ashrrev_i32_e32 v155, 31, v154
	v_readlane_b32 s25, v254, 17
	v_ashrrev_i32_e32 v157, 31, v156
	v_lshlrev_b64 v[128:129], 13, v[156:157]
	v_lshl_add_u64 v[158:159], v[154:155], 2, s[24:25]
	v_lshl_add_u64 v[214:215], v[158:159], 0, v[128:129]
	global_load_dwordx4 v[182:185], v[214:215], off offset:16
	global_load_dwordx4 v[186:189], v[214:215], off
	global_load_dwordx4 v[190:193], v[214:215], off offset:528
	global_load_dwordx4 v[194:197], v[214:215], off offset:512
	v_or_b32_e32 v174, 16, v156
	v_ashrrev_i32_e32 v175, 31, v174
	v_lshlrev_b64 v[128:129], 13, v[174:175]
	v_lshl_add_u64 v[176:177], v[158:159], 0, v[128:129]
	global_load_dwordx4 v[136:139], v[176:177], off offset:16
	global_load_dwordx4 v[140:143], v[176:177], off
	global_load_dwordx4 v[128:131], v[176:177], off offset:528
	global_load_dwordx4 v[132:135], v[176:177], off offset:512
	v_lshlrev_b64 v[216:217], 11, v[156:157]
	v_readlane_b32 s24, v250, 9
	v_lshl_add_u64 v[216:217], v[216:217], 0, v[154:155]
	v_readlane_b32 s25, v250, 10
	v_cmp_lt_i32_e32 vcc, v208, v206
	s_ashr_i32 s15, s14, 31
	s_waitcnt vmcnt(0)
	v_pk_add_f32 v[120:121], v[120:121], v[182:183]
	v_pk_add_f32 v[126:127], v[126:127], v[188:189]
	v_pk_add_f32 v[124:125], v[124:125], v[186:187]
	v_pk_add_f32 v[122:123], v[122:123], v[184:185]
	global_store_dwordx4 v[214:215], v[124:127], off
	global_store_dwordx4 v[214:215], v[120:123], off offset:16
	v_cvt_pk_bf16_f32 v184, v120, v121
	v_cvt_pk_bf16_f32 v182, v124, v125
	v_mul_f32_e32 v121, v121, v121
	v_cvt_pk_bf16_f32 v183, v126, v127
	v_cvt_pk_bf16_f32 v185, v122, v123
	v_lshl_add_u64 v[186:187], v[216:217], 1, s[24:25]
	v_fmac_f32_e32 v121, v120, v120
	v_pk_add_f32 v[118:119], v[118:119], v[196:197]
	v_pk_add_f32 v[116:117], v[116:117], v[194:195]
	v_pk_add_f32 v[112:113], v[112:113], v[190:191]
	global_store_dwordx4 v[186:187], v[182:185], off
	v_mul_f32_e32 v125, v125, v125
	v_fmac_f32_e32 v121, v122, v122
	v_pk_add_f32 v[114:115], v[114:115], v[192:193]
	global_store_dwordx4 v[214:215], v[116:119], off offset:512
	global_store_dwordx4 v[214:215], v[112:115], off offset:528
	v_cvt_pk_bf16_f32 v120, v116, v117
	v_cvt_pk_bf16_f32 v122, v112, v113
	v_mul_f32_e32 v117, v117, v117
	v_mul_f32_e32 v113, v113, v113
	v_fmac_f32_e32 v125, v124, v124
	v_fmac_f32_e32 v117, v116, v116
	v_fmac_f32_e32 v113, v112, v112
	v_fmac_f32_e32 v125, v126, v126
	v_fmac_f32_e32 v117, v118, v118
	v_fmac_f32_e32 v113, v114, v114
	v_fmac_f32_e32 v125, v127, v127
	v_fmac_f32_e32 v121, v123, v123
	v_fmac_f32_e32 v117, v119, v119
	v_fmac_f32_e32 v113, v115, v115
	v_add_f32_e32 v124, v125, v121
	v_add_f32_e32 v112, v117, v113
	v_cndmask_b32_e32 v113, v204, v208, vcc
	v_cvt_pk_bf16_f32 v121, v118, v119
	v_add_f32_e32 v112, v124, v112
	v_lshlrev_b32_e32 v118, 2, v113
	ds_bpermute_b32 v113, v118, v112
	v_cmp_lt_i32_e32 vcc, v207, v206
	v_cvt_pk_bf16_f32 v123, v114, v115
	global_store_dwordx4 v[186:187], v[120:123], off offset:256
	s_waitcnt lgkmcnt(0)
	v_add_f32_e32 v112, v112, v113
	v_cndmask_b32_e32 v113, v204, v207, vcc
	v_lshlrev_b32_e32 v119, 2, v113
	ds_bpermute_b32 v113, v119, v112
	s_and_saveexec_b64 s[24:25], s[6:7]
	s_cbranch_execz .LBB0_67
	s_waitcnt lgkmcnt(0)
	v_add_f32_e32 v112, v112, v113
	s_mov_b64 s[26:27], -1
	s_and_b64 vcc, exec, s[12:13]
	s_cbranch_vccz .LBB0_65
	v_readlane_b32 s26, v250, 37
	v_lshlrev_b64 v[114:115], 5, v[156:157]
	v_readlane_b32 s27, v250, 38
	s_nop 1
	v_lshl_add_u64 v[114:115], s[26:27], 0, v[114:115]
	v_lshl_add_u64 v[114:115], s[14:15], 2, v[114:115]
	global_atomic_add_f32 v[114:115], v112, off
	s_mov_b64 s[26:27], 0

; #define PG8_STAGE(bufoff, gbase, voff) do { _Pragma("unroll") for (int _i = 0; _i < 2; ++_i) \
;         __builtin_amdgcn_global_load_lds((const unsigned*)((const char*)(gbase) + (voff)[_i]), (LAS unsigned*)(lds + (bufoff) + ldsw + _i * 8192), 16, 0, 0); } while (0)
; #define PG8_LDA(dst, b, h) do { _Pragma("unroll") for (int m = 0; m < 4; ++m) _Pragma("unroll") for (int k = 0; k < 2; ++k) dst[m][k] = *(const LAS bf16x8*)(lds + PG8_SA(b, h) + aoff + m * 2048 + k * 1024); } while (0)
; #define PG8_LDB(dst, b, h) do { _Pragma("unroll") for (int n = 0; n < 2; ++n) _Pragma("unroll") for (int k = 0; k < 2; ++k) dst[n][k] = *(const LAS bf16x8*)(lds + PG8_SB(b, h) + boff + n * 2048 + k * 1024); } while (0)
; #define PG8_WAIT_V(n) asm volatile("s_waitcnt vmcnt(" #n ")" ::: "memory")
; #define PG8_WAIT_L(n) asm volatile("s_waitcnt lgkmcnt(" #n ")" ::: "memory")
; #define PG8_BAR __builtin_amdgcn_s_barrier()
; template <class Epi>
; DEV void gemm_phase(LAS unsigned char* lds, const Gemm g, const StaticOrder& S, const Epi& E) {
;     ...
;         for (int t = 0; t < nt; t += 2) {
;             const bool last = (t == nt - 2);
;             const char* a1 = cA + (size_t)(t + 1) * kstep;
;             const char* a2 = last ? nA : cA + (size_t)(t + 2) * kstep; const char* b2 = last ? nB : cB + (size_t)(t + 2) * kstep;
;             const char* a3 = a2 + kstep; const char* b3 = b2 + kstep;
;             PG8_LDB(B0, 0, 0); PG8_SCHED; PG8_LDA(At, 0, 0); PG8_STAGE(PG8_SA(1, 1), a1 + hstep, voffA);
;             PG8_WAIT_L(8); PG8_BAR; PG8_WAIT_L(0); PG8_MMA(0, 0, At, B0); PG8_BAR; PG8_SCHED;
;             PG8_LDB(B1, 0, 1); PG8_STAGE(PG8_SB(0, 0), b2, voffB);
;             PG8_BAR; PG8_WAIT_L(0); PG8_MMA(0, 1, At, B1); PG8_BAR;
;             PG8_LDA(At, 0, 1); PG8_STAGE(PG8_SA(0, 0), a2, voffA);
;             PG8_BAR; PG8_WAIT_L(0); PG8_MMA(1, 0, At, B0); PG8_BAR; PG8_SCHED;
;             PG8_STAGE(PG8_SB(0, 1), b2 + hstep, voffB);
;             PG8_WAIT_V(6); PG8_BAR; PG8_MMA(1, 1, At, B1); PG8_BAR;
;             PG8_LDB(B0, 1, 0); PG8_SCHED; PG8_LDA(At, 1, 0); PG8_STAGE(PG8_SA(0, 1), a2 + hstep, voffA);
;             PG8_WAIT_L(8); PG8_BAR; PG8_WAIT_L(0); PG8_MMA(0, 0, At, B0); PG8_BAR; PG8_SCHED;
;             PG8_LDB(B1, 1, 1); PG8_STAGE(PG8_SB(1, 0), b3, voffB);
;             PG8_BAR; PG8_WAIT_L(0); PG8_MMA(0, 1, At, B1); PG8_BAR;
.LBB0_152:
	s_add_u32 s20, s18, 0xfff80080
	s_addc_u32 s21, s19, -1
	s_add_i32 s41, 0, 0x10000
	v_add_u32_e32 v140, s41, v176
	ds_read_b128 v[128:131], v140
	ds_read_b128 v[132:135], v140 offset:1024
	ds_read_b128 v[136:139], v140 offset:2048
	ds_read_b128 v[140:143], v140 offset:3072
	s_cmp_eq_u32 s40, 28
	s_cselect_b32 s23, s5, s21
	s_cselect_b32 s22, s11, s20
	s_cselect_b32 s21, s9, s39
	s_cselect_b32 s20, s37, s38
	s_add_i32 m0, s17, 0xc000
	ds_read_b128 v[180:183], v178
	ds_read_b128 v[184:187], v178 offset:1024
	ds_read_b128 v[188:191], v178 offset:2048
	ds_read_b128 v[192:195], v178 offset:3072
	ds_read_b128 v[214:217], v178 offset:4096
	ds_read_b128 v[218:221], v178 offset:5120
	ds_read_b128 v[222:225], v178 offset:6144
	ds_read_b128 v[226:229], v178 offset:7168
	global_load_lds_dwordx4 v154, s[18:19]
	s_add_i32 m0, s17, 0xe000
	s_nop 0
	global_load_lds_dwordx4 v156, s[18:19]
	s_waitcnt lgkmcnt(8)
	s_barrier
	s_waitcnt lgkmcnt(0)
	v_mfma_f32_16x16x32_bf16 v[124:127], v[128:131], v[180:183], v[124:127]
	v_mfma_f32_16x16x32_bf16 v[120:123], v[136:139], v[180:183], v[120:123]
	v_mfma_f32_16x16x32_bf16 v[108:111], v[128:131], v[188:191], v[108:111]
	v_mfma_f32_16x16x32_bf16 v[104:107], v[136:139], v[188:191], v[104:107]
	v_mfma_f32_16x16x32_bf16 v[92:95], v[128:131], v[214:217], v[92:95]
	v_mfma_f32_16x16x32_bf16 v[88:91], v[136:139], v[214:217], v[88:91]
	v_mfma_f32_16x16x32_bf16 v[76:79], v[128:131], v[222:225], v[76:79]
	v_mfma_f32_16x16x32_bf16 v[72:75], v[136:139], v[222:225], v[72:75]
	v_mfma_f32_16x16x32_bf16 v[124:127], v[132:135], v[184:187], v[124:127]
	v_mfma_f32_16x16x32_bf16 v[120:123], v[140:143], v[184:187], v[120:123]
	v_mfma_f32_16x16x32_bf16 v[108:111], v[132:135], v[192:195], v[108:111]
	v_mfma_f32_16x16x32_bf16 v[104:107], v[140:143], v[192:195], v[104:107]
	v_mfma_f32_16x16x32_bf16 v[92:95], v[132:135], v[218:221], v[92:95]
	v_mfma_f32_16x16x32_bf16 v[88:91], v[140:143], v[218:221], v[88:91]
	v_mfma_f32_16x16x32_bf16 v[76:79], v[132:135], v[226:229], v[76:79]
	v_mfma_f32_16x16x32_bf16 v[72:75], v[140:143], v[226:229], v[72:75]
	s_barrier
	s_add_i32 s44, 0, 0x14000
	v_add_u32_e32 v158, s44, v176
	s_add_i32 s41, s41, s26
	ds_read_b128 v[230:233], v158
	ds_read_b128 v[234:237], v158 offset:1024
	ds_read_b128 v[238:241], v158 offset:2048
	ds_read_b128 v[242:245], v158 offset:3072
	v_lshl_add_u64 v[158:159], s[20:21], 0, v[160:161]
	s_mov_b32 m0, s41
	v_lshl_add_u64 v[174:175], s[20:21], 0, v[144:145]
	global_load_lds_dwordx4 v160, s[20:21]
	s_add_i32 m0, s41, 0x2000
	s_nop 0
	global_load_lds_dwordx4 v144, s[20:21]
	s_barrier
	s_waitcnt lgkmcnt(0)
	v_mfma_f32_16x16x32_bf16 v[116:119], v[230:233], v[180:183], v[116:119]
	v_mfma_f32_16x16x32_bf16 v[112:115], v[238:241], v[180:183], v[112:115]
	v_mfma_f32_16x16x32_bf16 v[100:103], v[230:233], v[188:191], v[100:103]
	v_mfma_f32_16x16x32_bf16 v[96:99], v[238:241], v[188:191], v[96:99]
	v_mfma_f32_16x16x32_bf16 v[84:87], v[230:233], v[214:217], v[84:87]
	v_mfma_f32_16x16x32_bf16 v[80:83], v[238:241], v[214:217], v[80:83]
	v_mfma_f32_16x16x32_bf16 v[68:71], v[230:233], v[222:225], v[68:71]
	v_mfma_f32_16x16x32_bf16 v[64:67], v[238:241], v[222:225], v[64:67]
	v_mfma_f32_16x16x32_bf16 v[116:119], v[234:237], v[184:187], v[116:119]
	v_mfma_f32_16x16x32_bf16 v[112:115], v[242:245], v[184:187], v[112:115]
	v_mfma_f32_16x16x32_bf16 v[100:103], v[234:237], v[192:195], v[100:103]
	v_mfma_f32_16x16x32_bf16 v[96:99], v[242:245], v[192:195], v[96:99]
	v_mfma_f32_16x16x32_bf16 v[84:87], v[234:237], v[218:221], v[84:87]
	v_mfma_f32_16x16x32_bf16 v[80:83], v[242:245], v[218:221], v[80:83]
	v_mfma_f32_16x16x32_bf16 v[68:71], v[234:237], v[226:229], v[68:71]
	v_mfma_f32_16x16x32_bf16 v[64:67], v[242:245], v[226:229], v[64:67]
	s_mov_b32 m0, s17
	v_lshl_add_u64 v[196:197], s[22:23], 0, v[160:161]
	s_barrier
	ds_read_b128 v[180:183], v178 offset:16384
	ds_read_b128 v[184:187], v178 offset:17408
	ds_read_b128 v[188:191], v178 offset:18432
	ds_read_b128 v[192:195], v178 offset:19456
	ds_read_b128 v[214:217], v178 offset:20480
	ds_read_b128 v[218:221], v178 offset:21504
	ds_read_b128 v[222:225], v178 offset:22528
	ds_read_b128 v[226:229], v178 offset:23552
	global_load_lds_dwordx4 v160, s[22:23]
	v_lshl_add_u64 v[246:247], s[22:23], 0, v[144:145]
	s_mov_b32 m0, s27
	s_nop 0
	global_load_lds_dwordx4 v144, s[22:23]
	s_barrier
	s_waitcnt lgkmcnt(0)
	v_mfma_f32_16x16x32_bf16 v[60:63], v[128:131], v[180:183], v[60:63]
	v_mfma_f32_16x16x32_bf16 v[56:59], v[136:139], v[180:183], v[56:59]
	v_mfma_f32_16x16x32_bf16 v[44:47], v[128:131], v[188:191], v[44:47]
	v_mfma_f32_16x16x32_bf16 v[40:43], v[136:139], v[188:191], v[40:43]
	v_mfma_f32_16x16x32_bf16 v[28:31], v[128:131], v[214:217], v[28:31]
	v_mfma_f32_16x16x32_bf16 v[24:27], v[136:139], v[214:217], v[24:27]
	v_mfma_f32_16x16x32_bf16 v[12:15], v[128:131], v[222:225], v[12:15]
	v_mfma_f32_16x16x32_bf16 v[8:11], v[136:139], v[222:225], v[8:11]
	v_mfma_f32_16x16x32_bf16 v[60:63], v[132:135], v[184:187], v[60:63]
	v_mfma_f32_16x16x32_bf16 v[56:59], v[140:143], v[184:187], v[56:59]
	v_mfma_f32_16x16x32_bf16 v[44:47], v[132:135], v[192:195], v[44:47]
	v_mfma_f32_16x16x32_bf16 v[40:43], v[140:143], v[192:195], v[40:43]
	v_mfma_f32_16x16x32_bf16 v[28:31], v[132:135], v[218:221], v[28:31]
	v_mfma_f32_16x16x32_bf16 v[24:27], v[140:143], v[218:221], v[24:27]
	v_mfma_f32_16x16x32_bf16 v[12:15], v[132:135], v[226:229], v[12:15]
	v_mfma_f32_16x16x32_bf16 v[8:11], v[140:143], v[226:229], v[8:11]
	s_barrier
	s_add_u32 s42, s20, 0x80000
	s_addc_u32 s43, s21, 0
	s_add_i32 s41, s44, s26
	s_mov_b32 m0, s41
	s_nop 0
	global_load_lds_dwordx4 v160, s[42:43]
	s_add_i32 m0, s41, 0x2000
	s_nop 0
	global_load_lds_dwordx4 v144, s[42:43]
	s_waitcnt vmcnt(6)
	s_barrier
; #define PG8_STAGE(bufoff, gbase, voff) do { _Pragma("unroll") for (int _i = 0; _i < 2; ++_i) \
;         __builtin_amdgcn_global_load_lds((const unsigned*)((const char*)(gbase) + (voff)[_i]), (LAS unsigned*)(lds + (bufoff) + ldsw + _i * 8192), 16, 0, 0); } while (0)
; #define PG8_LDA(dst, b, h) do { _Pragma("unroll") for (int m = 0; m < 4; ++m) _Pragma("unroll") for (int k = 0; k < 2; ++k) dst[m][k] = *(const LAS bf16x8*)(lds + PG8_SA(b, h) + aoff + m * 2048 + k * 1024); } while (0)
; #define PG8_LDB(dst, b, h) do { _Pragma("unroll") for (int n = 0; n < 2; ++n) _Pragma("unroll") for (int k = 0; k < 2; ++k) dst[n][k] = *(const LAS bf16x8*)(lds + PG8_SB(b, h) + boff + n * 2048 + k * 1024); } while (0)
; #define PG8_MMA(ai, bj, At, Bt) do { __builtin_amdgcn_s_setprio(1); _Pragma("unroll") for (int m = 0; m < 4; ++m) _Pragma("unroll") for (int n = 0; n < 2; ++n) _Pragma("unroll") for (int k = 0; k < 2; ++k) \
;         acc[ai][bj][m][n] = __builtin_amdgcn_mfma_f32_16x16x32_bf16(Bt[n][k], At[m][k], acc[ai][bj][m][n], 0, 0, 0); __builtin_amdgcn_s_setprio(0); } while (0)
; #define PG8_WAIT_V(n) asm volatile("s_waitcnt vmcnt(" #n ")" ::: "memory")
; #define PG8_WAIT_L(n) asm volatile("s_waitcnt lgkmcnt(" #n ")" ::: "memory")
; #define PG8_BAR __builtin_amdgcn_s_barrier()
; #define PG8_SCHED __builtin_amdgcn_sched_barrier(0)
; template <class Epi>
; DEV void gemm_phase(LAS unsigned char* lds, const Gemm g, const StaticOrder& S, const Epi& E) {
;     ...
;             PG8_WAIT_V(6); PG8_BAR; PG8_MMA(1, 1, At, B1); PG8_BAR;
;             PG8_LDB(B0, 1, 0); PG8_SCHED; PG8_LDA(At, 1, 0); PG8_STAGE(PG8_SA(0, 1), a2 + hstep, voffA);
;             PG8_WAIT_L(8); PG8_BAR; PG8_WAIT_L(0); PG8_MMA(0, 0, At, B0); PG8_BAR; PG8_SCHED;
;             PG8_LDB(B1, 1, 1); PG8_STAGE(PG8_SB(1, 0), b3, voffB);
;             PG8_BAR; PG8_WAIT_L(0); PG8_MMA(0, 1, At, B1); PG8_BAR;
;             PG8_LDA(At, 1, 1); PG8_STAGE(PG8_SA(1, 0), a3, voffA);
	v_mfma_f32_16x16x32_bf16 v[52:55], v[230:233], v[180:183], v[52:55]
	v_mfma_f32_16x16x32_bf16 v[48:51], v[238:241], v[180:183], v[48:51]
	v_mfma_f32_16x16x32_bf16 v[36:39], v[230:233], v[188:191], v[36:39]
	v_mfma_f32_16x16x32_bf16 v[32:35], v[238:241], v[188:191], v[32:35]
	v_mfma_f32_16x16x32_bf16 v[20:23], v[230:233], v[214:217], v[20:23]
	v_mfma_f32_16x16x32_bf16 v[16:19], v[238:241], v[214:217], v[16:19]
	v_mfma_f32_16x16x32_bf16 v[4:7], v[230:233], v[222:225], v[4:7]
	v_mfma_f32_16x16x32_bf16 v[0:3], v[238:241], v[222:225], v[0:3]
	v_mfma_f32_16x16x32_bf16 v[52:55], v[234:237], v[184:187], v[52:55]
	v_mfma_f32_16x16x32_bf16 v[48:51], v[242:245], v[184:187], v[48:51]
	v_mfma_f32_16x16x32_bf16 v[36:39], v[234:237], v[192:195], v[36:39]
	v_mfma_f32_16x16x32_bf16 v[32:35], v[242:245], v[192:195], v[32:35]
	v_mfma_f32_16x16x32_bf16 v[20:23], v[234:237], v[218:221], v[20:23]
	v_mfma_f32_16x16x32_bf16 v[16:19], v[242:245], v[218:221], v[16:19]
	v_mfma_f32_16x16x32_bf16 v[4:7], v[234:237], v[226:229], v[4:7]
	v_mfma_f32_16x16x32_bf16 v[0:3], v[242:245], v[226:229], v[0:3]
	s_add_i32 s41, 0, 0x18000
	v_add_u32_e32 v140, s41, v176
	s_barrier
	ds_read_b128 v[128:131], v140
	ds_read_b128 v[132:135], v140 offset:1024
	ds_read_b128 v[136:139], v140 offset:2048
	ds_read_b128 v[140:143], v140 offset:3072
	s_add_u32 s22, s22, 0x80000
	s_addc_u32 s23, s23, 0
	s_mov_b32 m0, s28
	ds_read_b128 v[180:183], v178 offset:32768
	ds_read_b128 v[184:187], v178 offset:33792
	ds_read_b128 v[188:191], v178 offset:34816
	ds_read_b128 v[192:195], v178 offset:35840
	ds_read_b128 v[214:217], v178 offset:36864
	ds_read_b128 v[218:221], v178 offset:37888
	ds_read_b128 v[222:225], v178 offset:38912
	ds_read_b128 v[226:229], v178 offset:39936
	global_load_lds_dwordx4 v160, s[22:23]
	s_mov_b32 m0, s29
	s_nop 0
	global_load_lds_dwordx4 v144, s[22:23]
	s_waitcnt lgkmcnt(8)
	s_barrier
	s_waitcnt lgkmcnt(0)
	v_mfma_f32_16x16x32_bf16 v[124:127], v[128:131], v[180:183], v[124:127]
	v_mfma_f32_16x16x32_bf16 v[120:123], v[136:139], v[180:183], v[120:123]
	v_mfma_f32_16x16x32_bf16 v[108:111], v[128:131], v[188:191], v[108:111]
	v_mfma_f32_16x16x32_bf16 v[104:107], v[136:139], v[188:191], v[104:107]
	v_mfma_f32_16x16x32_bf16 v[92:95], v[128:131], v[214:217], v[92:95]
	v_mfma_f32_16x16x32_bf16 v[88:91], v[136:139], v[214:217], v[88:91]
	v_mfma_f32_16x16x32_bf16 v[76:79], v[128:131], v[222:225], v[76:79]
	v_mfma_f32_16x16x32_bf16 v[72:75], v[136:139], v[222:225], v[72:75]
	v_mfma_f32_16x16x32_bf16 v[124:127], v[132:135], v[184:187], v[124:127]
	v_mfma_f32_16x16x32_bf16 v[120:123], v[140:143], v[184:187], v[120:123]
	v_mfma_f32_16x16x32_bf16 v[108:111], v[132:135], v[192:195], v[108:111]
	v_mfma_f32_16x16x32_bf16 v[104:107], v[140:143], v[192:195], v[104:107]
	v_mfma_f32_16x16x32_bf16 v[92:95], v[132:135], v[218:221], v[92:95]
	v_mfma_f32_16x16x32_bf16 v[88:91], v[140:143], v[218:221], v[88:91]
	v_mfma_f32_16x16x32_bf16 v[76:79], v[132:135], v[226:229], v[76:79]
	v_mfma_f32_16x16x32_bf16 v[72:75], v[140:143], v[226:229], v[72:75]
	s_barrier
	s_add_i32 s22, 0, 0x1c000
	s_add_i32 s23, s41, s26
	v_add_u32_e32 v179, s22, v176
	v_lshl_add_u64 v[158:159], v[158:159], 0, s[2:3]
	s_mov_b32 m0, s23
	ds_read_b128 v[230:233], v179
	ds_read_b128 v[234:237], v179 offset:1024
	ds_read_b128 v[238:241], v179 offset:2048
	ds_read_b128 v[242:245], v179 offset:3072
	global_load_lds_dwordx4 v[158:159], off
	v_lshl_add_u64 v[158:159], v[174:175], 0, s[2:3]
	s_add_i32 m0, s23, 0x2000
	s_nop 0
	global_load_lds_dwordx4 v[158:159], off
	s_barrier
	s_waitcnt lgkmcnt(0)
	v_mfma_f32_16x16x32_bf16 v[116:119], v[230:233], v[180:183], v[116:119]
	v_mfma_f32_16x16x32_bf16 v[112:115], v[238:241], v[180:183], v[112:115]
	v_mfma_f32_16x16x32_bf16 v[100:103], v[230:233], v[188:191], v[100:103]
	v_mfma_f32_16x16x32_bf16 v[96:99], v[238:241], v[188:191], v[96:99]
	v_mfma_f32_16x16x32_bf16 v[84:87], v[230:233], v[214:217], v[84:87]
	v_mfma_f32_16x16x32_bf16 v[80:83], v[238:241], v[214:217], v[80:83]
	v_mfma_f32_16x16x32_bf16 v[68:71], v[230:233], v[222:225], v[68:71]
	v_mfma_f32_16x16x32_bf16 v[64:67], v[238:241], v[222:225], v[64:67]
	v_mfma_f32_16x16x32_bf16 v[116:119], v[234:237], v[184:187], v[116:119]
	v_mfma_f32_16x16x32_bf16 v[112:115], v[242:245], v[184:187], v[112:115]
	v_mfma_f32_16x16x32_bf16 v[100:103], v[234:237], v[192:195], v[100:103]
	v_mfma_f32_16x16x32_bf16 v[96:99], v[242:245], v[192:195], v[96:99]
	v_mfma_f32_16x16x32_bf16 v[84:87], v[234:237], v[218:221], v[84:87]
	v_mfma_f32_16x16x32_bf16 v[80:83], v[242:245], v[218:221], v[80:83]
	v_mfma_f32_16x16x32_bf16 v[68:71], v[234:237], v[226:229], v[68:71]
	v_mfma_f32_16x16x32_bf16 v[64:67], v[242:245], v[226:229], v[64:67]
	s_mov_b32 m0, s30
	v_lshl_add_u64 v[158:159], v[196:197], 0, s[2:3]
	s_barrier
; #define PG8_STAGE(bufoff, gbase, voff) do { _Pragma("unroll") for (int _i = 0; _i < 2; ++_i) \
;         __builtin_amdgcn_global_load_lds((const unsigned*)((const char*)(gbase) + (voff)[_i]), (LAS unsigned*)(lds + (bufoff) + ldsw + _i * 8192), 16, 0, 0); } while (0)
; #define PG8_MMA(ai, bj, At, Bt) do { __builtin_amdgcn_s_setprio(1); _Pragma("unroll") for (int m = 0; m < 4; ++m) _Pragma("unroll") for (int n = 0; n < 2; ++n) _Pragma("unroll") for (int k = 0; k < 2; ++k) \
;         acc[ai][bj][m][n] = __builtin_amdgcn_mfma_f32_16x16x32_bf16(Bt[n][k], At[m][k], acc[ai][bj][m][n], 0, 0, 0); __builtin_amdgcn_s_setprio(0); } while (0)
; #define PG8_WAIT_V(n) asm volatile("s_waitcnt vmcnt(" #n ")" ::: "memory")
; #define PG8_WAIT_L(n) asm volatile("s_waitcnt lgkmcnt(" #n ")" ::: "memory")
; #define PG8_BAR __builtin_amdgcn_s_barrier()
; #define PG8_SCHED __builtin_amdgcn_sched_barrier(0)
; template <class Epi>
; DEV void gemm_phase(LAS unsigned char* lds, const Gemm g, const StaticOrder& S, const Epi& E) {
;     ...
;             PG8_BAR; PG8_WAIT_L(0); PG8_MMA(1, 0, At, B0); PG8_BAR; PG8_SCHED;
;             PG8_STAGE(PG8_SB(1, 1), b3 + hstep, voffB);
;             PG8_WAIT_V(6); PG8_BAR; PG8_MMA(1, 1, At, B1); PG8_BAR;
;     DEV void operator()(AccRef acc, const pg8::Unit& u, int wr, int wc, int fr, int fq) const {
;         const int row0 = u.pm * 256 + wr * 64 + fr, col0 = u.pn * 256 + wc * 32 + 4 * fq;
;         const bool rope = (u.pn < 9) && ((wc & 1) == 0);
; #pragma unroll
;         for (int ai = 0; ai < 2; ++ai)
; #pragma unroll
;             for (int m = 0; m < 4; ++m) { const int row = row0 + ai * 128 + m * 16; u16* rowp = O + (size_t)row * 2560 + col0; const float rs = rowscale(ss, row);
;                 f32x4 cs = (f32x4){1.f, 1.f, 1.f, 1.f}, sn = (f32x4){0.f, 0.f, 0.f, 0.f};
;                 if (rope) { cs = *(const f32x4*)(cosT + row * 8 + 4 * (fq & 1)); sn = *(const f32x4*)(sinT + row * 8 + 4 * (fq & 1)); }
	ds_read_b128 v[180:183], v178 offset:49152
	ds_read_b128 v[184:187], v178 offset:50176
	ds_read_b128 v[188:191], v178 offset:51200
	ds_read_b128 v[192:195], v178 offset:52224
	ds_read_b128 v[214:217], v178 offset:53248
	ds_read_b128 v[218:221], v178 offset:54272
	ds_read_b128 v[222:225], v178 offset:55296
	ds_read_b128 v[226:229], v178 offset:56320
	global_load_lds_dwordx4 v[158:159], off
	v_lshl_add_u64 v[158:159], v[246:247], 0, s[2:3]
	s_mov_b32 m0, s31
	s_nop 0
	global_load_lds_dwordx4 v[158:159], off
	s_barrier
	s_waitcnt lgkmcnt(0)
	v_mfma_f32_16x16x32_bf16 v[60:63], v[128:131], v[180:183], v[60:63]
	v_mfma_f32_16x16x32_bf16 v[56:59], v[136:139], v[180:183], v[56:59]
	v_mfma_f32_16x16x32_bf16 v[44:47], v[128:131], v[188:191], v[44:47]
	v_mfma_f32_16x16x32_bf16 v[40:43], v[136:139], v[188:191], v[40:43]
	v_mfma_f32_16x16x32_bf16 v[28:31], v[128:131], v[214:217], v[28:31]
	v_mfma_f32_16x16x32_bf16 v[24:27], v[136:139], v[214:217], v[24:27]
	v_mfma_f32_16x16x32_bf16 v[12:15], v[128:131], v[222:225], v[12:15]
	v_mfma_f32_16x16x32_bf16 v[8:11], v[136:139], v[222:225], v[8:11]
	v_mfma_f32_16x16x32_bf16 v[60:63], v[132:135], v[184:187], v[60:63]
	v_mfma_f32_16x16x32_bf16 v[56:59], v[140:143], v[184:187], v[56:59]
	v_mfma_f32_16x16x32_bf16 v[44:47], v[132:135], v[192:195], v[44:47]
	v_mfma_f32_16x16x32_bf16 v[40:43], v[140:143], v[192:195], v[40:43]
	v_mfma_f32_16x16x32_bf16 v[28:31], v[132:135], v[218:221], v[28:31]
	v_mfma_f32_16x16x32_bf16 v[24:27], v[140:143], v[218:221], v[24:27]
	v_mfma_f32_16x16x32_bf16 v[12:15], v[132:135], v[226:229], v[12:15]
	v_mfma_f32_16x16x32_bf16 v[8:11], v[140:143], v[226:229], v[8:11]
	s_barrier
	s_add_u32 s20, s20, 0x80080
	s_addc_u32 s21, s21, 0
	s_add_i32 s22, s22, s26
	s_mov_b32 m0, s22
	s_nop 0
	global_load_lds_dwordx4 v160, s[20:21]
	s_add_i32 m0, s22, 0x2000
	s_nop 0
	global_load_lds_dwordx4 v144, s[20:21]
	s_waitcnt vmcnt(6)
	s_barrier
	v_mfma_f32_16x16x32_bf16 v[52:55], v[230:233], v[180:183], v[52:55]
	v_mfma_f32_16x16x32_bf16 v[48:51], v[238:241], v[180:183], v[48:51]
	v_mfma_f32_16x16x32_bf16 v[36:39], v[230:233], v[188:191], v[36:39]
	v_mfma_f32_16x16x32_bf16 v[32:35], v[238:241], v[188:191], v[32:35]
	v_mfma_f32_16x16x32_bf16 v[20:23], v[230:233], v[214:217], v[20:23]
	v_mfma_f32_16x16x32_bf16 v[16:19], v[238:241], v[214:217], v[16:19]
	v_mfma_f32_16x16x32_bf16 v[4:7], v[230:233], v[222:225], v[4:7]
	v_mfma_f32_16x16x32_bf16 v[0:3], v[238:241], v[222:225], v[0:3]
	v_mfma_f32_16x16x32_bf16 v[52:55], v[234:237], v[184:187], v[52:55]
	v_mfma_f32_16x16x32_bf16 v[48:51], v[242:245], v[184:187], v[48:51]
	v_mfma_f32_16x16x32_bf16 v[36:39], v[234:237], v[192:195], v[36:39]
	v_mfma_f32_16x16x32_bf16 v[32:35], v[242:245], v[192:195], v[32:35]
	v_mfma_f32_16x16x32_bf16 v[20:23], v[234:237], v[218:221], v[20:23]
	v_mfma_f32_16x16x32_bf16 v[16:19], v[242:245], v[218:221], v[16:19]
	v_mfma_f32_16x16x32_bf16 v[4:7], v[234:237], v[226:229], v[4:7]
	v_mfma_f32_16x16x32_bf16 v[0:3], v[242:245], v[226:229], v[0:3]
	s_add_i32 s40, s40, 2
	s_add_u32 s18, s18, 0x100
	s_addc_u32 s19, s19, 0
	s_add_u32 s38, s38, 0x100
	s_addc_u32 s39, s39, 0
	s_cmp_gt_u32 s40, 29
	s_barrier
	s_cbranch_scc0 .LBB0_152
	v_lshl_add_u32 v174, s4, 8, v167
	v_ashrrev_i32_e32 v175, 31, v174
	v_readlane_b32 s20, v250, 47
	v_lshlrev_b64 v[128:129], 5, v[174:175]
	v_readlane_b32 s21, v250, 48
	s_cmp_lt_i32 s16, 9
	s_cselect_b64 s[4:5], -1, 0
	v_lshl_add_u64 v[128:129], s[20:21], 0, v[128:129]
	global_load_dwordx4 v[136:139], v[128:129], off offset:16
	global_load_dwordx4 v[140:143], v[128:129], off
	s_and_b64 s[18:19], s[6:7], s[4:5]
	v_cndmask_b32_e64 v128, 0, 1, s[18:19]
	v_cmp_ne_u32_e64 s[4:5], 1, v128
	s_andn2_b64 vcc, exec, s[18:19]
	s_cbranch_vccnz .LBB0_155
	v_lshlrev_b32_e32 v128, 3, v174
	v_ashrrev_i32_e32 v129, 31, v128
	v_lshlrev_b64 v[128:129], 2, v[128:129]
	v_lshl_add_u64 v[130:131], v[152:153], 0, v[128:129]
	v_lshl_add_u64 v[132:133], v[150:151], 0, v[128:129]
	global_load_dwordx4 v[128:131], v[130:131], off
	s_nop 0
	global_load_dwordx4 v[132:135], v[132:133], off
	s_branch .LBB0_156

; #define PG8_STAGE(bufoff, gbase, voff) do { _Pragma("unroll") for (int _i = 0; _i < 2; ++_i) \
;         __builtin_amdgcn_global_load_lds((const unsigned*)((const char*)(gbase) + (voff)[_i]), (LAS unsigned*)(lds + (bufoff) + ldsw + _i * 8192), 16, 0, 0); } while (0)
; #define PG8_LDA(dst, b, h) do { _Pragma("unroll") for (int m = 0; m < 4; ++m) _Pragma("unroll") for (int k = 0; k < 2; ++k) dst[m][k] = *(const LAS bf16x8*)(lds + PG8_SA(b, h) + aoff + m * 2048 + k * 1024); } while (0)
; #define PG8_LDB(dst, b, h) do { _Pragma("unroll") for (int n = 0; n < 2; ++n) _Pragma("unroll") for (int k = 0; k < 2; ++k) dst[n][k] = *(const LAS bf16x8*)(lds + PG8_SB(b, h) + boff + n * 2048 + k * 1024); } while (0)
; #define PG8_MMA(ai, bj, At, Bt) do { __builtin_amdgcn_s_setprio(1); _Pragma("unroll") for (int m = 0; m < 4; ++m) _Pragma("unroll") for (int n = 0; n < 2; ++n) _Pragma("unroll") for (int k = 0; k < 2; ++k) \
;         acc[ai][bj][m][n] = __builtin_amdgcn_mfma_f32_16x16x32_bf16(Bt[n][k], At[m][k], acc[ai][bj][m][n], 0, 0, 0); __builtin_amdgcn_s_setprio(0); } while (0)
; #define PG8_WAIT_V(n) asm volatile("s_waitcnt vmcnt(" #n ")" ::: "memory")
; #define PG8_WAIT_L(n) asm volatile("s_waitcnt lgkmcnt(" #n ")" ::: "memory")
; #define PG8_BAR __builtin_amdgcn_s_barrier()
; #define PG8_SCHED __builtin_amdgcn_sched_barrier(0)
; template <class Epi>
; DEV void gemm_phase(LAS unsigned char* lds, const Gemm g, const StaticOrder& S, const Epi& E) {
;     ...
;             const bool last = (t == nt - 2);
;             const char* a1 = cA + (size_t)(t + 1) * kstep;
;             const char* a2 = last ? nA : cA + (size_t)(t + 2) * kstep; const char* b2 = last ? nB : cB + (size_t)(t + 2) * kstep;
;             const char* a3 = a2 + kstep; const char* b3 = b2 + kstep;
;             PG8_LDB(B0, 0, 0); PG8_SCHED; PG8_LDA(At, 0, 0); PG8_STAGE(PG8_SA(1, 1), a1 + hstep, voffA);
;             PG8_WAIT_L(8); PG8_BAR; PG8_WAIT_L(0); PG8_MMA(0, 0, At, B0); PG8_BAR; PG8_SCHED;
;             PG8_LDB(B1, 0, 1); PG8_STAGE(PG8_SB(0, 0), b2, voffB);
;             PG8_BAR; PG8_WAIT_L(0); PG8_MMA(0, 1, At, B1); PG8_BAR;
;             PG8_LDA(At, 0, 1); PG8_STAGE(PG8_SA(0, 0), a2, voffA);
;             PG8_BAR; PG8_WAIT_L(0); PG8_MMA(1, 0, At, B0); PG8_BAR; PG8_SCHED;
;             PG8_STAGE(PG8_SB(0, 1), b2 + hstep, voffB);
;             PG8_WAIT_V(6); PG8_BAR; PG8_MMA(1, 1, At, B1); PG8_BAR;
.LBB0_260:
	s_add_u32 s34, s30, 0xfffe0080
	s_addc_u32 s35, s31, -1
	s_add_i32 s55, 0, 0x10000
	v_add_u32_e32 v140, s55, v178
	ds_read_b128 v[128:131], v140
	ds_read_b128 v[132:135], v140 offset:1024
	ds_read_b128 v[136:139], v140 offset:2048
	ds_read_b128 v[140:143], v140 offset:3072
	s_cmp_eq_u32 s54, 4
	s_cselect_b32 s37, s19, s35
	s_cselect_b32 s36, s23, s34
	s_cselect_b32 s35, s21, s53
	s_cselect_b32 s34, s29, s52
	s_add_i32 m0, s43, 0xc000
	ds_read_b128 v[154:157], v181
	ds_read_b128 v[174:177], v181 offset:1024
	ds_read_b128 v[182:185], v181 offset:2048
	ds_read_b128 v[186:189], v181 offset:3072
	ds_read_b128 v[190:193], v181 offset:4096
	ds_read_b128 v[194:197], v181 offset:5120
	ds_read_b128 v[214:217], v181 offset:6144
	ds_read_b128 v[218:221], v181 offset:7168
	global_load_lds_dwordx4 v150, s[30:31]
	s_add_i32 m0, s43, 0xe000
	s_nop 0
	global_load_lds_dwordx4 v152, s[30:31]
	s_waitcnt lgkmcnt(8)
	s_barrier
	s_waitcnt lgkmcnt(0)
	v_mfma_f32_16x16x32_bf16 v[124:127], v[128:131], v[154:157], v[124:127]
	v_mfma_f32_16x16x32_bf16 v[120:123], v[136:139], v[154:157], v[120:123]
	v_mfma_f32_16x16x32_bf16 v[108:111], v[128:131], v[182:185], v[108:111]
	v_mfma_f32_16x16x32_bf16 v[104:107], v[136:139], v[182:185], v[104:107]
	v_mfma_f32_16x16x32_bf16 v[92:95], v[128:131], v[190:193], v[92:95]
	v_mfma_f32_16x16x32_bf16 v[88:91], v[136:139], v[190:193], v[88:91]
	v_mfma_f32_16x16x32_bf16 v[76:79], v[128:131], v[214:217], v[76:79]
	v_mfma_f32_16x16x32_bf16 v[72:75], v[136:139], v[214:217], v[72:75]
	v_mfma_f32_16x16x32_bf16 v[124:127], v[132:135], v[174:177], v[124:127]
	v_mfma_f32_16x16x32_bf16 v[120:123], v[140:143], v[174:177], v[120:123]
	v_mfma_f32_16x16x32_bf16 v[108:111], v[132:135], v[186:189], v[108:111]
	v_mfma_f32_16x16x32_bf16 v[104:107], v[140:143], v[186:189], v[104:107]
	v_mfma_f32_16x16x32_bf16 v[92:95], v[132:135], v[194:197], v[92:95]
	v_mfma_f32_16x16x32_bf16 v[88:91], v[140:143], v[194:197], v[88:91]
	v_mfma_f32_16x16x32_bf16 v[76:79], v[132:135], v[218:221], v[76:79]
	v_mfma_f32_16x16x32_bf16 v[72:75], v[140:143], v[218:221], v[72:75]
	s_barrier
	s_add_i32 s58, 0, 0x14000
	v_add_u32_e32 v158, s58, v178
	s_add_i32 s55, s55, s42
	ds_read_b128 v[222:225], v158
	ds_read_b128 v[226:229], v158 offset:1024
	ds_read_b128 v[230:233], v158 offset:2048
	ds_read_b128 v[234:237], v158 offset:3072
	v_lshl_add_u64 v[158:159], s[34:35], 0, v[160:161]
	s_mov_b32 m0, s55
	v_lshl_add_u64 v[238:239], s[34:35], 0, v[148:149]
	global_load_lds_dwordx4 v160, s[34:35]
	s_add_i32 m0, s55, 0x2000
	s_nop 0
	global_load_lds_dwordx4 v148, s[34:35]
	s_barrier
	s_waitcnt lgkmcnt(0)
	v_mfma_f32_16x16x32_bf16 v[116:119], v[222:225], v[154:157], v[116:119]
	v_mfma_f32_16x16x32_bf16 v[112:115], v[230:233], v[154:157], v[112:115]
	v_mfma_f32_16x16x32_bf16 v[100:103], v[222:225], v[182:185], v[100:103]
	v_mfma_f32_16x16x32_bf16 v[96:99], v[230:233], v[182:185], v[96:99]
	v_mfma_f32_16x16x32_bf16 v[84:87], v[222:225], v[190:193], v[84:87]
	v_mfma_f32_16x16x32_bf16 v[80:83], v[230:233], v[190:193], v[80:83]
	v_mfma_f32_16x16x32_bf16 v[68:71], v[222:225], v[214:217], v[68:71]
	v_mfma_f32_16x16x32_bf16 v[64:67], v[230:233], v[214:217], v[64:67]
	v_mfma_f32_16x16x32_bf16 v[116:119], v[226:229], v[174:177], v[116:119]
	v_mfma_f32_16x16x32_bf16 v[112:115], v[234:237], v[174:177], v[112:115]
	v_mfma_f32_16x16x32_bf16 v[100:103], v[226:229], v[186:189], v[100:103]
	v_mfma_f32_16x16x32_bf16 v[96:99], v[234:237], v[186:189], v[96:99]
	v_mfma_f32_16x16x32_bf16 v[84:87], v[226:229], v[194:197], v[84:87]
	v_mfma_f32_16x16x32_bf16 v[80:83], v[234:237], v[194:197], v[80:83]
	v_mfma_f32_16x16x32_bf16 v[68:71], v[226:229], v[218:221], v[68:71]
	v_mfma_f32_16x16x32_bf16 v[64:67], v[234:237], v[218:221], v[64:67]
	s_mov_b32 m0, s43
	v_lshl_add_u64 v[240:241], s[36:37], 0, v[144:145]
	s_barrier
	ds_read_b128 v[154:157], v181 offset:16384
	ds_read_b128 v[174:177], v181 offset:17408
	ds_read_b128 v[182:185], v181 offset:18432
	ds_read_b128 v[186:189], v181 offset:19456
	ds_read_b128 v[190:193], v181 offset:20480
	ds_read_b128 v[194:197], v181 offset:21504
	ds_read_b128 v[214:217], v181 offset:22528
	ds_read_b128 v[218:221], v181 offset:23552
	global_load_lds_dwordx4 v144, s[36:37]
	v_lshl_add_u64 v[242:243], s[36:37], 0, v[146:147]
	s_mov_b32 m0, s44
	s_nop 0
	global_load_lds_dwordx4 v146, s[36:37]
	s_barrier
	s_waitcnt lgkmcnt(0)
	v_mfma_f32_16x16x32_bf16 v[60:63], v[128:131], v[154:157], v[60:63]
	v_mfma_f32_16x16x32_bf16 v[56:59], v[136:139], v[154:157], v[56:59]
	v_mfma_f32_16x16x32_bf16 v[44:47], v[128:131], v[182:185], v[44:47]
	v_mfma_f32_16x16x32_bf16 v[40:43], v[136:139], v[182:185], v[40:43]
	v_mfma_f32_16x16x32_bf16 v[28:31], v[128:131], v[190:193], v[28:31]
	v_mfma_f32_16x16x32_bf16 v[24:27], v[136:139], v[190:193], v[24:27]
	v_mfma_f32_16x16x32_bf16 v[12:15], v[128:131], v[214:217], v[12:15]
	v_mfma_f32_16x16x32_bf16 v[8:11], v[136:139], v[214:217], v[8:11]
	v_mfma_f32_16x16x32_bf16 v[60:63], v[132:135], v[174:177], v[60:63]
	v_mfma_f32_16x16x32_bf16 v[56:59], v[140:143], v[174:177], v[56:59]
	v_mfma_f32_16x16x32_bf16 v[44:47], v[132:135], v[186:189], v[44:47]
	v_mfma_f32_16x16x32_bf16 v[40:43], v[140:143], v[186:189], v[40:43]
	v_mfma_f32_16x16x32_bf16 v[28:31], v[132:135], v[194:197], v[28:31]
	v_mfma_f32_16x16x32_bf16 v[24:27], v[140:143], v[194:197], v[24:27]
	v_mfma_f32_16x16x32_bf16 v[12:15], v[132:135], v[218:221], v[12:15]
	v_mfma_f32_16x16x32_bf16 v[8:11], v[140:143], v[218:221], v[8:11]
	s_barrier
	s_add_u32 s56, s34, 0x20000
	s_addc_u32 s57, s35, 0
	s_add_i32 s55, s58, s42
	s_mov_b32 m0, s55
	s_nop 0
	global_load_lds_dwordx4 v160, s[56:57]
	s_add_i32 m0, s55, 0x2000
	s_nop 0
	global_load_lds_dwordx4 v148, s[56:57]
	s_waitcnt vmcnt(6)
	s_barrier
; #define PG8_STAGE(bufoff, gbase, voff) do { _Pragma("unroll") for (int _i = 0; _i < 2; ++_i) \
;         __builtin_amdgcn_global_load_lds((const unsigned*)((const char*)(gbase) + (voff)[_i]), (LAS unsigned*)(lds + (bufoff) + ldsw + _i * 8192), 16, 0, 0); } while (0)
; #define PG8_LDA(dst, b, h) do { _Pragma("unroll") for (int m = 0; m < 4; ++m) _Pragma("unroll") for (int k = 0; k < 2; ++k) dst[m][k] = *(const LAS bf16x8*)(lds + PG8_SA(b, h) + aoff + m * 2048 + k * 1024); } while (0)
; #define PG8_LDB(dst, b, h) do { _Pragma("unroll") for (int n = 0; n < 2; ++n) _Pragma("unroll") for (int k = 0; k < 2; ++k) dst[n][k] = *(const LAS bf16x8*)(lds + PG8_SB(b, h) + boff + n * 2048 + k * 1024); } while (0)
; #define PG8_MMA(ai, bj, At, Bt) do { __builtin_amdgcn_s_setprio(1); _Pragma("unroll") for (int m = 0; m < 4; ++m) _Pragma("unroll") for (int n = 0; n < 2; ++n) _Pragma("unroll") for (int k = 0; k < 2; ++k) \
;         acc[ai][bj][m][n] = __builtin_amdgcn_mfma_f32_16x16x32_bf16(Bt[n][k], At[m][k], acc[ai][bj][m][n], 0, 0, 0); __builtin_amdgcn_s_setprio(0); } while (0)
; #define PG8_WAIT_V(n) asm volatile("s_waitcnt vmcnt(" #n ")" ::: "memory")
; #define PG8_WAIT_L(n) asm volatile("s_waitcnt lgkmcnt(" #n ")" ::: "memory")
; #define PG8_BAR __builtin_amdgcn_s_barrier()
; #define PG8_SCHED __builtin_amdgcn_sched_barrier(0)
; template <class Epi>
; DEV void gemm_phase(LAS unsigned char* lds, const Gemm g, const StaticOrder& S, const Epi& E) {
;     ...
;             PG8_WAIT_V(6); PG8_BAR; PG8_MMA(1, 1, At, B1); PG8_BAR;
;             PG8_LDB(B0, 1, 0); PG8_SCHED; PG8_LDA(At, 1, 0); PG8_STAGE(PG8_SA(0, 1), a2 + hstep, voffA);
;             PG8_WAIT_L(8); PG8_BAR; PG8_WAIT_L(0); PG8_MMA(0, 0, At, B0); PG8_BAR; PG8_SCHED;
;             PG8_LDB(B1, 1, 1); PG8_STAGE(PG8_SB(1, 0), b3, voffB);
;             PG8_BAR; PG8_WAIT_L(0); PG8_MMA(0, 1, At, B1); PG8_BAR;
;             PG8_LDA(At, 1, 1); PG8_STAGE(PG8_SA(1, 0), a3, voffA);
;             PG8_BAR; PG8_WAIT_L(0); PG8_MMA(1, 0, At, B0); PG8_BAR; PG8_SCHED;
	v_mfma_f32_16x16x32_bf16 v[52:55], v[222:225], v[154:157], v[52:55]
	v_mfma_f32_16x16x32_bf16 v[48:51], v[230:233], v[154:157], v[48:51]
	v_mfma_f32_16x16x32_bf16 v[36:39], v[222:225], v[182:185], v[36:39]
	v_mfma_f32_16x16x32_bf16 v[32:35], v[230:233], v[182:185], v[32:35]
	v_mfma_f32_16x16x32_bf16 v[20:23], v[222:225], v[190:193], v[20:23]
	v_mfma_f32_16x16x32_bf16 v[16:19], v[230:233], v[190:193], v[16:19]
	v_mfma_f32_16x16x32_bf16 v[4:7], v[222:225], v[214:217], v[4:7]
	v_mfma_f32_16x16x32_bf16 v[0:3], v[230:233], v[214:217], v[0:3]
	v_mfma_f32_16x16x32_bf16 v[52:55], v[226:229], v[174:177], v[52:55]
	v_mfma_f32_16x16x32_bf16 v[48:51], v[234:237], v[174:177], v[48:51]
	v_mfma_f32_16x16x32_bf16 v[36:39], v[226:229], v[186:189], v[36:39]
	v_mfma_f32_16x16x32_bf16 v[32:35], v[234:237], v[186:189], v[32:35]
	v_mfma_f32_16x16x32_bf16 v[20:23], v[226:229], v[194:197], v[20:23]
	v_mfma_f32_16x16x32_bf16 v[16:19], v[234:237], v[194:197], v[16:19]
	v_mfma_f32_16x16x32_bf16 v[4:7], v[226:229], v[218:221], v[4:7]
	v_mfma_f32_16x16x32_bf16 v[0:3], v[234:237], v[218:221], v[0:3]
	s_add_i32 s55, 0, 0x18000
	v_add_u32_e32 v140, s55, v178
	s_barrier
	ds_read_b128 v[128:131], v140
	ds_read_b128 v[132:135], v140 offset:1024
	ds_read_b128 v[136:139], v140 offset:2048
	ds_read_b128 v[140:143], v140 offset:3072
	s_add_u32 s36, s36, 0x20000
	s_addc_u32 s37, s37, 0
	s_mov_b32 m0, s45
	ds_read_b128 v[154:157], v181 offset:32768
	ds_read_b128 v[174:177], v181 offset:33792
	ds_read_b128 v[182:185], v181 offset:34816
	ds_read_b128 v[186:189], v181 offset:35840
	ds_read_b128 v[190:193], v181 offset:36864
	ds_read_b128 v[194:197], v181 offset:37888
	ds_read_b128 v[214:217], v181 offset:38912
	ds_read_b128 v[218:221], v181 offset:39936
	global_load_lds_dwordx4 v144, s[36:37]
	s_mov_b32 m0, s46
	s_nop 0
	global_load_lds_dwordx4 v146, s[36:37]
	s_waitcnt lgkmcnt(8)
	s_barrier
	s_waitcnt lgkmcnt(0)
	v_mfma_f32_16x16x32_bf16 v[124:127], v[128:131], v[154:157], v[124:127]
	v_mfma_f32_16x16x32_bf16 v[120:123], v[136:139], v[154:157], v[120:123]
	v_mfma_f32_16x16x32_bf16 v[108:111], v[128:131], v[182:185], v[108:111]
	v_mfma_f32_16x16x32_bf16 v[104:107], v[136:139], v[182:185], v[104:107]
	v_mfma_f32_16x16x32_bf16 v[92:95], v[128:131], v[190:193], v[92:95]
	v_mfma_f32_16x16x32_bf16 v[88:91], v[136:139], v[190:193], v[88:91]
	v_mfma_f32_16x16x32_bf16 v[76:79], v[128:131], v[214:217], v[76:79]
	v_mfma_f32_16x16x32_bf16 v[72:75], v[136:139], v[214:217], v[72:75]
	v_mfma_f32_16x16x32_bf16 v[124:127], v[132:135], v[174:177], v[124:127]
	v_mfma_f32_16x16x32_bf16 v[120:123], v[140:143], v[174:177], v[120:123]
	v_mfma_f32_16x16x32_bf16 v[108:111], v[132:135], v[186:189], v[108:111]
	v_mfma_f32_16x16x32_bf16 v[104:107], v[140:143], v[186:189], v[104:107]
	v_mfma_f32_16x16x32_bf16 v[92:95], v[132:135], v[194:197], v[92:95]
	v_mfma_f32_16x16x32_bf16 v[88:91], v[140:143], v[194:197], v[88:91]
	v_mfma_f32_16x16x32_bf16 v[76:79], v[132:135], v[218:221], v[76:79]
	v_mfma_f32_16x16x32_bf16 v[72:75], v[140:143], v[218:221], v[72:75]
	s_barrier
	s_add_i32 s36, 0, 0x1c000
	s_add_i32 s37, s55, s42
	v_add_u32_e32 v234, s36, v178
	v_lshl_add_u64 v[158:159], v[158:159], 0, s[2:3]
	s_mov_b32 m0, s37
	ds_read_b128 v[222:225], v234
	ds_read_b128 v[226:229], v234 offset:1024
	ds_read_b128 v[230:233], v234 offset:2048
	ds_read_b128 v[234:237], v234 offset:3072
	global_load_lds_dwordx4 v[158:159], off
	v_lshl_add_u64 v[158:159], v[238:239], 0, s[2:3]
	s_add_i32 m0, s37, 0x2000
	s_nop 0
	global_load_lds_dwordx4 v[158:159], off
	s_barrier
	s_waitcnt lgkmcnt(0)
	v_mfma_f32_16x16x32_bf16 v[116:119], v[222:225], v[154:157], v[116:119]
	v_mfma_f32_16x16x32_bf16 v[112:115], v[230:233], v[154:157], v[112:115]
	v_mfma_f32_16x16x32_bf16 v[100:103], v[222:225], v[182:185], v[100:103]
	v_mfma_f32_16x16x32_bf16 v[96:99], v[230:233], v[182:185], v[96:99]
	v_mfma_f32_16x16x32_bf16 v[84:87], v[222:225], v[190:193], v[84:87]
	v_mfma_f32_16x16x32_bf16 v[80:83], v[230:233], v[190:193], v[80:83]
	v_mfma_f32_16x16x32_bf16 v[68:71], v[222:225], v[214:217], v[68:71]
	v_mfma_f32_16x16x32_bf16 v[64:67], v[230:233], v[214:217], v[64:67]
	v_mfma_f32_16x16x32_bf16 v[116:119], v[226:229], v[174:177], v[116:119]
	v_mfma_f32_16x16x32_bf16 v[112:115], v[234:237], v[174:177], v[112:115]
	v_mfma_f32_16x16x32_bf16 v[100:103], v[226:229], v[186:189], v[100:103]
	v_mfma_f32_16x16x32_bf16 v[96:99], v[234:237], v[186:189], v[96:99]
	v_mfma_f32_16x16x32_bf16 v[84:87], v[226:229], v[194:197], v[84:87]
	v_mfma_f32_16x16x32_bf16 v[80:83], v[234:237], v[194:197], v[80:83]
	v_mfma_f32_16x16x32_bf16 v[68:71], v[226:229], v[218:221], v[68:71]
	v_mfma_f32_16x16x32_bf16 v[64:67], v[234:237], v[218:221], v[64:67]
	s_mov_b32 m0, s47
	v_lshl_add_u64 v[158:159], v[240:241], 0, s[2:3]
	s_barrier
	ds_read_b128 v[154:157], v181 offset:49152
	ds_read_b128 v[174:177], v181 offset:50176
	ds_read_b128 v[182:185], v181 offset:51200
	ds_read_b128 v[186:189], v181 offset:52224
	ds_read_b128 v[190:193], v181 offset:53248
	ds_read_b128 v[194:197], v181 offset:54272
	ds_read_b128 v[214:217], v181 offset:55296
	ds_read_b128 v[218:221], v181 offset:56320
	global_load_lds_dwordx4 v[158:159], off
	v_lshl_add_u64 v[158:159], v[242:243], 0, s[2:3]
	s_mov_b32 m0, s48
	s_nop 0
	global_load_lds_dwordx4 v[158:159], off
	s_barrier
; DEV bf16x8 pack8(f32x4 a, f32x4 b) { u32x4 w; w.x = cvt_pk_bf16(a[0], a[1]); w.y = cvt_pk_bf16(a[2], a[3]); w.z = cvt_pk_bf16(b[0], b[1]); w.w = cvt_pk_bf16(b[2], b[3]); return __builtin_bit_cast(bf16x8, w); }
; #define PG8_WAIT_V(n) asm volatile("s_waitcnt vmcnt(" #n ")" ::: "memory")
; #define PG8_WAIT_L(n) asm volatile("s_waitcnt lgkmcnt(" #n ")" ::: "memory")
; #define PG8_BAR __builtin_amdgcn_s_barrier()
; #define PG8_SCHED __builtin_amdgcn_sched_barrier(0)
; template <class Epi>
; DEV void gemm_phase(LAS unsigned char* lds, const Gemm g, const StaticOrder& S, const Epi& E) {
;     ...
;             PG8_BAR; PG8_WAIT_L(0); PG8_MMA(1, 0, At, B0); PG8_BAR; PG8_SCHED;
;             PG8_STAGE(PG8_SB(1, 1), b3 + hstep, voffB);
;             PG8_WAIT_V(6); PG8_BAR; PG8_MMA(1, 1, At, B1); PG8_BAR;
;     DEV void operator()(AccRef acc, const pg8::Unit& u, int wr, int wc, int fr, int fq) const {
;         const int row0 = u.pm * 256 + wr * 64 + fr, col0 = u.pn * 256 + wc * 32 + 8 * fq;
; #pragma unroll
;         for (int am = 0; am < 4; ++am) { const int ai = am >> 1, m0 = (am & 1) * 2;
;             f32x4 bv[4][2][2];
; #pragma unroll
;             for (int m = m0; m < m0 + 2; ++m)
; #pragma unroll
;                 for (int bj = 0; bj < 2; ++bj)
; #pragma unroll
;                     for (int n = 0; n < 2; ++n) bv[m][bj][n] = *(const f32x4*)(base + (size_t)(row0 + ai * 128 + m * 16) * 2048 + col0 + bj * 128 + n * 4);
; #pragma unroll
;             for (int m = m0; m < m0 + 2; ++m) { const size_t off = (size_t)(row0 + ai * 128 + m * 16) * 2048 + col0; float sq = 0.f;
; #pragma unroll
;                 for (int bj = 0; bj < 2; ++bj) { const f32x4 o0 = bv[m][bj][0] + scale * acc[ai][bj][m][0], o1 = bv[m][bj][1] + scale * acc[ai][bj][m][1];
;                     *(f32x4*)(out + off + bj * 128) = o0; *(f32x4*)(out + off + bj * 128 + 4) = o1;
;                     if (xb) { *(u32x4*)(xb + off + bj * 128) = __builtin_bit_cast(u32x4, pack8(o0, o1));
;                         sq += (o0[0] * o0[0] + o0[1] * o0[1] + o0[2] * o0[2] + o0[3] * o0[3]) + (o1[0] * o1[0] + o1[1] * o1[1] + o1[2] * o1[2] + o1[3] * o1[3]); } }
;                 if (ssout) { sq += __shfl_xor(sq, 16); sq += __shfl_xor(sq, 32);
;                     if (fq == 0) { if (red) red[(ai * 128 + wr * 64 + m * 16 + fr) * 4 + wc] = sq; else atomicAdd(ssout + (size_t)(row0 + ai * 128 + m * 16) * 8 + u.pn, sq); } } }
	s_waitcnt lgkmcnt(0)
	v_mfma_f32_16x16x32_bf16 v[60:63], v[128:131], v[154:157], v[60:63]
	v_mfma_f32_16x16x32_bf16 v[56:59], v[136:139], v[154:157], v[56:59]
	v_mfma_f32_16x16x32_bf16 v[44:47], v[128:131], v[182:185], v[44:47]
	v_mfma_f32_16x16x32_bf16 v[40:43], v[136:139], v[182:185], v[40:43]
	v_mfma_f32_16x16x32_bf16 v[28:31], v[128:131], v[190:193], v[28:31]
	v_mfma_f32_16x16x32_bf16 v[24:27], v[136:139], v[190:193], v[24:27]
	v_mfma_f32_16x16x32_bf16 v[12:15], v[128:131], v[214:217], v[12:15]
	v_mfma_f32_16x16x32_bf16 v[8:11], v[136:139], v[214:217], v[8:11]
	v_mfma_f32_16x16x32_bf16 v[60:63], v[132:135], v[174:177], v[60:63]
	v_mfma_f32_16x16x32_bf16 v[56:59], v[140:143], v[174:177], v[56:59]
	v_mfma_f32_16x16x32_bf16 v[44:47], v[132:135], v[186:189], v[44:47]
	v_mfma_f32_16x16x32_bf16 v[40:43], v[140:143], v[186:189], v[40:43]
	v_mfma_f32_16x16x32_bf16 v[28:31], v[132:135], v[194:197], v[28:31]
	v_mfma_f32_16x16x32_bf16 v[24:27], v[140:143], v[194:197], v[24:27]
	v_mfma_f32_16x16x32_bf16 v[12:15], v[132:135], v[218:221], v[12:15]
	v_mfma_f32_16x16x32_bf16 v[8:11], v[140:143], v[218:221], v[8:11]
	s_barrier
	s_add_u32 s34, s34, 0x20080
	s_addc_u32 s35, s35, 0
	s_add_i32 s36, s36, s42
	s_mov_b32 m0, s36
	s_nop 0
	global_load_lds_dwordx4 v160, s[34:35]
	s_add_i32 m0, s36, 0x2000
	s_nop 0
	global_load_lds_dwordx4 v148, s[34:35]
	s_waitcnt vmcnt(6)
	s_barrier
	v_mfma_f32_16x16x32_bf16 v[52:55], v[222:225], v[154:157], v[52:55]
	v_mfma_f32_16x16x32_bf16 v[48:51], v[230:233], v[154:157], v[48:51]
	v_mfma_f32_16x16x32_bf16 v[36:39], v[222:225], v[182:185], v[36:39]
	v_mfma_f32_16x16x32_bf16 v[32:35], v[230:233], v[182:185], v[32:35]
	v_mfma_f32_16x16x32_bf16 v[20:23], v[222:225], v[190:193], v[20:23]
	v_mfma_f32_16x16x32_bf16 v[16:19], v[230:233], v[190:193], v[16:19]
	v_mfma_f32_16x16x32_bf16 v[4:7], v[222:225], v[214:217], v[4:7]
	v_mfma_f32_16x16x32_bf16 v[0:3], v[230:233], v[214:217], v[0:3]
	v_mfma_f32_16x16x32_bf16 v[52:55], v[226:229], v[174:177], v[52:55]
	v_mfma_f32_16x16x32_bf16 v[48:51], v[234:237], v[174:177], v[48:51]
	v_mfma_f32_16x16x32_bf16 v[36:39], v[226:229], v[186:189], v[36:39]
	v_mfma_f32_16x16x32_bf16 v[32:35], v[234:237], v[186:189], v[32:35]
	v_mfma_f32_16x16x32_bf16 v[20:23], v[226:229], v[194:197], v[20:23]
	v_mfma_f32_16x16x32_bf16 v[16:19], v[234:237], v[194:197], v[16:19]
	v_mfma_f32_16x16x32_bf16 v[4:7], v[226:229], v[218:221], v[4:7]
	v_mfma_f32_16x16x32_bf16 v[0:3], v[234:237], v[218:221], v[0:3]
	s_add_i32 s54, s54, 2
	s_add_u32 s30, s30, 0x100
	s_addc_u32 s31, s31, 0
	s_add_u32 s52, s52, 0x100
	s_addc_u32 s53, s53, 0
	s_cmp_gt_u32 s54, 5
	s_barrier
	s_cbranch_scc0 .LBB0_260
	v_lshl_add_u32 v156, s28, 8, v167
	v_lshl_or_b32 v154, s18, 8, v179
	v_readlane_b32 s28, v254, 16
	v_ashrrev_i32_e32 v155, 31, v154
	v_readlane_b32 s29, v254, 17
	v_ashrrev_i32_e32 v157, 31, v156
	v_lshlrev_b64 v[128:129], 13, v[156:157]
	v_lshl_add_u64 v[158:159], v[154:155], 2, s[28:29]
	v_lshl_add_u64 v[214:215], v[158:159], 0, v[128:129]
	global_load_dwordx4 v[182:185], v[214:215], off offset:16
	global_load_dwordx4 v[186:189], v[214:215], off
	global_load_dwordx4 v[190:193], v[214:215], off offset:528
	global_load_dwordx4 v[194:197], v[214:215], off offset:512
	v_or_b32_e32 v174, 16, v156
	v_ashrrev_i32_e32 v175, 31, v174
	v_lshlrev_b64 v[128:129], 13, v[174:175]
	v_lshl_add_u64 v[176:177], v[158:159], 0, v[128:129]
	global_load_dwordx4 v[136:139], v[176:177], off offset:16
	global_load_dwordx4 v[140:143], v[176:177], off
	global_load_dwordx4 v[128:131], v[176:177], off offset:528
	global_load_dwordx4 v[132:135], v[176:177], off offset:512
	v_lshlrev_b64 v[216:217], 11, v[156:157]
	v_readlane_b32 s28, v250, 9
	v_lshl_add_u64 v[216:217], v[216:217], 0, v[154:155]
	v_readlane_b32 s29, v250, 10
	v_cmp_lt_i32_e32 vcc, v208, v206
	s_ashr_i32 s19, s18, 31
	s_waitcnt vmcnt(0)
	v_pk_add_f32 v[120:121], v[120:121], v[182:183]
	v_pk_add_f32 v[126:127], v[126:127], v[188:189]
	v_pk_add_f32 v[124:125], v[124:125], v[186:187]
	v_pk_add_f32 v[122:123], v[122:123], v[184:185]
	global_store_dwordx4 v[214:215], v[124:127], off
	global_store_dwordx4 v[214:215], v[120:123], off offset:16
	v_cvt_pk_bf16_f32 v184, v120, v121
	v_cvt_pk_bf16_f32 v182, v124, v125
	v_mul_f32_e32 v121, v121, v121
	v_cvt_pk_bf16_f32 v183, v126, v127
	v_cvt_pk_bf16_f32 v185, v122, v123
	v_lshl_add_u64 v[186:187], v[216:217], 1, s[28:29]
	v_fmac_f32_e32 v121, v120, v120
	v_pk_add_f32 v[118:119], v[118:119], v[196:197]
	v_pk_add_f32 v[116:117], v[116:117], v[194:195]
	v_pk_add_f32 v[112:113], v[112:113], v[190:191]
	global_store_dwordx4 v[186:187], v[182:185], off
	v_mul_f32_e32 v125, v125, v125
	v_fmac_f32_e32 v121, v122, v122
	v_pk_add_f32 v[114:115], v[114:115], v[192:193]
	global_store_dwordx4 v[214:215], v[116:119], off offset:512
	global_store_dwordx4 v[214:215], v[112:115], off offset:528
	v_cvt_pk_bf16_f32 v120, v116, v117
	v_cvt_pk_bf16_f32 v122, v112, v113
	v_mul_f32_e32 v117, v117, v117
	v_mul_f32_e32 v113, v113, v113
	v_fmac_f32_e32 v125, v124, v124
	v_fmac_f32_e32 v117, v116, v116
	v_fmac_f32_e32 v113, v112, v112
	v_fmac_f32_e32 v125, v126, v126
	v_fmac_f32_e32 v117, v118, v118
	v_fmac_f32_e32 v113, v114, v114
	v_fmac_f32_e32 v125, v127, v127
	v_fmac_f32_e32 v121, v123, v123
	v_fmac_f32_e32 v117, v119, v119
	v_fmac_f32_e32 v113, v115, v115
	v_add_f32_e32 v124, v125, v121
	v_add_f32_e32 v112, v117, v113
	v_cndmask_b32_e32 v113, v204, v208, vcc
	v_cvt_pk_bf16_f32 v121, v118, v119
	v_add_f32_e32 v112, v124, v112
	v_lshlrev_b32_e32 v118, 2, v113
	ds_bpermute_b32 v113, v118, v112
	v_cmp_lt_i32_e32 vcc, v207, v206
	v_cvt_pk_bf16_f32 v123, v114, v115
	global_store_dwordx4 v[186:187], v[120:123], off offset:256
	s_waitcnt lgkmcnt(0)
	v_add_f32_e32 v112, v112, v113
	v_cndmask_b32_e32 v113, v204, v207, vcc
	v_lshlrev_b32_e32 v119, 2, v113
	ds_bpermute_b32 v113, v119, v112
	s_and_saveexec_b64 s[28:29], s[6:7]
	s_cbranch_execz .LBB0_266
	s_waitcnt lgkmcnt(0)
	v_add_f32_e32 v112, v112, v113
	s_mov_b64 s[30:31], -1
	s_and_b64 vcc, exec, s[16:17]
	s_cbranch_vccz .LBB0_264
	v_lshlrev_b64 v[114:115], 5, v[156:157]
	v_lshl_add_u64 v[114:115], s[12:13], 0, v[114:115]
	v_lshl_add_u64 v[114:115], s[18:19], 2, v[114:115]
	global_atomic_add_f32 v[114:115], v112, off
	s_mov_b64 s[30:31], 0

; #define PG8_STAGE(bufoff, gbase, voff) do { _Pragma("unroll") for (int _i = 0; _i < 2; ++_i) \
;         __builtin_amdgcn_global_load_lds((const unsigned*)((const char*)(gbase) + (voff)[_i]), (LAS unsigned*)(lds + (bufoff) + ldsw + _i * 8192), 16, 0, 0); } while (0)
; #define PG8_LDA(dst, b, h) do { _Pragma("unroll") for (int m = 0; m < 4; ++m) _Pragma("unroll") for (int k = 0; k < 2; ++k) dst[m][k] = *(const LAS bf16x8*)(lds + PG8_SA(b, h) + aoff + m * 2048 + k * 1024); } while (0)
; #define PG8_LDB(dst, b, h) do { _Pragma("unroll") for (int n = 0; n < 2; ++n) _Pragma("unroll") for (int k = 0; k < 2; ++k) dst[n][k] = *(const LAS bf16x8*)(lds + PG8_SB(b, h) + boff + n * 2048 + k * 1024); } while (0)
; #define PG8_MMA(ai, bj, At, Bt) do { __builtin_amdgcn_s_setprio(1); _Pragma("unroll") for (int m = 0; m < 4; ++m) _Pragma("unroll") for (int n = 0; n < 2; ++n) _Pragma("unroll") for (int k = 0; k < 2; ++k) \
;         acc[ai][bj][m][n] = __builtin_amdgcn_mfma_f32_16x16x32_bf16(Bt[n][k], At[m][k], acc[ai][bj][m][n], 0, 0, 0); __builtin_amdgcn_s_setprio(0); } while (0)
; #define PG8_WAIT_V(n) asm volatile("s_waitcnt vmcnt(" #n ")" ::: "memory")
; #define PG8_WAIT_L(n) asm volatile("s_waitcnt lgkmcnt(" #n ")" ::: "memory")
; #define PG8_BAR __builtin_amdgcn_s_barrier()
; #define PG8_SCHED __builtin_amdgcn_sched_barrier(0)
; template <class Epi>
; DEV void gemm_phase(LAS unsigned char* lds, const Gemm g, const StaticOrder& S, const Epi& E) {
;     ...
;             const bool last = (t == nt - 2);
;             const char* a1 = cA + (size_t)(t + 1) * kstep;
;             const char* a2 = last ? nA : cA + (size_t)(t + 2) * kstep; const char* b2 = last ? nB : cB + (size_t)(t + 2) * kstep;
;             const char* a3 = a2 + kstep; const char* b3 = b2 + kstep;
;             PG8_LDB(B0, 0, 0); PG8_SCHED; PG8_LDA(At, 0, 0); PG8_STAGE(PG8_SA(1, 1), a1 + hstep, voffA);
;             PG8_WAIT_L(8); PG8_BAR; PG8_WAIT_L(0); PG8_MMA(0, 0, At, B0); PG8_BAR; PG8_SCHED;
;             PG8_LDB(B1, 0, 1); PG8_STAGE(PG8_SB(0, 0), b2, voffB);
;             PG8_BAR; PG8_WAIT_L(0); PG8_MMA(0, 1, At, B1); PG8_BAR;
;             PG8_LDA(At, 0, 1); PG8_STAGE(PG8_SA(0, 0), a2, voffA);
;             PG8_BAR; PG8_WAIT_L(0); PG8_MMA(1, 0, At, B0); PG8_BAR; PG8_SCHED;
;             PG8_STAGE(PG8_SB(0, 1), b2 + hstep, voffB);
;             PG8_WAIT_V(6); PG8_BAR; PG8_MMA(1, 1, At, B1); PG8_BAR;
.LBB0_344:
	s_add_u32 s20, s18, 0xfff80080
	s_addc_u32 s21, s19, -1
	s_add_i32 s45, 0, 0x10000
	v_add_u32_e32 v146, s45, v149
	ds_read_b128 v[128:131], v146
	ds_read_b128 v[132:135], v146 offset:1024
	ds_read_b128 v[142:145], v146 offset:2048
	ds_read_b128 v[150:153], v146 offset:3072
	s_cmp_eq_u32 s44, 28
	s_cselect_b32 s23, s1, s21
	s_cselect_b32 s22, s13, s20
	s_cselect_b32 s21, s11, s43
	s_cselect_b32 s20, s41, s42
	s_add_i32 m0, s30, 0xc000
	ds_read_b128 v[174:177], v159
	ds_read_b128 v[178:181], v159 offset:1024
	ds_read_b128 v[182:185], v159 offset:2048
	ds_read_b128 v[186:189], v159 offset:3072
	ds_read_b128 v[190:193], v159 offset:4096
	ds_read_b128 v[194:197], v159 offset:5120
	ds_read_b128 v[214:217], v159 offset:6144
	ds_read_b128 v[218:221], v159 offset:7168
	global_load_lds_dwordx4 v138, s[18:19]
	s_add_i32 m0, s30, 0xe000
	s_nop 0
	global_load_lds_dwordx4 v140, s[18:19]
	s_waitcnt lgkmcnt(8)
	s_barrier
	s_waitcnt lgkmcnt(0)
	v_mfma_f32_16x16x32_bf16 v[124:127], v[128:131], v[174:177], v[124:127]
	v_mfma_f32_16x16x32_bf16 v[120:123], v[142:145], v[174:177], v[120:123]
	v_mfma_f32_16x16x32_bf16 v[116:119], v[128:131], v[182:185], v[116:119]
	v_mfma_f32_16x16x32_bf16 v[108:111], v[142:145], v[182:185], v[108:111]
	v_mfma_f32_16x16x32_bf16 v[100:103], v[128:131], v[190:193], v[100:103]
	v_mfma_f32_16x16x32_bf16 v[92:95], v[142:145], v[190:193], v[92:95]
	v_mfma_f32_16x16x32_bf16 v[84:87], v[128:131], v[214:217], v[84:87]
	v_mfma_f32_16x16x32_bf16 v[76:79], v[142:145], v[214:217], v[76:79]
	v_mfma_f32_16x16x32_bf16 v[124:127], v[132:135], v[178:181], v[124:127]
	v_mfma_f32_16x16x32_bf16 v[120:123], v[150:153], v[178:181], v[120:123]
	v_mfma_f32_16x16x32_bf16 v[116:119], v[132:135], v[186:189], v[116:119]
	v_mfma_f32_16x16x32_bf16 v[108:111], v[150:153], v[186:189], v[108:111]
	v_mfma_f32_16x16x32_bf16 v[100:103], v[132:135], v[194:197], v[100:103]
	v_mfma_f32_16x16x32_bf16 v[92:95], v[150:153], v[194:197], v[92:95]
	v_mfma_f32_16x16x32_bf16 v[84:87], v[132:135], v[218:221], v[84:87]
	v_mfma_f32_16x16x32_bf16 v[76:79], v[150:153], v[218:221], v[76:79]
	s_barrier
	s_add_i32 s48, 0, 0x14000
	s_add_i32 s45, s45, s29
	v_add_u32_e32 v146, s48, v149
	v_lshl_add_u64 v[154:155], s[20:21], 0, v[160:161]
	s_mov_b32 m0, s45
	ds_read_b128 v[222:225], v146
	ds_read_b128 v[226:229], v146 offset:1024
	ds_read_b128 v[230:233], v146 offset:2048
	ds_read_b128 v[234:237], v146 offset:3072
	global_load_lds_dwordx4 v160, s[20:21]
	v_lshl_add_u64 v[238:239], s[20:21], 0, v[136:137]
	s_add_i32 m0, s45, 0x2000
	s_nop 0
	global_load_lds_dwordx4 v136, s[20:21]
	s_barrier
	s_waitcnt lgkmcnt(0)
	v_mfma_f32_16x16x32_bf16 v[112:115], v[222:225], v[174:177], v[112:115]
	v_mfma_f32_16x16x32_bf16 v[104:107], v[230:233], v[174:177], v[104:107]
	v_mfma_f32_16x16x32_bf16 v[96:99], v[222:225], v[182:185], v[96:99]
	v_mfma_f32_16x16x32_bf16 v[88:91], v[230:233], v[182:185], v[88:91]
	v_mfma_f32_16x16x32_bf16 v[80:83], v[222:225], v[190:193], v[80:83]
	v_mfma_f32_16x16x32_bf16 v[72:75], v[230:233], v[190:193], v[72:75]
	v_mfma_f32_16x16x32_bf16 v[68:71], v[222:225], v[214:217], v[68:71]
	v_mfma_f32_16x16x32_bf16 v[64:67], v[230:233], v[214:217], v[64:67]
	v_mfma_f32_16x16x32_bf16 v[112:115], v[226:229], v[178:181], v[112:115]
	v_mfma_f32_16x16x32_bf16 v[104:107], v[234:237], v[178:181], v[104:107]
	v_mfma_f32_16x16x32_bf16 v[96:99], v[226:229], v[186:189], v[96:99]
	v_mfma_f32_16x16x32_bf16 v[88:91], v[234:237], v[186:189], v[88:91]
	v_mfma_f32_16x16x32_bf16 v[80:83], v[226:229], v[194:197], v[80:83]
	v_mfma_f32_16x16x32_bf16 v[72:75], v[234:237], v[194:197], v[72:75]
	v_mfma_f32_16x16x32_bf16 v[68:71], v[226:229], v[218:221], v[68:71]
	v_mfma_f32_16x16x32_bf16 v[64:67], v[234:237], v[218:221], v[64:67]
	s_mov_b32 m0, s30
	v_lshl_add_u64 v[240:241], s[22:23], 0, v[160:161]
	s_barrier
	ds_read_b128 v[174:177], v159 offset:16384
	ds_read_b128 v[178:181], v159 offset:17408
	ds_read_b128 v[182:185], v159 offset:18432
	ds_read_b128 v[186:189], v159 offset:19456
	ds_read_b128 v[190:193], v159 offset:20480
	ds_read_b128 v[194:197], v159 offset:21504
	ds_read_b128 v[214:217], v159 offset:22528
	ds_read_b128 v[218:221], v159 offset:23552
	global_load_lds_dwordx4 v160, s[22:23]
	v_lshl_add_u64 v[242:243], s[22:23], 0, v[136:137]
	s_mov_b32 m0, s31
	s_nop 0
	global_load_lds_dwordx4 v136, s[22:23]
	s_barrier
	s_waitcnt lgkmcnt(0)
	v_mfma_f32_16x16x32_bf16 v[60:63], v[128:131], v[174:177], v[60:63]
	v_mfma_f32_16x16x32_bf16 v[56:59], v[142:145], v[174:177], v[56:59]
	v_mfma_f32_16x16x32_bf16 v[52:55], v[128:131], v[182:185], v[52:55]
	v_mfma_f32_16x16x32_bf16 v[44:47], v[142:145], v[182:185], v[44:47]
	v_mfma_f32_16x16x32_bf16 v[36:39], v[128:131], v[190:193], v[36:39]
	v_mfma_f32_16x16x32_bf16 v[28:31], v[142:145], v[190:193], v[28:31]
	v_mfma_f32_16x16x32_bf16 v[20:23], v[128:131], v[214:217], v[20:23]
	v_mfma_f32_16x16x32_bf16 v[12:15], v[142:145], v[214:217], v[12:15]
	v_mfma_f32_16x16x32_bf16 v[60:63], v[132:135], v[178:181], v[60:63]
	v_mfma_f32_16x16x32_bf16 v[56:59], v[150:153], v[178:181], v[56:59]
	v_mfma_f32_16x16x32_bf16 v[52:55], v[132:135], v[186:189], v[52:55]
	v_mfma_f32_16x16x32_bf16 v[44:47], v[150:153], v[186:189], v[44:47]
	v_mfma_f32_16x16x32_bf16 v[36:39], v[132:135], v[194:197], v[36:39]
	v_mfma_f32_16x16x32_bf16 v[28:31], v[150:153], v[194:197], v[28:31]
	v_mfma_f32_16x16x32_bf16 v[20:23], v[132:135], v[218:221], v[20:23]
	v_mfma_f32_16x16x32_bf16 v[12:15], v[150:153], v[218:221], v[12:15]
	s_barrier
	s_add_u32 s46, s20, 0x80000
	s_addc_u32 s47, s21, 0
	s_add_i32 s45, s48, s29
	s_mov_b32 m0, s45
	s_nop 0
	global_load_lds_dwordx4 v160, s[46:47]
	s_add_i32 m0, s45, 0x2000
	s_nop 0
	global_load_lds_dwordx4 v136, s[46:47]
	s_waitcnt vmcnt(6)
	s_barrier
; #define PG8_STAGE(bufoff, gbase, voff) do { _Pragma("unroll") for (int _i = 0; _i < 2; ++_i) \
;         __builtin_amdgcn_global_load_lds((const unsigned*)((const char*)(gbase) + (voff)[_i]), (LAS unsigned*)(lds + (bufoff) + ldsw + _i * 8192), 16, 0, 0); } while (0)
; #define PG8_LDA(dst, b, h) do { _Pragma("unroll") for (int m = 0; m < 4; ++m) _Pragma("unroll") for (int k = 0; k < 2; ++k) dst[m][k] = *(const LAS bf16x8*)(lds + PG8_SA(b, h) + aoff + m * 2048 + k * 1024); } while (0)
; #define PG8_LDB(dst, b, h) do { _Pragma("unroll") for (int n = 0; n < 2; ++n) _Pragma("unroll") for (int k = 0; k < 2; ++k) dst[n][k] = *(const LAS bf16x8*)(lds + PG8_SB(b, h) + boff + n * 2048 + k * 1024); } while (0)
; #define PG8_MMA(ai, bj, At, Bt) do { __builtin_amdgcn_s_setprio(1); _Pragma("unroll") for (int m = 0; m < 4; ++m) _Pragma("unroll") for (int n = 0; n < 2; ++n) _Pragma("unroll") for (int k = 0; k < 2; ++k) \
;         acc[ai][bj][m][n] = __builtin_amdgcn_mfma_f32_16x16x32_bf16(Bt[n][k], At[m][k], acc[ai][bj][m][n], 0, 0, 0); __builtin_amdgcn_s_setprio(0); } while (0)
; #define PG8_WAIT_V(n) asm volatile("s_waitcnt vmcnt(" #n ")" ::: "memory")
; #define PG8_WAIT_L(n) asm volatile("s_waitcnt lgkmcnt(" #n ")" ::: "memory")
; #define PG8_BAR __builtin_amdgcn_s_barrier()
; #define PG8_SCHED __builtin_amdgcn_sched_barrier(0)
; template <class Epi>
; DEV void gemm_phase(LAS unsigned char* lds, const Gemm g, const StaticOrder& S, const Epi& E) {
;     ...
;             PG8_WAIT_V(6); PG8_BAR; PG8_MMA(1, 1, At, B1); PG8_BAR;
;             PG8_LDB(B0, 1, 0); PG8_SCHED; PG8_LDA(At, 1, 0); PG8_STAGE(PG8_SA(0, 1), a2 + hstep, voffA);
;             PG8_WAIT_L(8); PG8_BAR; PG8_WAIT_L(0); PG8_MMA(0, 0, At, B0); PG8_BAR; PG8_SCHED;
;             PG8_LDB(B1, 1, 1); PG8_STAGE(PG8_SB(1, 0), b3, voffB);
;             PG8_BAR; PG8_WAIT_L(0); PG8_MMA(0, 1, At, B1); PG8_BAR;
;             PG8_LDA(At, 1, 1); PG8_STAGE(PG8_SA(1, 0), a3, voffA);
;             PG8_BAR; PG8_WAIT_L(0); PG8_MMA(1, 0, At, B0); PG8_BAR; PG8_SCHED;
	v_mfma_f32_16x16x32_bf16 v[48:51], v[222:225], v[174:177], v[48:51]
	v_mfma_f32_16x16x32_bf16 v[40:43], v[230:233], v[174:177], v[40:43]
	v_mfma_f32_16x16x32_bf16 v[32:35], v[222:225], v[182:185], v[32:35]
	v_mfma_f32_16x16x32_bf16 v[24:27], v[230:233], v[182:185], v[24:27]
	v_mfma_f32_16x16x32_bf16 v[16:19], v[222:225], v[190:193], v[16:19]
	v_mfma_f32_16x16x32_bf16 v[8:11], v[230:233], v[190:193], v[8:11]
	v_mfma_f32_16x16x32_bf16 v[4:7], v[222:225], v[214:217], v[4:7]
	v_mfma_f32_16x16x32_bf16 v[0:3], v[230:233], v[214:217], v[0:3]
	v_mfma_f32_16x16x32_bf16 v[48:51], v[226:229], v[178:181], v[48:51]
	v_mfma_f32_16x16x32_bf16 v[40:43], v[234:237], v[178:181], v[40:43]
	v_mfma_f32_16x16x32_bf16 v[32:35], v[226:229], v[186:189], v[32:35]
	v_mfma_f32_16x16x32_bf16 v[24:27], v[234:237], v[186:189], v[24:27]
	v_mfma_f32_16x16x32_bf16 v[16:19], v[226:229], v[194:197], v[16:19]
	v_mfma_f32_16x16x32_bf16 v[8:11], v[234:237], v[194:197], v[8:11]
	v_mfma_f32_16x16x32_bf16 v[4:7], v[226:229], v[218:221], v[4:7]
	v_mfma_f32_16x16x32_bf16 v[0:3], v[234:237], v[218:221], v[0:3]
	s_add_i32 s45, 0, 0x18000
	v_add_u32_e32 v146, s45, v149
	s_barrier
	ds_read_b128 v[128:131], v146
	ds_read_b128 v[132:135], v146 offset:1024
	ds_read_b128 v[142:145], v146 offset:2048
	ds_read_b128 v[150:153], v146 offset:3072
	s_add_u32 s22, s22, 0x80000
	s_addc_u32 s23, s23, 0
	s_mov_b32 m0, s34
	ds_read_b128 v[174:177], v159 offset:32768
	ds_read_b128 v[178:181], v159 offset:33792
	ds_read_b128 v[182:185], v159 offset:34816
	ds_read_b128 v[186:189], v159 offset:35840
	ds_read_b128 v[190:193], v159 offset:36864
	ds_read_b128 v[194:197], v159 offset:37888
	ds_read_b128 v[214:217], v159 offset:38912
	ds_read_b128 v[218:221], v159 offset:39936
	global_load_lds_dwordx4 v160, s[22:23]
	s_mov_b32 m0, s35
	s_nop 0
	global_load_lds_dwordx4 v136, s[22:23]
	s_waitcnt lgkmcnt(8)
	s_barrier
	s_waitcnt lgkmcnt(0)
	v_mfma_f32_16x16x32_bf16 v[124:127], v[128:131], v[174:177], v[124:127]
	v_mfma_f32_16x16x32_bf16 v[120:123], v[142:145], v[174:177], v[120:123]
	v_mfma_f32_16x16x32_bf16 v[116:119], v[128:131], v[182:185], v[116:119]
	v_mfma_f32_16x16x32_bf16 v[108:111], v[142:145], v[182:185], v[108:111]
	v_mfma_f32_16x16x32_bf16 v[100:103], v[128:131], v[190:193], v[100:103]
	v_mfma_f32_16x16x32_bf16 v[92:95], v[142:145], v[190:193], v[92:95]
	v_mfma_f32_16x16x32_bf16 v[84:87], v[128:131], v[214:217], v[84:87]
	v_mfma_f32_16x16x32_bf16 v[76:79], v[142:145], v[214:217], v[76:79]
	v_mfma_f32_16x16x32_bf16 v[124:127], v[132:135], v[178:181], v[124:127]
	v_mfma_f32_16x16x32_bf16 v[120:123], v[150:153], v[178:181], v[120:123]
	v_mfma_f32_16x16x32_bf16 v[116:119], v[132:135], v[186:189], v[116:119]
	v_mfma_f32_16x16x32_bf16 v[108:111], v[150:153], v[186:189], v[108:111]
	v_mfma_f32_16x16x32_bf16 v[100:103], v[132:135], v[194:197], v[100:103]
	v_mfma_f32_16x16x32_bf16 v[92:95], v[150:153], v[194:197], v[92:95]
	v_mfma_f32_16x16x32_bf16 v[84:87], v[132:135], v[218:221], v[84:87]
	v_mfma_f32_16x16x32_bf16 v[76:79], v[150:153], v[218:221], v[76:79]
	s_barrier
	s_add_i32 s22, 0, 0x1c000
	s_add_i32 s23, s45, s29
	v_add_u32_e32 v146, s22, v149
	v_lshl_add_u64 v[154:155], v[154:155], 0, s[2:3]
	s_mov_b32 m0, s23
	ds_read_b128 v[222:225], v146
	ds_read_b128 v[226:229], v146 offset:1024
	ds_read_b128 v[230:233], v146 offset:2048
	ds_read_b128 v[234:237], v146 offset:3072
	global_load_lds_dwordx4 v[154:155], off
	v_lshl_add_u64 v[154:155], v[238:239], 0, s[2:3]
	s_add_i32 m0, s23, 0x2000
	s_nop 0
	global_load_lds_dwordx4 v[154:155], off
	s_barrier
	s_waitcnt lgkmcnt(0)
	v_mfma_f32_16x16x32_bf16 v[112:115], v[222:225], v[174:177], v[112:115]
	v_mfma_f32_16x16x32_bf16 v[104:107], v[230:233], v[174:177], v[104:107]
	v_mfma_f32_16x16x32_bf16 v[96:99], v[222:225], v[182:185], v[96:99]
	v_mfma_f32_16x16x32_bf16 v[88:91], v[230:233], v[182:185], v[88:91]
	v_mfma_f32_16x16x32_bf16 v[80:83], v[222:225], v[190:193], v[80:83]
	v_mfma_f32_16x16x32_bf16 v[72:75], v[230:233], v[190:193], v[72:75]
	v_mfma_f32_16x16x32_bf16 v[68:71], v[222:225], v[214:217], v[68:71]
	v_mfma_f32_16x16x32_bf16 v[64:67], v[230:233], v[214:217], v[64:67]
	v_mfma_f32_16x16x32_bf16 v[112:115], v[226:229], v[178:181], v[112:115]
	v_mfma_f32_16x16x32_bf16 v[104:107], v[234:237], v[178:181], v[104:107]
	v_mfma_f32_16x16x32_bf16 v[96:99], v[226:229], v[186:189], v[96:99]
	v_mfma_f32_16x16x32_bf16 v[88:91], v[234:237], v[186:189], v[88:91]
	v_mfma_f32_16x16x32_bf16 v[80:83], v[226:229], v[194:197], v[80:83]
	v_mfma_f32_16x16x32_bf16 v[72:75], v[234:237], v[194:197], v[72:75]
	v_mfma_f32_16x16x32_bf16 v[68:71], v[226:229], v[218:221], v[68:71]
	v_mfma_f32_16x16x32_bf16 v[64:67], v[234:237], v[218:221], v[64:67]
	s_mov_b32 m0, s37
	v_lshl_add_u64 v[154:155], v[240:241], 0, s[2:3]
	s_barrier
	ds_read_b128 v[174:177], v159 offset:49152
	ds_read_b128 v[178:181], v159 offset:50176
	ds_read_b128 v[182:185], v159 offset:51200
	ds_read_b128 v[186:189], v159 offset:52224
	ds_read_b128 v[190:193], v159 offset:53248
	ds_read_b128 v[194:197], v159 offset:54272
	ds_read_b128 v[214:217], v159 offset:55296
	ds_read_b128 v[218:221], v159 offset:56320
	global_load_lds_dwordx4 v[154:155], off
	v_lshl_add_u64 v[154:155], v[242:243], 0, s[2:3]
	s_mov_b32 m0, s38
	s_nop 0
	global_load_lds_dwordx4 v[154:155], off
	s_barrier
; DEV bf16x8 pack8(f32x4 a, f32x4 b) { u32x4 w; w.x = cvt_pk_bf16(a[0], a[1]); w.y = cvt_pk_bf16(a[2], a[3]); w.z = cvt_pk_bf16(b[0], b[1]); w.w = cvt_pk_bf16(b[2], b[3]); return __builtin_bit_cast(bf16x8, w); }
; DEV f32x4 gelu4(f32x4 v) { f32x2 a = gelu_pk((f32x2){v[0], v[1]}), b = gelu_pk((f32x2){v[2], v[3]}); return (f32x4){a.x, a.y, b.x, b.y}; }
; #define PG8_STAGE(bufoff, gbase, voff) do { _Pragma("unroll") for (int _i = 0; _i < 2; ++_i) \
;         __builtin_amdgcn_global_load_lds((const unsigned*)((const char*)(gbase) + (voff)[_i]), (LAS unsigned*)(lds + (bufoff) + ldsw + _i * 8192), 16, 0, 0); } while (0)
; #define PG8_MMA(ai, bj, At, Bt) do { __builtin_amdgcn_s_setprio(1); _Pragma("unroll") for (int m = 0; m < 4; ++m) _Pragma("unroll") for (int n = 0; n < 2; ++n) _Pragma("unroll") for (int k = 0; k < 2; ++k) \
;         acc[ai][bj][m][n] = __builtin_amdgcn_mfma_f32_16x16x32_bf16(Bt[n][k], At[m][k], acc[ai][bj][m][n], 0, 0, 0); __builtin_amdgcn_s_setprio(0); } while (0)
; template <class Epi>
; DEV void gemm_phase(LAS unsigned char* lds, const Gemm g, const StaticOrder& S, const Epi& E) {
;     ...
;             PG8_BAR; PG8_WAIT_L(0); PG8_MMA(1, 0, At, B0); PG8_BAR; PG8_SCHED;
;             PG8_STAGE(PG8_SB(1, 1), b3 + hstep, voffB);
;             PG8_WAIT_V(6); PG8_BAR; PG8_MMA(1, 1, At, B1); PG8_BAR;
; DEV float rowscale(const float* ss, int row) { const f32x4 a = *(const f32x4*)(ss + (size_t)row * 8), b = *(const f32x4*)(ss + (size_t)row * 8 + 4);
;     return rsqrtf(((a[0] + a[1]) + (a[2] + a[3]) + (b[0] + b[1]) + (b[2] + b[3])) * (1.0f / 2048.0f) + EPS); }
; template <int ACT, bool PERM>
; DEV void store_bf16_tile(AccRef acc, u16* O, int ld, int row0, int col0, const float* ss) {
;     float rsv[2][4];
; #pragma unroll
;     for (int ai = 0; ai < 2; ++ai)
; #pragma unroll
;         for (int m = 0; m < 4; ++m) rsv[ai][m] = ss ? rowscale(ss, row0 + ai * 128 + m * 16) : 1.0f;
; #pragma unroll
;     for (int ai = 0; ai < 2; ++ai)
; #pragma unroll
;         for (int m = 0; m < 4; ++m) { u16* rowp = O + (size_t)(row0 + ai * 128 + m * 16) * ld + col0; const float rs = rsv[ai][m];
; #pragma unroll
;             for (int bj = 0; bj < 2; ++bj) { f32x4 v0 = acc[ai][bj][m][0] * rs, v1 = acc[ai][bj][m][1] * rs; if (ACT == 1) { v0 = gelu4(v0); v1 = gelu4(v1); }
;                 if (PERM) *(u32x4*)(rowp + bj * 128) = __builtin_bit_cast(u32x4, pack8(v0, v1));
	s_waitcnt lgkmcnt(0)
	v_mfma_f32_16x16x32_bf16 v[60:63], v[128:131], v[174:177], v[60:63]
	v_mfma_f32_16x16x32_bf16 v[56:59], v[142:145], v[174:177], v[56:59]
	v_mfma_f32_16x16x32_bf16 v[52:55], v[128:131], v[182:185], v[52:55]
	v_mfma_f32_16x16x32_bf16 v[44:47], v[142:145], v[182:185], v[44:47]
	v_mfma_f32_16x16x32_bf16 v[36:39], v[128:131], v[190:193], v[36:39]
	v_mfma_f32_16x16x32_bf16 v[28:31], v[142:145], v[190:193], v[28:31]
	v_mfma_f32_16x16x32_bf16 v[20:23], v[128:131], v[214:217], v[20:23]
	v_mfma_f32_16x16x32_bf16 v[12:15], v[142:145], v[214:217], v[12:15]
	v_mfma_f32_16x16x32_bf16 v[60:63], v[132:135], v[178:181], v[60:63]
	v_mfma_f32_16x16x32_bf16 v[56:59], v[150:153], v[178:181], v[56:59]
	v_mfma_f32_16x16x32_bf16 v[52:55], v[132:135], v[186:189], v[52:55]
	v_mfma_f32_16x16x32_bf16 v[44:47], v[150:153], v[186:189], v[44:47]
	v_mfma_f32_16x16x32_bf16 v[36:39], v[132:135], v[194:197], v[36:39]
	v_mfma_f32_16x16x32_bf16 v[28:31], v[150:153], v[194:197], v[28:31]
	v_mfma_f32_16x16x32_bf16 v[20:23], v[132:135], v[218:221], v[20:23]
	v_mfma_f32_16x16x32_bf16 v[12:15], v[150:153], v[218:221], v[12:15]
	s_barrier
	s_add_u32 s20, s20, 0x80080
	s_addc_u32 s21, s21, 0
	s_add_i32 s22, s22, s29
	s_mov_b32 m0, s22
	s_nop 0
	global_load_lds_dwordx4 v160, s[20:21]
	s_add_i32 m0, s22, 0x2000
	s_nop 0
	global_load_lds_dwordx4 v136, s[20:21]
	s_waitcnt vmcnt(6)
	s_barrier
	v_mfma_f32_16x16x32_bf16 v[48:51], v[222:225], v[174:177], v[48:51]
	v_mfma_f32_16x16x32_bf16 v[40:43], v[230:233], v[174:177], v[40:43]
	v_mfma_f32_16x16x32_bf16 v[32:35], v[222:225], v[182:185], v[32:35]
	v_mfma_f32_16x16x32_bf16 v[24:27], v[230:233], v[182:185], v[24:27]
	v_mfma_f32_16x16x32_bf16 v[16:19], v[222:225], v[190:193], v[16:19]
	v_mfma_f32_16x16x32_bf16 v[8:11], v[230:233], v[190:193], v[8:11]
	v_mfma_f32_16x16x32_bf16 v[4:7], v[222:225], v[214:217], v[4:7]
	v_mfma_f32_16x16x32_bf16 v[0:3], v[230:233], v[214:217], v[0:3]
	v_mfma_f32_16x16x32_bf16 v[48:51], v[226:229], v[178:181], v[48:51]
	v_mfma_f32_16x16x32_bf16 v[40:43], v[234:237], v[178:181], v[40:43]
	v_mfma_f32_16x16x32_bf16 v[32:35], v[226:229], v[186:189], v[32:35]
	v_mfma_f32_16x16x32_bf16 v[24:27], v[234:237], v[186:189], v[24:27]
	v_mfma_f32_16x16x32_bf16 v[16:19], v[226:229], v[194:197], v[16:19]
	v_mfma_f32_16x16x32_bf16 v[8:11], v[234:237], v[194:197], v[8:11]
	v_mfma_f32_16x16x32_bf16 v[4:7], v[226:229], v[218:221], v[4:7]
	v_mfma_f32_16x16x32_bf16 v[0:3], v[234:237], v[218:221], v[0:3]
	s_add_i32 s44, s44, 2
	s_add_u32 s18, s18, 0x100
	s_addc_u32 s19, s19, 0
	s_add_u32 s42, s42, 0x100
	s_addc_u32 s43, s43, 0
	s_cmp_gt_u32 s44, 29
	s_barrier
	s_cbranch_scc0 .LBB0_344
	v_lshl_add_u32 v142, s0, 8, v147
	v_ashrrev_i32_e32 v143, 31, v142
	v_lshlrev_b64 v[128:129], 5, v[142:143]
	v_lshl_add_u64 v[132:133], s[4:5], 0, v[128:129]
	global_load_dwordx4 v[128:131], v[132:133], off offset:16
	s_nop 0
	global_load_dwordx4 v[132:135], v[132:133], off
	s_mov_b32 s0, 0x3727c5ac
	s_mov_b32 s18, 0x3a000000
	s_mov_b32 s11, 0x800000
	s_mov_b64 s[20:21], s[16:17]
	s_waitcnt vmcnt(0)
	v_mov_b32_e32 v144, v133
	v_mov_b32_e32 v145, v134
	v_mov_b32_e32 v133, v135
	v_pk_add_f32 v[150:151], v[144:145], v[132:133]
	v_or_b32_e32 v144, 16, v142
	v_mov_b32_e32 v132, v130
	v_mov_b32_e32 v133, v128
	v_mov_b32_e32 v128, v131
	v_ashrrev_i32_e32 v145, 31, v144
	v_pk_add_f32 v[152:153], v[132:133], v[128:129]
	v_lshlrev_b64 v[128:129], 5, v[144:145]
	v_lshl_add_u64 v[132:133], s[4:5], 0, v[128:129]
	global_load_dwordx4 v[128:131], v[132:133], off offset:16
	s_nop 0
	global_load_dwordx4 v[132:135], v[132:133], off
	s_waitcnt vmcnt(0)
	v_mov_b32_e32 v154, v133
	v_mov_b32_e32 v155, v134
	v_mov_b32_e32 v133, v135
	v_pk_add_f32 v[132:133], v[154:155], v[132:133]
	v_mov_b32_e32 v134, v130
	v_mov_b32_e32 v135, v128
	v_mov_b32_e32 v128, v131
	v_pk_add_f32 v[128:129], v[134:135], v[128:129]
	v_mov_b32_e32 v130, v132
	v_mov_b32_e32 v131, v150
	v_mov_b32_e32 v150, v133
	v_pk_add_f32 v[130:131], v[130:131], v[150:151]
	v_mov_b32_e32 v132, v129
	v_mov_b32_e32 v133, v153
	v_pk_add_f32 v[130:131], v[130:131], v[132:133]
	v_mov_b32_e32 v129, v152
	v_pk_add_f32 v[128:129], v[128:129], v[130:131]
	v_mov_b64_e32 v[150:151], s[0:1]
	v_pk_fma_f32 v[128:129], v[128:129], s[18:19], v[150:151] op_sel_hi:[1,0,0]
	v_or_b32_e32 v152, 32, v142
	v_mul_f32_e32 v130, 0x4b800000, v129
	v_cmp_gt_f32_e64 s[0:1], s11, v129
	v_cmp_gt_f32_e32 vcc, s11, v128
	v_ashrrev_i32_e32 v153, 31, v152
	v_cndmask_b32_e64 v129, v129, v130, s[0:1]
	v_rsq_f32_e32 v129, v129
	s_nop 0
	v_mul_f32_e32 v130, 0x45800000, v129
	v_cndmask_b32_e64 v148, v129, v130, s[0:1]
	v_mul_f32_e32 v129, 0x4b800000, v128
	v_cndmask_b32_e32 v128, v128, v129, vcc
	v_rsq_f32_e32 v128, v128
	v_pk_mul_f32 v[106:107], v[106:107], v[148:149] op_sel_hi:[1,0]
	v_pk_mul_f32 v[104:105], v[104:105], v[148:149] op_sel_hi:[1,0]
	v_pk_mul_f32 v[114:115], v[114:115], v[148:149] op_sel_hi:[1,0]
	v_mul_f32_e32 v129, 0x45800000, v128
	v_cndmask_b32_e32 v146, v128, v129, vcc
	v_lshlrev_b64 v[128:129], 5, v[152:153]
	v_lshl_add_u64 v[132:133], s[4:5], 0, v[128:129]
	global_load_dwordx4 v[128:131], v[132:133], off offset:16
	s_nop 0
	global_load_dwordx4 v[132:135], v[132:133], off
	v_cvt_pk_bf16_f32 v104, v104, v105
	v_cvt_pk_bf16_f32 v105, v106, v107
	v_pk_mul_f32 v[90:91], v[90:91], v[146:147] op_sel_hi:[1,0]
	v_pk_mul_f32 v[88:89], v[88:89], v[146:147] op_sel_hi:[1,0]
	v_pk_mul_f32 v[112:113], v[112:113], v[148:149] op_sel_hi:[1,0]
	v_cvt_pk_bf16_f32 v88, v88, v89
	v_cvt_pk_bf16_f32 v89, v90, v91
	v_pk_mul_f32 v[98:99], v[98:99], v[146:147] op_sel_hi:[1,0]
	v_pk_mul_f32 v[96:97], v[96:97], v[146:147] op_sel_hi:[1,0]
	v_cvt_pk_bf16_f32 v112, v112, v113
	v_cvt_pk_bf16_f32 v113, v114, v115
	v_cvt_pk_bf16_f32 v96, v96, v97
	v_cvt_pk_bf16_f32 v97, v98, v99
	v_pk_mul_f32 v[126:127], v[126:127], v[148:149] op_sel_hi:[1,0]
	v_pk_mul_f32 v[124:125], v[124:125], v[148:149] op_sel_hi:[1,0]
	v_pk_mul_f32 v[122:123], v[122:123], v[148:149] op_sel_hi:[1,0]
	v_pk_mul_f32 v[120:121], v[120:121], v[148:149] op_sel_hi:[1,0]
	v_pk_mul_f32 v[106:107], v[118:119], v[146:147] op_sel_hi:[1,0]
	v_pk_mul_f32 v[110:111], v[110:111], v[146:147] op_sel_hi:[1,0]
	v_pk_mul_f32 v[108:109], v[108:109], v[146:147] op_sel_hi:[1,0]
	v_cvt_pk_bf16_f32 v124, v124, v125
	v_cvt_pk_bf16_f32 v125, v126, v127
	v_cvt_pk_bf16_f32 v120, v120, v121
	v_cvt_pk_bf16_f32 v121, v122, v123
	s_waitcnt vmcnt(0)
; DEV bf16x8 pack8(f32x4 a, f32x4 b) { u32x4 w; w.x = cvt_pk_bf16(a[0], a[1]); w.y = cvt_pk_bf16(a[2], a[3]); w.z = cvt_pk_bf16(b[0], b[1]); w.w = cvt_pk_bf16(b[2], b[3]); return __builtin_bit_cast(bf16x8, w); }
; DEV f32x4 gelu4(f32x4 v) { f32x2 a = gelu_pk((f32x2){v[0], v[1]}), b = gelu_pk((f32x2){v[2], v[3]}); return (f32x4){a.x, a.y, b.x, b.y}; }
; DEV float rowscale(const float* ss, int row) { const f32x4 a = *(const f32x4*)(ss + (size_t)row * 8), b = *(const f32x4*)(ss + (size_t)row * 8 + 4);
;     return rsqrtf(((a[0] + a[1]) + (a[2] + a[3]) + (b[0] + b[1]) + (b[2] + b[3])) * (1.0f / 2048.0f) + EPS); }
; template <int ACT, bool PERM>
; DEV void store_bf16_tile(AccRef acc, u16* O, int ld, int row0, int col0, const float* ss) {
;     float rsv[2][4];
; #pragma unroll
;     for (int ai = 0; ai < 2; ++ai)
; #pragma unroll
;         for (int m = 0; m < 4; ++m) rsv[ai][m] = ss ? rowscale(ss, row0 + ai * 128 + m * 16) : 1.0f;
; #pragma unroll
;     for (int ai = 0; ai < 2; ++ai)
; #pragma unroll
;         for (int m = 0; m < 4; ++m) { u16* rowp = O + (size_t)(row0 + ai * 128 + m * 16) * ld + col0; const float rs = rsv[ai][m];
; #pragma unroll
;             for (int bj = 0; bj < 2; ++bj) { f32x4 v0 = acc[ai][bj][m][0] * rs, v1 = acc[ai][bj][m][1] * rs; if (ACT == 1) { v0 = gelu4(v0); v1 = gelu4(v1); }
;                 if (PERM) *(u32x4*)(rowp + bj * 128) = __builtin_bit_cast(u32x4, pack8(v0, v1));
	v_mov_b32_e32 v154, v133
	v_mov_b32_e32 v155, v134
	v_mov_b32_e32 v133, v135
	v_pk_add_f32 v[174:175], v[154:155], v[132:133]
	v_or_b32_e32 v154, 48, v142
	v_mov_b32_e32 v132, v130
	v_mov_b32_e32 v133, v128
	v_mov_b32_e32 v128, v131
	v_ashrrev_i32_e32 v155, 31, v154
	v_pk_add_f32 v[176:177], v[132:133], v[128:129]
	v_lshlrev_b64 v[128:129], 5, v[154:155]
	v_lshl_add_u64 v[132:133], s[4:5], 0, v[128:129]
	global_load_dwordx4 v[128:131], v[132:133], off offset:16
	s_nop 0
	global_load_dwordx4 v[132:135], v[132:133], off
	s_waitcnt vmcnt(0)
	v_mov_b32_e32 v178, v133
	v_mov_b32_e32 v179, v134
	v_mov_b32_e32 v133, v135
	v_pk_add_f32 v[132:133], v[178:179], v[132:133]
	v_mov_b32_e32 v134, v130
	v_mov_b32_e32 v135, v128
	v_mov_b32_e32 v128, v131
	v_pk_add_f32 v[128:129], v[134:135], v[128:129]
	v_mov_b32_e32 v130, v132
	v_mov_b32_e32 v131, v174
	v_mov_b32_e32 v174, v133
	v_pk_add_f32 v[130:131], v[130:131], v[174:175]
	v_mov_b32_e32 v132, v129
	v_mov_b32_e32 v133, v177
	v_pk_add_f32 v[130:131], v[130:131], v[132:133]
	v_mov_b32_e32 v129, v176
	v_pk_add_f32 v[128:129], v[128:129], v[130:131]
	v_add_u32_e32 v174, 0x80, v142
	v_pk_fma_f32 v[128:129], v[128:129], s[18:19], v[150:151] op_sel_hi:[1,0,0]
	v_ashrrev_i32_e32 v175, 31, v174
	v_mul_f32_e32 v130, 0x4b800000, v129
	v_cmp_gt_f32_e64 s[0:1], s11, v129
	v_cmp_gt_f32_e32 vcc, s11, v128
	s_nop 0
	v_cndmask_b32_e64 v129, v129, v130, s[0:1]
	v_rsq_f32_e32 v129, v129
	s_nop 0
	v_mul_f32_e32 v130, 0x45800000, v129
	v_cndmask_b32_e64 v158, v129, v130, s[0:1]
	v_mul_f32_e32 v129, 0x4b800000, v128
	v_cndmask_b32_e32 v128, v128, v129, vcc
	v_rsq_f32_e32 v128, v128
	v_pk_mul_f32 v[74:75], v[74:75], v[158:159] op_sel_hi:[1,0]
	v_pk_mul_f32 v[72:73], v[72:73], v[158:159] op_sel_hi:[1,0]
	v_pk_mul_f32 v[82:83], v[82:83], v[158:159] op_sel_hi:[1,0]
	v_mul_f32_e32 v129, 0x45800000, v128
	v_cndmask_b32_e32 v156, v128, v129, vcc
	v_lshlrev_b64 v[128:129], 5, v[174:175]
	v_lshl_add_u64 v[132:133], s[4:5], 0, v[128:129]
	global_load_dwordx4 v[128:131], v[132:133], off offset:16
	s_nop 0
	global_load_dwordx4 v[132:135], v[132:133], off
	v_cvt_pk_bf16_f32 v72, v72, v73
	v_cvt_pk_bf16_f32 v73, v74, v75
	v_pk_mul_f32 v[66:67], v[66:67], v[156:157] op_sel_hi:[1,0]
	v_pk_mul_f32 v[64:65], v[64:65], v[156:157] op_sel_hi:[1,0]
	v_pk_mul_f32 v[80:81], v[80:81], v[158:159] op_sel_hi:[1,0]
	v_cvt_pk_bf16_f32 v64, v64, v65
	v_cvt_pk_bf16_f32 v65, v66, v67
	v_cvt_pk_bf16_f32 v80, v80, v81
	v_cvt_pk_bf16_f32 v81, v82, v83
	v_pk_mul_f32 v[90:91], v[102:103], v[158:159] op_sel_hi:[1,0]
	v_pk_mul_f32 v[94:95], v[94:95], v[158:159] op_sel_hi:[1,0]
	v_pk_mul_f32 v[92:93], v[92:93], v[158:159] op_sel_hi:[1,0]
	v_pk_mul_f32 v[74:75], v[86:87], v[156:157] op_sel_hi:[1,0]
	v_pk_mul_f32 v[78:79], v[78:79], v[156:157] op_sel_hi:[1,0]
	v_pk_mul_f32 v[76:77], v[76:77], v[156:157] op_sel_hi:[1,0]
	v_pk_mul_f32 v[70:71], v[70:71], v[156:157] op_sel_hi:[1,0]
	v_pk_mul_f32 v[68:69], v[68:69], v[156:157] op_sel_hi:[1,0]
	s_waitcnt vmcnt(0)
	v_mov_b32_e32 v176, v133
	v_mov_b32_e32 v177, v134
	v_mov_b32_e32 v133, v135
	v_pk_add_f32 v[178:179], v[176:177], v[132:133]
	v_add_u32_e32 v176, 0x90, v142
	v_mov_b32_e32 v132, v130
	v_mov_b32_e32 v133, v128
	v_mov_b32_e32 v128, v131
	v_ashrrev_i32_e32 v177, 31, v176
	v_pk_add_f32 v[180:181], v[132:133], v[128:129]
	v_lshlrev_b64 v[128:129], 5, v[176:177]
	v_lshl_add_u64 v[132:133], s[4:5], 0, v[128:129]
	global_load_dwordx4 v[128:131], v[132:133], off offset:16
	s_nop 0
	global_load_dwordx4 v[132:135], v[132:133], off
	v_cvt_pk_bf16_f32 v68, v68, v69
	v_cvt_pk_bf16_f32 v69, v70, v71
	s_waitcnt vmcnt(0)
	v_mov_b32_e32 v182, v133
	v_mov_b32_e32 v183, v134
	v_mov_b32_e32 v133, v135
	v_pk_add_f32 v[132:133], v[182:183], v[132:133]
	v_mov_b32_e32 v134, v130
	v_mov_b32_e32 v135, v128
	v_mov_b32_e32 v128, v131
	v_pk_add_f32 v[128:129], v[134:135], v[128:129]
	v_mov_b32_e32 v130, v132
	v_mov_b32_e32 v131, v178
	v_mov_b32_e32 v178, v133
	v_pk_add_f32 v[130:131], v[130:131], v[178:179]
	v_mov_b32_e32 v132, v129
	v_mov_b32_e32 v133, v181
	v_pk_add_f32 v[130:131], v[130:131], v[132:133]
	v_mov_b32_e32 v129, v180
	v_pk_add_f32 v[128:129], v[128:129], v[130:131]
	v_add_u32_e32 v182, 0xa0, v142
	v_pk_fma_f32 v[128:129], v[128:129], s[18:19], v[150:151] op_sel_hi:[1,0,0]
	v_ashrrev_i32_e32 v183, 31, v182
	v_mul_f32_e32 v130, 0x4b800000, v129
	v_cmp_gt_f32_e64 s[0:1], s11, v129
	v_cmp_gt_f32_e32 vcc, s11, v128
	s_nop 0
	v_cndmask_b32_e64 v129, v129, v130, s[0:1]
	v_rsq_f32_e32 v129, v129
	s_nop 0
	v_mul_f32_e32 v130, 0x45800000, v129
	v_cndmask_b32_e64 v180, v129, v130, s[0:1]
	v_mul_f32_e32 v129, 0x4b800000, v128
	v_cndmask_b32_e32 v128, v128, v129, vcc
	v_rsq_f32_e32 v128, v128
	v_pk_mul_f32 v[42:43], v[42:43], v[180:181] op_sel_hi:[1,0]
	v_pk_mul_f32 v[40:41], v[40:41], v[180:181] op_sel_hi:[1,0]
	v_pk_mul_f32 v[50:51], v[50:51], v[180:181] op_sel_hi:[1,0]
	v_mul_f32_e32 v129, 0x45800000, v128
	v_cndmask_b32_e32 v178, v128, v129, vcc
	v_lshlrev_b64 v[128:129], 5, v[182:183]
	v_lshl_add_u64 v[132:133], s[4:5], 0, v[128:129]
	global_load_dwordx4 v[128:131], v[132:133], off offset:16
	s_nop 0
	global_load_dwordx4 v[132:135], v[132:133], off
	v_cvt_pk_bf16_f32 v40, v40, v41
	v_cvt_pk_bf16_f32 v41, v42, v43
	v_pk_mul_f32 v[26:27], v[26:27], v[178:179] op_sel_hi:[1,0]
	v_pk_mul_f32 v[24:25], v[24:25], v[178:179] op_sel_hi:[1,0]
	v_pk_mul_f32 v[48:49], v[48:49], v[180:181] op_sel_hi:[1,0]
	v_cvt_pk_bf16_f32 v24, v24, v25
	v_cvt_pk_bf16_f32 v25, v26, v27
	v_pk_mul_f32 v[34:35], v[34:35], v[178:179] op_sel_hi:[1,0]
	v_pk_mul_f32 v[32:33], v[32:33], v[178:179] op_sel_hi:[1,0]
	v_cvt_pk_bf16_f32 v48, v48, v49
	v_cvt_pk_bf16_f32 v49, v50, v51
	v_cvt_pk_bf16_f32 v32, v32, v33
	v_cvt_pk_bf16_f32 v33, v34, v35
	v_pk_mul_f32 v[62:63], v[62:63], v[180:181] op_sel_hi:[1,0]
	v_pk_mul_f32 v[60:61], v[60:61], v[180:181] op_sel_hi:[1,0]
	v_pk_mul_f32 v[58:59], v[58:59], v[180:181] op_sel_hi:[1,0]
	v_pk_mul_f32 v[56:57], v[56:57], v[180:181] op_sel_hi:[1,0]
	v_pk_mul_f32 v[42:43], v[54:55], v[178:179] op_sel_hi:[1,0]
	v_pk_mul_f32 v[46:47], v[46:47], v[178:179] op_sel_hi:[1,0]
	v_pk_mul_f32 v[44:45], v[44:45], v[178:179] op_sel_hi:[1,0]
	v_cvt_pk_bf16_f32 v60, v60, v61
	v_cvt_pk_bf16_f32 v61, v62, v63
	v_cvt_pk_bf16_f32 v56, v56, v57
	v_cvt_pk_bf16_f32 v57, v58, v59
	s_waitcnt vmcnt(0)
; DEV bf16x8 pack8(f32x4 a, f32x4 b) { u32x4 w; w.x = cvt_pk_bf16(a[0], a[1]); w.y = cvt_pk_bf16(a[2], a[3]); w.z = cvt_pk_bf16(b[0], b[1]); w.w = cvt_pk_bf16(b[2], b[3]); return __builtin_bit_cast(bf16x8, w); }
; DEV u32x2 pack4(f32x4 a) { u32x2 w; w.x = cvt_pk_bf16(a[0], a[1]); w.y = cvt_pk_bf16(a[2], a[3]); return w; }
; DEV f32x4 gelu4(f32x4 v) { f32x2 a = gelu_pk((f32x2){v[0], v[1]}), b = gelu_pk((f32x2){v[2], v[3]}); return (f32x4){a.x, a.y, b.x, b.y}; }
; template <int ACT, bool PERM>
; DEV void store_bf16_tile(AccRef acc, u16* O, int ld, int row0, int col0, const float* ss) {
;     ...
;     for (int ai = 0; ai < 2; ++ai)
; #pragma unroll
;         for (int m = 0; m < 4; ++m) { u16* rowp = O + (size_t)(row0 + ai * 128 + m * 16) * ld + col0; const float rs = rsv[ai][m];
; #pragma unroll
;             for (int bj = 0; bj < 2; ++bj) { f32x4 v0 = acc[ai][bj][m][0] * rs, v1 = acc[ai][bj][m][1] * rs; if (ACT == 1) { v0 = gelu4(v0); v1 = gelu4(v1); }
;                 if (PERM) *(u32x4*)(rowp + bj * 128) = __builtin_bit_cast(u32x4, pack8(v0, v1));
;                 else { *(u32x2*)(rowp + bj * 128) = pack4(v0); *(u32x2*)(rowp + bj * 128 + 16) = pack4(v1); } } }
	v_mov_b32_e32 v184, v133
	v_mov_b32_e32 v185, v134
	v_mov_b32_e32 v133, v135
	v_pk_add_f32 v[188:189], v[184:185], v[132:133]
	v_add_u32_e32 v184, 0xb0, v142
	v_mov_b32_e32 v132, v130
	v_mov_b32_e32 v133, v128
	v_mov_b32_e32 v128, v131
	v_ashrrev_i32_e32 v185, 31, v184
	v_pk_add_f32 v[186:187], v[132:133], v[128:129]
	v_lshlrev_b64 v[128:129], 5, v[184:185]
	v_lshl_add_u64 v[132:133], s[4:5], 0, v[128:129]
	global_load_dwordx4 v[128:131], v[132:133], off offset:16
	s_nop 0
	global_load_dwordx4 v[132:135], v[132:133], off
	s_waitcnt vmcnt(0)
	v_mov_b32_e32 v190, v133
	v_mov_b32_e32 v191, v134
	v_mov_b32_e32 v133, v135
	v_pk_add_f32 v[132:133], v[190:191], v[132:133]
	v_mov_b32_e32 v134, v130
	v_mov_b32_e32 v135, v128
	v_mov_b32_e32 v128, v131
	v_pk_add_f32 v[128:129], v[134:135], v[128:129]
	v_mov_b32_e32 v130, v132
	v_mov_b32_e32 v131, v188
	v_mov_b32_e32 v188, v133
	v_pk_add_f32 v[130:131], v[130:131], v[188:189]
	v_mov_b32_e32 v132, v129
	v_mov_b32_e32 v133, v187
	v_pk_add_f32 v[130:131], v[130:131], v[132:133]
	v_mov_b32_e32 v129, v186
	v_pk_add_f32 v[128:129], v[128:129], v[130:131]
	v_lshl_or_b32 v132, s40, 8, v157
	v_pk_fma_f32 v[128:129], v[128:129], s[18:19], v[150:151] op_sel_hi:[1,0,0]
	v_ashrrev_i32_e32 v133, 31, v132
	v_mul_f32_e32 v130, 0x4b800000, v129
	v_cmp_gt_f32_e64 s[0:1], s11, v129
	v_lshlrev_b64 v[134:135], 10, v[142:143]
	v_cmp_gt_f32_e32 vcc, s11, v128
	v_cndmask_b32_e64 v129, v129, v130, s[0:1]
	v_rsq_f32_e32 v129, v129
	s_mov_b32 s40, s10
	s_mov_b64 s[18:19], s[14:15]
	v_mul_f32_e32 v130, 0x45800000, v129
	v_cndmask_b32_e64 v130, v129, v130, s[0:1]
	v_readlane_b32 s0, v250, 11
	v_readlane_b32 s1, v250, 12
	v_mul_f32_e32 v129, 0x4b800000, v128
	v_cndmask_b32_e32 v128, v128, v129, vcc
	v_lshl_add_u64 v[132:133], v[132:133], 1, s[0:1]
	v_lshl_add_u64 v[134:135], v[132:133], 0, v[134:135]
	global_store_dwordx2 v[134:135], v[104:105], off offset:288
	v_lshlrev_b64 v[104:105], 10, v[144:145]
	v_lshl_add_u64 v[104:105], v[132:133], 0, v[104:105]
	global_store_dwordx2 v[104:105], v[88:89], off offset:288
	v_lshlrev_b64 v[88:89], 10, v[152:153]
	v_lshl_add_u64 v[88:89], v[132:133], 0, v[88:89]
	global_store_dwordx2 v[88:89], v[72:73], off offset:288
	v_lshlrev_b64 v[72:73], 10, v[154:155]
	v_lshl_add_u64 v[72:73], v[132:133], 0, v[72:73]
	v_rsq_f32_e32 v128, v128
	global_store_dwordx2 v[72:73], v[64:65], off offset:288
	v_lshlrev_b64 v[64:65], 10, v[174:175]
	v_lshl_add_u64 v[64:65], v[132:133], 0, v[64:65]
	global_store_dwordx2 v[64:65], v[40:41], off offset:288
	v_lshlrev_b64 v[40:41], 10, v[176:177]
	v_lshl_add_u64 v[40:41], v[132:133], 0, v[40:41]
	v_mul_f32_e32 v129, 0x45800000, v128
	global_store_dwordx2 v[40:41], v[24:25], off offset:288
	v_lshlrev_b64 v[24:25], 10, v[182:183]
	v_pk_mul_f32 v[18:19], v[18:19], v[130:131] op_sel_hi:[1,0]
	v_pk_mul_f32 v[16:17], v[16:17], v[130:131] op_sel_hi:[1,0]
	v_pk_mul_f32 v[10:11], v[10:11], v[130:131] op_sel_hi:[1,0]
	v_pk_mul_f32 v[8:9], v[8:9], v[130:131] op_sel_hi:[1,0]
	v_cndmask_b32_e32 v128, v128, v129, vcc
	v_lshl_add_u64 v[24:25], v[132:133], 0, v[24:25]
	v_cvt_pk_bf16_f32 v16, v16, v17
	v_cvt_pk_bf16_f32 v17, v18, v19
	v_cvt_pk_bf16_f32 v8, v8, v9
	v_cvt_pk_bf16_f32 v9, v10, v11
	global_store_dwordx2 v[134:135], v[112:113], off offset:256
	v_pk_mul_f32 v[112:113], v[116:117], v[146:147] op_sel_hi:[1,0]
	global_store_dwordx2 v[104:105], v[96:97], off offset:256
	v_pk_mul_f32 v[96:97], v[100:101], v[158:159] op_sel_hi:[1,0]
	global_store_dwordx2 v[88:89], v[80:81], off offset:256
	v_pk_mul_f32 v[80:81], v[84:85], v[156:157] op_sel_hi:[1,0]
	global_store_dwordx2 v[64:65], v[48:49], off offset:256
	v_pk_mul_f32 v[48:49], v[52:53], v[178:179] op_sel_hi:[1,0]
	global_store_dwordx2 v[40:41], v[32:33], off offset:256
	v_pk_mul_f32 v[26:27], v[38:39], v[130:131] op_sel_hi:[1,0]
	v_pk_mul_f32 v[32:33], v[36:37], v[130:131] op_sel_hi:[1,0]
	v_pk_mul_f32 v[30:31], v[30:31], v[130:131] op_sel_hi:[1,0]
	v_pk_mul_f32 v[28:29], v[28:29], v[130:131] op_sel_hi:[1,0]
	global_store_dwordx2 v[24:25], v[16:17], off offset:256
	global_store_dwordx2 v[24:25], v[8:9], off offset:288
	v_lshlrev_b64 v[8:9], 10, v[184:185]
	v_pk_mul_f32 v[10:11], v[22:23], v[128:129] op_sel_hi:[1,0]
	v_pk_mul_f32 v[16:17], v[20:21], v[128:129] op_sel_hi:[1,0]
	v_pk_mul_f32 v[14:15], v[14:15], v[128:129] op_sel_hi:[1,0]
	v_pk_mul_f32 v[12:13], v[12:13], v[128:129] op_sel_hi:[1,0]
	v_pk_mul_f32 v[6:7], v[6:7], v[128:129] op_sel_hi:[1,0]
	v_pk_mul_f32 v[4:5], v[4:5], v[128:129] op_sel_hi:[1,0]
	v_pk_mul_f32 v[2:3], v[2:3], v[128:129] op_sel_hi:[1,0]
	v_pk_mul_f32 v[0:1], v[0:1], v[128:129] op_sel_hi:[1,0]
	v_cvt_pk_bf16_f32 v112, v112, v113
	v_cvt_pk_bf16_f32 v113, v106, v107
	v_cvt_pk_bf16_f32 v106, v108, v109
	v_cvt_pk_bf16_f32 v107, v110, v111
	v_cvt_pk_bf16_f32 v96, v96, v97
	v_cvt_pk_bf16_f32 v97, v90, v91
	v_cvt_pk_bf16_f32 v90, v92, v93
	v_cvt_pk_bf16_f32 v91, v94, v95
	v_cvt_pk_bf16_f32 v80, v80, v81
	v_cvt_pk_bf16_f32 v81, v74, v75
	v_cvt_pk_bf16_f32 v74, v76, v77
	v_cvt_pk_bf16_f32 v75, v78, v79
	v_cvt_pk_bf16_f32 v48, v48, v49
	v_cvt_pk_bf16_f32 v49, v42, v43
	v_cvt_pk_bf16_f32 v42, v44, v45
	v_cvt_pk_bf16_f32 v43, v46, v47
	v_cvt_pk_bf16_f32 v32, v32, v33
	v_cvt_pk_bf16_f32 v33, v26, v27
	v_cvt_pk_bf16_f32 v26, v28, v29
	v_cvt_pk_bf16_f32 v27, v30, v31
	v_lshl_add_u64 v[8:9], v[132:133], 0, v[8:9]
	v_cvt_pk_bf16_f32 v16, v16, v17
	v_cvt_pk_bf16_f32 v17, v10, v11
	v_cvt_pk_bf16_f32 v10, v12, v13
	v_cvt_pk_bf16_f32 v11, v14, v15
	v_cvt_pk_bf16_f32 v4, v4, v5
	v_cvt_pk_bf16_f32 v5, v6, v7
	v_cvt_pk_bf16_f32 v0, v0, v1
	v_cvt_pk_bf16_f32 v1, v2, v3
	s_and_b64 vcc, exec, s[6:7]
	s_mov_b32 s0, s12
	global_store_dwordx2 v[134:135], v[124:125], off
	global_store_dwordx2 v[134:135], v[120:121], off offset:32
	global_store_dwordx2 v[104:105], v[112:113], off
	global_store_dwordx2 v[104:105], v[106:107], off offset:32
	global_store_dwordx2 v[88:89], v[96:97], off
	global_store_dwordx2 v[88:89], v[90:91], off offset:32
	global_store_dwordx2 v[72:73], v[80:81], off
	global_store_dwordx2 v[72:73], v[74:75], off offset:32
	global_store_dwordx2 v[72:73], v[68:69], off offset:256
	global_store_dwordx2 v[64:65], v[60:61], off
	global_store_dwordx2 v[64:65], v[56:57], off offset:32
	global_store_dwordx2 v[40:41], v[48:49], off
	global_store_dwordx2 v[40:41], v[42:43], off offset:32
	global_store_dwordx2 v[24:25], v[32:33], off
	global_store_dwordx2 v[24:25], v[26:27], off offset:32
	global_store_dwordx2 v[8:9], v[16:17], off
	global_store_dwordx2 v[8:9], v[10:11], off offset:32
	global_store_dwordx2 v[8:9], v[4:5], off offset:256
	global_store_dwordx2 v[8:9], v[0:1], off offset:288
	s_cbranch_vccz .LBB0_337
	s_waitcnt vmcnt(0)
	s_cmpk_gt_u32 s25, 0xff
	s_cbranch_scc1 .LBB0_348
	s_barrier

; #define PG8_STAGE(bufoff, gbase, voff) do { _Pragma("unroll") for (int _i = 0; _i < 2; ++_i) \
;         __builtin_amdgcn_global_load_lds((const unsigned*)((const char*)(gbase) + (voff)[_i]), (LAS unsigned*)(lds + (bufoff) + ldsw + _i * 8192), 16, 0, 0); } while (0)
; #define PG8_LDA(dst, b, h) do { _Pragma("unroll") for (int m = 0; m < 4; ++m) _Pragma("unroll") for (int k = 0; k < 2; ++k) dst[m][k] = *(const LAS bf16x8*)(lds + PG8_SA(b, h) + aoff + m * 2048 + k * 1024); } while (0)
; #define PG8_LDB(dst, b, h) do { _Pragma("unroll") for (int n = 0; n < 2; ++n) _Pragma("unroll") for (int k = 0; k < 2; ++k) dst[n][k] = *(const LAS bf16x8*)(lds + PG8_SB(b, h) + boff + n * 2048 + k * 1024); } while (0)
; #define PG8_MMA(ai, bj, At, Bt) do { __builtin_amdgcn_s_setprio(1); _Pragma("unroll") for (int m = 0; m < 4; ++m) _Pragma("unroll") for (int n = 0; n < 2; ++n) _Pragma("unroll") for (int k = 0; k < 2; ++k) \
;         acc[ai][bj][m][n] = __builtin_amdgcn_mfma_f32_16x16x32_bf16(Bt[n][k], At[m][k], acc[ai][bj][m][n], 0, 0, 0); __builtin_amdgcn_s_setprio(0); } while (0)
; #define PG8_WAIT_V(n) asm volatile("s_waitcnt vmcnt(" #n ")" ::: "memory")
; #define PG8_WAIT_L(n) asm volatile("s_waitcnt lgkmcnt(" #n ")" ::: "memory")
; #define PG8_BAR __builtin_amdgcn_s_barrier()
; #define PG8_SCHED __builtin_amdgcn_sched_barrier(0)
; template <class Epi>
; DEV void gemm_phase(LAS unsigned char* lds, const Gemm g, const StaticOrder& S, const Epi& E) {
;     ...
;             const bool last = (t == nt - 2);
;             const char* a1 = cA + (size_t)(t + 1) * kstep;
;             const char* a2 = last ? nA : cA + (size_t)(t + 2) * kstep; const char* b2 = last ? nB : cB + (size_t)(t + 2) * kstep;
;             const char* a3 = a2 + kstep; const char* b3 = b2 + kstep;
;             PG8_LDB(B0, 0, 0); PG8_SCHED; PG8_LDA(At, 0, 0); PG8_STAGE(PG8_SA(1, 1), a1 + hstep, voffA);
;             PG8_WAIT_L(8); PG8_BAR; PG8_WAIT_L(0); PG8_MMA(0, 0, At, B0); PG8_BAR; PG8_SCHED;
;             PG8_LDB(B1, 0, 1); PG8_STAGE(PG8_SB(0, 0), b2, voffB);
;             PG8_BAR; PG8_WAIT_L(0); PG8_MMA(0, 1, At, B1); PG8_BAR;
;             PG8_LDA(At, 0, 1); PG8_STAGE(PG8_SA(0, 0), a2, voffA);
;             PG8_BAR; PG8_WAIT_L(0); PG8_MMA(1, 0, At, B0); PG8_BAR; PG8_SCHED;
;             PG8_STAGE(PG8_SB(0, 1), b2 + hstep, voffB);
;             PG8_WAIT_V(6); PG8_BAR; PG8_MMA(1, 1, At, B1); PG8_BAR;
.LBB0_362:
	s_add_u32 s26, s24, 0xfff80080
	s_addc_u32 s27, s25, -1
	s_add_i32 s56, 0, 0x10000
	v_add_u32_e32 v150, s56, v135
	ds_read_b128 v[138:141], v150
	ds_read_b128 v[142:145], v150 offset:1024
	ds_read_b128 v[146:149], v150 offset:2048
	ds_read_b128 v[150:153], v150 offset:3072
	s_cmp_eq_u32 s55, 28
	s_cselect_b32 s29, s19, s27
	s_cselect_b32 s28, s51, s26
	s_cselect_b32 s27, s17, s54
	s_cselect_b32 s26, s52, s53
	s_add_i32 m0, s13, 0xc000
	ds_read_b128 v[154:157], v137
	ds_read_b128 v[174:177], v137 offset:1024
	ds_read_b128 v[178:181], v137 offset:2048
	ds_read_b128 v[182:185], v137 offset:3072
	ds_read_b128 v[186:189], v137 offset:4096
	ds_read_b128 v[190:193], v137 offset:5120
	ds_read_b128 v[194:197], v137 offset:6144
	ds_read_b128 v[214:217], v137 offset:7168
	global_load_lds_dwordx4 v130, s[24:25]
	s_add_i32 m0, s13, 0xe000
	s_nop 0
	global_load_lds_dwordx4 v132, s[24:25]
	s_waitcnt lgkmcnt(8)
	s_barrier
	s_waitcnt lgkmcnt(0)
	v_mfma_f32_16x16x32_bf16 v[124:127], v[138:141], v[154:157], v[124:127]
	v_mfma_f32_16x16x32_bf16 v[120:123], v[146:149], v[154:157], v[120:123]
	v_mfma_f32_16x16x32_bf16 v[116:119], v[138:141], v[178:181], v[116:119]
	v_mfma_f32_16x16x32_bf16 v[108:111], v[146:149], v[178:181], v[108:111]
	v_mfma_f32_16x16x32_bf16 v[100:103], v[138:141], v[186:189], v[100:103]
	v_mfma_f32_16x16x32_bf16 v[92:95], v[146:149], v[186:189], v[92:95]
	v_mfma_f32_16x16x32_bf16 v[84:87], v[138:141], v[194:197], v[84:87]
	v_mfma_f32_16x16x32_bf16 v[76:79], v[146:149], v[194:197], v[76:79]
	v_mfma_f32_16x16x32_bf16 v[124:127], v[142:145], v[174:177], v[124:127]
	v_mfma_f32_16x16x32_bf16 v[120:123], v[150:153], v[174:177], v[120:123]
	v_mfma_f32_16x16x32_bf16 v[116:119], v[142:145], v[182:185], v[116:119]
	v_mfma_f32_16x16x32_bf16 v[108:111], v[150:153], v[182:185], v[108:111]
	v_mfma_f32_16x16x32_bf16 v[100:103], v[142:145], v[190:193], v[100:103]
	v_mfma_f32_16x16x32_bf16 v[92:95], v[150:153], v[190:193], v[92:95]
	v_mfma_f32_16x16x32_bf16 v[84:87], v[142:145], v[214:217], v[84:87]
	v_mfma_f32_16x16x32_bf16 v[76:79], v[150:153], v[214:217], v[76:79]
	s_barrier
	s_add_i32 s58, 0, 0x14000
	v_add_u32_e32 v158, s58, v135
	s_add_i32 s56, s56, s41
	ds_read_b128 v[218:221], v158
	ds_read_b128 v[222:225], v158 offset:1024
	ds_read_b128 v[226:229], v158 offset:2048
	ds_read_b128 v[230:233], v158 offset:3072
	v_lshl_add_u64 v[158:159], s[26:27], 0, v[160:161]
	s_mov_b32 m0, s56
	v_lshl_add_u64 v[234:235], s[26:27], 0, v[128:129]
	global_load_lds_dwordx4 v160, s[26:27]
	s_add_i32 m0, s56, 0x2000
	s_nop 0
	global_load_lds_dwordx4 v128, s[26:27]
	s_barrier
	s_waitcnt lgkmcnt(0)
	v_mfma_f32_16x16x32_bf16 v[112:115], v[218:221], v[154:157], v[112:115]
	v_mfma_f32_16x16x32_bf16 v[104:107], v[226:229], v[154:157], v[104:107]
	v_mfma_f32_16x16x32_bf16 v[96:99], v[218:221], v[178:181], v[96:99]
	v_mfma_f32_16x16x32_bf16 v[88:91], v[226:229], v[178:181], v[88:91]
	v_mfma_f32_16x16x32_bf16 v[80:83], v[218:221], v[186:189], v[80:83]
	v_mfma_f32_16x16x32_bf16 v[72:75], v[226:229], v[186:189], v[72:75]
	v_mfma_f32_16x16x32_bf16 v[68:71], v[218:221], v[194:197], v[68:71]
	v_mfma_f32_16x16x32_bf16 v[64:67], v[226:229], v[194:197], v[64:67]
	v_mfma_f32_16x16x32_bf16 v[112:115], v[222:225], v[174:177], v[112:115]
	v_mfma_f32_16x16x32_bf16 v[104:107], v[230:233], v[174:177], v[104:107]
	v_mfma_f32_16x16x32_bf16 v[96:99], v[222:225], v[182:185], v[96:99]
	v_mfma_f32_16x16x32_bf16 v[88:91], v[230:233], v[182:185], v[88:91]
	v_mfma_f32_16x16x32_bf16 v[80:83], v[222:225], v[190:193], v[80:83]
	v_mfma_f32_16x16x32_bf16 v[72:75], v[230:233], v[190:193], v[72:75]
	v_mfma_f32_16x16x32_bf16 v[68:71], v[222:225], v[214:217], v[68:71]
	v_mfma_f32_16x16x32_bf16 v[64:67], v[230:233], v[214:217], v[64:67]
	s_mov_b32 m0, s13
	v_lshl_add_u64 v[236:237], s[28:29], 0, v[160:161]
	s_barrier
	ds_read_b128 v[154:157], v137 offset:16384
	ds_read_b128 v[174:177], v137 offset:17408
	ds_read_b128 v[178:181], v137 offset:18432
	ds_read_b128 v[182:185], v137 offset:19456
	ds_read_b128 v[186:189], v137 offset:20480
	ds_read_b128 v[190:193], v137 offset:21504
	ds_read_b128 v[194:197], v137 offset:22528
	ds_read_b128 v[214:217], v137 offset:23552
	global_load_lds_dwordx4 v160, s[28:29]
	v_lshl_add_u64 v[238:239], s[28:29], 0, v[128:129]
	s_mov_b32 m0, s43
	s_nop 0
	global_load_lds_dwordx4 v128, s[28:29]
	s_barrier
	s_waitcnt lgkmcnt(0)
	v_mfma_f32_16x16x32_bf16 v[60:63], v[138:141], v[154:157], v[60:63]
	v_mfma_f32_16x16x32_bf16 v[56:59], v[146:149], v[154:157], v[56:59]
	v_mfma_f32_16x16x32_bf16 v[52:55], v[138:141], v[178:181], v[52:55]
	v_mfma_f32_16x16x32_bf16 v[44:47], v[146:149], v[178:181], v[44:47]
	v_mfma_f32_16x16x32_bf16 v[36:39], v[138:141], v[186:189], v[36:39]
	v_mfma_f32_16x16x32_bf16 v[28:31], v[146:149], v[186:189], v[28:31]
	v_mfma_f32_16x16x32_bf16 v[20:23], v[138:141], v[194:197], v[20:23]
	v_mfma_f32_16x16x32_bf16 v[12:15], v[146:149], v[194:197], v[12:15]
	v_mfma_f32_16x16x32_bf16 v[60:63], v[142:145], v[174:177], v[60:63]
	v_mfma_f32_16x16x32_bf16 v[56:59], v[150:153], v[174:177], v[56:59]
	v_mfma_f32_16x16x32_bf16 v[52:55], v[142:145], v[182:185], v[52:55]
	v_mfma_f32_16x16x32_bf16 v[44:47], v[150:153], v[182:185], v[44:47]
	v_mfma_f32_16x16x32_bf16 v[36:39], v[142:145], v[190:193], v[36:39]
	v_mfma_f32_16x16x32_bf16 v[28:31], v[150:153], v[190:193], v[28:31]
	v_mfma_f32_16x16x32_bf16 v[20:23], v[142:145], v[214:217], v[20:23]
	v_mfma_f32_16x16x32_bf16 v[12:15], v[150:153], v[214:217], v[12:15]
	s_barrier
	s_add_u32 s56, s26, 0x80000
	s_addc_u32 s57, s27, 0
	s_add_i32 s58, s58, s41
	s_mov_b32 m0, s58
	s_nop 0
	global_load_lds_dwordx4 v160, s[56:57]
	s_add_i32 m0, s58, 0x2000
	s_nop 0
	global_load_lds_dwordx4 v128, s[56:57]
	s_waitcnt vmcnt(6)
	s_barrier
; #define PG8_STAGE(bufoff, gbase, voff) do { _Pragma("unroll") for (int _i = 0; _i < 2; ++_i) \
;         __builtin_amdgcn_global_load_lds((const unsigned*)((const char*)(gbase) + (voff)[_i]), (LAS unsigned*)(lds + (bufoff) + ldsw + _i * 8192), 16, 0, 0); } while (0)
; #define PG8_LDA(dst, b, h) do { _Pragma("unroll") for (int m = 0; m < 4; ++m) _Pragma("unroll") for (int k = 0; k < 2; ++k) dst[m][k] = *(const LAS bf16x8*)(lds + PG8_SA(b, h) + aoff + m * 2048 + k * 1024); } while (0)
; #define PG8_LDB(dst, b, h) do { _Pragma("unroll") for (int n = 0; n < 2; ++n) _Pragma("unroll") for (int k = 0; k < 2; ++k) dst[n][k] = *(const LAS bf16x8*)(lds + PG8_SB(b, h) + boff + n * 2048 + k * 1024); } while (0)
; #define PG8_MMA(ai, bj, At, Bt) do { __builtin_amdgcn_s_setprio(1); _Pragma("unroll") for (int m = 0; m < 4; ++m) _Pragma("unroll") for (int n = 0; n < 2; ++n) _Pragma("unroll") for (int k = 0; k < 2; ++k) \
;         acc[ai][bj][m][n] = __builtin_amdgcn_mfma_f32_16x16x32_bf16(Bt[n][k], At[m][k], acc[ai][bj][m][n], 0, 0, 0); __builtin_amdgcn_s_setprio(0); } while (0)
; #define PG8_WAIT_V(n) asm volatile("s_waitcnt vmcnt(" #n ")" ::: "memory")
; #define PG8_WAIT_L(n) asm volatile("s_waitcnt lgkmcnt(" #n ")" ::: "memory")
; #define PG8_BAR __builtin_amdgcn_s_barrier()
; #define PG8_SCHED __builtin_amdgcn_sched_barrier(0)
; template <class Epi>
; DEV void gemm_phase(LAS unsigned char* lds, const Gemm g, const StaticOrder& S, const Epi& E) {
;     ...
;             PG8_WAIT_V(6); PG8_BAR; PG8_MMA(1, 1, At, B1); PG8_BAR;
;             PG8_LDB(B0, 1, 0); PG8_SCHED; PG8_LDA(At, 1, 0); PG8_STAGE(PG8_SA(0, 1), a2 + hstep, voffA);
;             PG8_WAIT_L(8); PG8_BAR; PG8_WAIT_L(0); PG8_MMA(0, 0, At, B0); PG8_BAR; PG8_SCHED;
;             PG8_LDB(B1, 1, 1); PG8_STAGE(PG8_SB(1, 0), b3, voffB);
;             PG8_BAR; PG8_WAIT_L(0); PG8_MMA(0, 1, At, B1); PG8_BAR;
;             PG8_LDA(At, 1, 1); PG8_STAGE(PG8_SA(1, 0), a3, voffA);
;             PG8_BAR; PG8_WAIT_L(0); PG8_MMA(1, 0, At, B0); PG8_BAR; PG8_SCHED;
	v_mfma_f32_16x16x32_bf16 v[48:51], v[218:221], v[154:157], v[48:51]
	v_mfma_f32_16x16x32_bf16 v[40:43], v[226:229], v[154:157], v[40:43]
	v_mfma_f32_16x16x32_bf16 v[32:35], v[218:221], v[178:181], v[32:35]
	v_mfma_f32_16x16x32_bf16 v[24:27], v[226:229], v[178:181], v[24:27]
	v_mfma_f32_16x16x32_bf16 v[16:19], v[218:221], v[186:189], v[16:19]
	v_mfma_f32_16x16x32_bf16 v[8:11], v[226:229], v[186:189], v[8:11]
	v_mfma_f32_16x16x32_bf16 v[4:7], v[218:221], v[194:197], v[4:7]
	v_mfma_f32_16x16x32_bf16 v[0:3], v[226:229], v[194:197], v[0:3]
	v_mfma_f32_16x16x32_bf16 v[48:51], v[222:225], v[174:177], v[48:51]
	v_mfma_f32_16x16x32_bf16 v[40:43], v[230:233], v[174:177], v[40:43]
	v_mfma_f32_16x16x32_bf16 v[32:35], v[222:225], v[182:185], v[32:35]
	v_mfma_f32_16x16x32_bf16 v[24:27], v[230:233], v[182:185], v[24:27]
	v_mfma_f32_16x16x32_bf16 v[16:19], v[222:225], v[190:193], v[16:19]
	v_mfma_f32_16x16x32_bf16 v[8:11], v[230:233], v[190:193], v[8:11]
	v_mfma_f32_16x16x32_bf16 v[4:7], v[222:225], v[214:217], v[4:7]
	v_mfma_f32_16x16x32_bf16 v[0:3], v[230:233], v[214:217], v[0:3]
	s_add_i32 s56, 0, 0x18000
	v_add_u32_e32 v150, s56, v135
	s_barrier
	ds_read_b128 v[138:141], v150
	ds_read_b128 v[142:145], v150 offset:1024
	ds_read_b128 v[146:149], v150 offset:2048
	ds_read_b128 v[150:153], v150 offset:3072
	s_add_u32 s28, s28, 0x80000
	s_addc_u32 s29, s29, 0
	s_mov_b32 m0, s44
	ds_read_b128 v[154:157], v137 offset:32768
	ds_read_b128 v[174:177], v137 offset:33792
	ds_read_b128 v[178:181], v137 offset:34816
	ds_read_b128 v[182:185], v137 offset:35840
	ds_read_b128 v[186:189], v137 offset:36864
	ds_read_b128 v[190:193], v137 offset:37888
	ds_read_b128 v[194:197], v137 offset:38912
	ds_read_b128 v[214:217], v137 offset:39936
	global_load_lds_dwordx4 v160, s[28:29]
	s_mov_b32 m0, s45
	s_nop 0
	global_load_lds_dwordx4 v128, s[28:29]
	s_waitcnt lgkmcnt(8)
	s_barrier
	s_waitcnt lgkmcnt(0)
	v_mfma_f32_16x16x32_bf16 v[124:127], v[138:141], v[154:157], v[124:127]
	v_mfma_f32_16x16x32_bf16 v[120:123], v[146:149], v[154:157], v[120:123]
	v_mfma_f32_16x16x32_bf16 v[116:119], v[138:141], v[178:181], v[116:119]
	v_mfma_f32_16x16x32_bf16 v[108:111], v[146:149], v[178:181], v[108:111]
	v_mfma_f32_16x16x32_bf16 v[100:103], v[138:141], v[186:189], v[100:103]
	v_mfma_f32_16x16x32_bf16 v[92:95], v[146:149], v[186:189], v[92:95]
	v_mfma_f32_16x16x32_bf16 v[84:87], v[138:141], v[194:197], v[84:87]
	v_mfma_f32_16x16x32_bf16 v[76:79], v[146:149], v[194:197], v[76:79]
	v_mfma_f32_16x16x32_bf16 v[124:127], v[142:145], v[174:177], v[124:127]
	v_mfma_f32_16x16x32_bf16 v[120:123], v[150:153], v[174:177], v[120:123]
	v_mfma_f32_16x16x32_bf16 v[116:119], v[142:145], v[182:185], v[116:119]
	v_mfma_f32_16x16x32_bf16 v[108:111], v[150:153], v[182:185], v[108:111]
	v_mfma_f32_16x16x32_bf16 v[100:103], v[142:145], v[190:193], v[100:103]
	v_mfma_f32_16x16x32_bf16 v[92:95], v[150:153], v[190:193], v[92:95]
	v_mfma_f32_16x16x32_bf16 v[84:87], v[142:145], v[214:217], v[84:87]
	v_mfma_f32_16x16x32_bf16 v[76:79], v[150:153], v[214:217], v[76:79]
	s_barrier
	s_add_i32 s28, 0, 0x1c000
	s_add_i32 s29, s56, s41
	v_add_u32_e32 v167, s28, v135
	v_lshl_add_u64 v[158:159], v[158:159], 0, s[2:3]
	s_mov_b32 m0, s29
	ds_read_b128 v[218:221], v167
	ds_read_b128 v[222:225], v167 offset:1024
	ds_read_b128 v[226:229], v167 offset:2048
	ds_read_b128 v[230:233], v167 offset:3072
	global_load_lds_dwordx4 v[158:159], off
	v_lshl_add_u64 v[158:159], v[234:235], 0, s[2:3]
	s_add_i32 m0, s29, 0x2000
	s_nop 0
	global_load_lds_dwordx4 v[158:159], off
	s_barrier
	s_waitcnt lgkmcnt(0)
	v_mfma_f32_16x16x32_bf16 v[112:115], v[218:221], v[154:157], v[112:115]
	v_mfma_f32_16x16x32_bf16 v[104:107], v[226:229], v[154:157], v[104:107]
	v_mfma_f32_16x16x32_bf16 v[96:99], v[218:221], v[178:181], v[96:99]
	v_mfma_f32_16x16x32_bf16 v[88:91], v[226:229], v[178:181], v[88:91]
	v_mfma_f32_16x16x32_bf16 v[80:83], v[218:221], v[186:189], v[80:83]
	v_mfma_f32_16x16x32_bf16 v[72:75], v[226:229], v[186:189], v[72:75]
	v_mfma_f32_16x16x32_bf16 v[68:71], v[218:221], v[194:197], v[68:71]
	v_mfma_f32_16x16x32_bf16 v[64:67], v[226:229], v[194:197], v[64:67]
	v_mfma_f32_16x16x32_bf16 v[112:115], v[222:225], v[174:177], v[112:115]
	v_mfma_f32_16x16x32_bf16 v[104:107], v[230:233], v[174:177], v[104:107]
	v_mfma_f32_16x16x32_bf16 v[96:99], v[222:225], v[182:185], v[96:99]
	v_mfma_f32_16x16x32_bf16 v[88:91], v[230:233], v[182:185], v[88:91]
	v_mfma_f32_16x16x32_bf16 v[80:83], v[222:225], v[190:193], v[80:83]
	v_mfma_f32_16x16x32_bf16 v[72:75], v[230:233], v[190:193], v[72:75]
	v_mfma_f32_16x16x32_bf16 v[68:71], v[222:225], v[214:217], v[68:71]
	v_mfma_f32_16x16x32_bf16 v[64:67], v[230:233], v[214:217], v[64:67]
	s_mov_b32 m0, s46
	v_lshl_add_u64 v[158:159], v[236:237], 0, s[2:3]
	s_barrier
	ds_read_b128 v[154:157], v137 offset:49152
	ds_read_b128 v[174:177], v137 offset:50176
	ds_read_b128 v[178:181], v137 offset:51200
	ds_read_b128 v[182:185], v137 offset:52224
	ds_read_b128 v[186:189], v137 offset:53248
	ds_read_b128 v[190:193], v137 offset:54272
	ds_read_b128 v[194:197], v137 offset:55296
	ds_read_b128 v[214:217], v137 offset:56320
	global_load_lds_dwordx4 v[158:159], off
	v_lshl_add_u64 v[158:159], v[238:239], 0, s[2:3]
	s_mov_b32 m0, s47
	s_nop 0
	global_load_lds_dwordx4 v[158:159], off
	s_barrier
; #define PG8_STAGE(bufoff, gbase, voff) do { _Pragma("unroll") for (int _i = 0; _i < 2; ++_i) \
;         __builtin_amdgcn_global_load_lds((const unsigned*)((const char*)(gbase) + (voff)[_i]), (LAS unsigned*)(lds + (bufoff) + ldsw + _i * 8192), 16, 0, 0); } while (0)
; #define PG8_MMA(ai, bj, At, Bt) do { __builtin_amdgcn_s_setprio(1); _Pragma("unroll") for (int m = 0; m < 4; ++m) _Pragma("unroll") for (int n = 0; n < 2; ++n) _Pragma("unroll") for (int k = 0; k < 2; ++k) \
;         acc[ai][bj][m][n] = __builtin_amdgcn_mfma_f32_16x16x32_bf16(Bt[n][k], At[m][k], acc[ai][bj][m][n], 0, 0, 0); __builtin_amdgcn_s_setprio(0); } while (0)
; #define PG8_WAIT_V(n) asm volatile("s_waitcnt vmcnt(" #n ")" ::: "memory")
; #define PG8_WAIT_L(n) asm volatile("s_waitcnt lgkmcnt(" #n ")" ::: "memory")
; #define PG8_BAR __builtin_amdgcn_s_barrier()
; #define PG8_SCHED __builtin_amdgcn_sched_barrier(0)
; template <class Epi>
; DEV void gemm_phase(LAS unsigned char* lds, const Gemm g, const StaticOrder& S, const Epi& E) {
;     ...
;             PG8_BAR; PG8_WAIT_L(0); PG8_MMA(1, 0, At, B0); PG8_BAR; PG8_SCHED;
;             PG8_STAGE(PG8_SB(1, 1), b3 + hstep, voffB);
;             PG8_WAIT_V(6); PG8_BAR; PG8_MMA(1, 1, At, B1); PG8_BAR;
	s_waitcnt lgkmcnt(0)
	v_mfma_f32_16x16x32_bf16 v[60:63], v[138:141], v[154:157], v[60:63]
	v_mfma_f32_16x16x32_bf16 v[56:59], v[146:149], v[154:157], v[56:59]
	v_mfma_f32_16x16x32_bf16 v[52:55], v[138:141], v[178:181], v[52:55]
	v_mfma_f32_16x16x32_bf16 v[44:47], v[146:149], v[178:181], v[44:47]
	v_mfma_f32_16x16x32_bf16 v[36:39], v[138:141], v[186:189], v[36:39]
	v_mfma_f32_16x16x32_bf16 v[28:31], v[146:149], v[186:189], v[28:31]
	v_mfma_f32_16x16x32_bf16 v[20:23], v[138:141], v[194:197], v[20:23]
	v_mfma_f32_16x16x32_bf16 v[12:15], v[146:149], v[194:197], v[12:15]
	v_mfma_f32_16x16x32_bf16 v[60:63], v[142:145], v[174:177], v[60:63]
	v_mfma_f32_16x16x32_bf16 v[56:59], v[150:153], v[174:177], v[56:59]
	v_mfma_f32_16x16x32_bf16 v[52:55], v[142:145], v[182:185], v[52:55]
	v_mfma_f32_16x16x32_bf16 v[44:47], v[150:153], v[182:185], v[44:47]
	v_mfma_f32_16x16x32_bf16 v[36:39], v[142:145], v[190:193], v[36:39]
	v_mfma_f32_16x16x32_bf16 v[28:31], v[150:153], v[190:193], v[28:31]
	v_mfma_f32_16x16x32_bf16 v[20:23], v[142:145], v[214:217], v[20:23]
	v_mfma_f32_16x16x32_bf16 v[12:15], v[150:153], v[214:217], v[12:15]
	s_barrier
	s_add_u32 s26, s26, 0x80080
	s_addc_u32 s27, s27, 0
	s_add_i32 s28, s28, s41
	s_mov_b32 m0, s28
	s_nop 0
	global_load_lds_dwordx4 v160, s[26:27]
	s_add_i32 m0, s28, 0x2000
	s_nop 0
	global_load_lds_dwordx4 v128, s[26:27]
	s_waitcnt vmcnt(6)
	s_barrier
	v_mfma_f32_16x16x32_bf16 v[48:51], v[218:221], v[154:157], v[48:51]
	v_mfma_f32_16x16x32_bf16 v[40:43], v[226:229], v[154:157], v[40:43]
	v_mfma_f32_16x16x32_bf16 v[32:35], v[218:221], v[178:181], v[32:35]
	v_mfma_f32_16x16x32_bf16 v[24:27], v[226:229], v[178:181], v[24:27]
	v_mfma_f32_16x16x32_bf16 v[16:19], v[218:221], v[186:189], v[16:19]
	v_mfma_f32_16x16x32_bf16 v[8:11], v[226:229], v[186:189], v[8:11]
	v_mfma_f32_16x16x32_bf16 v[4:7], v[218:221], v[194:197], v[4:7]
	v_mfma_f32_16x16x32_bf16 v[0:3], v[226:229], v[194:197], v[0:3]
	v_mfma_f32_16x16x32_bf16 v[48:51], v[222:225], v[174:177], v[48:51]
	v_mfma_f32_16x16x32_bf16 v[40:43], v[230:233], v[174:177], v[40:43]
	v_mfma_f32_16x16x32_bf16 v[32:35], v[222:225], v[182:185], v[32:35]
	v_mfma_f32_16x16x32_bf16 v[24:27], v[230:233], v[182:185], v[24:27]
	v_mfma_f32_16x16x32_bf16 v[16:19], v[222:225], v[190:193], v[16:19]
	v_mfma_f32_16x16x32_bf16 v[8:11], v[230:233], v[190:193], v[8:11]
	v_mfma_f32_16x16x32_bf16 v[4:7], v[222:225], v[214:217], v[4:7]
	v_mfma_f32_16x16x32_bf16 v[0:3], v[230:233], v[214:217], v[0:3]
	s_add_i32 s55, s55, 2
	s_add_u32 s24, s24, 0x100
	s_addc_u32 s25, s25, 0
	s_add_u32 s53, s53, 0x100
	s_addc_u32 s54, s54, 0
	s_cmp_gt_u32 s55, 29
	s_barrier
	s_cbranch_scc0 .LBB0_362
; DEV bf16x8 pack8(f32x4 a, f32x4 b) { u32x4 w; w.x = cvt_pk_bf16(a[0], a[1]); w.y = cvt_pk_bf16(a[2], a[3]); w.z = cvt_pk_bf16(b[0], b[1]); w.w = cvt_pk_bf16(b[2], b[3]); return __builtin_bit_cast(bf16x8, w); }
; DEV u32x2 pack4(f32x4 a) { u32x2 w; w.x = cvt_pk_bf16(a[0], a[1]); w.y = cvt_pk_bf16(a[2], a[3]); return w; }
; DEV f32x4 gelu4(f32x4 v) { f32x2 a = gelu_pk((f32x2){v[0], v[1]}), b = gelu_pk((f32x2){v[2], v[3]}); return (f32x4){a.x, a.y, b.x, b.y}; }
; template <int ACT, bool PERM>
; DEV void store_bf16_tile(AccRef acc, u16* O, int ld, int row0, int col0, const float* ss) {
;     ...
;     for (int ai = 0; ai < 2; ++ai)
; #pragma unroll
;         for (int m = 0; m < 4; ++m) { u16* rowp = O + (size_t)(row0 + ai * 128 + m * 16) * ld + col0; const float rs = rsv[ai][m];
; #pragma unroll
;             for (int bj = 0; bj < 2; ++bj) { f32x4 v0 = acc[ai][bj][m][0] * rs, v1 = acc[ai][bj][m][1] * rs; if (ACT == 1) { v0 = gelu4(v0); v1 = gelu4(v1); }
;                 if (PERM) *(u32x4*)(rowp + bj * 128) = __builtin_bit_cast(u32x4, pack8(v0, v1));
;                 else { *(u32x2*)(rowp + bj * 128) = pack4(v0); *(u32x2*)(rowp + bj * 128 + 16) = pack4(v1); } } }
	v_lshl_add_u32 v138, s12, 8, v134
	v_lshl_or_b32 v140, s50, 8, v136
	v_ashrrev_i32_e32 v141, 31, v140
	v_ashrrev_i32_e32 v139, 31, v138
	v_lshl_add_u64 v[140:141], v[140:141], 1, s[10:11]
	v_lshlrev_b64 v[142:143], 11, v[138:139]
	v_lshl_add_u64 v[142:143], v[140:141], 0, v[142:143]
	v_cvt_pk_bf16_f32 v104, v104, v105
	v_cvt_pk_bf16_f32 v105, v106, v107
	global_store_dwordx2 v[142:143], v[104:105], off offset:288
	v_or_b32_e32 v104, 16, v138
	v_ashrrev_i32_e32 v105, 31, v104
	v_lshlrev_b64 v[104:105], 11, v[104:105]
	v_lshl_add_u64 v[104:105], v[140:141], 0, v[104:105]
	v_cvt_pk_bf16_f32 v88, v88, v89
	v_cvt_pk_bf16_f32 v89, v90, v91
	global_store_dwordx2 v[104:105], v[88:89], off offset:288
	v_or_b32_e32 v88, 32, v138
	v_ashrrev_i32_e32 v89, 31, v88
	v_lshlrev_b64 v[88:89], 11, v[88:89]
	v_lshl_add_u64 v[88:89], v[140:141], 0, v[88:89]
	v_cvt_pk_bf16_f32 v72, v72, v73
	v_cvt_pk_bf16_f32 v73, v74, v75
	global_store_dwordx2 v[88:89], v[72:73], off offset:288
	v_or_b32_e32 v72, 48, v138
	v_ashrrev_i32_e32 v73, 31, v72
	v_lshlrev_b64 v[72:73], 11, v[72:73]
	s_mov_b32 s12, 0x40000
	v_lshl_add_u64 v[72:73], v[140:141], 0, v[72:73]
	v_cvt_pk_bf16_f32 v64, v64, v65
	v_cvt_pk_bf16_f32 v65, v66, v67
	s_mov_b64 s[24:25], 0x40000
	v_cvt_pk_bf16_f32 v60, v60, v61
	v_cvt_pk_bf16_f32 v61, v62, v63
	v_add_co_u32_e32 v62, vcc, s12, v142
	global_store_dwordx2 v[72:73], v[64:65], off offset:288
	v_lshl_add_u64 v[64:65], v[142:143], 0, s[24:25]
	v_addc_co_u32_e32 v63, vcc, 0, v143, vcc
	v_cvt_pk_bf16_f32 v48, v48, v49
	v_cvt_pk_bf16_f32 v49, v50, v51
	s_mov_b32 s12, 0x48000
	global_store_dwordx2 v[64:65], v[48:49], off offset:256
	v_cvt_pk_bf16_f32 v40, v40, v41
	v_cvt_pk_bf16_f32 v41, v42, v43
	s_mov_b64 s[24:25], 0x48000
	v_add_co_u32_e32 v48, vcc, s12, v142
	global_store_dwordx2 v[64:65], v[40:41], off offset:288
	v_lshl_add_u64 v[40:41], v[142:143], 0, s[24:25]
	v_addc_co_u32_e32 v49, vcc, 0, v143, vcc
	v_cvt_pk_bf16_f32 v32, v32, v33
	v_cvt_pk_bf16_f32 v33, v34, v35
	s_mov_b32 s12, 0x50000
	global_store_dwordx2 v[40:41], v[32:33], off offset:256
	v_cvt_pk_bf16_f32 v24, v24, v25
	v_cvt_pk_bf16_f32 v25, v26, v27
	s_mov_b64 s[24:25], 0x50000
	v_add_co_u32_e32 v32, vcc, s12, v142
	global_store_dwordx2 v[40:41], v[24:25], off offset:288
	v_lshl_add_u64 v[24:25], v[142:143], 0, s[24:25]
	v_addc_co_u32_e32 v33, vcc, 0, v143, vcc
	v_cvt_pk_bf16_f32 v16, v16, v17
	v_cvt_pk_bf16_f32 v17, v18, v19
	global_store_dwordx2 v[24:25], v[16:17], off offset:256
	v_add_co_u32_e32 v16, vcc, s59, v142
	v_cvt_pk_bf16_f32 v106, v116, v117
	v_cvt_pk_bf16_f32 v107, v118, v119
	v_cvt_pk_bf16_f32 v90, v100, v101
	v_cvt_pk_bf16_f32 v91, v102, v103
	v_cvt_pk_bf16_f32 v74, v84, v85
	v_cvt_pk_bf16_f32 v75, v86, v87
	v_cvt_pk_bf16_f32 v42, v52, v53
	v_cvt_pk_bf16_f32 v43, v54, v55
	v_cvt_pk_bf16_f32 v26, v36, v37
	v_cvt_pk_bf16_f32 v27, v38, v39
	v_cvt_pk_bf16_f32 v8, v8, v9
	v_cvt_pk_bf16_f32 v9, v10, v11
	s_mov_b64 s[24:25], 0x58000
	v_cvt_pk_bf16_f32 v10, v20, v21
	v_cvt_pk_bf16_f32 v11, v22, v23
	v_addc_co_u32_e32 v17, vcc, 0, v143, vcc
	v_cvt_pk_bf16_f32 v124, v124, v125
	v_cvt_pk_bf16_f32 v125, v126, v127
	v_cvt_pk_bf16_f32 v120, v120, v121
	v_cvt_pk_bf16_f32 v121, v122, v123
	v_cvt_pk_bf16_f32 v112, v112, v113
	v_cvt_pk_bf16_f32 v113, v114, v115
	global_store_dwordx2 v[104:105], v[106:107], off
	v_cvt_pk_bf16_f32 v106, v108, v109
	v_cvt_pk_bf16_f32 v107, v110, v111
	v_cvt_pk_bf16_f32 v96, v96, v97
	v_cvt_pk_bf16_f32 v97, v98, v99
	global_store_dwordx2 v[88:89], v[90:91], off
	v_cvt_pk_bf16_f32 v90, v92, v93
	v_cvt_pk_bf16_f32 v91, v94, v95
	v_cvt_pk_bf16_f32 v80, v80, v81
	v_cvt_pk_bf16_f32 v81, v82, v83
	global_store_dwordx2 v[72:73], v[74:75], off
	v_cvt_pk_bf16_f32 v74, v76, v77
	v_cvt_pk_bf16_f32 v75, v78, v79
	v_cvt_pk_bf16_f32 v68, v68, v69
	v_cvt_pk_bf16_f32 v69, v70, v71
	v_cvt_pk_bf16_f32 v56, v56, v57
	v_cvt_pk_bf16_f32 v57, v58, v59
	global_store_dwordx2 v[48:49], v[42:43], off
	v_cvt_pk_bf16_f32 v42, v44, v45
	v_cvt_pk_bf16_f32 v43, v46, v47
	global_store_dwordx2 v[32:33], v[26:27], off
	v_cvt_pk_bf16_f32 v26, v28, v29
	v_cvt_pk_bf16_f32 v27, v30, v31
	global_store_dwordx2 v[24:25], v[8:9], off offset:288
	v_lshl_add_u64 v[8:9], v[142:143], 0, s[24:25]
	global_store_dwordx2 v[16:17], v[10:11], off
	v_cvt_pk_bf16_f32 v10, v12, v13
	v_cvt_pk_bf16_f32 v11, v14, v15
	v_cvt_pk_bf16_f32 v4, v4, v5
	v_cvt_pk_bf16_f32 v5, v6, v7
	v_cvt_pk_bf16_f32 v0, v0, v1
	v_cvt_pk_bf16_f32 v1, v2, v3
	s_and_b64 vcc, exec, s[14:15]
	s_mov_b32 s50, s16
	s_mov_b32 s12, s18
	s_mov_b64 s[26:27], s[22:23]
	s_mov_b64 s[24:25], s[20:21]
	global_store_dwordx2 v[142:143], v[124:125], off
	global_store_dwordx2 v[142:143], v[120:121], off offset:32
	global_store_dwordx2 v[142:143], v[112:113], off offset:256
	global_store_dwordx2 v[104:105], v[106:107], off offset:32
	global_store_dwordx2 v[104:105], v[96:97], off offset:256
	global_store_dwordx2 v[88:89], v[90:91], off offset:32
	global_store_dwordx2 v[88:89], v[80:81], off offset:256
	global_store_dwordx2 v[72:73], v[74:75], off offset:32
	global_store_dwordx2 v[72:73], v[68:69], off offset:256
	global_store_dwordx2 v[62:63], v[60:61], off
	global_store_dwordx2 v[64:65], v[56:57], off offset:32
	global_store_dwordx2 v[40:41], v[42:43], off offset:32
	global_store_dwordx2 v[24:25], v[26:27], off offset:32
	global_store_dwordx2 v[8:9], v[10:11], off offset:32
	global_store_dwordx2 v[8:9], v[4:5], off offset:256
	global_store_dwordx2 v[8:9], v[0:1], off offset:288
	s_cbranch_vccz .LBB0_359
	s_waitcnt vmcnt(0)
	s_cmpk_gt_u32 s36, 0xff
	s_cbranch_scc1 .LBB0_353
	s_barrier
	s_branch .LBB0_353

; #define PG8_STAGE(bufoff, gbase, voff) do { _Pragma("unroll") for (int _i = 0; _i < 2; ++_i) \
;         __builtin_amdgcn_global_load_lds((const unsigned*)((const char*)(gbase) + (voff)[_i]), (LAS unsigned*)(lds + (bufoff) + ldsw + _i * 8192), 16, 0, 0); } while (0)
; #define PG8_LDA(dst, b, h) do { _Pragma("unroll") for (int m = 0; m < 4; ++m) _Pragma("unroll") for (int k = 0; k < 2; ++k) dst[m][k] = *(const LAS bf16x8*)(lds + PG8_SA(b, h) + aoff + m * 2048 + k * 1024); } while (0)
; #define PG8_LDB(dst, b, h) do { _Pragma("unroll") for (int n = 0; n < 2; ++n) _Pragma("unroll") for (int k = 0; k < 2; ++k) dst[n][k] = *(const LAS bf16x8*)(lds + PG8_SB(b, h) + boff + n * 2048 + k * 1024); } while (0)
; #define PG8_MMA(ai, bj, At, Bt) do { __builtin_amdgcn_s_setprio(1); _Pragma("unroll") for (int m = 0; m < 4; ++m) _Pragma("unroll") for (int n = 0; n < 2; ++n) _Pragma("unroll") for (int k = 0; k < 2; ++k) \
;         acc[ai][bj][m][n] = __builtin_amdgcn_mfma_f32_16x16x32_bf16(Bt[n][k], At[m][k], acc[ai][bj][m][n], 0, 0, 0); __builtin_amdgcn_s_setprio(0); } while (0)
; #define PG8_WAIT_V(n) asm volatile("s_waitcnt vmcnt(" #n ")" ::: "memory")
; #define PG8_WAIT_L(n) asm volatile("s_waitcnt lgkmcnt(" #n ")" ::: "memory")
; #define PG8_BAR __builtin_amdgcn_s_barrier()
; #define PG8_SCHED __builtin_amdgcn_sched_barrier(0)
; template <class Epi>
; DEV void gemm_phase(LAS unsigned char* lds, const Gemm g, const StaticOrder& S, const Epi& E) {
;     ...
;             const bool last = (t == nt - 2);
;             const char* a1 = cA + (size_t)(t + 1) * kstep;
;             const char* a2 = last ? nA : cA + (size_t)(t + 2) * kstep; const char* b2 = last ? nB : cB + (size_t)(t + 2) * kstep;
;             const char* a3 = a2 + kstep; const char* b3 = b2 + kstep;
;             PG8_LDB(B0, 0, 0); PG8_SCHED; PG8_LDA(At, 0, 0); PG8_STAGE(PG8_SA(1, 1), a1 + hstep, voffA);
;             PG8_WAIT_L(8); PG8_BAR; PG8_WAIT_L(0); PG8_MMA(0, 0, At, B0); PG8_BAR; PG8_SCHED;
;             PG8_LDB(B1, 0, 1); PG8_STAGE(PG8_SB(0, 0), b2, voffB);
;             PG8_BAR; PG8_WAIT_L(0); PG8_MMA(0, 1, At, B1); PG8_BAR;
;             PG8_LDA(At, 0, 1); PG8_STAGE(PG8_SA(0, 0), a2, voffA);
;             PG8_BAR; PG8_WAIT_L(0); PG8_MMA(1, 0, At, B0); PG8_BAR; PG8_SCHED;
;             PG8_STAGE(PG8_SB(0, 1), b2 + hstep, voffB);
;             PG8_WAIT_V(6); PG8_BAR; PG8_MMA(1, 1, At, B1); PG8_BAR;
.LBB0_404:
	s_add_u32 s28, s26, 0xfff00080
	s_addc_u32 s29, s27, -1
	s_add_i32 s49, 0, 0x10000
	v_add_u32_e32 v140, s49, v178
	ds_read_b128 v[128:131], v140
	ds_read_b128 v[132:135], v140 offset:1024
	ds_read_b128 v[136:139], v140 offset:2048
	ds_read_b128 v[140:143], v140 offset:3072
	s_cmp_eq_u32 s48, 60
	s_cselect_b32 s31, s15, s29
	s_cselect_b32 s30, s19, s28
	s_cselect_b32 s29, s17, s47
	s_cselect_b32 s28, s25, s46
	s_add_i32 m0, s37, 0xc000
	ds_read_b128 v[154:157], v181
	ds_read_b128 v[174:177], v181 offset:1024
	ds_read_b128 v[182:185], v181 offset:2048
	ds_read_b128 v[186:189], v181 offset:3072
	ds_read_b128 v[190:193], v181 offset:4096
	ds_read_b128 v[194:197], v181 offset:5120
	ds_read_b128 v[214:217], v181 offset:6144
	ds_read_b128 v[218:221], v181 offset:7168
	global_load_lds_dwordx4 v150, s[26:27]
	s_add_i32 m0, s37, 0xe000
	s_nop 0
	global_load_lds_dwordx4 v152, s[26:27]
	s_waitcnt lgkmcnt(8)
	s_barrier
	s_waitcnt lgkmcnt(0)
	v_mfma_f32_16x16x32_bf16 v[124:127], v[128:131], v[154:157], v[124:127]
	v_mfma_f32_16x16x32_bf16 v[120:123], v[136:139], v[154:157], v[120:123]
	v_mfma_f32_16x16x32_bf16 v[108:111], v[128:131], v[182:185], v[108:111]
	v_mfma_f32_16x16x32_bf16 v[104:107], v[136:139], v[182:185], v[104:107]
	v_mfma_f32_16x16x32_bf16 v[92:95], v[128:131], v[190:193], v[92:95]
	v_mfma_f32_16x16x32_bf16 v[88:91], v[136:139], v[190:193], v[88:91]
	v_mfma_f32_16x16x32_bf16 v[76:79], v[128:131], v[214:217], v[76:79]
	v_mfma_f32_16x16x32_bf16 v[72:75], v[136:139], v[214:217], v[72:75]
	v_mfma_f32_16x16x32_bf16 v[124:127], v[132:135], v[174:177], v[124:127]
	v_mfma_f32_16x16x32_bf16 v[120:123], v[140:143], v[174:177], v[120:123]
	v_mfma_f32_16x16x32_bf16 v[108:111], v[132:135], v[186:189], v[108:111]
	v_mfma_f32_16x16x32_bf16 v[104:107], v[140:143], v[186:189], v[104:107]
	v_mfma_f32_16x16x32_bf16 v[92:95], v[132:135], v[194:197], v[92:95]
	v_mfma_f32_16x16x32_bf16 v[88:91], v[140:143], v[194:197], v[88:91]
	v_mfma_f32_16x16x32_bf16 v[76:79], v[132:135], v[218:221], v[76:79]
	v_mfma_f32_16x16x32_bf16 v[72:75], v[140:143], v[218:221], v[72:75]
	s_barrier
	s_add_i32 s52, 0, 0x14000
	v_add_u32_e32 v158, s52, v178
	s_add_i32 s49, s49, s36
	ds_read_b128 v[222:225], v158
	ds_read_b128 v[226:229], v158 offset:1024
	ds_read_b128 v[230:233], v158 offset:2048
	ds_read_b128 v[234:237], v158 offset:3072
	v_lshl_add_u64 v[158:159], s[28:29], 0, v[160:161]
	s_mov_b32 m0, s49
	v_lshl_add_u64 v[238:239], s[28:29], 0, v[148:149]
	global_load_lds_dwordx4 v160, s[28:29]
	s_add_i32 m0, s49, 0x2000
	s_nop 0
	global_load_lds_dwordx4 v148, s[28:29]
	s_barrier
	s_waitcnt lgkmcnt(0)
	v_mfma_f32_16x16x32_bf16 v[116:119], v[222:225], v[154:157], v[116:119]
	v_mfma_f32_16x16x32_bf16 v[112:115], v[230:233], v[154:157], v[112:115]
	v_mfma_f32_16x16x32_bf16 v[100:103], v[222:225], v[182:185], v[100:103]
	v_mfma_f32_16x16x32_bf16 v[96:99], v[230:233], v[182:185], v[96:99]
	v_mfma_f32_16x16x32_bf16 v[84:87], v[222:225], v[190:193], v[84:87]
	v_mfma_f32_16x16x32_bf16 v[80:83], v[230:233], v[190:193], v[80:83]
	v_mfma_f32_16x16x32_bf16 v[68:71], v[222:225], v[214:217], v[68:71]
	v_mfma_f32_16x16x32_bf16 v[64:67], v[230:233], v[214:217], v[64:67]
	v_mfma_f32_16x16x32_bf16 v[116:119], v[226:229], v[174:177], v[116:119]
	v_mfma_f32_16x16x32_bf16 v[112:115], v[234:237], v[174:177], v[112:115]
	v_mfma_f32_16x16x32_bf16 v[100:103], v[226:229], v[186:189], v[100:103]
	v_mfma_f32_16x16x32_bf16 v[96:99], v[234:237], v[186:189], v[96:99]
	v_mfma_f32_16x16x32_bf16 v[84:87], v[226:229], v[194:197], v[84:87]
	v_mfma_f32_16x16x32_bf16 v[80:83], v[234:237], v[194:197], v[80:83]
	v_mfma_f32_16x16x32_bf16 v[68:71], v[226:229], v[218:221], v[68:71]
	v_mfma_f32_16x16x32_bf16 v[64:67], v[234:237], v[218:221], v[64:67]
	s_mov_b32 m0, s37
	v_lshl_add_u64 v[240:241], s[30:31], 0, v[144:145]
	s_barrier
	ds_read_b128 v[154:157], v181 offset:16384
	ds_read_b128 v[174:177], v181 offset:17408
	ds_read_b128 v[182:185], v181 offset:18432
	ds_read_b128 v[186:189], v181 offset:19456
	ds_read_b128 v[190:193], v181 offset:20480
	ds_read_b128 v[194:197], v181 offset:21504
	ds_read_b128 v[214:217], v181 offset:22528
	ds_read_b128 v[218:221], v181 offset:23552
	global_load_lds_dwordx4 v144, s[30:31]
	v_lshl_add_u64 v[242:243], s[30:31], 0, v[146:147]
	s_mov_b32 m0, s38
	s_nop 0
	global_load_lds_dwordx4 v146, s[30:31]
	s_barrier
	s_waitcnt lgkmcnt(0)
	v_mfma_f32_16x16x32_bf16 v[60:63], v[128:131], v[154:157], v[60:63]
	v_mfma_f32_16x16x32_bf16 v[56:59], v[136:139], v[154:157], v[56:59]
	v_mfma_f32_16x16x32_bf16 v[44:47], v[128:131], v[182:185], v[44:47]
	v_mfma_f32_16x16x32_bf16 v[40:43], v[136:139], v[182:185], v[40:43]
	v_mfma_f32_16x16x32_bf16 v[28:31], v[128:131], v[190:193], v[28:31]
	v_mfma_f32_16x16x32_bf16 v[24:27], v[136:139], v[190:193], v[24:27]
	v_mfma_f32_16x16x32_bf16 v[12:15], v[128:131], v[214:217], v[12:15]
	v_mfma_f32_16x16x32_bf16 v[8:11], v[136:139], v[214:217], v[8:11]
	v_mfma_f32_16x16x32_bf16 v[60:63], v[132:135], v[174:177], v[60:63]
	v_mfma_f32_16x16x32_bf16 v[56:59], v[140:143], v[174:177], v[56:59]
	v_mfma_f32_16x16x32_bf16 v[44:47], v[132:135], v[186:189], v[44:47]
	v_mfma_f32_16x16x32_bf16 v[40:43], v[140:143], v[186:189], v[40:43]
	v_mfma_f32_16x16x32_bf16 v[28:31], v[132:135], v[194:197], v[28:31]
	v_mfma_f32_16x16x32_bf16 v[24:27], v[140:143], v[194:197], v[24:27]
	v_mfma_f32_16x16x32_bf16 v[12:15], v[132:135], v[218:221], v[12:15]
	v_mfma_f32_16x16x32_bf16 v[8:11], v[140:143], v[218:221], v[8:11]
	s_barrier
	s_add_u32 s50, s28, 0x100000
	s_addc_u32 s51, s29, 0
	s_add_i32 s49, s52, s36
	s_mov_b32 m0, s49
	s_nop 0
	global_load_lds_dwordx4 v160, s[50:51]
	s_add_i32 m0, s49, 0x2000
	s_nop 0
	global_load_lds_dwordx4 v148, s[50:51]
	s_waitcnt vmcnt(6)
	s_barrier
; #define PG8_STAGE(bufoff, gbase, voff) do { _Pragma("unroll") for (int _i = 0; _i < 2; ++_i) \
;         __builtin_amdgcn_global_load_lds((const unsigned*)((const char*)(gbase) + (voff)[_i]), (LAS unsigned*)(lds + (bufoff) + ldsw + _i * 8192), 16, 0, 0); } while (0)
; #define PG8_LDA(dst, b, h) do { _Pragma("unroll") for (int m = 0; m < 4; ++m) _Pragma("unroll") for (int k = 0; k < 2; ++k) dst[m][k] = *(const LAS bf16x8*)(lds + PG8_SA(b, h) + aoff + m * 2048 + k * 1024); } while (0)
; #define PG8_LDB(dst, b, h) do { _Pragma("unroll") for (int n = 0; n < 2; ++n) _Pragma("unroll") for (int k = 0; k < 2; ++k) dst[n][k] = *(const LAS bf16x8*)(lds + PG8_SB(b, h) + boff + n * 2048 + k * 1024); } while (0)
; #define PG8_MMA(ai, bj, At, Bt) do { __builtin_amdgcn_s_setprio(1); _Pragma("unroll") for (int m = 0; m < 4; ++m) _Pragma("unroll") for (int n = 0; n < 2; ++n) _Pragma("unroll") for (int k = 0; k < 2; ++k) \
;         acc[ai][bj][m][n] = __builtin_amdgcn_mfma_f32_16x16x32_bf16(Bt[n][k], At[m][k], acc[ai][bj][m][n], 0, 0, 0); __builtin_amdgcn_s_setprio(0); } while (0)
; #define PG8_WAIT_V(n) asm volatile("s_waitcnt vmcnt(" #n ")" ::: "memory")
; #define PG8_WAIT_L(n) asm volatile("s_waitcnt lgkmcnt(" #n ")" ::: "memory")
; #define PG8_BAR __builtin_amdgcn_s_barrier()
; #define PG8_SCHED __builtin_amdgcn_sched_barrier(0)
; template <class Epi>
; DEV void gemm_phase(LAS unsigned char* lds, const Gemm g, const StaticOrder& S, const Epi& E) {
;     ...
;             PG8_WAIT_V(6); PG8_BAR; PG8_MMA(1, 1, At, B1); PG8_BAR;
;             PG8_LDB(B0, 1, 0); PG8_SCHED; PG8_LDA(At, 1, 0); PG8_STAGE(PG8_SA(0, 1), a2 + hstep, voffA);
;             PG8_WAIT_L(8); PG8_BAR; PG8_WAIT_L(0); PG8_MMA(0, 0, At, B0); PG8_BAR; PG8_SCHED;
;             PG8_LDB(B1, 1, 1); PG8_STAGE(PG8_SB(1, 0), b3, voffB);
;             PG8_BAR; PG8_WAIT_L(0); PG8_MMA(0, 1, At, B1); PG8_BAR;
;             PG8_LDA(At, 1, 1); PG8_STAGE(PG8_SA(1, 0), a3, voffA);
;             PG8_BAR; PG8_WAIT_L(0); PG8_MMA(1, 0, At, B0); PG8_BAR; PG8_SCHED;
	v_mfma_f32_16x16x32_bf16 v[52:55], v[222:225], v[154:157], v[52:55]
	v_mfma_f32_16x16x32_bf16 v[48:51], v[230:233], v[154:157], v[48:51]
	v_mfma_f32_16x16x32_bf16 v[36:39], v[222:225], v[182:185], v[36:39]
	v_mfma_f32_16x16x32_bf16 v[32:35], v[230:233], v[182:185], v[32:35]
	v_mfma_f32_16x16x32_bf16 v[20:23], v[222:225], v[190:193], v[20:23]
	v_mfma_f32_16x16x32_bf16 v[16:19], v[230:233], v[190:193], v[16:19]
	v_mfma_f32_16x16x32_bf16 v[4:7], v[222:225], v[214:217], v[4:7]
	v_mfma_f32_16x16x32_bf16 v[0:3], v[230:233], v[214:217], v[0:3]
	v_mfma_f32_16x16x32_bf16 v[52:55], v[226:229], v[174:177], v[52:55]
	v_mfma_f32_16x16x32_bf16 v[48:51], v[234:237], v[174:177], v[48:51]
	v_mfma_f32_16x16x32_bf16 v[36:39], v[226:229], v[186:189], v[36:39]
	v_mfma_f32_16x16x32_bf16 v[32:35], v[234:237], v[186:189], v[32:35]
	v_mfma_f32_16x16x32_bf16 v[20:23], v[226:229], v[194:197], v[20:23]
	v_mfma_f32_16x16x32_bf16 v[16:19], v[234:237], v[194:197], v[16:19]
	v_mfma_f32_16x16x32_bf16 v[4:7], v[226:229], v[218:221], v[4:7]
	v_mfma_f32_16x16x32_bf16 v[0:3], v[234:237], v[218:221], v[0:3]
	s_add_i32 s49, 0, 0x18000
	v_add_u32_e32 v140, s49, v178
	s_barrier
	ds_read_b128 v[128:131], v140
	ds_read_b128 v[132:135], v140 offset:1024
	ds_read_b128 v[136:139], v140 offset:2048
	ds_read_b128 v[140:143], v140 offset:3072
	s_add_u32 s30, s30, 0x100000
	s_addc_u32 s31, s31, 0
	s_mov_b32 m0, s39
	ds_read_b128 v[154:157], v181 offset:32768
	ds_read_b128 v[174:177], v181 offset:33792
	ds_read_b128 v[182:185], v181 offset:34816
	ds_read_b128 v[186:189], v181 offset:35840
	ds_read_b128 v[190:193], v181 offset:36864
	ds_read_b128 v[194:197], v181 offset:37888
	ds_read_b128 v[214:217], v181 offset:38912
	ds_read_b128 v[218:221], v181 offset:39936
	global_load_lds_dwordx4 v144, s[30:31]
	s_mov_b32 m0, s40
	s_nop 0
	global_load_lds_dwordx4 v146, s[30:31]
	s_waitcnt lgkmcnt(8)
	s_barrier
	s_waitcnt lgkmcnt(0)
	v_mfma_f32_16x16x32_bf16 v[124:127], v[128:131], v[154:157], v[124:127]
	v_mfma_f32_16x16x32_bf16 v[120:123], v[136:139], v[154:157], v[120:123]
	v_mfma_f32_16x16x32_bf16 v[108:111], v[128:131], v[182:185], v[108:111]
	v_mfma_f32_16x16x32_bf16 v[104:107], v[136:139], v[182:185], v[104:107]
	v_mfma_f32_16x16x32_bf16 v[92:95], v[128:131], v[190:193], v[92:95]
	v_mfma_f32_16x16x32_bf16 v[88:91], v[136:139], v[190:193], v[88:91]
	v_mfma_f32_16x16x32_bf16 v[76:79], v[128:131], v[214:217], v[76:79]
	v_mfma_f32_16x16x32_bf16 v[72:75], v[136:139], v[214:217], v[72:75]
	v_mfma_f32_16x16x32_bf16 v[124:127], v[132:135], v[174:177], v[124:127]
	v_mfma_f32_16x16x32_bf16 v[120:123], v[140:143], v[174:177], v[120:123]
	v_mfma_f32_16x16x32_bf16 v[108:111], v[132:135], v[186:189], v[108:111]
	v_mfma_f32_16x16x32_bf16 v[104:107], v[140:143], v[186:189], v[104:107]
	v_mfma_f32_16x16x32_bf16 v[92:95], v[132:135], v[194:197], v[92:95]
	v_mfma_f32_16x16x32_bf16 v[88:91], v[140:143], v[194:197], v[88:91]
	v_mfma_f32_16x16x32_bf16 v[76:79], v[132:135], v[218:221], v[76:79]
	v_mfma_f32_16x16x32_bf16 v[72:75], v[140:143], v[218:221], v[72:75]
	s_barrier
	s_add_i32 s30, 0, 0x1c000
	s_add_i32 s31, s49, s36
	v_add_u32_e32 v234, s30, v178
	v_lshl_add_u64 v[158:159], v[158:159], 0, s[2:3]
	s_mov_b32 m0, s31
	ds_read_b128 v[222:225], v234
	ds_read_b128 v[226:229], v234 offset:1024
	ds_read_b128 v[230:233], v234 offset:2048
	ds_read_b128 v[234:237], v234 offset:3072
	global_load_lds_dwordx4 v[158:159], off
	v_lshl_add_u64 v[158:159], v[238:239], 0, s[2:3]
	s_add_i32 m0, s31, 0x2000
	s_nop 0
	global_load_lds_dwordx4 v[158:159], off
	s_barrier
	s_waitcnt lgkmcnt(0)
	v_mfma_f32_16x16x32_bf16 v[116:119], v[222:225], v[154:157], v[116:119]
	v_mfma_f32_16x16x32_bf16 v[112:115], v[230:233], v[154:157], v[112:115]
	v_mfma_f32_16x16x32_bf16 v[100:103], v[222:225], v[182:185], v[100:103]
	v_mfma_f32_16x16x32_bf16 v[96:99], v[230:233], v[182:185], v[96:99]
	v_mfma_f32_16x16x32_bf16 v[84:87], v[222:225], v[190:193], v[84:87]
	v_mfma_f32_16x16x32_bf16 v[80:83], v[230:233], v[190:193], v[80:83]
	v_mfma_f32_16x16x32_bf16 v[68:71], v[222:225], v[214:217], v[68:71]
	v_mfma_f32_16x16x32_bf16 v[64:67], v[230:233], v[214:217], v[64:67]
	v_mfma_f32_16x16x32_bf16 v[116:119], v[226:229], v[174:177], v[116:119]
	v_mfma_f32_16x16x32_bf16 v[112:115], v[234:237], v[174:177], v[112:115]
	v_mfma_f32_16x16x32_bf16 v[100:103], v[226:229], v[186:189], v[100:103]
	v_mfma_f32_16x16x32_bf16 v[96:99], v[234:237], v[186:189], v[96:99]
	v_mfma_f32_16x16x32_bf16 v[84:87], v[226:229], v[194:197], v[84:87]
	v_mfma_f32_16x16x32_bf16 v[80:83], v[234:237], v[194:197], v[80:83]
	v_mfma_f32_16x16x32_bf16 v[68:71], v[226:229], v[218:221], v[68:71]
	v_mfma_f32_16x16x32_bf16 v[64:67], v[234:237], v[218:221], v[64:67]
	s_mov_b32 m0, s41
	v_lshl_add_u64 v[158:159], v[240:241], 0, s[2:3]
	s_barrier
	ds_read_b128 v[154:157], v181 offset:49152
	ds_read_b128 v[174:177], v181 offset:50176
	ds_read_b128 v[182:185], v181 offset:51200
	ds_read_b128 v[186:189], v181 offset:52224
	ds_read_b128 v[190:193], v181 offset:53248
	ds_read_b128 v[194:197], v181 offset:54272
	ds_read_b128 v[214:217], v181 offset:55296
	ds_read_b128 v[218:221], v181 offset:56320
	global_load_lds_dwordx4 v[158:159], off
	v_lshl_add_u64 v[158:159], v[242:243], 0, s[2:3]
	s_mov_b32 m0, s42
	s_nop 0
	global_load_lds_dwordx4 v[158:159], off
	s_barrier
; DEV bf16x8 pack8(f32x4 a, f32x4 b) { u32x4 w; w.x = cvt_pk_bf16(a[0], a[1]); w.y = cvt_pk_bf16(a[2], a[3]); w.z = cvt_pk_bf16(b[0], b[1]); w.w = cvt_pk_bf16(b[2], b[3]); return __builtin_bit_cast(bf16x8, w); }
; #define PG8_WAIT_V(n) asm volatile("s_waitcnt vmcnt(" #n ")" ::: "memory")
; #define PG8_WAIT_L(n) asm volatile("s_waitcnt lgkmcnt(" #n ")" ::: "memory")
; #define PG8_BAR __builtin_amdgcn_s_barrier()
; #define PG8_SCHED __builtin_amdgcn_sched_barrier(0)
; template <class Epi>
; DEV void gemm_phase(LAS unsigned char* lds, const Gemm g, const StaticOrder& S, const Epi& E) {
;     ...
;             PG8_BAR; PG8_WAIT_L(0); PG8_MMA(1, 0, At, B0); PG8_BAR; PG8_SCHED;
;             PG8_STAGE(PG8_SB(1, 1), b3 + hstep, voffB);
;             PG8_WAIT_V(6); PG8_BAR; PG8_MMA(1, 1, At, B1); PG8_BAR;
;     DEV void operator()(AccRef acc, const pg8::Unit& u, int wr, int wc, int fr, int fq) const {
;         const int row0 = u.pm * 256 + wr * 64 + fr, col0 = u.pn * 256 + wc * 32 + 8 * fq;
; #pragma unroll
;         for (int am = 0; am < 4; ++am) { const int ai = am >> 1, m0 = (am & 1) * 2;
;             f32x4 bv[4][2][2];
; #pragma unroll
;             for (int m = m0; m < m0 + 2; ++m)
; #pragma unroll
;                 for (int bj = 0; bj < 2; ++bj)
; #pragma unroll
;                     for (int n = 0; n < 2; ++n) bv[m][bj][n] = *(const f32x4*)(base + (size_t)(row0 + ai * 128 + m * 16) * 2048 + col0 + bj * 128 + n * 4);
; #pragma unroll
;             for (int m = m0; m < m0 + 2; ++m) { const size_t off = (size_t)(row0 + ai * 128 + m * 16) * 2048 + col0; float sq = 0.f;
; #pragma unroll
;                 for (int bj = 0; bj < 2; ++bj) { const f32x4 o0 = bv[m][bj][0] + scale * acc[ai][bj][m][0], o1 = bv[m][bj][1] + scale * acc[ai][bj][m][1];
;                     *(f32x4*)(out + off + bj * 128) = o0; *(f32x4*)(out + off + bj * 128 + 4) = o1;
;                     if (xb) { *(u32x4*)(xb + off + bj * 128) = __builtin_bit_cast(u32x4, pack8(o0, o1));
;                         sq += (o0[0] * o0[0] + o0[1] * o0[1] + o0[2] * o0[2] + o0[3] * o0[3]) + (o1[0] * o1[0] + o1[1] * o1[1] + o1[2] * o1[2] + o1[3] * o1[3]); } }
;                 if (ssout) { sq += __shfl_xor(sq, 16); sq += __shfl_xor(sq, 32);
;                     if (fq == 0) { if (red) red[(ai * 128 + wr * 64 + m * 16 + fr) * 4 + wc] = sq; else atomicAdd(ssout + (size_t)(row0 + ai * 128 + m * 16) * 8 + u.pn, sq); } } }
	s_waitcnt lgkmcnt(0)
	v_mfma_f32_16x16x32_bf16 v[60:63], v[128:131], v[154:157], v[60:63]
	v_mfma_f32_16x16x32_bf16 v[56:59], v[136:139], v[154:157], v[56:59]
	v_mfma_f32_16x16x32_bf16 v[44:47], v[128:131], v[182:185], v[44:47]
	v_mfma_f32_16x16x32_bf16 v[40:43], v[136:139], v[182:185], v[40:43]
	v_mfma_f32_16x16x32_bf16 v[28:31], v[128:131], v[190:193], v[28:31]
	v_mfma_f32_16x16x32_bf16 v[24:27], v[136:139], v[190:193], v[24:27]
	v_mfma_f32_16x16x32_bf16 v[12:15], v[128:131], v[214:217], v[12:15]
	v_mfma_f32_16x16x32_bf16 v[8:11], v[136:139], v[214:217], v[8:11]
	v_mfma_f32_16x16x32_bf16 v[60:63], v[132:135], v[174:177], v[60:63]
	v_mfma_f32_16x16x32_bf16 v[56:59], v[140:143], v[174:177], v[56:59]
	v_mfma_f32_16x16x32_bf16 v[44:47], v[132:135], v[186:189], v[44:47]
	v_mfma_f32_16x16x32_bf16 v[40:43], v[140:143], v[186:189], v[40:43]
	v_mfma_f32_16x16x32_bf16 v[28:31], v[132:135], v[194:197], v[28:31]
	v_mfma_f32_16x16x32_bf16 v[24:27], v[140:143], v[194:197], v[24:27]
	v_mfma_f32_16x16x32_bf16 v[12:15], v[132:135], v[218:221], v[12:15]
	v_mfma_f32_16x16x32_bf16 v[8:11], v[140:143], v[218:221], v[8:11]
	s_barrier
	s_add_u32 s28, s28, 0x100080
	s_addc_u32 s29, s29, 0
	s_add_i32 s30, s30, s36
	s_mov_b32 m0, s30
	s_nop 0
	global_load_lds_dwordx4 v160, s[28:29]
	s_add_i32 m0, s30, 0x2000
	s_nop 0
	global_load_lds_dwordx4 v148, s[28:29]
	s_waitcnt vmcnt(6)
	s_barrier
	v_mfma_f32_16x16x32_bf16 v[52:55], v[222:225], v[154:157], v[52:55]
	v_mfma_f32_16x16x32_bf16 v[48:51], v[230:233], v[154:157], v[48:51]
	v_mfma_f32_16x16x32_bf16 v[36:39], v[222:225], v[182:185], v[36:39]
	v_mfma_f32_16x16x32_bf16 v[32:35], v[230:233], v[182:185], v[32:35]
	v_mfma_f32_16x16x32_bf16 v[20:23], v[222:225], v[190:193], v[20:23]
	v_mfma_f32_16x16x32_bf16 v[16:19], v[230:233], v[190:193], v[16:19]
	v_mfma_f32_16x16x32_bf16 v[4:7], v[222:225], v[214:217], v[4:7]
	v_mfma_f32_16x16x32_bf16 v[0:3], v[230:233], v[214:217], v[0:3]
	v_mfma_f32_16x16x32_bf16 v[52:55], v[226:229], v[174:177], v[52:55]
	v_mfma_f32_16x16x32_bf16 v[48:51], v[234:237], v[174:177], v[48:51]
	v_mfma_f32_16x16x32_bf16 v[36:39], v[226:229], v[186:189], v[36:39]
	v_mfma_f32_16x16x32_bf16 v[32:35], v[234:237], v[186:189], v[32:35]
	v_mfma_f32_16x16x32_bf16 v[20:23], v[226:229], v[194:197], v[20:23]
	v_mfma_f32_16x16x32_bf16 v[16:19], v[234:237], v[194:197], v[16:19]
	v_mfma_f32_16x16x32_bf16 v[4:7], v[226:229], v[218:221], v[4:7]
	v_mfma_f32_16x16x32_bf16 v[0:3], v[234:237], v[218:221], v[0:3]
	s_add_i32 s48, s48, 2
	s_add_u32 s26, s26, 0x100
	s_addc_u32 s27, s27, 0
	s_add_u32 s46, s46, 0x100
	s_addc_u32 s47, s47, 0
	s_cmp_gt_u32 s48, 61
	s_barrier
	s_cbranch_scc0 .LBB0_404
	v_lshl_add_u32 v156, s24, 8, v167
	v_lshl_or_b32 v154, s14, 8, v179
	v_readlane_b32 s24, v254, 16
	v_ashrrev_i32_e32 v155, 31, v154
	v_readlane_b32 s25, v254, 17
	v_ashrrev_i32_e32 v157, 31, v156
	v_lshlrev_b64 v[128:129], 13, v[156:157]
	v_lshl_add_u64 v[158:159], v[154:155], 2, s[24:25]
	v_lshl_add_u64 v[214:215], v[158:159], 0, v[128:129]
	global_load_dwordx4 v[182:185], v[214:215], off offset:16
	global_load_dwordx4 v[186:189], v[214:215], off
	global_load_dwordx4 v[190:193], v[214:215], off offset:528
	global_load_dwordx4 v[194:197], v[214:215], off offset:512
	v_or_b32_e32 v174, 16, v156
	v_ashrrev_i32_e32 v175, 31, v174
	v_lshlrev_b64 v[128:129], 13, v[174:175]
	v_lshl_add_u64 v[176:177], v[158:159], 0, v[128:129]
	global_load_dwordx4 v[136:139], v[176:177], off offset:16
	global_load_dwordx4 v[140:143], v[176:177], off
	global_load_dwordx4 v[128:131], v[176:177], off offset:528
	global_load_dwordx4 v[132:135], v[176:177], off offset:512
	v_lshlrev_b64 v[216:217], 11, v[156:157]
	v_readlane_b32 s24, v250, 9
	v_lshl_add_u64 v[216:217], v[216:217], 0, v[154:155]
	v_readlane_b32 s25, v250, 10
	v_cmp_lt_i32_e32 vcc, v208, v206
	s_ashr_i32 s15, s14, 31
	s_waitcnt vmcnt(0)
	v_pk_add_f32 v[120:121], v[120:121], v[182:183]
	v_pk_add_f32 v[126:127], v[126:127], v[188:189]
	v_pk_add_f32 v[124:125], v[124:125], v[186:187]
	v_pk_add_f32 v[122:123], v[122:123], v[184:185]
	global_store_dwordx4 v[214:215], v[124:127], off
	global_store_dwordx4 v[214:215], v[120:123], off offset:16
	v_cvt_pk_bf16_f32 v184, v120, v121
	v_cvt_pk_bf16_f32 v182, v124, v125
	v_mul_f32_e32 v121, v121, v121
	v_cvt_pk_bf16_f32 v183, v126, v127
	v_cvt_pk_bf16_f32 v185, v122, v123
	v_lshl_add_u64 v[186:187], v[216:217], 1, s[24:25]
	v_fmac_f32_e32 v121, v120, v120
	v_pk_add_f32 v[118:119], v[118:119], v[196:197]
	v_pk_add_f32 v[116:117], v[116:117], v[194:195]
	v_pk_add_f32 v[112:113], v[112:113], v[190:191]
	global_store_dwordx4 v[186:187], v[182:185], off
	v_mul_f32_e32 v125, v125, v125
	v_fmac_f32_e32 v121, v122, v122
	v_pk_add_f32 v[114:115], v[114:115], v[192:193]
	global_store_dwordx4 v[214:215], v[116:119], off offset:512
	global_store_dwordx4 v[214:215], v[112:115], off offset:528
	v_cvt_pk_bf16_f32 v120, v116, v117
	v_cvt_pk_bf16_f32 v122, v112, v113
	v_mul_f32_e32 v117, v117, v117
	v_mul_f32_e32 v113, v113, v113
	v_fmac_f32_e32 v125, v124, v124
	v_fmac_f32_e32 v117, v116, v116
	v_fmac_f32_e32 v113, v112, v112
	v_fmac_f32_e32 v125, v126, v126
	v_fmac_f32_e32 v117, v118, v118
	v_fmac_f32_e32 v113, v114, v114
	v_fmac_f32_e32 v125, v127, v127
	v_fmac_f32_e32 v121, v123, v123
	v_fmac_f32_e32 v117, v119, v119
	v_fmac_f32_e32 v113, v115, v115
	v_add_f32_e32 v124, v125, v121
	v_add_f32_e32 v112, v117, v113
	v_cndmask_b32_e32 v113, v204, v208, vcc
	v_cvt_pk_bf16_f32 v121, v118, v119
	v_add_f32_e32 v112, v124, v112
	v_lshlrev_b32_e32 v118, 2, v113
	ds_bpermute_b32 v113, v118, v112
	v_cmp_lt_i32_e32 vcc, v207, v206
	v_cvt_pk_bf16_f32 v123, v114, v115
	global_store_dwordx4 v[186:187], v[120:123], off offset:256
	s_waitcnt lgkmcnt(0)
	v_add_f32_e32 v112, v112, v113
	v_cndmask_b32_e32 v113, v204, v207, vcc
	v_lshlrev_b32_e32 v119, 2, v113
	ds_bpermute_b32 v113, v119, v112
	s_and_saveexec_b64 s[24:25], s[6:7]
	s_cbranch_execz .LBB0_410
	s_waitcnt lgkmcnt(0)
	v_add_f32_e32 v112, v112, v113
	s_mov_b64 s[26:27], -1
	s_and_b64 vcc, exec, s[12:13]
	s_cbranch_vccz .LBB0_408
	v_readlane_b32 s26, v250, 59
	v_lshlrev_b64 v[114:115], 5, v[156:157]
	v_readlane_b32 s27, v250, 60
	s_nop 1
	v_lshl_add_u64 v[114:115], s[26:27], 0, v[114:115]
	v_lshl_add_u64 v[114:115], s[14:15], 2, v[114:115]
	global_atomic_add_f32 v[114:115], v112, off
	s_mov_b64 s[26:27], 0

; #define PG8_STAGE(bufoff, gbase, voff) do { _Pragma("unroll") for (int _i = 0; _i < 2; ++_i) \
;         __builtin_amdgcn_global_load_lds((const unsigned*)((const char*)(gbase) + (voff)[_i]), (LAS unsigned*)(lds + (bufoff) + ldsw + _i * 8192), 16, 0, 0); } while (0)
; #define PG8_LDA(dst, b, h) do { _Pragma("unroll") for (int m = 0; m < 4; ++m) _Pragma("unroll") for (int k = 0; k < 2; ++k) dst[m][k] = *(const LAS bf16x8*)(lds + PG8_SA(b, h) + aoff + m * 2048 + k * 1024); } while (0)
; #define PG8_LDB(dst, b, h) do { _Pragma("unroll") for (int n = 0; n < 2; ++n) _Pragma("unroll") for (int k = 0; k < 2; ++k) dst[n][k] = *(const LAS bf16x8*)(lds + PG8_SB(b, h) + boff + n * 2048 + k * 1024); } while (0)
; #define PG8_MMA(ai, bj, At, Bt) do { __builtin_amdgcn_s_setprio(1); _Pragma("unroll") for (int m = 0; m < 4; ++m) _Pragma("unroll") for (int n = 0; n < 2; ++n) _Pragma("unroll") for (int k = 0; k < 2; ++k) \
;         acc[ai][bj][m][n] = __builtin_amdgcn_mfma_f32_16x16x32_bf16(Bt[n][k], At[m][k], acc[ai][bj][m][n], 0, 0, 0); __builtin_amdgcn_s_setprio(0); } while (0)
; #define PG8_WAIT_V(n) asm volatile("s_waitcnt vmcnt(" #n ")" ::: "memory")
; #define PG8_WAIT_L(n) asm volatile("s_waitcnt lgkmcnt(" #n ")" ::: "memory")
; #define PG8_BAR __builtin_amdgcn_s_barrier()
; #define PG8_SCHED __builtin_amdgcn_sched_barrier(0)
; template <class Epi>
; DEV void gemm_phase(LAS unsigned char* lds, const Gemm g, const StaticOrder& S, const Epi& E) {
;     ...
;             const bool last = (t == nt - 2);
;             const char* a1 = cA + (size_t)(t + 1) * kstep;
;             const char* a2 = last ? nA : cA + (size_t)(t + 2) * kstep; const char* b2 = last ? nB : cB + (size_t)(t + 2) * kstep;
;             const char* a3 = a2 + kstep; const char* b3 = b2 + kstep;
;             PG8_LDB(B0, 0, 0); PG8_SCHED; PG8_LDA(At, 0, 0); PG8_STAGE(PG8_SA(1, 1), a1 + hstep, voffA);
;             PG8_WAIT_L(8); PG8_BAR; PG8_WAIT_L(0); PG8_MMA(0, 0, At, B0); PG8_BAR; PG8_SCHED;
;             PG8_LDB(B1, 0, 1); PG8_STAGE(PG8_SB(0, 0), b2, voffB);
;             PG8_BAR; PG8_WAIT_L(0); PG8_MMA(0, 1, At, B1); PG8_BAR;
;             PG8_LDA(At, 0, 1); PG8_STAGE(PG8_SA(0, 0), a2, voffA);
;             PG8_BAR; PG8_WAIT_L(0); PG8_MMA(1, 0, At, B0); PG8_BAR; PG8_SCHED;
;             PG8_STAGE(PG8_SB(0, 1), b2 + hstep, voffB);
;             PG8_WAIT_V(6); PG8_BAR; PG8_MMA(1, 1, At, B1); PG8_BAR;
.LBB0_588:
	s_add_u32 s16, s14, 0xfff80080
	s_addc_u32 s17, s15, -1
	s_add_i32 s41, 0, 0x10000
	v_add_u32_e32 v154, s41, v167
	ds_read_b128 v[128:131], v154
	ds_read_b128 v[132:135], v154 offset:1024
	ds_read_b128 v[150:153], v154 offset:2048
	ds_read_b128 v[174:177], v154 offset:3072
	s_cmp_eq_u32 s40, 28
	s_cselect_b32 s19, s1, s17
	s_cselect_b32 s18, s9, s16
	s_cselect_b32 s17, s7, s37
	s_cselect_b32 s16, s35, s36
	s_add_i32 m0, s24, 0xc000
	ds_read_b128 v[182:185], v219
	ds_read_b128 v[190:193], v219 offset:1024
	ds_read_b128 v[194:197], v219 offset:2048
	ds_read_b128 v[220:223], v219 offset:3072
	ds_read_b128 v[224:227], v219 offset:4096
	ds_read_b128 v[228:231], v219 offset:5120
	ds_read_b128 v[232:235], v219 offset:6144
	ds_read_b128 v[236:239], v219 offset:7168
	global_load_lds_dwordx4 v146, s[14:15]
	s_add_i32 m0, s24, 0xe000
	s_nop 0
	global_load_lds_dwordx4 v148, s[14:15]
	s_waitcnt lgkmcnt(8)
	s_barrier
	s_waitcnt lgkmcnt(0)
	v_mfma_f32_16x16x32_bf16 v[124:127], v[128:131], v[182:185], v[124:127]
	v_mfma_f32_16x16x32_bf16 v[120:123], v[150:153], v[182:185], v[120:123]
	v_mfma_f32_16x16x32_bf16 v[108:111], v[128:131], v[194:197], v[108:111]
	v_mfma_f32_16x16x32_bf16 v[104:107], v[150:153], v[194:197], v[104:107]
	v_mfma_f32_16x16x32_bf16 v[92:95], v[128:131], v[224:227], v[92:95]
	v_mfma_f32_16x16x32_bf16 v[88:91], v[150:153], v[224:227], v[88:91]
	v_mfma_f32_16x16x32_bf16 v[76:79], v[128:131], v[232:235], v[76:79]
	v_mfma_f32_16x16x32_bf16 v[72:75], v[150:153], v[232:235], v[72:75]
	v_mfma_f32_16x16x32_bf16 v[124:127], v[132:135], v[190:193], v[124:127]
	v_mfma_f32_16x16x32_bf16 v[120:123], v[174:177], v[190:193], v[120:123]
	v_mfma_f32_16x16x32_bf16 v[108:111], v[132:135], v[220:223], v[108:111]
	v_mfma_f32_16x16x32_bf16 v[104:107], v[174:177], v[220:223], v[104:107]
	v_mfma_f32_16x16x32_bf16 v[92:95], v[132:135], v[228:231], v[92:95]
	v_mfma_f32_16x16x32_bf16 v[88:91], v[174:177], v[228:231], v[88:91]
	v_mfma_f32_16x16x32_bf16 v[76:79], v[132:135], v[236:239], v[76:79]
	v_mfma_f32_16x16x32_bf16 v[72:75], v[174:177], v[236:239], v[72:75]
	s_barrier
	s_add_i32 s44, 0, 0x14000
	v_add_u32_e32 v154, s44, v167
	s_add_i32 s41, s41, s22
	ds_read_b128 v[240:243], v154
	ds_read_b128 v[244:247], v154 offset:1024
	ds_read_b128 v[186:189], v154 offset:2048
	ds_read_b128 v[214:217], v154 offset:3072
	v_lshl_add_u64 v[154:155], s[16:17], 0, v[140:141]
	s_mov_b32 m0, s41
	v_lshl_add_u64 v[158:159], s[16:17], 0, v[136:137]
	global_load_lds_dwordx4 v140, s[16:17]
	s_add_i32 m0, s41, 0x2000
	s_nop 0
	global_load_lds_dwordx4 v136, s[16:17]
	s_barrier
	s_waitcnt lgkmcnt(0)
	v_mfma_f32_16x16x32_bf16 v[116:119], v[240:243], v[182:185], v[116:119]
	v_mfma_f32_16x16x32_bf16 v[112:115], v[186:189], v[182:185], v[112:115]
	v_mfma_f32_16x16x32_bf16 v[100:103], v[240:243], v[194:197], v[100:103]
	v_mfma_f32_16x16x32_bf16 v[96:99], v[186:189], v[194:197], v[96:99]
	v_mfma_f32_16x16x32_bf16 v[84:87], v[240:243], v[224:227], v[84:87]
	v_mfma_f32_16x16x32_bf16 v[80:83], v[186:189], v[224:227], v[80:83]
	v_mfma_f32_16x16x32_bf16 v[68:71], v[240:243], v[232:235], v[68:71]
	v_mfma_f32_16x16x32_bf16 v[64:67], v[186:189], v[232:235], v[64:67]
	v_mfma_f32_16x16x32_bf16 v[116:119], v[244:247], v[190:193], v[116:119]
	v_mfma_f32_16x16x32_bf16 v[112:115], v[214:217], v[190:193], v[112:115]
	v_mfma_f32_16x16x32_bf16 v[100:103], v[244:247], v[220:223], v[100:103]
	v_mfma_f32_16x16x32_bf16 v[96:99], v[214:217], v[220:223], v[96:99]
	v_mfma_f32_16x16x32_bf16 v[84:87], v[244:247], v[228:231], v[84:87]
	v_mfma_f32_16x16x32_bf16 v[80:83], v[214:217], v[228:231], v[80:83]
	v_mfma_f32_16x16x32_bf16 v[68:71], v[244:247], v[236:239], v[68:71]
	v_mfma_f32_16x16x32_bf16 v[64:67], v[214:217], v[236:239], v[64:67]
	s_mov_b32 m0, s24
	v_lshl_add_u64 v[178:179], s[18:19], 0, v[142:143]
	s_barrier
	ds_read_b128 v[182:185], v219 offset:16384
	ds_read_b128 v[190:193], v219 offset:17408
	ds_read_b128 v[194:197], v219 offset:18432
	ds_read_b128 v[220:223], v219 offset:19456
	ds_read_b128 v[224:227], v219 offset:20480
	ds_read_b128 v[228:231], v219 offset:21504
	ds_read_b128 v[232:235], v219 offset:22528
	ds_read_b128 v[236:239], v219 offset:23552
	global_load_lds_dwordx4 v142, s[18:19]
	v_lshl_add_u64 v[248:249], s[18:19], 0, v[138:139]
	s_mov_b32 m0, s25
	s_nop 0
	global_load_lds_dwordx4 v138, s[18:19]
	s_barrier
	s_waitcnt lgkmcnt(0)
	v_mfma_f32_16x16x32_bf16 v[60:63], v[128:131], v[182:185], v[60:63]
	v_mfma_f32_16x16x32_bf16 v[56:59], v[150:153], v[182:185], v[56:59]
	v_mfma_f32_16x16x32_bf16 v[44:47], v[128:131], v[194:197], v[44:47]
	v_mfma_f32_16x16x32_bf16 v[40:43], v[150:153], v[194:197], v[40:43]
	v_mfma_f32_16x16x32_bf16 v[28:31], v[128:131], v[224:227], v[28:31]
	v_mfma_f32_16x16x32_bf16 v[24:27], v[150:153], v[224:227], v[24:27]
	v_mfma_f32_16x16x32_bf16 v[12:15], v[128:131], v[232:235], v[12:15]
	v_mfma_f32_16x16x32_bf16 v[8:11], v[150:153], v[232:235], v[8:11]
	v_mfma_f32_16x16x32_bf16 v[60:63], v[132:135], v[190:193], v[60:63]
	v_mfma_f32_16x16x32_bf16 v[56:59], v[174:177], v[190:193], v[56:59]
	v_mfma_f32_16x16x32_bf16 v[44:47], v[132:135], v[220:223], v[44:47]
	v_mfma_f32_16x16x32_bf16 v[40:43], v[174:177], v[220:223], v[40:43]
	v_mfma_f32_16x16x32_bf16 v[28:31], v[132:135], v[228:231], v[28:31]
	v_mfma_f32_16x16x32_bf16 v[24:27], v[174:177], v[228:231], v[24:27]
	v_mfma_f32_16x16x32_bf16 v[12:15], v[132:135], v[236:239], v[12:15]
	v_mfma_f32_16x16x32_bf16 v[8:11], v[174:177], v[236:239], v[8:11]
	s_barrier
	s_add_u32 s42, s16, 0x80000
	s_addc_u32 s43, s17, 0
	s_add_i32 s41, s44, s22
	s_mov_b32 m0, s41
	s_nop 0
	global_load_lds_dwordx4 v140, s[42:43]
	s_add_i32 m0, s41, 0x2000
	s_nop 0
	global_load_lds_dwordx4 v136, s[42:43]
	s_waitcnt vmcnt(6)
	s_barrier
; #define PG8_STAGE(bufoff, gbase, voff) do { _Pragma("unroll") for (int _i = 0; _i < 2; ++_i) \
;         __builtin_amdgcn_global_load_lds((const unsigned*)((const char*)(gbase) + (voff)[_i]), (LAS unsigned*)(lds + (bufoff) + ldsw + _i * 8192), 16, 0, 0); } while (0)
; #define PG8_LDA(dst, b, h) do { _Pragma("unroll") for (int m = 0; m < 4; ++m) _Pragma("unroll") for (int k = 0; k < 2; ++k) dst[m][k] = *(const LAS bf16x8*)(lds + PG8_SA(b, h) + aoff + m * 2048 + k * 1024); } while (0)
; #define PG8_LDB(dst, b, h) do { _Pragma("unroll") for (int n = 0; n < 2; ++n) _Pragma("unroll") for (int k = 0; k < 2; ++k) dst[n][k] = *(const LAS bf16x8*)(lds + PG8_SB(b, h) + boff + n * 2048 + k * 1024); } while (0)
; #define PG8_MMA(ai, bj, At, Bt) do { __builtin_amdgcn_s_setprio(1); _Pragma("unroll") for (int m = 0; m < 4; ++m) _Pragma("unroll") for (int n = 0; n < 2; ++n) _Pragma("unroll") for (int k = 0; k < 2; ++k) \
;         acc[ai][bj][m][n] = __builtin_amdgcn_mfma_f32_16x16x32_bf16(Bt[n][k], At[m][k], acc[ai][bj][m][n], 0, 0, 0); __builtin_amdgcn_s_setprio(0); } while (0)
; #define PG8_WAIT_V(n) asm volatile("s_waitcnt vmcnt(" #n ")" ::: "memory")
; #define PG8_WAIT_L(n) asm volatile("s_waitcnt lgkmcnt(" #n ")" ::: "memory")
; #define PG8_BAR __builtin_amdgcn_s_barrier()
; #define PG8_SCHED __builtin_amdgcn_sched_barrier(0)
; template <class Epi>
; DEV void gemm_phase(LAS unsigned char* lds, const Gemm g, const StaticOrder& S, const Epi& E) {
;     ...
;             PG8_WAIT_V(6); PG8_BAR; PG8_MMA(1, 1, At, B1); PG8_BAR;
;             PG8_LDB(B0, 1, 0); PG8_SCHED; PG8_LDA(At, 1, 0); PG8_STAGE(PG8_SA(0, 1), a2 + hstep, voffA);
;             PG8_WAIT_L(8); PG8_BAR; PG8_WAIT_L(0); PG8_MMA(0, 0, At, B0); PG8_BAR; PG8_SCHED;
;             PG8_LDB(B1, 1, 1); PG8_STAGE(PG8_SB(1, 0), b3, voffB);
;             PG8_BAR; PG8_WAIT_L(0); PG8_MMA(0, 1, At, B1); PG8_BAR;
;             PG8_LDA(At, 1, 1); PG8_STAGE(PG8_SA(1, 0), a3, voffA);
;             PG8_BAR; PG8_WAIT_L(0); PG8_MMA(1, 0, At, B0); PG8_BAR; PG8_SCHED;
	v_mfma_f32_16x16x32_bf16 v[52:55], v[240:243], v[182:185], v[52:55]
	v_mfma_f32_16x16x32_bf16 v[48:51], v[186:189], v[182:185], v[48:51]
	v_mfma_f32_16x16x32_bf16 v[36:39], v[240:243], v[194:197], v[36:39]
	v_mfma_f32_16x16x32_bf16 v[32:35], v[186:189], v[194:197], v[32:35]
	v_mfma_f32_16x16x32_bf16 v[20:23], v[240:243], v[224:227], v[20:23]
	v_mfma_f32_16x16x32_bf16 v[16:19], v[186:189], v[224:227], v[16:19]
	v_mfma_f32_16x16x32_bf16 v[4:7], v[240:243], v[232:235], v[4:7]
	v_mfma_f32_16x16x32_bf16 v[0:3], v[186:189], v[232:235], v[0:3]
	v_mfma_f32_16x16x32_bf16 v[52:55], v[244:247], v[190:193], v[52:55]
	v_mfma_f32_16x16x32_bf16 v[48:51], v[214:217], v[190:193], v[48:51]
	v_mfma_f32_16x16x32_bf16 v[36:39], v[244:247], v[220:223], v[36:39]
	v_mfma_f32_16x16x32_bf16 v[32:35], v[214:217], v[220:223], v[32:35]
	v_mfma_f32_16x16x32_bf16 v[20:23], v[244:247], v[228:231], v[20:23]
	v_mfma_f32_16x16x32_bf16 v[16:19], v[214:217], v[228:231], v[16:19]
	v_mfma_f32_16x16x32_bf16 v[4:7], v[244:247], v[236:239], v[4:7]
	v_mfma_f32_16x16x32_bf16 v[0:3], v[214:217], v[236:239], v[0:3]
	s_add_i32 s41, 0, 0x18000
	v_add_u32_e32 v156, s41, v167
	s_barrier
	ds_read_b128 v[128:131], v156
	ds_read_b128 v[132:135], v156 offset:1024
	ds_read_b128 v[150:153], v156 offset:2048
	ds_read_b128 v[174:177], v156 offset:3072
	s_add_u32 s18, s18, 0x80000
	s_addc_u32 s19, s19, 0
	s_mov_b32 m0, s26
	ds_read_b128 v[182:185], v219 offset:32768
	ds_read_b128 v[186:189], v219 offset:33792
	ds_read_b128 v[190:193], v219 offset:34816
	ds_read_b128 v[194:197], v219 offset:35840
	ds_read_b128 v[214:217], v219 offset:36864
	ds_read_b128 v[220:223], v219 offset:37888
	ds_read_b128 v[224:227], v219 offset:38912
	ds_read_b128 v[228:231], v219 offset:39936
	global_load_lds_dwordx4 v142, s[18:19]
	s_mov_b32 m0, s27
	s_nop 0
	global_load_lds_dwordx4 v138, s[18:19]
	s_waitcnt lgkmcnt(8)
	s_barrier
	s_waitcnt lgkmcnt(0)
	v_mfma_f32_16x16x32_bf16 v[124:127], v[128:131], v[182:185], v[124:127]
	v_mfma_f32_16x16x32_bf16 v[120:123], v[150:153], v[182:185], v[120:123]
	v_mfma_f32_16x16x32_bf16 v[108:111], v[128:131], v[190:193], v[108:111]
	v_mfma_f32_16x16x32_bf16 v[104:107], v[150:153], v[190:193], v[104:107]
	v_mfma_f32_16x16x32_bf16 v[92:95], v[128:131], v[214:217], v[92:95]
	v_mfma_f32_16x16x32_bf16 v[88:91], v[150:153], v[214:217], v[88:91]
	v_mfma_f32_16x16x32_bf16 v[76:79], v[128:131], v[224:227], v[76:79]
	v_mfma_f32_16x16x32_bf16 v[72:75], v[150:153], v[224:227], v[72:75]
	v_mfma_f32_16x16x32_bf16 v[124:127], v[132:135], v[186:189], v[124:127]
	v_mfma_f32_16x16x32_bf16 v[120:123], v[174:177], v[186:189], v[120:123]
	v_mfma_f32_16x16x32_bf16 v[108:111], v[132:135], v[194:197], v[108:111]
	v_mfma_f32_16x16x32_bf16 v[104:107], v[174:177], v[194:197], v[104:107]
	v_mfma_f32_16x16x32_bf16 v[92:95], v[132:135], v[220:223], v[92:95]
	v_mfma_f32_16x16x32_bf16 v[88:91], v[174:177], v[220:223], v[88:91]
	v_mfma_f32_16x16x32_bf16 v[76:79], v[132:135], v[228:231], v[76:79]
	v_mfma_f32_16x16x32_bf16 v[72:75], v[174:177], v[228:231], v[72:75]
	s_barrier
	s_add_i32 s18, 0, 0x1c000
	s_add_i32 s19, s41, s22
	v_add_u32_e32 v156, s18, v167
	v_lshl_add_u64 v[154:155], v[154:155], 0, s[2:3]
	s_mov_b32 m0, s19
	ds_read_b128 v[232:235], v156
	ds_read_b128 v[236:239], v156 offset:1024
	ds_read_b128 v[240:243], v156 offset:2048
	ds_read_b128 v[244:247], v156 offset:3072
	global_load_lds_dwordx4 v[154:155], off
	v_lshl_add_u64 v[154:155], v[158:159], 0, s[2:3]
	s_add_i32 m0, s19, 0x2000
	s_nop 0
	global_load_lds_dwordx4 v[154:155], off
	s_barrier
	s_waitcnt lgkmcnt(0)
	v_mfma_f32_16x16x32_bf16 v[116:119], v[232:235], v[182:185], v[116:119]
	v_mfma_f32_16x16x32_bf16 v[112:115], v[240:243], v[182:185], v[112:115]
	v_mfma_f32_16x16x32_bf16 v[100:103], v[232:235], v[190:193], v[100:103]
	v_mfma_f32_16x16x32_bf16 v[96:99], v[240:243], v[190:193], v[96:99]
	v_mfma_f32_16x16x32_bf16 v[84:87], v[232:235], v[214:217], v[84:87]
	v_mfma_f32_16x16x32_bf16 v[80:83], v[240:243], v[214:217], v[80:83]
	v_mfma_f32_16x16x32_bf16 v[68:71], v[232:235], v[224:227], v[68:71]
	v_mfma_f32_16x16x32_bf16 v[64:67], v[240:243], v[224:227], v[64:67]
	v_mfma_f32_16x16x32_bf16 v[116:119], v[236:239], v[186:189], v[116:119]
	v_mfma_f32_16x16x32_bf16 v[112:115], v[244:247], v[186:189], v[112:115]
	v_mfma_f32_16x16x32_bf16 v[100:103], v[236:239], v[194:197], v[100:103]
	v_mfma_f32_16x16x32_bf16 v[96:99], v[244:247], v[194:197], v[96:99]
	v_mfma_f32_16x16x32_bf16 v[84:87], v[236:239], v[220:223], v[84:87]
	v_mfma_f32_16x16x32_bf16 v[80:83], v[244:247], v[220:223], v[80:83]
	v_mfma_f32_16x16x32_bf16 v[68:71], v[236:239], v[228:231], v[68:71]
	v_mfma_f32_16x16x32_bf16 v[64:67], v[244:247], v[228:231], v[64:67]
	s_mov_b32 m0, s28
	v_lshl_add_u64 v[154:155], v[178:179], 0, s[2:3]
	s_barrier
	ds_read_b128 v[182:185], v219 offset:49152
	ds_read_b128 v[186:189], v219 offset:50176
	ds_read_b128 v[190:193], v219 offset:51200
	ds_read_b128 v[194:197], v219 offset:52224
	ds_read_b128 v[214:217], v219 offset:53248
	ds_read_b128 v[220:223], v219 offset:54272
	ds_read_b128 v[224:227], v219 offset:55296
	ds_read_b128 v[228:231], v219 offset:56320
	global_load_lds_dwordx4 v[154:155], off
	v_lshl_add_u64 v[154:155], v[248:249], 0, s[2:3]
	s_mov_b32 m0, s29
	s_nop 0
	global_load_lds_dwordx4 v[154:155], off
	s_barrier
; #define PG8_STAGE(bufoff, gbase, voff) do { _Pragma("unroll") for (int _i = 0; _i < 2; ++_i) \
;         __builtin_amdgcn_global_load_lds((const unsigned*)((const char*)(gbase) + (voff)[_i]), (LAS unsigned*)(lds + (bufoff) + ldsw + _i * 8192), 16, 0, 0); } while (0)
; #define PG8_MMA(ai, bj, At, Bt) do { __builtin_amdgcn_s_setprio(1); _Pragma("unroll") for (int m = 0; m < 4; ++m) _Pragma("unroll") for (int n = 0; n < 2; ++n) _Pragma("unroll") for (int k = 0; k < 2; ++k) \
;         acc[ai][bj][m][n] = __builtin_amdgcn_mfma_f32_16x16x32_bf16(Bt[n][k], At[m][k], acc[ai][bj][m][n], 0, 0, 0); __builtin_amdgcn_s_setprio(0); } while (0)
; #define PG8_WAIT_V(n) asm volatile("s_waitcnt vmcnt(" #n ")" ::: "memory")
; #define PG8_WAIT_L(n) asm volatile("s_waitcnt lgkmcnt(" #n ")" ::: "memory")
; #define PG8_BAR __builtin_amdgcn_s_barrier()
; #define PG8_SCHED __builtin_amdgcn_sched_barrier(0)
;     DEV void operator()(AccRef acc, const pg8::Unit& u, int wr, int wc, int fr, int fq) const { store_bf16_tile<0, false>(acc, O, ld, u.pm * 256 + wr * 64 + fr, u.pn * 256 + wc * 32 + 4 * fq, ss); }
; template <class Epi>
; DEV void gemm_phase(LAS unsigned char* lds, const Gemm g, const StaticOrder& S, const Epi& E) {
;     ...
;             PG8_BAR; PG8_WAIT_L(0); PG8_MMA(1, 0, At, B0); PG8_BAR; PG8_SCHED;
;             PG8_STAGE(PG8_SB(1, 1), b3 + hstep, voffB);
;             PG8_WAIT_V(6); PG8_BAR; PG8_MMA(1, 1, At, B1); PG8_BAR;
;     DEV void operator()(AccRef acc, const pg8::Unit& u, int wr, int wc, int fr, int fq) const {
;         const int ct = u.pn * 256, row0 = u.pm * 256 + wr * 64 + fr, cw = wc * 32 + 8 * fq;
;         if (ct < 4096) store_bf16_tile<1, true>(acc, UV, 4096, row0, ct + cw, ss);
;         else if (ct < 6144) store_bf16_tile<0, true>(acc, Z, 2048, row0, ct - 4096 + cw, ss);
;         else if (ct < 9216) store_bf16_tile<0, true>(acc, XBC, 3072, row0, ct - 6144 + cw, ss);
;         else if (wc == 0) {
; #pragma unroll
;             for (int ai = 0; ai < 2; ++ai)
; #pragma unroll
;                 for (int m = 0; m < 4; ++m) { const float rs = rowscale(ss, row0 + ai * 128 + m * 16);
; #pragma unroll
;                     for (int n = 0; n < 2; ++n) *(f32x4*)(DTR + (size_t)(row0 + ai * 128 + m * 16) * 32 + 8 * fq + 4 * n) = acc[ai][0][m][n] * rs; }
	s_waitcnt lgkmcnt(0)
	v_mfma_f32_16x16x32_bf16 v[60:63], v[128:131], v[182:185], v[60:63]
	v_mfma_f32_16x16x32_bf16 v[56:59], v[150:153], v[182:185], v[56:59]
	v_mfma_f32_16x16x32_bf16 v[44:47], v[128:131], v[190:193], v[44:47]
	v_mfma_f32_16x16x32_bf16 v[40:43], v[150:153], v[190:193], v[40:43]
	v_mfma_f32_16x16x32_bf16 v[28:31], v[128:131], v[214:217], v[28:31]
	v_mfma_f32_16x16x32_bf16 v[24:27], v[150:153], v[214:217], v[24:27]
	v_mfma_f32_16x16x32_bf16 v[12:15], v[128:131], v[224:227], v[12:15]
	v_mfma_f32_16x16x32_bf16 v[8:11], v[150:153], v[224:227], v[8:11]
	v_mfma_f32_16x16x32_bf16 v[60:63], v[132:135], v[186:189], v[60:63]
	v_mfma_f32_16x16x32_bf16 v[56:59], v[174:177], v[186:189], v[56:59]
	v_mfma_f32_16x16x32_bf16 v[44:47], v[132:135], v[194:197], v[44:47]
	v_mfma_f32_16x16x32_bf16 v[40:43], v[174:177], v[194:197], v[40:43]
	v_mfma_f32_16x16x32_bf16 v[28:31], v[132:135], v[220:223], v[28:31]
	v_mfma_f32_16x16x32_bf16 v[24:27], v[174:177], v[220:223], v[24:27]
	v_mfma_f32_16x16x32_bf16 v[12:15], v[132:135], v[228:231], v[12:15]
	v_mfma_f32_16x16x32_bf16 v[8:11], v[174:177], v[228:231], v[8:11]
	s_barrier
	s_add_u32 s16, s16, 0x80080
	s_addc_u32 s17, s17, 0
	s_add_i32 s18, s18, s22
	s_mov_b32 m0, s18
	s_nop 0
	global_load_lds_dwordx4 v140, s[16:17]
	s_add_i32 m0, s18, 0x2000
	s_nop 0
	global_load_lds_dwordx4 v136, s[16:17]
	s_waitcnt vmcnt(6)
	s_barrier
	v_mfma_f32_16x16x32_bf16 v[52:55], v[232:235], v[182:185], v[52:55]
	v_mfma_f32_16x16x32_bf16 v[48:51], v[240:243], v[182:185], v[48:51]
	v_mfma_f32_16x16x32_bf16 v[36:39], v[232:235], v[190:193], v[36:39]
	v_mfma_f32_16x16x32_bf16 v[32:35], v[240:243], v[190:193], v[32:35]
	v_mfma_f32_16x16x32_bf16 v[20:23], v[232:235], v[214:217], v[20:23]
	v_mfma_f32_16x16x32_bf16 v[16:19], v[240:243], v[214:217], v[16:19]
	v_mfma_f32_16x16x32_bf16 v[4:7], v[232:235], v[224:227], v[4:7]
	v_mfma_f32_16x16x32_bf16 v[0:3], v[240:243], v[224:227], v[0:3]
	v_mfma_f32_16x16x32_bf16 v[52:55], v[236:239], v[186:189], v[52:55]
	v_mfma_f32_16x16x32_bf16 v[48:51], v[244:247], v[186:189], v[48:51]
	v_mfma_f32_16x16x32_bf16 v[36:39], v[236:239], v[194:197], v[36:39]
	v_mfma_f32_16x16x32_bf16 v[32:35], v[244:247], v[194:197], v[32:35]
	v_mfma_f32_16x16x32_bf16 v[20:23], v[236:239], v[220:223], v[20:23]
	v_mfma_f32_16x16x32_bf16 v[16:19], v[244:247], v[220:223], v[16:19]
	v_mfma_f32_16x16x32_bf16 v[4:7], v[236:239], v[228:231], v[4:7]
	v_mfma_f32_16x16x32_bf16 v[0:3], v[244:247], v[228:231], v[0:3]
	s_add_i32 s40, s40, 2
	s_add_u32 s14, s14, 0x100
	s_addc_u32 s15, s15, 0
	s_add_u32 s36, s36, 0x100
	s_addc_u32 s37, s37, 0
	s_cmp_gt_u32 s40, 29
	s_barrier
	s_cbranch_scc0 .LBB0_588
	s_lshl_b32 s7, s34, 8
	v_lshl_add_u32 v150, s0, 8, v157
	s_cmp_gt_i32 s34, 15
	s_mov_b64 s[0:1], -1
	s_cbranch_scc0 .LBB0_601
	s_cmp_gt_u32 s34, 23
	s_cbranch_scc0 .LBB0_598
	s_cmp_gt_u32 s34, 35
	s_cbranch_scc0 .LBB0_595
	s_andn2_b64 vcc, exec, s[4:5]
	s_cbranch_vccnz .LBB0_594
	v_ashrrev_i32_e32 v151, 31, v150
	v_readlane_b32 s0, v251, 39
	v_lshlrev_b64 v[128:129], 5, v[150:151]
	v_readlane_b32 s1, v251, 40
	s_mov_b32 s9, 0x800000
	s_nop 0
	v_lshl_add_u64 v[132:133], s[0:1], 0, v[128:129]
	global_load_dwordx4 v[128:131], v[132:133], off offset:16
	s_nop 0
	global_load_dwordx4 v[132:135], v[132:133], off
	s_waitcnt vmcnt(0)
	v_mov_b32_e32 v152, v133
	v_mov_b32_e32 v153, v134
	v_mov_b32_e32 v133, v135
	v_pk_add_f32 v[132:133], v[152:153], v[132:133]
	v_mov_b32_e32 v134, v130
	v_mov_b32_e32 v135, v128
	v_mov_b32_e32 v128, v131
	v_pk_add_f32 v[128:129], v[134:135], v[128:129]
	v_add_f32_e32 v130, v132, v133
	v_add_f32_e32 v129, v130, v129
	v_add_f32_e32 v128, v128, v129
	v_fmamk_f32 v128, v128, 0x3a000000, v199
	v_cmp_gt_f32_e32 vcc, s9, v128
	v_mul_f32_e32 v129, 0x4b800000, v128
	v_lshlrev_b64 v[134:135], 7, v[150:151]
	v_cndmask_b32_e32 v128, v128, v129, vcc
	v_rsq_f32_e32 v128, v128
	v_lshl_add_u64 v[134:135], v[144:145], 0, v[134:135]
	v_or_b32_e32 v152, 16, v150
	v_ashrrev_i32_e32 v153, 31, v152
	v_mul_f32_e32 v129, 0x45800000, v128
	v_cndmask_b32_e32 v132, v128, v129, vcc
	v_pk_mul_f32 v[130:131], v[126:127], v[132:133] op_sel_hi:[1,0]
	v_pk_mul_f32 v[128:129], v[124:125], v[132:133] op_sel_hi:[1,0]
	global_store_dwordx4 v[134:135], v[128:131], off
	s_nop 1
	v_pk_mul_f32 v[130:131], v[122:123], v[132:133] op_sel_hi:[1,0]
	v_pk_mul_f32 v[128:129], v[120:121], v[132:133] op_sel_hi:[1,0]
	global_store_dwordx4 v[134:135], v[128:131], off offset:16
	s_nop 1
	v_lshlrev_b64 v[128:129], 5, v[152:153]
	v_lshl_add_u64 v[132:133], s[0:1], 0, v[128:129]
	global_load_dwordx4 v[128:131], v[132:133], off offset:16
	s_nop 0
	global_load_dwordx4 v[132:135], v[132:133], off
	s_waitcnt vmcnt(0)
	v_mov_b32_e32 v154, v133
	v_mov_b32_e32 v155, v134
	v_mov_b32_e32 v133, v135
	v_pk_add_f32 v[132:133], v[154:155], v[132:133]
	v_mov_b32_e32 v134, v130
	v_mov_b32_e32 v135, v128
	v_mov_b32_e32 v128, v131
	v_pk_add_f32 v[128:129], v[134:135], v[128:129]
	v_add_f32_e32 v130, v132, v133
	v_add_f32_e32 v129, v130, v129
	v_add_f32_e32 v128, v128, v129
	v_fmamk_f32 v128, v128, 0x3a000000, v199
	v_cmp_gt_f32_e32 vcc, s9, v128
	v_mul_f32_e32 v129, 0x4b800000, v128
	v_lshlrev_b64 v[134:135], 7, v[152:153]
	v_cndmask_b32_e32 v128, v128, v129, vcc
	v_rsq_f32_e32 v128, v128
	v_lshl_add_u64 v[134:135], v[144:145], 0, v[134:135]
	v_or_b32_e32 v152, 32, v150
	v_ashrrev_i32_e32 v153, 31, v152
	v_mul_f32_e32 v129, 0x45800000, v128
	v_cndmask_b32_e32 v132, v128, v129, vcc
	v_pk_mul_f32 v[130:131], v[110:111], v[132:133] op_sel_hi:[1,0]
	v_pk_mul_f32 v[128:129], v[108:109], v[132:133] op_sel_hi:[1,0]
	global_store_dwordx4 v[134:135], v[128:131], off
	s_nop 1
	v_pk_mul_f32 v[130:131], v[106:107], v[132:133] op_sel_hi:[1,0]
	v_pk_mul_f32 v[128:129], v[104:105], v[132:133] op_sel_hi:[1,0]
	global_store_dwordx4 v[134:135], v[128:131], off offset:16
	s_nop 1
	v_lshlrev_b64 v[128:129], 5, v[152:153]
	v_lshl_add_u64 v[132:133], s[0:1], 0, v[128:129]
	global_load_dwordx4 v[128:131], v[132:133], off offset:16
	s_nop 0
	global_load_dwordx4 v[132:135], v[132:133], off
	s_waitcnt vmcnt(0)
;     DEV void operator()(AccRef acc, const pg8::Unit& u, int wr, int wc, int fr, int fq) const {
;     ...
;                 for (int m = 0; m < 4; ++m) { const float rs = rowscale(ss, row0 + ai * 128 + m * 16);
; #pragma unroll
;                     for (int n = 0; n < 2; ++n) *(f32x4*)(DTR + (size_t)(row0 + ai * 128 + m * 16) * 32 + 8 * fq + 4 * n) = acc[ai][0][m][n] * rs; }
	v_mov_b32_e32 v154, v133
	v_mov_b32_e32 v155, v134
	v_mov_b32_e32 v133, v135
	v_pk_add_f32 v[132:133], v[154:155], v[132:133]
	v_mov_b32_e32 v134, v130
	v_mov_b32_e32 v135, v128
	v_mov_b32_e32 v128, v131
	v_pk_add_f32 v[128:129], v[134:135], v[128:129]
	v_add_f32_e32 v130, v132, v133
	v_add_f32_e32 v129, v130, v129
	v_add_f32_e32 v128, v128, v129
	v_fmamk_f32 v128, v128, 0x3a000000, v199
	v_cmp_gt_f32_e32 vcc, s9, v128
	v_mul_f32_e32 v129, 0x4b800000, v128
	v_lshlrev_b64 v[134:135], 7, v[152:153]
	v_cndmask_b32_e32 v128, v128, v129, vcc
	v_rsq_f32_e32 v128, v128
	v_lshl_add_u64 v[134:135], v[144:145], 0, v[134:135]
	v_or_b32_e32 v152, 48, v150
	v_ashrrev_i32_e32 v153, 31, v152
	v_mul_f32_e32 v129, 0x45800000, v128
	v_cndmask_b32_e32 v132, v128, v129, vcc
	v_pk_mul_f32 v[130:131], v[94:95], v[132:133] op_sel_hi:[1,0]
	v_pk_mul_f32 v[128:129], v[92:93], v[132:133] op_sel_hi:[1,0]
	global_store_dwordx4 v[134:135], v[128:131], off
	s_nop 1
	v_pk_mul_f32 v[130:131], v[90:91], v[132:133] op_sel_hi:[1,0]
	v_pk_mul_f32 v[128:129], v[88:89], v[132:133] op_sel_hi:[1,0]
	global_store_dwordx4 v[134:135], v[128:131], off offset:16
	s_nop 1
	v_lshlrev_b64 v[128:129], 5, v[152:153]
	v_lshl_add_u64 v[132:133], s[0:1], 0, v[128:129]
	global_load_dwordx4 v[128:131], v[132:133], off offset:16
	s_nop 0
	global_load_dwordx4 v[132:135], v[132:133], off
	s_waitcnt vmcnt(0)
	v_mov_b32_e32 v154, v133
	v_mov_b32_e32 v155, v134
	v_mov_b32_e32 v133, v135
	v_pk_add_f32 v[132:133], v[154:155], v[132:133]
	v_mov_b32_e32 v134, v130
	v_mov_b32_e32 v135, v128
	v_mov_b32_e32 v128, v131
	v_pk_add_f32 v[128:129], v[134:135], v[128:129]
	v_add_f32_e32 v130, v132, v133
	v_add_f32_e32 v129, v130, v129
	v_add_f32_e32 v128, v128, v129
	v_fmamk_f32 v128, v128, 0x3a000000, v199
	v_cmp_gt_f32_e32 vcc, s9, v128
	v_mul_f32_e32 v129, 0x4b800000, v128
	v_lshlrev_b64 v[134:135], 7, v[152:153]
	v_cndmask_b32_e32 v128, v128, v129, vcc
	v_rsq_f32_e32 v128, v128
	v_lshl_add_u64 v[134:135], v[144:145], 0, v[134:135]
	v_add_u32_e32 v152, 0x80, v150
	v_ashrrev_i32_e32 v153, 31, v152
	v_mul_f32_e32 v129, 0x45800000, v128
	v_cndmask_b32_e32 v132, v128, v129, vcc
	v_pk_mul_f32 v[130:131], v[78:79], v[132:133] op_sel_hi:[1,0]
	v_pk_mul_f32 v[128:129], v[76:77], v[132:133] op_sel_hi:[1,0]
	global_store_dwordx4 v[134:135], v[128:131], off
	s_nop 1
	v_pk_mul_f32 v[130:131], v[74:75], v[132:133] op_sel_hi:[1,0]
	v_pk_mul_f32 v[128:129], v[72:73], v[132:133] op_sel_hi:[1,0]
	global_store_dwordx4 v[134:135], v[128:131], off offset:16
	s_nop 1
	v_lshlrev_b64 v[128:129], 5, v[152:153]
	v_lshl_add_u64 v[132:133], s[0:1], 0, v[128:129]
	global_load_dwordx4 v[128:131], v[132:133], off offset:16
	s_nop 0
	global_load_dwordx4 v[132:135], v[132:133], off
	s_waitcnt vmcnt(0)
	v_mov_b32_e32 v154, v133
	v_mov_b32_e32 v155, v134
	v_mov_b32_e32 v133, v135
	v_pk_add_f32 v[132:133], v[154:155], v[132:133]
	v_mov_b32_e32 v134, v130
	v_mov_b32_e32 v135, v128
	v_mov_b32_e32 v128, v131
	v_pk_add_f32 v[128:129], v[134:135], v[128:129]
	v_add_f32_e32 v130, v132, v133
	v_add_f32_e32 v129, v130, v129
	v_add_f32_e32 v128, v128, v129
	v_fmamk_f32 v128, v128, 0x3a000000, v199
	v_cmp_gt_f32_e32 vcc, s9, v128
	v_mul_f32_e32 v129, 0x4b800000, v128
	v_lshlrev_b64 v[134:135], 7, v[152:153]
	v_cndmask_b32_e32 v128, v128, v129, vcc
	v_rsq_f32_e32 v128, v128
	v_lshl_add_u64 v[134:135], v[144:145], 0, v[134:135]
	v_add_u32_e32 v152, 0x90, v150
	v_ashrrev_i32_e32 v153, 31, v152
	v_mul_f32_e32 v129, 0x45800000, v128
	v_cndmask_b32_e32 v132, v128, v129, vcc
	v_pk_mul_f32 v[130:131], v[62:63], v[132:133] op_sel_hi:[1,0]
	v_pk_mul_f32 v[128:129], v[60:61], v[132:133] op_sel_hi:[1,0]
	global_store_dwordx4 v[134:135], v[128:131], off
	s_nop 1
	v_pk_mul_f32 v[130:131], v[58:59], v[132:133] op_sel_hi:[1,0]
	v_pk_mul_f32 v[128:129], v[56:57], v[132:133] op_sel_hi:[1,0]
	global_store_dwordx4 v[134:135], v[128:131], off offset:16
	s_nop 1
	v_lshlrev_b64 v[128:129], 5, v[152:153]
	v_lshl_add_u64 v[132:133], s[0:1], 0, v[128:129]
	global_load_dwordx4 v[128:131], v[132:133], off offset:16
	s_nop 0
	global_load_dwordx4 v[132:135], v[132:133], off
	s_waitcnt vmcnt(0)
;     DEV void operator()(AccRef acc, const pg8::Unit& u, int wr, int wc, int fr, int fq) const {
;     ...
;                 for (int m = 0; m < 4; ++m) { const float rs = rowscale(ss, row0 + ai * 128 + m * 16);
; #pragma unroll
;                     for (int n = 0; n < 2; ++n) *(f32x4*)(DTR + (size_t)(row0 + ai * 128 + m * 16) * 32 + 8 * fq + 4 * n) = acc[ai][0][m][n] * rs; }
	v_mov_b32_e32 v154, v133
	v_mov_b32_e32 v155, v134
	v_mov_b32_e32 v133, v135
	v_pk_add_f32 v[132:133], v[154:155], v[132:133]
	v_mov_b32_e32 v134, v130
	v_mov_b32_e32 v135, v128
	v_mov_b32_e32 v128, v131
	v_pk_add_f32 v[128:129], v[134:135], v[128:129]
	v_add_f32_e32 v130, v132, v133
	v_add_f32_e32 v129, v130, v129
	v_add_f32_e32 v128, v128, v129
	v_fmamk_f32 v128, v128, 0x3a000000, v199
	v_cmp_gt_f32_e32 vcc, s9, v128
	v_mul_f32_e32 v129, 0x4b800000, v128
	v_lshlrev_b64 v[134:135], 7, v[152:153]
	v_cndmask_b32_e32 v128, v128, v129, vcc
	v_rsq_f32_e32 v128, v128
	v_lshl_add_u64 v[134:135], v[144:145], 0, v[134:135]
	v_add_u32_e32 v152, 0xa0, v150
	v_ashrrev_i32_e32 v153, 31, v152
	v_mul_f32_e32 v129, 0x45800000, v128
	v_cndmask_b32_e32 v132, v128, v129, vcc
	v_pk_mul_f32 v[130:131], v[46:47], v[132:133] op_sel_hi:[1,0]
	v_pk_mul_f32 v[128:129], v[44:45], v[132:133] op_sel_hi:[1,0]
	global_store_dwordx4 v[134:135], v[128:131], off
	s_nop 1
	v_pk_mul_f32 v[130:131], v[42:43], v[132:133] op_sel_hi:[1,0]
	v_pk_mul_f32 v[128:129], v[40:41], v[132:133] op_sel_hi:[1,0]
	global_store_dwordx4 v[134:135], v[128:131], off offset:16
	s_nop 1
	v_lshlrev_b64 v[128:129], 5, v[152:153]
	v_lshl_add_u64 v[132:133], s[0:1], 0, v[128:129]
	global_load_dwordx4 v[128:131], v[132:133], off offset:16
	s_nop 0
	global_load_dwordx4 v[132:135], v[132:133], off
	s_waitcnt vmcnt(0)
	v_mov_b32_e32 v154, v133
	v_mov_b32_e32 v155, v134
	v_mov_b32_e32 v133, v135
	v_pk_add_f32 v[132:133], v[154:155], v[132:133]
	v_mov_b32_e32 v134, v130
	v_mov_b32_e32 v135, v128
	v_mov_b32_e32 v128, v131
	v_pk_add_f32 v[128:129], v[134:135], v[128:129]
	v_add_f32_e32 v130, v132, v133
	v_add_f32_e32 v129, v130, v129
	v_add_f32_e32 v128, v128, v129
	v_fmamk_f32 v128, v128, 0x3a000000, v199
	v_cmp_gt_f32_e32 vcc, s9, v128
	v_mul_f32_e32 v129, 0x4b800000, v128
	v_lshlrev_b64 v[134:135], 7, v[152:153]
	v_cndmask_b32_e32 v128, v128, v129, vcc
	v_rsq_f32_e32 v128, v128
	v_lshl_add_u64 v[134:135], v[144:145], 0, v[134:135]
	v_add_u32_e32 v152, 0xb0, v150
	v_ashrrev_i32_e32 v153, 31, v152
	v_mul_f32_e32 v129, 0x45800000, v128
	v_cndmask_b32_e32 v132, v128, v129, vcc
	v_pk_mul_f32 v[130:131], v[30:31], v[132:133] op_sel_hi:[1,0]
	v_pk_mul_f32 v[128:129], v[28:29], v[132:133] op_sel_hi:[1,0]
	global_store_dwordx4 v[134:135], v[128:131], off
	s_nop 1
	v_pk_mul_f32 v[130:131], v[26:27], v[132:133] op_sel_hi:[1,0]
	v_pk_mul_f32 v[128:129], v[24:25], v[132:133] op_sel_hi:[1,0]
	global_store_dwordx4 v[134:135], v[128:131], off offset:16
	s_nop 1
	v_lshlrev_b64 v[128:129], 5, v[152:153]
	v_lshl_add_u64 v[132:133], s[0:1], 0, v[128:129]
	global_load_dwordx4 v[128:131], v[132:133], off offset:16
	s_nop 0
	global_load_dwordx4 v[132:135], v[132:133], off
	s_waitcnt vmcnt(0)
	v_mov_b32_e32 v154, v133
	v_mov_b32_e32 v155, v134
	v_mov_b32_e32 v133, v135
	v_pk_add_f32 v[132:133], v[154:155], v[132:133]
	v_mov_b32_e32 v134, v130
	v_mov_b32_e32 v135, v128
	v_mov_b32_e32 v128, v131
	v_pk_add_f32 v[128:129], v[134:135], v[128:129]
	v_add_f32_e32 v130, v132, v133
	v_add_f32_e32 v129, v130, v129
	v_add_f32_e32 v128, v128, v129
	v_fmamk_f32 v128, v128, 0x3a000000, v199
	v_cmp_gt_f32_e32 vcc, s9, v128
	v_mul_f32_e32 v129, 0x4b800000, v128
	v_lshlrev_b64 v[134:135], 7, v[152:153]
	v_cndmask_b32_e32 v128, v128, v129, vcc
	v_rsq_f32_e32 v128, v128
	v_lshl_add_u64 v[134:135], v[144:145], 0, v[134:135]
	v_mul_f32_e32 v129, 0x45800000, v128
	v_cndmask_b32_e32 v132, v128, v129, vcc
	v_pk_mul_f32 v[130:131], v[14:15], v[132:133] op_sel_hi:[1,0]
	v_pk_mul_f32 v[128:129], v[12:13], v[132:133] op_sel_hi:[1,0]
	global_store_dwordx4 v[134:135], v[128:131], off
	s_nop 1
	v_pk_mul_f32 v[130:131], v[10:11], v[132:133] op_sel_hi:[1,0]
	v_pk_mul_f32 v[128:129], v[8:9], v[132:133] op_sel_hi:[1,0]
	global_store_dwordx4 v[134:135], v[128:131], off offset:16

; #define PG8_STAGE(bufoff, gbase, voff) do { _Pragma("unroll") for (int _i = 0; _i < 2; ++_i) \
;         __builtin_amdgcn_global_load_lds((const unsigned*)((const char*)(gbase) + (voff)[_i]), (LAS unsigned*)(lds + (bufoff) + ldsw + _i * 8192), 16, 0, 0); } while (0)
; #define PG8_LDA(dst, b, h) do { _Pragma("unroll") for (int m = 0; m < 4; ++m) _Pragma("unroll") for (int k = 0; k < 2; ++k) dst[m][k] = *(const LAS bf16x8*)(lds + PG8_SA(b, h) + aoff + m * 2048 + k * 1024); } while (0)
; #define PG8_LDB(dst, b, h) do { _Pragma("unroll") for (int n = 0; n < 2; ++n) _Pragma("unroll") for (int k = 0; k < 2; ++k) dst[n][k] = *(const LAS bf16x8*)(lds + PG8_SB(b, h) + boff + n * 2048 + k * 1024); } while (0)
; #define PG8_MMA(ai, bj, At, Bt) do { __builtin_amdgcn_s_setprio(1); _Pragma("unroll") for (int m = 0; m < 4; ++m) _Pragma("unroll") for (int n = 0; n < 2; ++n) _Pragma("unroll") for (int k = 0; k < 2; ++k) \
;         acc[ai][bj][m][n] = __builtin_amdgcn_mfma_f32_16x16x32_bf16(Bt[n][k], At[m][k], acc[ai][bj][m][n], 0, 0, 0); __builtin_amdgcn_s_setprio(0); } while (0)
; #define PG8_WAIT_V(n) asm volatile("s_waitcnt vmcnt(" #n ")" ::: "memory")
; #define PG8_WAIT_L(n) asm volatile("s_waitcnt lgkmcnt(" #n ")" ::: "memory")
; #define PG8_BAR __builtin_amdgcn_s_barrier()
; template <class Epi>
; DEV void gemm_phase(LAS unsigned char* lds, const Gemm g, const StaticOrder& S, const Epi& E) {
;     ...
;         for (int t = 0; t < nt; t += 2) {
;             const bool last = (t == nt - 2);
;             const char* a1 = cA + (size_t)(t + 1) * kstep;
;             const char* a2 = last ? nA : cA + (size_t)(t + 2) * kstep; const char* b2 = last ? nB : cB + (size_t)(t + 2) * kstep;
;             const char* a3 = a2 + kstep; const char* b3 = b2 + kstep;
;             PG8_LDB(B0, 0, 0); PG8_SCHED; PG8_LDA(At, 0, 0); PG8_STAGE(PG8_SA(1, 1), a1 + hstep, voffA);
;             PG8_WAIT_L(8); PG8_BAR; PG8_WAIT_L(0); PG8_MMA(0, 0, At, B0); PG8_BAR; PG8_SCHED;
;             PG8_LDB(B1, 0, 1); PG8_STAGE(PG8_SB(0, 0), b2, voffB);
;             PG8_BAR; PG8_WAIT_L(0); PG8_MMA(0, 1, At, B1); PG8_BAR;
;             PG8_LDA(At, 0, 1); PG8_STAGE(PG8_SA(0, 0), a2, voffA);
;             PG8_BAR; PG8_WAIT_L(0); PG8_MMA(1, 0, At, B0); PG8_BAR; PG8_SCHED;
;             PG8_STAGE(PG8_SB(0, 1), b2 + hstep, voffB);
;             PG8_WAIT_V(6); PG8_BAR; PG8_MMA(1, 1, At, B1); PG8_BAR;
.LBB0_657:
	s_add_u32 s6, s28, 0x100
	s_addc_u32 s7, s29, 0
	s_add_i32 s55, 0, 0x10000
	v_add_u32_e32 v140, s55, v196
	ds_read_b128 v[128:131], v140
	ds_read_b128 v[132:135], v140 offset:1024
	ds_read_b128 v[136:139], v140 offset:2048
	ds_read_b128 v[140:143], v140 offset:3072
	s_cmpk_eq_i32 s54, 0x54
	s_cselect_b32 s35, s27, s7
	s_cselect_b32 s34, s26, s6
	s_cselect_b32 s31, s9, s53
	s_cselect_b32 s30, s8, s52
	s_add_i32 m0, s41, 0xc000
	ds_read_b128 v[144:147], v219
	ds_read_b128 v[148:151], v219 offset:1024
	ds_read_b128 v[152:155], v219 offset:2048
	ds_read_b128 v[156:159], v219 offset:3072
	ds_read_b128 v[184:187], v219 offset:4096
	ds_read_b128 v[188:191], v219 offset:5120
	ds_read_b128 v[192:195], v219 offset:6144
	ds_read_b128 v[220:223], v219 offset:7168
	global_load_lds_dwordx4 v180, s[28:29]
	s_add_i32 m0, s41, 0xe000
	s_nop 0
	global_load_lds_dwordx4 v182, s[28:29]
	s_waitcnt lgkmcnt(8)
	s_barrier
	s_waitcnt lgkmcnt(0)
	v_mfma_f32_16x16x32_bf16 v[124:127], v[128:131], v[144:147], v[124:127]
	v_mfma_f32_16x16x32_bf16 v[120:123], v[136:139], v[144:147], v[120:123]
	v_mfma_f32_16x16x32_bf16 v[112:115], v[128:131], v[152:155], v[112:115]
	v_mfma_f32_16x16x32_bf16 v[104:107], v[136:139], v[152:155], v[104:107]
	v_mfma_f32_16x16x32_bf16 v[92:95], v[128:131], v[184:187], v[92:95]
	v_mfma_f32_16x16x32_bf16 v[88:91], v[136:139], v[184:187], v[88:91]
	v_mfma_f32_16x16x32_bf16 v[80:83], v[128:131], v[192:195], v[80:83]
	v_mfma_f32_16x16x32_bf16 v[72:75], v[136:139], v[192:195], v[72:75]
	v_mfma_f32_16x16x32_bf16 v[124:127], v[132:135], v[148:151], v[124:127]
	v_mfma_f32_16x16x32_bf16 v[120:123], v[140:143], v[148:151], v[120:123]
	v_mfma_f32_16x16x32_bf16 v[112:115], v[132:135], v[156:159], v[112:115]
	v_mfma_f32_16x16x32_bf16 v[104:107], v[140:143], v[156:159], v[104:107]
	v_mfma_f32_16x16x32_bf16 v[92:95], v[132:135], v[188:191], v[92:95]
	v_mfma_f32_16x16x32_bf16 v[88:91], v[140:143], v[188:191], v[88:91]
	v_mfma_f32_16x16x32_bf16 v[80:83], v[132:135], v[220:223], v[80:83]
	v_mfma_f32_16x16x32_bf16 v[72:75], v[140:143], v[220:223], v[72:75]
	s_barrier
	s_add_i32 s56, 0, 0x14000
	v_add_u32_e32 v214, s56, v196
	s_add_i32 s28, s55, s40
	ds_read_b128 v[224:227], v214
	ds_read_b128 v[228:231], v214 offset:1024
	ds_read_b128 v[232:235], v214 offset:2048
	ds_read_b128 v[236:239], v214 offset:3072
	v_lshl_add_u64 v[214:215], s[30:31], 0, v[160:161]
	s_mov_b32 m0, s28
	v_lshl_add_u64 v[216:217], s[30:31], 0, v[178:179]
	global_load_lds_dwordx4 v160, s[30:31]
	s_add_i32 m0, s28, 0x2000
	s_nop 0
	global_load_lds_dwordx4 v178, s[30:31]
	s_barrier
	s_waitcnt lgkmcnt(0)
	v_mfma_f32_16x16x32_bf16 v[116:119], v[224:227], v[144:147], v[116:119]
	v_mfma_f32_16x16x32_bf16 v[108:111], v[232:235], v[144:147], v[108:111]
	v_mfma_f32_16x16x32_bf16 v[100:103], v[224:227], v[152:155], v[100:103]
	v_mfma_f32_16x16x32_bf16 v[96:99], v[232:235], v[152:155], v[96:99]
	v_mfma_f32_16x16x32_bf16 v[84:87], v[224:227], v[184:187], v[84:87]
	v_mfma_f32_16x16x32_bf16 v[76:79], v[232:235], v[184:187], v[76:79]
	v_mfma_f32_16x16x32_bf16 v[68:71], v[224:227], v[192:195], v[68:71]
	v_mfma_f32_16x16x32_bf16 v[64:67], v[232:235], v[192:195], v[64:67]
	v_mfma_f32_16x16x32_bf16 v[116:119], v[228:231], v[148:151], v[116:119]
	v_mfma_f32_16x16x32_bf16 v[108:111], v[236:239], v[148:151], v[108:111]
	v_mfma_f32_16x16x32_bf16 v[100:103], v[228:231], v[156:159], v[100:103]
	v_mfma_f32_16x16x32_bf16 v[96:99], v[236:239], v[156:159], v[96:99]
	v_mfma_f32_16x16x32_bf16 v[84:87], v[228:231], v[188:191], v[84:87]
	v_mfma_f32_16x16x32_bf16 v[76:79], v[236:239], v[188:191], v[76:79]
	v_mfma_f32_16x16x32_bf16 v[68:71], v[228:231], v[220:223], v[68:71]
	v_mfma_f32_16x16x32_bf16 v[64:67], v[236:239], v[220:223], v[64:67]
	s_mov_b32 m0, s41
	v_lshl_add_u64 v[240:241], s[34:35], 0, v[174:175]
	s_barrier
	ds_read_b128 v[144:147], v219 offset:16384
	ds_read_b128 v[148:151], v219 offset:17408
	ds_read_b128 v[152:155], v219 offset:18432
	ds_read_b128 v[156:159], v219 offset:19456
	ds_read_b128 v[184:187], v219 offset:20480
	ds_read_b128 v[188:191], v219 offset:21504
	ds_read_b128 v[192:195], v219 offset:22528
	ds_read_b128 v[220:223], v219 offset:23552
	global_load_lds_dwordx4 v174, s[34:35]
	v_lshl_add_u64 v[242:243], s[34:35], 0, v[176:177]
	s_mov_b32 m0, s42
	s_nop 0
	global_load_lds_dwordx4 v176, s[34:35]
	s_barrier
	s_waitcnt lgkmcnt(0)
	v_mfma_f32_16x16x32_bf16 v[60:63], v[128:131], v[144:147], v[60:63]
	v_mfma_f32_16x16x32_bf16 v[56:59], v[136:139], v[144:147], v[56:59]
	v_mfma_f32_16x16x32_bf16 v[48:51], v[128:131], v[152:155], v[48:51]
	v_mfma_f32_16x16x32_bf16 v[40:43], v[136:139], v[152:155], v[40:43]
	v_mfma_f32_16x16x32_bf16 v[28:31], v[128:131], v[184:187], v[28:31]
	v_mfma_f32_16x16x32_bf16 v[24:27], v[136:139], v[184:187], v[24:27]
	v_mfma_f32_16x16x32_bf16 v[16:19], v[128:131], v[192:195], v[16:19]
	v_mfma_f32_16x16x32_bf16 v[8:11], v[136:139], v[192:195], v[8:11]
	v_mfma_f32_16x16x32_bf16 v[60:63], v[132:135], v[148:151], v[60:63]
	v_mfma_f32_16x16x32_bf16 v[56:59], v[140:143], v[148:151], v[56:59]
	v_mfma_f32_16x16x32_bf16 v[48:51], v[132:135], v[156:159], v[48:51]
	v_mfma_f32_16x16x32_bf16 v[40:43], v[140:143], v[156:159], v[40:43]
	v_mfma_f32_16x16x32_bf16 v[28:31], v[132:135], v[188:191], v[28:31]
	v_mfma_f32_16x16x32_bf16 v[24:27], v[140:143], v[188:191], v[24:27]
	v_mfma_f32_16x16x32_bf16 v[16:19], v[132:135], v[220:223], v[16:19]
	v_mfma_f32_16x16x32_bf16 v[8:11], v[140:143], v[220:223], v[8:11]
	s_barrier
	s_add_u32 s28, s30, 0x160000
	s_addc_u32 s29, s31, 0
	s_add_i32 s55, s56, s40
	s_mov_b32 m0, s55
	s_nop 0
	global_load_lds_dwordx4 v160, s[28:29]
	s_add_i32 m0, s55, 0x2000
	s_nop 0
	global_load_lds_dwordx4 v178, s[28:29]
	s_waitcnt vmcnt(6)
	s_barrier
; #define PG8_STAGE(bufoff, gbase, voff) do { _Pragma("unroll") for (int _i = 0; _i < 2; ++_i) \
;         __builtin_amdgcn_global_load_lds((const unsigned*)((const char*)(gbase) + (voff)[_i]), (LAS unsigned*)(lds + (bufoff) + ldsw + _i * 8192), 16, 0, 0); } while (0)
; #define PG8_LDA(dst, b, h) do { _Pragma("unroll") for (int m = 0; m < 4; ++m) _Pragma("unroll") for (int k = 0; k < 2; ++k) dst[m][k] = *(const LAS bf16x8*)(lds + PG8_SA(b, h) + aoff + m * 2048 + k * 1024); } while (0)
; #define PG8_LDB(dst, b, h) do { _Pragma("unroll") for (int n = 0; n < 2; ++n) _Pragma("unroll") for (int k = 0; k < 2; ++k) dst[n][k] = *(const LAS bf16x8*)(lds + PG8_SB(b, h) + boff + n * 2048 + k * 1024); } while (0)
; #define PG8_MMA(ai, bj, At, Bt) do { __builtin_amdgcn_s_setprio(1); _Pragma("unroll") for (int m = 0; m < 4; ++m) _Pragma("unroll") for (int n = 0; n < 2; ++n) _Pragma("unroll") for (int k = 0; k < 2; ++k) \
;         acc[ai][bj][m][n] = __builtin_amdgcn_mfma_f32_16x16x32_bf16(Bt[n][k], At[m][k], acc[ai][bj][m][n], 0, 0, 0); __builtin_amdgcn_s_setprio(0); } while (0)
; #define PG8_WAIT_V(n) asm volatile("s_waitcnt vmcnt(" #n ")" ::: "memory")
; #define PG8_WAIT_L(n) asm volatile("s_waitcnt lgkmcnt(" #n ")" ::: "memory")
; #define PG8_BAR __builtin_amdgcn_s_barrier()
; #define PG8_SCHED __builtin_amdgcn_sched_barrier(0)
; template <class Epi>
; DEV void gemm_phase(LAS unsigned char* lds, const Gemm g, const StaticOrder& S, const Epi& E) {
;     ...
;             PG8_WAIT_V(6); PG8_BAR; PG8_MMA(1, 1, At, B1); PG8_BAR;
;             PG8_LDB(B0, 1, 0); PG8_SCHED; PG8_LDA(At, 1, 0); PG8_STAGE(PG8_SA(0, 1), a2 + hstep, voffA);
;             PG8_WAIT_L(8); PG8_BAR; PG8_WAIT_L(0); PG8_MMA(0, 0, At, B0); PG8_BAR; PG8_SCHED;
;             PG8_LDB(B1, 1, 1); PG8_STAGE(PG8_SB(1, 0), b3, voffB);
;             PG8_BAR; PG8_WAIT_L(0); PG8_MMA(0, 1, At, B1); PG8_BAR;
;             PG8_LDA(At, 1, 1); PG8_STAGE(PG8_SA(1, 0), a3, voffA);
;             PG8_BAR; PG8_WAIT_L(0); PG8_MMA(1, 0, At, B0); PG8_BAR; PG8_SCHED;
;             PG8_STAGE(PG8_SB(1, 1), b3 + hstep, voffB);
;             PG8_WAIT_V(6); PG8_BAR; PG8_MMA(1, 1, At, B1); PG8_BAR;
	v_mfma_f32_16x16x32_bf16 v[52:55], v[224:227], v[144:147], v[52:55]
	v_mfma_f32_16x16x32_bf16 v[44:47], v[232:235], v[144:147], v[44:47]
	v_mfma_f32_16x16x32_bf16 v[36:39], v[224:227], v[152:155], v[36:39]
	v_mfma_f32_16x16x32_bf16 v[32:35], v[232:235], v[152:155], v[32:35]
	v_mfma_f32_16x16x32_bf16 v[20:23], v[224:227], v[184:187], v[20:23]
	v_mfma_f32_16x16x32_bf16 v[12:15], v[232:235], v[184:187], v[12:15]
	v_mfma_f32_16x16x32_bf16 v[4:7], v[224:227], v[192:195], v[4:7]
	v_mfma_f32_16x16x32_bf16 v[0:3], v[232:235], v[192:195], v[0:3]
	v_mfma_f32_16x16x32_bf16 v[52:55], v[228:231], v[148:151], v[52:55]
	v_mfma_f32_16x16x32_bf16 v[44:47], v[236:239], v[148:151], v[44:47]
	v_mfma_f32_16x16x32_bf16 v[36:39], v[228:231], v[156:159], v[36:39]
	v_mfma_f32_16x16x32_bf16 v[32:35], v[236:239], v[156:159], v[32:35]
	v_mfma_f32_16x16x32_bf16 v[20:23], v[228:231], v[188:191], v[20:23]
	v_mfma_f32_16x16x32_bf16 v[12:15], v[236:239], v[188:191], v[12:15]
	v_mfma_f32_16x16x32_bf16 v[4:7], v[228:231], v[220:223], v[4:7]
	v_mfma_f32_16x16x32_bf16 v[0:3], v[236:239], v[220:223], v[0:3]
	s_add_i32 s55, 0, 0x18000
	v_add_u32_e32 v140, s55, v196
	s_barrier
	ds_read_b128 v[128:131], v140
	ds_read_b128 v[132:135], v140 offset:1024
	ds_read_b128 v[136:139], v140 offset:2048
	ds_read_b128 v[140:143], v140 offset:3072
	s_add_u32 s28, s34, 0x160000
	s_addc_u32 s29, s35, 0
	s_mov_b32 m0, s43
	ds_read_b128 v[144:147], v219 offset:32768
	ds_read_b128 v[148:151], v219 offset:33792
	ds_read_b128 v[152:155], v219 offset:34816
	ds_read_b128 v[156:159], v219 offset:35840
	ds_read_b128 v[184:187], v219 offset:36864
	ds_read_b128 v[188:191], v219 offset:37888
	ds_read_b128 v[192:195], v219 offset:38912
	ds_read_b128 v[220:223], v219 offset:39936
	global_load_lds_dwordx4 v174, s[28:29]
	s_mov_b32 m0, s44
	s_nop 0
	global_load_lds_dwordx4 v176, s[28:29]
	s_waitcnt lgkmcnt(8)
	s_barrier
	s_waitcnt lgkmcnt(0)
	v_mfma_f32_16x16x32_bf16 v[124:127], v[128:131], v[144:147], v[124:127]
	v_mfma_f32_16x16x32_bf16 v[120:123], v[136:139], v[144:147], v[120:123]
	v_mfma_f32_16x16x32_bf16 v[112:115], v[128:131], v[152:155], v[112:115]
	v_mfma_f32_16x16x32_bf16 v[104:107], v[136:139], v[152:155], v[104:107]
	v_mfma_f32_16x16x32_bf16 v[92:95], v[128:131], v[184:187], v[92:95]
	v_mfma_f32_16x16x32_bf16 v[88:91], v[136:139], v[184:187], v[88:91]
	v_mfma_f32_16x16x32_bf16 v[80:83], v[128:131], v[192:195], v[80:83]
	v_mfma_f32_16x16x32_bf16 v[72:75], v[136:139], v[192:195], v[72:75]
	v_mfma_f32_16x16x32_bf16 v[124:127], v[132:135], v[148:151], v[124:127]
	v_mfma_f32_16x16x32_bf16 v[120:123], v[140:143], v[148:151], v[120:123]
	v_mfma_f32_16x16x32_bf16 v[112:115], v[132:135], v[156:159], v[112:115]
	v_mfma_f32_16x16x32_bf16 v[104:107], v[140:143], v[156:159], v[104:107]
	v_mfma_f32_16x16x32_bf16 v[92:95], v[132:135], v[188:191], v[92:95]
	v_mfma_f32_16x16x32_bf16 v[88:91], v[140:143], v[188:191], v[88:91]
	v_mfma_f32_16x16x32_bf16 v[80:83], v[132:135], v[220:223], v[80:83]
	v_mfma_f32_16x16x32_bf16 v[72:75], v[140:143], v[220:223], v[72:75]
	s_barrier
	s_add_i32 s34, 0, 0x1c000
	s_add_i32 s28, s55, s40
	v_add_u32_e32 v236, s34, v196
	v_lshl_add_u64 v[214:215], v[214:215], 0, s[2:3]
	s_mov_b32 m0, s28
	ds_read_b128 v[224:227], v236
	ds_read_b128 v[228:231], v236 offset:1024
	ds_read_b128 v[232:235], v236 offset:2048
	ds_read_b128 v[236:239], v236 offset:3072
	global_load_lds_dwordx4 v[214:215], off
	v_lshl_add_u64 v[214:215], v[216:217], 0, s[2:3]
	s_add_i32 m0, s28, 0x2000
	s_nop 0
	global_load_lds_dwordx4 v[214:215], off
	s_barrier
	s_waitcnt lgkmcnt(0)
	v_mfma_f32_16x16x32_bf16 v[116:119], v[224:227], v[144:147], v[116:119]
	v_mfma_f32_16x16x32_bf16 v[108:111], v[232:235], v[144:147], v[108:111]
	v_mfma_f32_16x16x32_bf16 v[100:103], v[224:227], v[152:155], v[100:103]
	v_mfma_f32_16x16x32_bf16 v[96:99], v[232:235], v[152:155], v[96:99]
	v_mfma_f32_16x16x32_bf16 v[84:87], v[224:227], v[184:187], v[84:87]
	v_mfma_f32_16x16x32_bf16 v[76:79], v[232:235], v[184:187], v[76:79]
	v_mfma_f32_16x16x32_bf16 v[68:71], v[224:227], v[192:195], v[68:71]
	v_mfma_f32_16x16x32_bf16 v[64:67], v[232:235], v[192:195], v[64:67]
	v_mfma_f32_16x16x32_bf16 v[116:119], v[228:231], v[148:151], v[116:119]
	v_mfma_f32_16x16x32_bf16 v[108:111], v[236:239], v[148:151], v[108:111]
	v_mfma_f32_16x16x32_bf16 v[100:103], v[228:231], v[156:159], v[100:103]
	v_mfma_f32_16x16x32_bf16 v[96:99], v[236:239], v[156:159], v[96:99]
	v_mfma_f32_16x16x32_bf16 v[84:87], v[228:231], v[188:191], v[84:87]
	v_mfma_f32_16x16x32_bf16 v[76:79], v[236:239], v[188:191], v[76:79]
	v_mfma_f32_16x16x32_bf16 v[68:71], v[228:231], v[220:223], v[68:71]
	v_mfma_f32_16x16x32_bf16 v[64:67], v[236:239], v[220:223], v[64:67]
	s_mov_b32 m0, s45
	v_lshl_add_u64 v[214:215], v[240:241], 0, s[2:3]
	s_barrier
	ds_read_b128 v[144:147], v219 offset:49152
	ds_read_b128 v[148:151], v219 offset:50176
	ds_read_b128 v[152:155], v219 offset:51200
	ds_read_b128 v[156:159], v219 offset:52224
	ds_read_b128 v[184:187], v219 offset:53248
	ds_read_b128 v[188:191], v219 offset:54272
	ds_read_b128 v[192:195], v219 offset:55296
	ds_read_b128 v[220:223], v219 offset:56320
	global_load_lds_dwordx4 v[214:215], off
	v_lshl_add_u64 v[214:215], v[242:243], 0, s[2:3]
	s_mov_b32 m0, s46
	s_nop 0
	global_load_lds_dwordx4 v[214:215], off
	s_barrier
; DEV bf16x8 pack8(f32x4 a, f32x4 b) { u32x4 w; w.x = cvt_pk_bf16(a[0], a[1]); w.y = cvt_pk_bf16(a[2], a[3]); w.z = cvt_pk_bf16(b[0], b[1]); w.w = cvt_pk_bf16(b[2], b[3]); return __builtin_bit_cast(bf16x8, w); }
; #define PG8_STAGE(bufoff, gbase, voff) do { _Pragma("unroll") for (int _i = 0; _i < 2; ++_i) \
;         __builtin_amdgcn_global_load_lds((const unsigned*)((const char*)(gbase) + (voff)[_i]), (LAS unsigned*)(lds + (bufoff) + ldsw + _i * 8192), 16, 0, 0); } while (0)
; #define PG8_BAR __builtin_amdgcn_s_barrier()
; template <class Epi>
; DEV void gemm_phase(LAS unsigned char* lds, const Gemm g, const StaticOrder& S, const Epi& E) {
;     ...
;             PG8_STAGE(PG8_SB(1, 1), b3 + hstep, voffB);
;             PG8_WAIT_V(6); PG8_BAR; PG8_MMA(1, 1, At, B1); PG8_BAR;
;         }
;     DEV void operator()(AccRef acc, const pg8::Unit& u, int wr, int wc, int fr, int fq) const {
;         const int row0 = u.pm * 256 + wr * 64 + fr, col0 = u.pn * 256 + wc * 32 + 8 * fq;
; #pragma unroll
;         for (int am = 0; am < 4; ++am) { const int ai = am >> 1, m0 = (am & 1) * 2;
;             f32x4 bv[4][2][2];
; #pragma unroll
;             for (int m = m0; m < m0 + 2; ++m)
; #pragma unroll
;                 for (int bj = 0; bj < 2; ++bj)
; #pragma unroll
;                     for (int n = 0; n < 2; ++n) bv[m][bj][n] = *(const f32x4*)(base + (size_t)(row0 + ai * 128 + m * 16) * 2048 + col0 + bj * 128 + n * 4);
; #pragma unroll
;             for (int m = m0; m < m0 + 2; ++m) { const size_t off = (size_t)(row0 + ai * 128 + m * 16) * 2048 + col0; float sq = 0.f;
; #pragma unroll
;                 for (int bj = 0; bj < 2; ++bj) { const f32x4 o0 = bv[m][bj][0] + scale * acc[ai][bj][m][0], o1 = bv[m][bj][1] + scale * acc[ai][bj][m][1];
;                     *(f32x4*)(out + off + bj * 128) = o0; *(f32x4*)(out + off + bj * 128 + 4) = o1;
;                     if (xb) { *(u32x4*)(xb + off + bj * 128) = __builtin_bit_cast(u32x4, pack8(o0, o1));
;                         sq += (o0[0] * o0[0] + o0[1] * o0[1] + o0[2] * o0[2] + o0[3] * o0[3]) + (o1[0] * o1[0] + o1[1] * o1[1] + o1[2] * o1[2] + o1[3] * o1[3]); } }
;                 if (ssout) { sq += __shfl_xor(sq, 16); sq += __shfl_xor(sq, 32);
;                     if (fq == 0) { if (red) red[(ai * 128 + wr * 64 + m * 16 + fr) * 4 + wc] = sq; else atomicAdd(ssout + (size_t)(row0 + ai * 128 + m * 16) * 8 + u.pn, sq); } } }
	s_waitcnt lgkmcnt(0)
	v_mfma_f32_16x16x32_bf16 v[60:63], v[128:131], v[144:147], v[60:63]
	v_mfma_f32_16x16x32_bf16 v[56:59], v[136:139], v[144:147], v[56:59]
	v_mfma_f32_16x16x32_bf16 v[48:51], v[128:131], v[152:155], v[48:51]
	v_mfma_f32_16x16x32_bf16 v[40:43], v[136:139], v[152:155], v[40:43]
	v_mfma_f32_16x16x32_bf16 v[28:31], v[128:131], v[184:187], v[28:31]
	v_mfma_f32_16x16x32_bf16 v[24:27], v[136:139], v[184:187], v[24:27]
	v_mfma_f32_16x16x32_bf16 v[16:19], v[128:131], v[192:195], v[16:19]
	v_mfma_f32_16x16x32_bf16 v[8:11], v[136:139], v[192:195], v[8:11]
	v_mfma_f32_16x16x32_bf16 v[60:63], v[132:135], v[148:151], v[60:63]
	v_mfma_f32_16x16x32_bf16 v[56:59], v[140:143], v[148:151], v[56:59]
	v_mfma_f32_16x16x32_bf16 v[48:51], v[132:135], v[156:159], v[48:51]
	v_mfma_f32_16x16x32_bf16 v[40:43], v[140:143], v[156:159], v[40:43]
	v_mfma_f32_16x16x32_bf16 v[28:31], v[132:135], v[188:191], v[28:31]
	v_mfma_f32_16x16x32_bf16 v[24:27], v[140:143], v[188:191], v[24:27]
	v_mfma_f32_16x16x32_bf16 v[16:19], v[132:135], v[220:223], v[16:19]
	v_mfma_f32_16x16x32_bf16 v[8:11], v[140:143], v[220:223], v[8:11]
	s_barrier
	s_add_u32 s28, s30, 0x160080
	s_addc_u32 s29, s31, 0
	s_add_i32 s30, s34, s40
	s_mov_b32 m0, s30
	s_nop 0
	global_load_lds_dwordx4 v160, s[28:29]
	s_add_i32 m0, s30, 0x2000
	s_nop 0
	global_load_lds_dwordx4 v178, s[28:29]
	s_waitcnt vmcnt(6)
	s_barrier
	v_mfma_f32_16x16x32_bf16 v[52:55], v[224:227], v[144:147], v[52:55]
	v_mfma_f32_16x16x32_bf16 v[44:47], v[232:235], v[144:147], v[44:47]
	v_mfma_f32_16x16x32_bf16 v[36:39], v[224:227], v[152:155], v[36:39]
	v_mfma_f32_16x16x32_bf16 v[32:35], v[232:235], v[152:155], v[32:35]
	v_mfma_f32_16x16x32_bf16 v[20:23], v[224:227], v[184:187], v[20:23]
	v_mfma_f32_16x16x32_bf16 v[12:15], v[232:235], v[184:187], v[12:15]
	v_mfma_f32_16x16x32_bf16 v[4:7], v[224:227], v[192:195], v[4:7]
	v_mfma_f32_16x16x32_bf16 v[0:3], v[232:235], v[192:195], v[0:3]
	v_mfma_f32_16x16x32_bf16 v[52:55], v[228:231], v[148:151], v[52:55]
	v_mfma_f32_16x16x32_bf16 v[44:47], v[236:239], v[148:151], v[44:47]
	v_mfma_f32_16x16x32_bf16 v[36:39], v[228:231], v[156:159], v[36:39]
	v_mfma_f32_16x16x32_bf16 v[32:35], v[236:239], v[156:159], v[32:35]
	v_mfma_f32_16x16x32_bf16 v[20:23], v[228:231], v[188:191], v[20:23]
	v_mfma_f32_16x16x32_bf16 v[12:15], v[236:239], v[188:191], v[12:15]
	v_mfma_f32_16x16x32_bf16 v[4:7], v[228:231], v[220:223], v[4:7]
	v_mfma_f32_16x16x32_bf16 v[0:3], v[236:239], v[220:223], v[0:3]
	s_add_i32 s54, s54, 2
	s_add_u32 s52, s52, 0x100
	s_addc_u32 s53, s53, 0
	s_cmpk_gt_u32 s54, 0x55
	s_mov_b64 s[28:29], s[6:7]
	s_barrier
	s_cbranch_scc0 .LBB0_657
	v_lshl_add_u32 v186, s23, 8, v167
	v_lshl_or_b32 v184, s22, 8, v197
	v_ashrrev_i32_e32 v185, 31, v184
	v_ashrrev_i32_e32 v187, 31, v186
	v_lshl_add_u64 v[188:189], v[184:185], 2, s[24:25]
	v_lshlrev_b64 v[128:129], 13, v[186:187]
	v_or_b32_e32 v190, 16, v186
	v_lshl_add_u64 v[128:129], v[188:189], 0, v[128:129]
	v_ashrrev_i32_e32 v191, 31, v190
	global_load_dwordx4 v[152:155], v[128:129], off offset:16
	global_load_dwordx4 v[156:159], v[128:129], off
	global_load_dwordx4 v[144:147], v[128:129], off offset:528
	global_load_dwordx4 v[148:151], v[128:129], off offset:512
	v_lshlrev_b64 v[128:129], 13, v[190:191]
	v_lshl_add_u64 v[132:133], v[188:189], 0, v[128:129]
	global_load_dwordx4 v[136:139], v[132:133], off offset:16
	global_load_dwordx4 v[140:143], v[132:133], off
	global_load_dwordx4 v[128:131], v[132:133], off offset:528
	s_nop 0
	global_load_dwordx4 v[132:135], v[132:133], off offset:512
	v_lshlrev_b64 v[192:193], 11, v[186:187]
	v_lshl_add_u64 v[194:195], v[192:193], 0, v[184:185]
	s_ashr_i32 s23, s22, 31
	v_lshl_add_u64 v[192:193], v[194:195], 2, s[68:69]
	s_mov_b64 s[28:29], -1
	s_andn2_b64 vcc, exec, s[18:19]
	s_waitcnt vmcnt(0)
	v_pk_fma_f32 v[152:153], v[120:121], 0.5, v[152:153] op_sel_hi:[1,0,1]
	v_cndmask_b32_e64 v120, 0, 1, s[18:19]
	v_pk_fma_f32 v[158:159], v[126:127], 0.5, v[158:159] op_sel_hi:[1,0,1]
	v_pk_fma_f32 v[156:157], v[124:125], 0.5, v[156:157] op_sel_hi:[1,0,1]
	v_pk_fma_f32 v[154:155], v[122:123], 0.5, v[154:155] op_sel_hi:[1,0,1]
	v_cmp_ne_u32_e64 s[6:7], 1, v120
	v_pk_fma_f32 v[120:121], v[116:117], 0.5, v[148:149] op_sel_hi:[1,0,1]
	v_pk_fma_f32 v[124:125], v[108:109], 0.5, v[144:145] op_sel_hi:[1,0,1]
	global_store_dwordx4 v[192:193], v[156:159], off
	global_store_dwordx4 v[192:193], v[152:155], off offset:16
	s_cbranch_vccnz .LBB0_665
	v_mul_f32_e32 v108, v157, v157
	v_mul_f32_e32 v109, v153, v153
	v_fmac_f32_e32 v108, v156, v156
	v_fmac_f32_e32 v109, v152, v152
	v_fmac_f32_e32 v108, v158, v158
	v_fmac_f32_e32 v109, v154, v154
	v_fmac_f32_e32 v108, v159, v159
	v_fmac_f32_e32 v109, v155, v155
	v_add_f32_e32 v108, v108, v109
	v_mul_f32_e32 v109, v121, v121
	v_mul_f32_e32 v144, v125, v125
	v_pk_fma_f32 v[122:123], v[118:119], 0.5, v[150:151] op_sel_hi:[1,0,1]
	v_pk_fma_f32 v[126:127], v[110:111], 0.5, v[146:147] op_sel_hi:[1,0,1]
	v_fmac_f32_e32 v109, v120, v120
	v_fmac_f32_e32 v144, v124, v124
	v_fmac_f32_e32 v109, v122, v122
	v_fmac_f32_e32 v144, v126, v126
	v_fmac_f32_e32 v109, v123, v123
	v_fmac_f32_e32 v144, v127, v127
	v_add_f32_e32 v109, v109, v144
	v_cmp_lt_i32_e32 vcc, v208, v206
	v_add_f32_e32 v108, v108, v109
	v_readlane_b32 s28, v250, 9
	v_cndmask_b32_e32 v109, v204, v208, vcc
	v_lshlrev_b32_e32 v109, 2, v109
	ds_bpermute_b32 v109, v109, v108
	v_cmp_lt_i32_e32 vcc, v207, v206
	v_readlane_b32 s29, v250, 10
	v_cvt_pk_bf16_f32 v220, v156, v157
	v_cvt_pk_bf16_f32 v221, v158, v159
	s_waitcnt lgkmcnt(0)
	v_add_f32_e32 v108, v108, v109
	v_cndmask_b32_e32 v109, v204, v207, vcc
	v_lshlrev_b32_e32 v109, 2, v109
	ds_bpermute_b32 v109, v109, v108
	v_cvt_pk_bf16_f32 v222, v152, v153
	v_cvt_pk_bf16_f32 v223, v154, v155
	v_lshl_add_u64 v[116:117], v[194:195], 1, s[28:29]
	v_cvt_pk_bf16_f32 v152, v120, v121
	v_cvt_pk_bf16_f32 v153, v122, v123
	v_cvt_pk_bf16_f32 v154, v124, v125
	v_cvt_pk_bf16_f32 v155, v126, v127
	global_store_dwordx4 v[116:117], v[220:223], off
	global_store_dwordx4 v[192:193], v[120:123], off offset:512
	global_store_dwordx4 v[192:193], v[124:127], off offset:528
	global_store_dwordx4 v[116:117], v[152:155], off offset:256
	s_and_saveexec_b64 s[28:29], s[10:11]
	s_cbranch_execz .LBB0_664
	s_waitcnt lgkmcnt(0)
	v_add_f32_e32 v108, v108, v109
	s_andn2_b64 vcc, exec, s[20:21]
	s_mov_b64 s[30:31], -1
	s_cbranch_vccnz .LBB0_662
	s_mov_b64 s[30:31], 0
	ds_write_b32 v218, v108

; #define PG8_STAGE(bufoff, gbase, voff) do { _Pragma("unroll") for (int _i = 0; _i < 2; ++_i) \
;         __builtin_amdgcn_global_load_lds((const unsigned*)((const char*)(gbase) + (voff)[_i]), (LAS unsigned*)(lds + (bufoff) + ldsw + _i * 8192), 16, 0, 0); } while (0)
; #define PG8_LDA(dst, b, h) do { _Pragma("unroll") for (int m = 0; m < 4; ++m) _Pragma("unroll") for (int k = 0; k < 2; ++k) dst[m][k] = *(const LAS bf16x8*)(lds + PG8_SA(b, h) + aoff + m * 2048 + k * 1024); } while (0)
; #define PG8_LDB(dst, b, h) do { _Pragma("unroll") for (int n = 0; n < 2; ++n) _Pragma("unroll") for (int k = 0; k < 2; ++k) dst[n][k] = *(const LAS bf16x8*)(lds + PG8_SB(b, h) + boff + n * 2048 + k * 1024); } while (0)
; #define PG8_MMA(ai, bj, At, Bt) do { __builtin_amdgcn_s_setprio(1); _Pragma("unroll") for (int m = 0; m < 4; ++m) _Pragma("unroll") for (int n = 0; n < 2; ++n) _Pragma("unroll") for (int k = 0; k < 2; ++k) \
;         acc[ai][bj][m][n] = __builtin_amdgcn_mfma_f32_16x16x32_bf16(Bt[n][k], At[m][k], acc[ai][bj][m][n], 0, 0, 0); __builtin_amdgcn_s_setprio(0); } while (0)
; #define PG8_WAIT_V(n) asm volatile("s_waitcnt vmcnt(" #n ")" ::: "memory")
; #define PG8_WAIT_L(n) asm volatile("s_waitcnt lgkmcnt(" #n ")" ::: "memory")
; #define PG8_BAR __builtin_amdgcn_s_barrier()
; template <class Epi>
; DEV void gemm_phase(LAS unsigned char* lds, const Gemm g, const StaticOrder& S, const Epi& E) {
;     ...
;         for (int t = 0; t < nt; t += 2) {
;             const bool last = (t == nt - 2);
;             const char* a1 = cA + (size_t)(t + 1) * kstep;
;             const char* a2 = last ? nA : cA + (size_t)(t + 2) * kstep; const char* b2 = last ? nB : cB + (size_t)(t + 2) * kstep;
;             const char* a3 = a2 + kstep; const char* b3 = b2 + kstep;
;             PG8_LDB(B0, 0, 0); PG8_SCHED; PG8_LDA(At, 0, 0); PG8_STAGE(PG8_SA(1, 1), a1 + hstep, voffA);
;             PG8_WAIT_L(8); PG8_BAR; PG8_WAIT_L(0); PG8_MMA(0, 0, At, B0); PG8_BAR; PG8_SCHED;
;             PG8_LDB(B1, 0, 1); PG8_STAGE(PG8_SB(0, 0), b2, voffB);
;             PG8_BAR; PG8_WAIT_L(0); PG8_MMA(0, 1, At, B1); PG8_BAR;
;             PG8_LDA(At, 0, 1); PG8_STAGE(PG8_SA(0, 0), a2, voffA);
;             PG8_BAR; PG8_WAIT_L(0); PG8_MMA(1, 0, At, B0); PG8_BAR; PG8_SCHED;
;             PG8_STAGE(PG8_SB(0, 1), b2 + hstep, voffB);
;             PG8_WAIT_V(6); PG8_BAR; PG8_MMA(1, 1, At, B1); PG8_BAR;
.LBB0_755:
	s_add_u32 s22, s20, 0xfff80080
	s_addc_u32 s23, s21, -1
	s_add_i32 s47, 0, 0x10000
	v_add_u32_e32 v146, s47, v155
	ds_read_b128 v[128:131], v146
	ds_read_b128 v[132:135], v146 offset:1024
	ds_read_b128 v[150:153], v146 offset:2048
	ds_read_b128 v[174:177], v146 offset:3072
	s_cmp_eq_u32 s46, 28
	s_cselect_b32 s25, s5, s23
	s_cselect_b32 s24, s15, s22
	s_cselect_b32 s23, s11, s45
	s_cselect_b32 s22, s43, s44
	s_add_i32 m0, s34, 0xc000
	ds_read_b128 v[178:181], v167
	ds_read_b128 v[182:185], v167 offset:1024
	ds_read_b128 v[186:189], v167 offset:2048
	ds_read_b128 v[190:193], v167 offset:3072
	ds_read_b128 v[194:197], v167 offset:4096
	ds_read_b128 v[218:221], v167 offset:5120
	ds_read_b128 v[222:225], v167 offset:6144
	ds_read_b128 v[226:229], v167 offset:7168
	global_load_lds_dwordx4 v142, s[20:21]
	s_add_i32 m0, s34, 0xe000
	s_nop 0
	global_load_lds_dwordx4 v144, s[20:21]
	s_waitcnt lgkmcnt(8)
	s_barrier
	s_waitcnt lgkmcnt(0)
	v_mfma_f32_16x16x32_bf16 v[124:127], v[128:131], v[178:181], v[124:127]
	v_mfma_f32_16x16x32_bf16 v[116:119], v[150:153], v[178:181], v[116:119]
	v_mfma_f32_16x16x32_bf16 v[108:111], v[128:131], v[186:189], v[108:111]
	v_mfma_f32_16x16x32_bf16 v[100:103], v[150:153], v[186:189], v[100:103]
	v_mfma_f32_16x16x32_bf16 v[92:95], v[128:131], v[194:197], v[92:95]
	v_mfma_f32_16x16x32_bf16 v[84:87], v[150:153], v[194:197], v[84:87]
	v_mfma_f32_16x16x32_bf16 v[76:79], v[128:131], v[222:225], v[76:79]
	v_mfma_f32_16x16x32_bf16 v[68:71], v[150:153], v[222:225], v[68:71]
	v_mfma_f32_16x16x32_bf16 v[124:127], v[132:135], v[182:185], v[124:127]
	v_mfma_f32_16x16x32_bf16 v[116:119], v[174:177], v[182:185], v[116:119]
	v_mfma_f32_16x16x32_bf16 v[108:111], v[132:135], v[190:193], v[108:111]
	v_mfma_f32_16x16x32_bf16 v[100:103], v[174:177], v[190:193], v[100:103]
	v_mfma_f32_16x16x32_bf16 v[92:95], v[132:135], v[218:221], v[92:95]
	v_mfma_f32_16x16x32_bf16 v[84:87], v[174:177], v[218:221], v[84:87]
	v_mfma_f32_16x16x32_bf16 v[76:79], v[132:135], v[226:229], v[76:79]
	v_mfma_f32_16x16x32_bf16 v[68:71], v[174:177], v[226:229], v[68:71]
	s_barrier
	s_add_i32 s50, 0, 0x14000
	v_add_u32_e32 v146, s50, v155
	s_add_i32 s47, s47, s30
	ds_read_b128 v[230:233], v146
	ds_read_b128 v[234:237], v146 offset:1024
	ds_read_b128 v[238:241], v146 offset:2048
	ds_read_b128 v[242:245], v146 offset:3072
	v_lshl_add_u64 v[146:147], s[22:23], 0, v[160:161]
	s_mov_b32 m0, s47
	v_lshl_add_u64 v[158:159], s[22:23], 0, v[136:137]
	global_load_lds_dwordx4 v160, s[22:23]
	s_add_i32 m0, s47, 0x2000
	s_nop 0
	global_load_lds_dwordx4 v136, s[22:23]
	s_barrier
	s_waitcnt lgkmcnt(0)
	v_mfma_f32_16x16x32_bf16 v[120:123], v[230:233], v[178:181], v[120:123]
	v_mfma_f32_16x16x32_bf16 v[112:115], v[238:241], v[178:181], v[112:115]
	v_mfma_f32_16x16x32_bf16 v[104:107], v[230:233], v[186:189], v[104:107]
	v_mfma_f32_16x16x32_bf16 v[96:99], v[238:241], v[186:189], v[96:99]
	v_mfma_f32_16x16x32_bf16 v[88:91], v[230:233], v[194:197], v[88:91]
	v_mfma_f32_16x16x32_bf16 v[80:83], v[238:241], v[194:197], v[80:83]
	v_mfma_f32_16x16x32_bf16 v[72:75], v[230:233], v[222:225], v[72:75]
	v_mfma_f32_16x16x32_bf16 v[64:67], v[238:241], v[222:225], v[64:67]
	v_mfma_f32_16x16x32_bf16 v[120:123], v[234:237], v[182:185], v[120:123]
	v_mfma_f32_16x16x32_bf16 v[112:115], v[242:245], v[182:185], v[112:115]
	v_mfma_f32_16x16x32_bf16 v[104:107], v[234:237], v[190:193], v[104:107]
	v_mfma_f32_16x16x32_bf16 v[96:99], v[242:245], v[190:193], v[96:99]
	v_mfma_f32_16x16x32_bf16 v[88:91], v[234:237], v[218:221], v[88:91]
	v_mfma_f32_16x16x32_bf16 v[80:83], v[242:245], v[218:221], v[80:83]
	v_mfma_f32_16x16x32_bf16 v[72:75], v[234:237], v[226:229], v[72:75]
	v_mfma_f32_16x16x32_bf16 v[64:67], v[242:245], v[226:229], v[64:67]
	s_mov_b32 m0, s34
	v_lshl_add_u64 v[214:215], s[24:25], 0, v[140:141]
	s_barrier
	ds_read_b128 v[178:181], v167 offset:16384
	ds_read_b128 v[182:185], v167 offset:17408
	ds_read_b128 v[186:189], v167 offset:18432
	ds_read_b128 v[190:193], v167 offset:19456
	ds_read_b128 v[194:197], v167 offset:20480
	ds_read_b128 v[218:221], v167 offset:21504
	ds_read_b128 v[222:225], v167 offset:22528
	ds_read_b128 v[226:229], v167 offset:23552
	global_load_lds_dwordx4 v140, s[24:25]
	v_lshl_add_u64 v[216:217], s[24:25], 0, v[138:139]
	s_mov_b32 m0, s35
	s_nop 0
	global_load_lds_dwordx4 v138, s[24:25]
	s_barrier
	s_waitcnt lgkmcnt(0)
	v_mfma_f32_16x16x32_bf16 v[60:63], v[128:131], v[178:181], v[60:63]
	v_mfma_f32_16x16x32_bf16 v[52:55], v[150:153], v[178:181], v[52:55]
	v_mfma_f32_16x16x32_bf16 v[44:47], v[128:131], v[186:189], v[44:47]
	v_mfma_f32_16x16x32_bf16 v[36:39], v[150:153], v[186:189], v[36:39]
	v_mfma_f32_16x16x32_bf16 v[28:31], v[128:131], v[194:197], v[28:31]
	v_mfma_f32_16x16x32_bf16 v[20:23], v[150:153], v[194:197], v[20:23]
	v_mfma_f32_16x16x32_bf16 v[12:15], v[128:131], v[222:225], v[12:15]
	v_mfma_f32_16x16x32_bf16 v[4:7], v[150:153], v[222:225], v[4:7]
	v_mfma_f32_16x16x32_bf16 v[60:63], v[132:135], v[182:185], v[60:63]
	v_mfma_f32_16x16x32_bf16 v[52:55], v[174:177], v[182:185], v[52:55]
	v_mfma_f32_16x16x32_bf16 v[44:47], v[132:135], v[190:193], v[44:47]
	v_mfma_f32_16x16x32_bf16 v[36:39], v[174:177], v[190:193], v[36:39]
	v_mfma_f32_16x16x32_bf16 v[28:31], v[132:135], v[218:221], v[28:31]
	v_mfma_f32_16x16x32_bf16 v[20:23], v[174:177], v[218:221], v[20:23]
	v_mfma_f32_16x16x32_bf16 v[12:15], v[132:135], v[226:229], v[12:15]
	v_mfma_f32_16x16x32_bf16 v[4:7], v[174:177], v[226:229], v[4:7]
	s_barrier
	s_add_u32 s48, s22, 0x80000
	s_addc_u32 s49, s23, 0
	s_add_i32 s47, s50, s30
	s_mov_b32 m0, s47
	s_nop 0
	global_load_lds_dwordx4 v160, s[48:49]
	s_add_i32 m0, s47, 0x2000
	s_nop 0
	global_load_lds_dwordx4 v136, s[48:49]
	s_waitcnt vmcnt(6)
	s_barrier
; #define PG8_STAGE(bufoff, gbase, voff) do { _Pragma("unroll") for (int _i = 0; _i < 2; ++_i) \
;         __builtin_amdgcn_global_load_lds((const unsigned*)((const char*)(gbase) + (voff)[_i]), (LAS unsigned*)(lds + (bufoff) + ldsw + _i * 8192), 16, 0, 0); } while (0)
; #define PG8_LDA(dst, b, h) do { _Pragma("unroll") for (int m = 0; m < 4; ++m) _Pragma("unroll") for (int k = 0; k < 2; ++k) dst[m][k] = *(const LAS bf16x8*)(lds + PG8_SA(b, h) + aoff + m * 2048 + k * 1024); } while (0)
; #define PG8_LDB(dst, b, h) do { _Pragma("unroll") for (int n = 0; n < 2; ++n) _Pragma("unroll") for (int k = 0; k < 2; ++k) dst[n][k] = *(const LAS bf16x8*)(lds + PG8_SB(b, h) + boff + n * 2048 + k * 1024); } while (0)
; #define PG8_MMA(ai, bj, At, Bt) do { __builtin_amdgcn_s_setprio(1); _Pragma("unroll") for (int m = 0; m < 4; ++m) _Pragma("unroll") for (int n = 0; n < 2; ++n) _Pragma("unroll") for (int k = 0; k < 2; ++k) \
;         acc[ai][bj][m][n] = __builtin_amdgcn_mfma_f32_16x16x32_bf16(Bt[n][k], At[m][k], acc[ai][bj][m][n], 0, 0, 0); __builtin_amdgcn_s_setprio(0); } while (0)
; #define PG8_WAIT_V(n) asm volatile("s_waitcnt vmcnt(" #n ")" ::: "memory")
; #define PG8_WAIT_L(n) asm volatile("s_waitcnt lgkmcnt(" #n ")" ::: "memory")
; #define PG8_BAR __builtin_amdgcn_s_barrier()
; #define PG8_SCHED __builtin_amdgcn_sched_barrier(0)
; template <class Epi>
; DEV void gemm_phase(LAS unsigned char* lds, const Gemm g, const StaticOrder& S, const Epi& E) {
;     ...
;             PG8_WAIT_V(6); PG8_BAR; PG8_MMA(1, 1, At, B1); PG8_BAR;
;             PG8_LDB(B0, 1, 0); PG8_SCHED; PG8_LDA(At, 1, 0); PG8_STAGE(PG8_SA(0, 1), a2 + hstep, voffA);
;             PG8_WAIT_L(8); PG8_BAR; PG8_WAIT_L(0); PG8_MMA(0, 0, At, B0); PG8_BAR; PG8_SCHED;
;             PG8_LDB(B1, 1, 1); PG8_STAGE(PG8_SB(1, 0), b3, voffB);
;             PG8_BAR; PG8_WAIT_L(0); PG8_MMA(0, 1, At, B1); PG8_BAR;
;             PG8_LDA(At, 1, 1); PG8_STAGE(PG8_SA(1, 0), a3, voffA);
;             PG8_BAR; PG8_WAIT_L(0); PG8_MMA(1, 0, At, B0); PG8_BAR; PG8_SCHED;
;             PG8_STAGE(PG8_SB(1, 1), b3 + hstep, voffB);
;             PG8_WAIT_V(6); PG8_BAR; PG8_MMA(1, 1, At, B1); PG8_BAR;
	v_mfma_f32_16x16x32_bf16 v[56:59], v[230:233], v[178:181], v[56:59]
	v_mfma_f32_16x16x32_bf16 v[48:51], v[238:241], v[178:181], v[48:51]
	v_mfma_f32_16x16x32_bf16 v[40:43], v[230:233], v[186:189], v[40:43]
	v_mfma_f32_16x16x32_bf16 v[32:35], v[238:241], v[186:189], v[32:35]
	v_mfma_f32_16x16x32_bf16 v[24:27], v[230:233], v[194:197], v[24:27]
	v_mfma_f32_16x16x32_bf16 v[16:19], v[238:241], v[194:197], v[16:19]
	v_mfma_f32_16x16x32_bf16 v[8:11], v[230:233], v[222:225], v[8:11]
	v_mfma_f32_16x16x32_bf16 v[0:3], v[238:241], v[222:225], v[0:3]
	v_mfma_f32_16x16x32_bf16 v[56:59], v[234:237], v[182:185], v[56:59]
	v_mfma_f32_16x16x32_bf16 v[48:51], v[242:245], v[182:185], v[48:51]
	v_mfma_f32_16x16x32_bf16 v[40:43], v[234:237], v[190:193], v[40:43]
	v_mfma_f32_16x16x32_bf16 v[32:35], v[242:245], v[190:193], v[32:35]
	v_mfma_f32_16x16x32_bf16 v[24:27], v[234:237], v[218:221], v[24:27]
	v_mfma_f32_16x16x32_bf16 v[16:19], v[242:245], v[218:221], v[16:19]
	v_mfma_f32_16x16x32_bf16 v[8:11], v[234:237], v[226:229], v[8:11]
	v_mfma_f32_16x16x32_bf16 v[0:3], v[242:245], v[226:229], v[0:3]
	s_add_i32 s47, 0, 0x18000
	v_add_u32_e32 v148, s47, v155
	s_barrier
	ds_read_b128 v[128:131], v148
	ds_read_b128 v[132:135], v148 offset:1024
	ds_read_b128 v[150:153], v148 offset:2048
	ds_read_b128 v[174:177], v148 offset:3072
	s_add_u32 s24, s24, 0x80000
	s_addc_u32 s25, s25, 0
	s_mov_b32 m0, s36
	ds_read_b128 v[178:181], v167 offset:32768
	ds_read_b128 v[182:185], v167 offset:33792
	ds_read_b128 v[186:189], v167 offset:34816
	ds_read_b128 v[190:193], v167 offset:35840
	ds_read_b128 v[194:197], v167 offset:36864
	ds_read_b128 v[218:221], v167 offset:37888
	ds_read_b128 v[222:225], v167 offset:38912
	ds_read_b128 v[226:229], v167 offset:39936
	global_load_lds_dwordx4 v140, s[24:25]
	s_mov_b32 m0, s37
	s_nop 0
	global_load_lds_dwordx4 v138, s[24:25]
	s_waitcnt lgkmcnt(8)
	s_barrier
	s_waitcnt lgkmcnt(0)
	v_mfma_f32_16x16x32_bf16 v[124:127], v[128:131], v[178:181], v[124:127]
	v_mfma_f32_16x16x32_bf16 v[116:119], v[150:153], v[178:181], v[116:119]
	v_mfma_f32_16x16x32_bf16 v[108:111], v[128:131], v[186:189], v[108:111]
	v_mfma_f32_16x16x32_bf16 v[100:103], v[150:153], v[186:189], v[100:103]
	v_mfma_f32_16x16x32_bf16 v[92:95], v[128:131], v[194:197], v[92:95]
	v_mfma_f32_16x16x32_bf16 v[84:87], v[150:153], v[194:197], v[84:87]
	v_mfma_f32_16x16x32_bf16 v[76:79], v[128:131], v[222:225], v[76:79]
	v_mfma_f32_16x16x32_bf16 v[68:71], v[150:153], v[222:225], v[68:71]
	v_mfma_f32_16x16x32_bf16 v[124:127], v[132:135], v[182:185], v[124:127]
	v_mfma_f32_16x16x32_bf16 v[116:119], v[174:177], v[182:185], v[116:119]
	v_mfma_f32_16x16x32_bf16 v[108:111], v[132:135], v[190:193], v[108:111]
	v_mfma_f32_16x16x32_bf16 v[100:103], v[174:177], v[190:193], v[100:103]
	v_mfma_f32_16x16x32_bf16 v[92:95], v[132:135], v[218:221], v[92:95]
	v_mfma_f32_16x16x32_bf16 v[84:87], v[174:177], v[218:221], v[84:87]
	v_mfma_f32_16x16x32_bf16 v[76:79], v[132:135], v[226:229], v[76:79]
	v_mfma_f32_16x16x32_bf16 v[68:71], v[174:177], v[226:229], v[68:71]
	s_barrier
	s_add_i32 s24, 0, 0x1c000
	s_add_i32 s25, s47, s30
	v_add_u32_e32 v148, s24, v155
	v_lshl_add_u64 v[146:147], v[146:147], 0, s[2:3]
	s_mov_b32 m0, s25
	ds_read_b128 v[230:233], v148
	ds_read_b128 v[234:237], v148 offset:1024
	ds_read_b128 v[238:241], v148 offset:2048
	ds_read_b128 v[242:245], v148 offset:3072
	global_load_lds_dwordx4 v[146:147], off
	v_lshl_add_u64 v[146:147], v[158:159], 0, s[2:3]
	s_add_i32 m0, s25, 0x2000
	s_nop 0
	global_load_lds_dwordx4 v[146:147], off
	s_barrier
	s_waitcnt lgkmcnt(0)
	v_mfma_f32_16x16x32_bf16 v[120:123], v[230:233], v[178:181], v[120:123]
	v_mfma_f32_16x16x32_bf16 v[112:115], v[238:241], v[178:181], v[112:115]
	v_mfma_f32_16x16x32_bf16 v[104:107], v[230:233], v[186:189], v[104:107]
	v_mfma_f32_16x16x32_bf16 v[96:99], v[238:241], v[186:189], v[96:99]
	v_mfma_f32_16x16x32_bf16 v[88:91], v[230:233], v[194:197], v[88:91]
	v_mfma_f32_16x16x32_bf16 v[80:83], v[238:241], v[194:197], v[80:83]
	v_mfma_f32_16x16x32_bf16 v[72:75], v[230:233], v[222:225], v[72:75]
	v_mfma_f32_16x16x32_bf16 v[64:67], v[238:241], v[222:225], v[64:67]
	v_mfma_f32_16x16x32_bf16 v[120:123], v[234:237], v[182:185], v[120:123]
	v_mfma_f32_16x16x32_bf16 v[112:115], v[242:245], v[182:185], v[112:115]
	v_mfma_f32_16x16x32_bf16 v[104:107], v[234:237], v[190:193], v[104:107]
	v_mfma_f32_16x16x32_bf16 v[96:99], v[242:245], v[190:193], v[96:99]
	v_mfma_f32_16x16x32_bf16 v[88:91], v[234:237], v[218:221], v[88:91]
	v_mfma_f32_16x16x32_bf16 v[80:83], v[242:245], v[218:221], v[80:83]
	v_mfma_f32_16x16x32_bf16 v[72:75], v[234:237], v[226:229], v[72:75]
	v_mfma_f32_16x16x32_bf16 v[64:67], v[242:245], v[226:229], v[64:67]
	s_mov_b32 m0, s38
	v_lshl_add_u64 v[146:147], v[214:215], 0, s[2:3]
	s_barrier
	ds_read_b128 v[178:181], v167 offset:49152
	ds_read_b128 v[182:185], v167 offset:50176
	ds_read_b128 v[186:189], v167 offset:51200
	ds_read_b128 v[190:193], v167 offset:52224
	ds_read_b128 v[194:197], v167 offset:53248
	ds_read_b128 v[218:221], v167 offset:54272
	ds_read_b128 v[222:225], v167 offset:55296
	ds_read_b128 v[226:229], v167 offset:56320
	global_load_lds_dwordx4 v[146:147], off
	v_lshl_add_u64 v[146:147], v[216:217], 0, s[2:3]
	s_mov_b32 m0, s39
	s_nop 0
	global_load_lds_dwordx4 v[146:147], off
	s_barrier
; #define PG8_STAGE(bufoff, gbase, voff) do { _Pragma("unroll") for (int _i = 0; _i < 2; ++_i) \
;         __builtin_amdgcn_global_load_lds((const unsigned*)((const char*)(gbase) + (voff)[_i]), (LAS unsigned*)(lds + (bufoff) + ldsw + _i * 8192), 16, 0, 0); } while (0)
; #define PG8_MMA(ai, bj, At, Bt) do { __builtin_amdgcn_s_setprio(1); _Pragma("unroll") for (int m = 0; m < 4; ++m) _Pragma("unroll") for (int n = 0; n < 2; ++n) _Pragma("unroll") for (int k = 0; k < 2; ++k) \
;         acc[ai][bj][m][n] = __builtin_amdgcn_mfma_f32_16x16x32_bf16(Bt[n][k], At[m][k], acc[ai][bj][m][n], 0, 0, 0); __builtin_amdgcn_s_setprio(0); } while (0)
; #define PG8_WAIT_V(n) asm volatile("s_waitcnt vmcnt(" #n ")" ::: "memory")
; #define PG8_BAR __builtin_amdgcn_s_barrier()
;     DEV void operator()(AccRef acc, const pg8::Unit& u, int wr, int wc, int fr, int fq) const { store_bf16_tile<0, false>(acc, O, ld, u.pm * 256 + wr * 64 + fr, u.pn * 256 + wc * 32 + 4 * fq, ss); }
; template <class Epi>
; DEV void gemm_phase(LAS unsigned char* lds, const Gemm g, const StaticOrder& S, const Epi& E) {
;     ...
;             PG8_STAGE(PG8_SB(1, 1), b3 + hstep, voffB);
;             PG8_WAIT_V(6); PG8_BAR; PG8_MMA(1, 1, At, B1); PG8_BAR;
;         }
; DEV float rowscale(const float* ss, int row) { const f32x4 a = *(const f32x4*)(ss + (size_t)row * 8), b = *(const f32x4*)(ss + (size_t)row * 8 + 4);
;     return rsqrtf(((a[0] + a[1]) + (a[2] + a[3]) + (b[0] + b[1]) + (b[2] + b[3])) * (1.0f / 2048.0f) + EPS); }
;     DEV void operator()(AccRef acc, const pg8::Unit& u, int wr, int wc, int fr, int fq) const {
;         const int row0 = u.pm * 256 + wr * 64 + fr, col0 = u.pn * 128 + wc * 32 + 8 * fq;
;         float rsv[2][4];
; #pragma unroll
;         for (int ai = 0; ai < 2; ++ai)
; #pragma unroll
;             for (int m = 0; m < 4; ++m) rsv[ai][m] = rowscale(ss, row0 + ai * 128 + m * 16);
; #pragma unroll
;         for (int ai = 0; ai < 2; ++ai)
; #pragma unroll
;             for (int m = 0; m < 4; ++m) { u16* rowp = O + (size_t)(row0 + ai * 128 + m * 16) * 5632 + col0; const float rs = rsv[ai][m]; f32x4 r[2];
; #pragma unroll
;                 for (int n = 0; n < 2; ++n) { const f32x4 g = acc[ai][0][m][n] * rs, uu = acc[ai][1][m][n] * rs;
	s_waitcnt lgkmcnt(0)
	v_mfma_f32_16x16x32_bf16 v[60:63], v[128:131], v[178:181], v[60:63]
	v_mfma_f32_16x16x32_bf16 v[52:55], v[150:153], v[178:181], v[52:55]
	v_mfma_f32_16x16x32_bf16 v[44:47], v[128:131], v[186:189], v[44:47]
	v_mfma_f32_16x16x32_bf16 v[36:39], v[150:153], v[186:189], v[36:39]
	v_mfma_f32_16x16x32_bf16 v[28:31], v[128:131], v[194:197], v[28:31]
	v_mfma_f32_16x16x32_bf16 v[20:23], v[150:153], v[194:197], v[20:23]
	v_mfma_f32_16x16x32_bf16 v[12:15], v[128:131], v[222:225], v[12:15]
	v_mfma_f32_16x16x32_bf16 v[4:7], v[150:153], v[222:225], v[4:7]
	v_mfma_f32_16x16x32_bf16 v[60:63], v[132:135], v[182:185], v[60:63]
	v_mfma_f32_16x16x32_bf16 v[52:55], v[174:177], v[182:185], v[52:55]
	v_mfma_f32_16x16x32_bf16 v[44:47], v[132:135], v[190:193], v[44:47]
	v_mfma_f32_16x16x32_bf16 v[36:39], v[174:177], v[190:193], v[36:39]
	v_mfma_f32_16x16x32_bf16 v[28:31], v[132:135], v[218:221], v[28:31]
	v_mfma_f32_16x16x32_bf16 v[20:23], v[174:177], v[218:221], v[20:23]
	v_mfma_f32_16x16x32_bf16 v[12:15], v[132:135], v[226:229], v[12:15]
	v_mfma_f32_16x16x32_bf16 v[4:7], v[174:177], v[226:229], v[4:7]
	s_barrier
	s_add_u32 s22, s22, 0x80080
	s_addc_u32 s23, s23, 0
	s_add_i32 s24, s24, s30
	s_mov_b32 m0, s24
	s_nop 0
	global_load_lds_dwordx4 v160, s[22:23]
	s_add_i32 m0, s24, 0x2000
	s_nop 0
	global_load_lds_dwordx4 v136, s[22:23]
	s_waitcnt vmcnt(6)
	s_barrier
	v_mfma_f32_16x16x32_bf16 v[56:59], v[230:233], v[178:181], v[56:59]
	v_mfma_f32_16x16x32_bf16 v[48:51], v[238:241], v[178:181], v[48:51]
	v_mfma_f32_16x16x32_bf16 v[40:43], v[230:233], v[186:189], v[40:43]
	v_mfma_f32_16x16x32_bf16 v[32:35], v[238:241], v[186:189], v[32:35]
	v_mfma_f32_16x16x32_bf16 v[24:27], v[230:233], v[194:197], v[24:27]
	v_mfma_f32_16x16x32_bf16 v[16:19], v[238:241], v[194:197], v[16:19]
	v_mfma_f32_16x16x32_bf16 v[8:11], v[230:233], v[222:225], v[8:11]
	v_mfma_f32_16x16x32_bf16 v[0:3], v[238:241], v[222:225], v[0:3]
	v_mfma_f32_16x16x32_bf16 v[56:59], v[234:237], v[182:185], v[56:59]
	v_mfma_f32_16x16x32_bf16 v[48:51], v[242:245], v[182:185], v[48:51]
	v_mfma_f32_16x16x32_bf16 v[40:43], v[234:237], v[190:193], v[40:43]
	v_mfma_f32_16x16x32_bf16 v[32:35], v[242:245], v[190:193], v[32:35]
	v_mfma_f32_16x16x32_bf16 v[24:27], v[234:237], v[218:221], v[24:27]
	v_mfma_f32_16x16x32_bf16 v[16:19], v[242:245], v[218:221], v[16:19]
	v_mfma_f32_16x16x32_bf16 v[8:11], v[234:237], v[226:229], v[8:11]
	v_mfma_f32_16x16x32_bf16 v[0:3], v[242:245], v[226:229], v[0:3]
	s_add_i32 s46, s46, 2
	s_add_u32 s20, s20, 0x100
	s_addc_u32 s21, s21, 0
	s_add_u32 s44, s44, 0x100
	s_addc_u32 s45, s45, 0
	s_cmp_gt_u32 s46, 29
	s_barrier
	s_cbranch_scc0 .LBB0_755
	v_lshl_add_u32 v186, s4, 8, v149
	v_ashrrev_i32_e32 v187, 31, v186
	v_lshlrev_b64 v[146:147], 5, v[186:187]
	v_lshl_add_u64 v[146:147], s[8:9], 0, v[146:147]
	v_add_co_u32_e32 v158, vcc, 0x1000, v146
	global_load_dwordx4 v[218:221], v[146:147], off
	global_load_dwordx4 v[222:225], v[146:147], off offset:16
	v_addc_co_u32_e32 v159, vcc, 0, v147, vcc
	global_load_dwordx4 v[174:177], v[146:147], off offset:512
	global_load_dwordx4 v[230:233], v[146:147], off offset:528
	global_load_dwordx4 v[234:237], v[146:147], off offset:1024
	global_load_dwordx4 v[238:241], v[146:147], off offset:1040
	global_load_dwordx4 v[242:245], v[146:147], off offset:1536
	global_load_dwordx4 v[246:249], v[146:147], off offset:1552
	global_load_dwordx4 v[190:193], v[158:159], off
	global_load_dwordx4 v[194:197], v[158:159], off offset:16
	global_load_dwordx4 v[214:217], v[158:159], off offset:512
	global_load_dwordx4 v[132:135], v[158:159], off offset:528
	global_load_dwordx4 v[150:153], v[158:159], off offset:1024
	global_load_dwordx4 v[128:131], v[158:159], off offset:1040
	global_load_dwordx4 v[226:229], v[158:159], off offset:1536
	global_load_dwordx4 v[180:183], v[158:159], off offset:1552
	s_mov_b32 s12, 0x3a000000
	s_mov_b64 s[22:23], s[18:19]
	s_mov_b64 s[20:21], s[16:17]
	s_movk_i32 s11, 0x2c00
	v_readlane_b32 s4, v250, 11
	v_readlane_b32 s5, v250, 12
	s_waitcnt vmcnt(14)
	v_add_f32_e32 v218, v218, v219
	v_add_f32_e32 v220, v220, v221
	v_add_f32_e32 v222, v222, v223
	v_add_f32_e32 v224, v224, v225
	v_add_f32_e32 v218, v218, v220
	v_add_f32_e32 v218, v218, v222
	v_add_f32_e32 v218, v218, v224
	v_fmamk_f32 v218, v218, 0x3a000000, v199
	v_rsq_f32_e32 v184, v218
	s_waitcnt vmcnt(12)
	v_add_f32_e32 v174, v174, v175
	v_add_f32_e32 v176, v176, v177
	v_add_f32_e32 v230, v230, v231
	v_add_f32_e32 v232, v232, v233
	v_add_f32_e32 v174, v174, v176
	v_add_f32_e32 v174, v174, v230
	v_add_f32_e32 v174, v174, v232
	v_fmamk_f32 v174, v174, 0x3a000000, v199
	v_rsq_f32_e32 v176, v174
	v_pk_mul_f32 v[124:125], v[124:125], v[184:185] op_sel_hi:[1,0]
	v_pk_mul_f32 v[120:121], v[120:121], v[184:185] op_sel_hi:[1,0]
	v_pk_mul_f32 v[122:123], v[122:123], v[184:185] op_sel_hi:[1,0]
	v_pk_mul_f32 v[116:117], v[116:117], v[184:185] op_sel_hi:[1,0]
	v_pk_mul_f32 v[112:113], v[112:113], v[184:185] op_sel_hi:[1,0]
	v_pk_mul_f32 v[114:115], v[114:115], v[184:185] op_sel_hi:[1,0]
	s_waitcnt vmcnt(10)
	v_add_f32_e32 v234, v234, v235
	v_add_f32_e32 v236, v236, v237
	v_add_f32_e32 v238, v238, v239
	v_add_f32_e32 v240, v240, v241
	v_add_f32_e32 v234, v234, v236
	v_add_f32_e32 v234, v234, v238
	v_add_f32_e32 v234, v234, v240
	v_fmamk_f32 v234, v234, 0x3a000000, v199
	v_rsq_f32_e32 v178, v234
	v_pk_mul_f32 v[108:109], v[108:109], v[176:177] op_sel_hi:[1,0]
	v_pk_mul_f32 v[104:105], v[104:105], v[176:177] op_sel_hi:[1,0]
	v_pk_mul_f32 v[106:107], v[106:107], v[176:177] op_sel_hi:[1,0]
	v_pk_mul_f32 v[100:101], v[100:101], v[176:177] op_sel_hi:[1,0]
	v_pk_mul_f32 v[96:97], v[96:97], v[176:177] op_sel_hi:[1,0]
	v_pk_mul_f32 v[98:99], v[98:99], v[176:177] op_sel_hi:[1,0]
	s_waitcnt vmcnt(8)
; DEV float siluf(float x) { return x * __builtin_amdgcn_rcpf(1.0f + __builtin_amdgcn_exp2f(x * -1.4426950408889634f)); }
; DEV bf16x8 pack8(f32x4 a, f32x4 b) { u32x4 w; w.x = cvt_pk_bf16(a[0], a[1]); w.y = cvt_pk_bf16(a[2], a[3]); w.z = cvt_pk_bf16(b[0], b[1]); w.w = cvt_pk_bf16(b[2], b[3]); return __builtin_bit_cast(bf16x8, w); }
;     DEV void operator()(AccRef acc, const pg8::Unit& u, int wr, int wc, int fr, int fq) const { store_bf16_tile<0, false>(acc, O, ld, u.pm * 256 + wr * 64 + fr, u.pn * 256 + wc * 32 + 4 * fq, ss); }
; DEV float rowscale(const float* ss, int row) { const f32x4 a = *(const f32x4*)(ss + (size_t)row * 8), b = *(const f32x4*)(ss + (size_t)row * 8 + 4);
;     return rsqrtf(((a[0] + a[1]) + (a[2] + a[3]) + (b[0] + b[1]) + (b[2] + b[3])) * (1.0f / 2048.0f) + EPS); }
;     DEV void operator()(AccRef acc, const pg8::Unit& u, int wr, int wc, int fr, int fq) const {
;         const int row0 = u.pm * 256 + wr * 64 + fr, col0 = u.pn * 128 + wc * 32 + 8 * fq;
;         float rsv[2][4];
; #pragma unroll
;         for (int ai = 0; ai < 2; ++ai)
; #pragma unroll
;             for (int m = 0; m < 4; ++m) rsv[ai][m] = rowscale(ss, row0 + ai * 128 + m * 16);
; #pragma unroll
;         for (int ai = 0; ai < 2; ++ai)
; #pragma unroll
;             for (int m = 0; m < 4; ++m) { u16* rowp = O + (size_t)(row0 + ai * 128 + m * 16) * 5632 + col0; const float rs = rsv[ai][m]; f32x4 r[2];
; #pragma unroll
;                 for (int n = 0; n < 2; ++n) { const f32x4 g = acc[ai][0][m][n] * rs, uu = acc[ai][1][m][n] * rs;
; #pragma unroll
;                     for (int e = 0; e < 4; ++e) r[n][e] = siluf(g[e]) * uu[e]; }
;                 *(u32x4*)rowp = __builtin_bit_cast(u32x4, pack8(r[0], r[1])); }
	v_add_f32_e32 v242, v242, v243
	v_add_f32_e32 v244, v244, v245
	v_add_f32_e32 v246, v246, v247
	v_add_f32_e32 v248, v248, v249
	v_add_f32_e32 v242, v242, v244
	v_add_f32_e32 v242, v242, v246
	v_add_f32_e32 v242, v242, v248
	v_fmamk_f32 v242, v242, 0x3a000000, v199
	v_rsq_f32_e32 v154, v242
	v_pk_mul_f32 v[92:93], v[92:93], v[178:179] op_sel_hi:[1,0]
	v_pk_mul_f32 v[88:89], v[88:89], v[178:179] op_sel_hi:[1,0]
	v_pk_mul_f32 v[90:91], v[90:91], v[178:179] op_sel_hi:[1,0]
	v_pk_mul_f32 v[84:85], v[84:85], v[178:179] op_sel_hi:[1,0]
	v_pk_mul_f32 v[80:81], v[80:81], v[178:179] op_sel_hi:[1,0]
	v_pk_mul_f32 v[82:83], v[82:83], v[178:179] op_sel_hi:[1,0]
	s_waitcnt vmcnt(6)
	v_add_f32_e32 v190, v190, v191
	v_add_f32_e32 v192, v192, v193
	v_add_f32_e32 v194, v194, v195
	v_add_f32_e32 v196, v196, v197
	v_add_f32_e32 v190, v190, v192
	v_add_f32_e32 v190, v190, v194
	v_add_f32_e32 v190, v190, v196
	v_fmamk_f32 v190, v190, 0x3a000000, v199
	v_rsq_f32_e32 v156, v190
	v_pk_mul_f32 v[76:77], v[76:77], v[154:155] op_sel_hi:[1,0]
	v_pk_mul_f32 v[72:73], v[72:73], v[154:155] op_sel_hi:[1,0]
	v_pk_mul_f32 v[74:75], v[74:75], v[154:155] op_sel_hi:[1,0]
	v_pk_mul_f32 v[68:69], v[68:69], v[154:155] op_sel_hi:[1,0]
	v_pk_mul_f32 v[64:65], v[64:65], v[154:155] op_sel_hi:[1,0]
	v_pk_mul_f32 v[66:67], v[66:67], v[154:155] op_sel_hi:[1,0]
	s_waitcnt vmcnt(4)
	v_add_f32_e32 v214, v214, v215
	v_add_f32_e32 v216, v216, v217
	v_add_f32_e32 v132, v132, v133
	v_add_f32_e32 v134, v134, v135
	v_add_f32_e32 v214, v214, v216
	v_add_f32_e32 v214, v214, v132
	v_add_f32_e32 v214, v214, v134
	v_fmamk_f32 v214, v214, 0x3a000000, v199
	v_rsq_f32_e32 v148, v214
	v_pk_mul_f32 v[60:61], v[60:61], v[156:157] op_sel_hi:[1,0]
	v_pk_mul_f32 v[56:57], v[56:57], v[156:157] op_sel_hi:[1,0]
	v_pk_mul_f32 v[58:59], v[58:59], v[156:157] op_sel_hi:[1,0]
	v_pk_mul_f32 v[52:53], v[52:53], v[156:157] op_sel_hi:[1,0]
	v_pk_mul_f32 v[48:49], v[48:49], v[156:157] op_sel_hi:[1,0]
	v_pk_mul_f32 v[50:51], v[50:51], v[156:157] op_sel_hi:[1,0]
	s_waitcnt vmcnt(2)
	v_add_f32_e32 v150, v150, v151
	v_add_f32_e32 v152, v152, v153
	v_add_f32_e32 v128, v128, v129
	v_add_f32_e32 v130, v130, v131
	v_add_f32_e32 v150, v150, v152
	v_add_f32_e32 v150, v150, v128
	v_add_f32_e32 v150, v150, v130
	v_fmamk_f32 v150, v150, 0x3a000000, v199
	v_rsq_f32_e32 v130, v150
	v_pk_mul_f32 v[44:45], v[44:45], v[148:149] op_sel_hi:[1,0]
	v_pk_mul_f32 v[40:41], v[40:41], v[148:149] op_sel_hi:[1,0]
	v_pk_mul_f32 v[42:43], v[42:43], v[148:149] op_sel_hi:[1,0]
	v_pk_mul_f32 v[36:37], v[36:37], v[148:149] op_sel_hi:[1,0]
	v_pk_mul_f32 v[32:33], v[32:33], v[148:149] op_sel_hi:[1,0]
	v_pk_mul_f32 v[34:35], v[34:35], v[148:149] op_sel_hi:[1,0]
	s_waitcnt vmcnt(0)
	v_add_f32_e32 v226, v226, v227
	v_add_f32_e32 v228, v228, v229
	v_add_f32_e32 v180, v180, v181
	v_add_f32_e32 v182, v182, v183
	v_add_f32_e32 v226, v226, v228
	v_add_f32_e32 v226, v226, v180
	v_add_f32_e32 v226, v226, v182
	v_fmamk_f32 v226, v226, 0x3a000000, v199
	v_rsq_f32_e32 v128, v226
	v_pk_mul_f32 v[28:29], v[28:29], v[130:131] op_sel_hi:[1,0]
	v_or_b32_e32 v182, 16, v186
	v_ashrrev_i32_e32 v183, 31, v182
	v_or_b32_e32 v180, 32, v186
	v_ashrrev_i32_e32 v181, 31, v180
	v_or_b32_e32 v174, 48, v186
	v_ashrrev_i32_e32 v175, 31, v174
	v_add_u32_e32 v158, 0x80, v186
	v_ashrrev_i32_e32 v159, 31, v158
	v_add_u32_e32 v152, 0x90, v186
	v_ashrrev_i32_e32 v153, 31, v152
	v_add_u32_e32 v150, 0xa0, v186
	v_ashrrev_i32_e32 v151, 31, v150
	v_add_u32_e32 v146, 0xb0, v186
	v_ashrrev_i32_e32 v147, 31, v146
	v_lshl_or_b32 v134, s42, 7, v157
	v_ashrrev_i32_e32 v135, 31, v134
	s_mov_b32 s42, s10
	v_mul_f32_e32 v129, 0xbfb8aa3b, v124
	v_exp_f32_e32 v129, v129
	v_mov_b64_e32 v[132:133], s[4:5]
	v_mad_i64_i32 v[186:187], s[4:5], v186, s11, v[132:133]
	v_add_f32_e32 v129, 1.0, v129
	v_rcp_f32_e32 v188, v129
	v_mul_f32_e32 v129, 0xbfb8aa3b, v125
	v_exp_f32_e32 v129, v129
	v_pk_mul_f32 v[24:25], v[24:25], v[130:131] op_sel_hi:[1,0]
	v_pk_mul_f32 v[26:27], v[26:27], v[130:131] op_sel_hi:[1,0]
	v_pk_mul_f32 v[20:21], v[20:21], v[130:131] op_sel_hi:[1,0]
	v_add_f32_e32 v129, 1.0, v129
	v_rcp_f32_e32 v189, v129
	v_pk_mul_f32 v[16:17], v[16:17], v[130:131] op_sel_hi:[1,0]
	v_pk_mul_f32 v[18:19], v[18:19], v[130:131] op_sel_hi:[1,0]
	v_pk_mul_f32 v[12:13], v[12:13], v[128:129] op_sel_hi:[1,0]
	v_pk_mul_f32 v[124:125], v[124:125], v[188:189]
	v_pk_mul_f32 v[8:9], v[8:9], v[128:129] op_sel_hi:[1,0]
	v_pk_mul_f32 v[120:121], v[120:121], v[124:125]
	v_pk_mul_f32 v[124:125], v[126:127], v[184:185] op_sel_hi:[1,0]
	v_pk_mul_f32 v[10:11], v[10:11], v[128:129] op_sel_hi:[1,0]
	v_mul_f32_e32 v126, 0xbfb8aa3b, v124
	v_mul_f32_e32 v127, 0xbfb8aa3b, v125
	v_exp_f32_e32 v126, v126
	v_exp_f32_e32 v127, v127
	v_pk_mul_f32 v[4:5], v[4:5], v[128:129] op_sel_hi:[1,0]
	v_pk_mul_f32 v[0:1], v[0:1], v[128:129] op_sel_hi:[1,0]
	v_add_f32_e32 v126, 1.0, v126
	v_add_f32_e32 v127, 1.0, v127
	v_rcp_f32_e32 v126, v126
	v_rcp_f32_e32 v127, v127
	v_pk_mul_f32 v[2:3], v[2:3], v[128:129] op_sel_hi:[1,0]
	s_and_b64 vcc, exec, s[0:1]
	v_pk_mul_f32 v[124:125], v[124:125], v[126:127]
	s_nop 0
	v_pk_mul_f32 v[122:123], v[122:123], v[124:125]
	v_mul_f32_e32 v124, 0xbfb8aa3b, v116
	v_mul_f32_e32 v125, 0xbfb8aa3b, v117
	v_exp_f32_e32 v124, v124
	v_exp_f32_e32 v125, v125
	v_add_f32_e32 v124, 1.0, v124
	v_add_f32_e32 v125, 1.0, v125
	v_rcp_f32_e32 v124, v124
	v_rcp_f32_e32 v125, v125
	s_nop 0
	v_pk_mul_f32 v[116:117], v[116:117], v[124:125]
	s_nop 0
	v_pk_mul_f32 v[116:117], v[112:113], v[116:117]
	v_pk_mul_f32 v[112:113], v[118:119], v[184:185] op_sel_hi:[1,0]
	v_cvt_pk_bf16_f32 v116, v116, v117
	v_mul_f32_e32 v118, 0xbfb8aa3b, v112
; DEV float siluf(float x) { return x * __builtin_amdgcn_rcpf(1.0f + __builtin_amdgcn_exp2f(x * -1.4426950408889634f)); }
; DEV bf16x8 pack8(f32x4 a, f32x4 b) { u32x4 w; w.x = cvt_pk_bf16(a[0], a[1]); w.y = cvt_pk_bf16(a[2], a[3]); w.z = cvt_pk_bf16(b[0], b[1]); w.w = cvt_pk_bf16(b[2], b[3]); return __builtin_bit_cast(bf16x8, w); }
;     DEV void operator()(AccRef acc, const pg8::Unit& u, int wr, int wc, int fr, int fq) const {
;     ...
;             for (int m = 0; m < 4; ++m) { u16* rowp = O + (size_t)(row0 + ai * 128 + m * 16) * 5632 + col0; const float rs = rsv[ai][m]; f32x4 r[2];
; #pragma unroll
;                 for (int n = 0; n < 2; ++n) { const f32x4 g = acc[ai][0][m][n] * rs, uu = acc[ai][1][m][n] * rs;
; #pragma unroll
;                     for (int e = 0; e < 4; ++e) r[n][e] = siluf(g[e]) * uu[e]; }
;                 *(u32x4*)rowp = __builtin_bit_cast(u32x4, pack8(r[0], r[1])); }
	v_mul_f32_e32 v119, 0xbfb8aa3b, v113
	v_exp_f32_e32 v118, v118
	v_exp_f32_e32 v119, v119
	v_add_f32_e32 v118, 1.0, v118
	v_add_f32_e32 v119, 1.0, v119
	v_rcp_f32_e32 v118, v118
	v_rcp_f32_e32 v119, v119
	s_nop 0
	v_pk_mul_f32 v[112:113], v[112:113], v[118:119]
	s_nop 0
	v_pk_mul_f32 v[118:119], v[114:115], v[112:113]
	v_lshlrev_b64 v[112:113], 1, v[134:135]
	v_lshl_add_u64 v[124:125], v[186:187], 0, v[112:113]
	v_cvt_pk_bf16_f32 v114, v120, v121
	v_cvt_pk_bf16_f32 v115, v122, v123
	v_cvt_pk_bf16_f32 v117, v118, v119
	global_store_dwordx4 v[124:125], v[114:117], off
	s_nop 1
	v_mul_f32_e32 v116, 0xbfb8aa3b, v108
	v_mul_f32_e32 v117, 0xbfb8aa3b, v109
	v_exp_f32_e32 v116, v116
	v_exp_f32_e32 v117, v117
	v_mad_i64_i32 v[114:115], s[4:5], v182, s11, v[132:133]
	v_add_f32_e32 v116, 1.0, v116
	v_add_f32_e32 v117, 1.0, v117
	v_rcp_f32_e32 v116, v116
	v_rcp_f32_e32 v117, v117
	s_nop 0
	v_pk_mul_f32 v[108:109], v[108:109], v[116:117]
	s_nop 0
	v_pk_mul_f32 v[104:105], v[104:105], v[108:109]
	v_pk_mul_f32 v[108:109], v[110:111], v[176:177] op_sel_hi:[1,0]
	s_nop 0
	v_mul_f32_e32 v110, 0xbfb8aa3b, v108
	v_mul_f32_e32 v111, 0xbfb8aa3b, v109
	v_exp_f32_e32 v110, v110
	v_exp_f32_e32 v111, v111
	v_add_f32_e32 v110, 1.0, v110
	v_add_f32_e32 v111, 1.0, v111
	v_rcp_f32_e32 v110, v110
	v_rcp_f32_e32 v111, v111
	s_nop 0
	v_pk_mul_f32 v[108:109], v[108:109], v[110:111]
	s_nop 0
	v_pk_mul_f32 v[106:107], v[106:107], v[108:109]
	v_mul_f32_e32 v108, 0xbfb8aa3b, v100
	v_mul_f32_e32 v109, 0xbfb8aa3b, v101
	v_exp_f32_e32 v108, v108
	v_exp_f32_e32 v109, v109
	v_add_f32_e32 v108, 1.0, v108
	v_add_f32_e32 v109, 1.0, v109
	v_rcp_f32_e32 v108, v108
	v_rcp_f32_e32 v109, v109
	s_nop 0
	v_pk_mul_f32 v[100:101], v[100:101], v[108:109]
	s_nop 0
	v_pk_mul_f32 v[100:101], v[96:97], v[100:101]
	v_pk_mul_f32 v[96:97], v[102:103], v[176:177] op_sel_hi:[1,0]
	v_lshl_add_u64 v[108:109], v[114:115], 0, v[112:113]
	v_mul_f32_e32 v102, 0xbfb8aa3b, v96
	v_mul_f32_e32 v103, 0xbfb8aa3b, v97
	v_exp_f32_e32 v102, v102
	v_exp_f32_e32 v103, v103
	v_add_f32_e32 v102, 1.0, v102
	v_add_f32_e32 v103, 1.0, v103
	v_rcp_f32_e32 v102, v102
	v_rcp_f32_e32 v103, v103
	s_nop 0
	v_pk_mul_f32 v[96:97], v[96:97], v[102:103]
	s_nop 0
	v_pk_mul_f32 v[102:103], v[98:99], v[96:97]
	v_cvt_pk_bf16_f32 v96, v104, v105
	v_cvt_pk_bf16_f32 v97, v106, v107
	v_cvt_pk_bf16_f32 v98, v100, v101
	v_cvt_pk_bf16_f32 v99, v102, v103
	global_store_dwordx4 v[108:109], v[96:99], off
	s_nop 1
	v_mul_f32_e32 v98, 0xbfb8aa3b, v92
	v_mul_f32_e32 v99, 0xbfb8aa3b, v93
	v_exp_f32_e32 v98, v98
	v_exp_f32_e32 v99, v99
	v_mad_i64_i32 v[96:97], s[4:5], v180, s11, v[132:133]
	v_add_f32_e32 v98, 1.0, v98
	v_add_f32_e32 v99, 1.0, v99
	v_rcp_f32_e32 v98, v98
	v_rcp_f32_e32 v99, v99
	s_nop 0
	v_pk_mul_f32 v[92:93], v[92:93], v[98:99]
	s_nop 0
	v_pk_mul_f32 v[88:89], v[88:89], v[92:93]
	v_pk_mul_f32 v[92:93], v[94:95], v[178:179] op_sel_hi:[1,0]
	s_nop 0
	v_mul_f32_e32 v94, 0xbfb8aa3b, v92
	v_mul_f32_e32 v95, 0xbfb8aa3b, v93
	v_exp_f32_e32 v94, v94
	v_exp_f32_e32 v95, v95
	v_add_f32_e32 v94, 1.0, v94
	v_add_f32_e32 v95, 1.0, v95
	v_rcp_f32_e32 v94, v94
	v_rcp_f32_e32 v95, v95
	s_nop 0
	v_pk_mul_f32 v[92:93], v[92:93], v[94:95]
	s_nop 0
	v_pk_mul_f32 v[90:91], v[90:91], v[92:93]
	v_mul_f32_e32 v92, 0xbfb8aa3b, v84
	v_mul_f32_e32 v93, 0xbfb8aa3b, v85
	v_exp_f32_e32 v92, v92
	v_exp_f32_e32 v93, v93
	v_add_f32_e32 v92, 1.0, v92
	v_add_f32_e32 v93, 1.0, v93
	v_rcp_f32_e32 v92, v92
	v_rcp_f32_e32 v93, v93
	s_nop 0
	v_pk_mul_f32 v[84:85], v[84:85], v[92:93]
	s_nop 0
	v_pk_mul_f32 v[84:85], v[80:81], v[84:85]
	v_pk_mul_f32 v[80:81], v[86:87], v[178:179] op_sel_hi:[1,0]
	v_lshl_add_u64 v[92:93], v[96:97], 0, v[112:113]
	v_mul_f32_e32 v86, 0xbfb8aa3b, v80
	v_mul_f32_e32 v87, 0xbfb8aa3b, v81
	v_exp_f32_e32 v86, v86
	v_exp_f32_e32 v87, v87
	v_add_f32_e32 v86, 1.0, v86
	v_add_f32_e32 v87, 1.0, v87
	v_rcp_f32_e32 v86, v86
	v_rcp_f32_e32 v87, v87
	s_nop 0
	v_pk_mul_f32 v[80:81], v[80:81], v[86:87]
	s_nop 0
	v_pk_mul_f32 v[86:87], v[82:83], v[80:81]
	v_cvt_pk_bf16_f32 v80, v88, v89
	v_cvt_pk_bf16_f32 v81, v90, v91
	v_cvt_pk_bf16_f32 v82, v84, v85
	v_cvt_pk_bf16_f32 v83, v86, v87
	global_store_dwordx4 v[92:93], v[80:83], off
	s_nop 1
	v_mul_f32_e32 v82, 0xbfb8aa3b, v76
	v_mul_f32_e32 v83, 0xbfb8aa3b, v77
	v_exp_f32_e32 v82, v82
	v_exp_f32_e32 v83, v83
	v_mad_i64_i32 v[80:81], s[4:5], v174, s11, v[132:133]
	v_add_f32_e32 v82, 1.0, v82
	v_add_f32_e32 v83, 1.0, v83
	v_rcp_f32_e32 v82, v82
	v_rcp_f32_e32 v83, v83
	s_nop 0
	v_pk_mul_f32 v[76:77], v[76:77], v[82:83]
	s_nop 0
	v_pk_mul_f32 v[72:73], v[72:73], v[76:77]
	v_pk_mul_f32 v[76:77], v[78:79], v[154:155] op_sel_hi:[1,0]
	s_nop 0
	v_mul_f32_e32 v78, 0xbfb8aa3b, v76
	v_mul_f32_e32 v79, 0xbfb8aa3b, v77
	v_exp_f32_e32 v78, v78
	v_exp_f32_e32 v79, v79
	v_add_f32_e32 v78, 1.0, v78
	v_add_f32_e32 v79, 1.0, v79
	v_rcp_f32_e32 v78, v78
	v_rcp_f32_e32 v79, v79
	s_nop 0
	v_pk_mul_f32 v[76:77], v[76:77], v[78:79]
	s_nop 0
	v_pk_mul_f32 v[74:75], v[74:75], v[76:77]
	v_mul_f32_e32 v76, 0xbfb8aa3b, v68
	v_mul_f32_e32 v77, 0xbfb8aa3b, v69
	v_exp_f32_e32 v76, v76
	v_exp_f32_e32 v77, v77
	v_add_f32_e32 v76, 1.0, v76
	v_add_f32_e32 v77, 1.0, v77
	v_rcp_f32_e32 v76, v76
	v_rcp_f32_e32 v77, v77
	s_nop 0
	v_pk_mul_f32 v[68:69], v[68:69], v[76:77]
	s_nop 0
	v_pk_mul_f32 v[68:69], v[64:65], v[68:69]
	v_pk_mul_f32 v[64:65], v[70:71], v[154:155] op_sel_hi:[1,0]
	v_lshl_add_u64 v[76:77], v[80:81], 0, v[112:113]
	v_mul_f32_e32 v70, 0xbfb8aa3b, v64
	v_mul_f32_e32 v71, 0xbfb8aa3b, v65
	v_exp_f32_e32 v70, v70
	v_exp_f32_e32 v71, v71
	v_add_f32_e32 v70, 1.0, v70
	v_add_f32_e32 v71, 1.0, v71
	v_rcp_f32_e32 v70, v70
	v_rcp_f32_e32 v71, v71
; DEV float siluf(float x) { return x * __builtin_amdgcn_rcpf(1.0f + __builtin_amdgcn_exp2f(x * -1.4426950408889634f)); }
; DEV bf16x8 pack8(f32x4 a, f32x4 b) { u32x4 w; w.x = cvt_pk_bf16(a[0], a[1]); w.y = cvt_pk_bf16(a[2], a[3]); w.z = cvt_pk_bf16(b[0], b[1]); w.w = cvt_pk_bf16(b[2], b[3]); return __builtin_bit_cast(bf16x8, w); }
;     DEV void operator()(AccRef acc, const pg8::Unit& u, int wr, int wc, int fr, int fq) const {
;     ...
;             for (int m = 0; m < 4; ++m) { u16* rowp = O + (size_t)(row0 + ai * 128 + m * 16) * 5632 + col0; const float rs = rsv[ai][m]; f32x4 r[2];
; #pragma unroll
;                 for (int n = 0; n < 2; ++n) { const f32x4 g = acc[ai][0][m][n] * rs, uu = acc[ai][1][m][n] * rs;
; #pragma unroll
;                     for (int e = 0; e < 4; ++e) r[n][e] = siluf(g[e]) * uu[e]; }
;                 *(u32x4*)rowp = __builtin_bit_cast(u32x4, pack8(r[0], r[1])); }
	s_nop 0
	v_pk_mul_f32 v[64:65], v[64:65], v[70:71]
	s_nop 0
	v_pk_mul_f32 v[70:71], v[66:67], v[64:65]
	v_cvt_pk_bf16_f32 v64, v72, v73
	v_cvt_pk_bf16_f32 v65, v74, v75
	v_cvt_pk_bf16_f32 v66, v68, v69
	v_cvt_pk_bf16_f32 v67, v70, v71
	global_store_dwordx4 v[76:77], v[64:67], off
	s_nop 1
	v_mul_f32_e32 v66, 0xbfb8aa3b, v60
	v_mul_f32_e32 v67, 0xbfb8aa3b, v61
	v_exp_f32_e32 v66, v66
	v_exp_f32_e32 v67, v67
	v_mad_i64_i32 v[64:65], s[4:5], v158, s11, v[132:133]
	v_add_f32_e32 v66, 1.0, v66
	v_add_f32_e32 v67, 1.0, v67
	v_rcp_f32_e32 v66, v66
	v_rcp_f32_e32 v67, v67
	s_nop 0
	v_pk_mul_f32 v[60:61], v[60:61], v[66:67]
	s_nop 0
	v_pk_mul_f32 v[56:57], v[56:57], v[60:61]
	v_pk_mul_f32 v[60:61], v[62:63], v[156:157] op_sel_hi:[1,0]
	s_nop 0
	v_mul_f32_e32 v62, 0xbfb8aa3b, v60
	v_mul_f32_e32 v63, 0xbfb8aa3b, v61
	v_exp_f32_e32 v62, v62
	v_exp_f32_e32 v63, v63
	v_add_f32_e32 v62, 1.0, v62
	v_add_f32_e32 v63, 1.0, v63
	v_rcp_f32_e32 v62, v62
	v_rcp_f32_e32 v63, v63
	s_nop 0
	v_pk_mul_f32 v[60:61], v[60:61], v[62:63]
	s_nop 0
	v_pk_mul_f32 v[58:59], v[58:59], v[60:61]
	v_mul_f32_e32 v60, 0xbfb8aa3b, v52
	v_mul_f32_e32 v61, 0xbfb8aa3b, v53
	v_exp_f32_e32 v60, v60
	v_exp_f32_e32 v61, v61
	v_add_f32_e32 v60, 1.0, v60
	v_add_f32_e32 v61, 1.0, v61
	v_rcp_f32_e32 v60, v60
	v_rcp_f32_e32 v61, v61
	s_nop 0
	v_pk_mul_f32 v[52:53], v[52:53], v[60:61]
	s_nop 0
	v_pk_mul_f32 v[52:53], v[48:49], v[52:53]
	v_pk_mul_f32 v[48:49], v[54:55], v[156:157] op_sel_hi:[1,0]
	v_lshl_add_u64 v[60:61], v[64:65], 0, v[112:113]
	v_mul_f32_e32 v54, 0xbfb8aa3b, v48
	v_mul_f32_e32 v55, 0xbfb8aa3b, v49
	v_exp_f32_e32 v54, v54
	v_exp_f32_e32 v55, v55
	v_add_f32_e32 v54, 1.0, v54
	v_add_f32_e32 v55, 1.0, v55
	v_rcp_f32_e32 v54, v54
	v_rcp_f32_e32 v55, v55
	s_nop 0
	v_pk_mul_f32 v[48:49], v[48:49], v[54:55]
	s_nop 0
	v_pk_mul_f32 v[54:55], v[50:51], v[48:49]
	v_cvt_pk_bf16_f32 v48, v56, v57
	v_cvt_pk_bf16_f32 v49, v58, v59
	v_cvt_pk_bf16_f32 v50, v52, v53
	v_cvt_pk_bf16_f32 v51, v54, v55
	global_store_dwordx4 v[60:61], v[48:51], off
	s_nop 1
	v_mul_f32_e32 v50, 0xbfb8aa3b, v44
	v_mul_f32_e32 v51, 0xbfb8aa3b, v45
	v_exp_f32_e32 v50, v50
	v_exp_f32_e32 v51, v51
	v_mad_i64_i32 v[48:49], s[4:5], v152, s11, v[132:133]
	v_add_f32_e32 v50, 1.0, v50
	v_add_f32_e32 v51, 1.0, v51
	v_rcp_f32_e32 v50, v50
	v_rcp_f32_e32 v51, v51
	s_nop 0
	v_pk_mul_f32 v[44:45], v[44:45], v[50:51]
	s_nop 0
	v_pk_mul_f32 v[40:41], v[40:41], v[44:45]
	v_pk_mul_f32 v[44:45], v[46:47], v[148:149] op_sel_hi:[1,0]
	s_nop 0
	v_mul_f32_e32 v46, 0xbfb8aa3b, v44
	v_mul_f32_e32 v47, 0xbfb8aa3b, v45
	v_exp_f32_e32 v46, v46
	v_exp_f32_e32 v47, v47
	v_add_f32_e32 v46, 1.0, v46
	v_add_f32_e32 v47, 1.0, v47
	v_rcp_f32_e32 v46, v46
	v_rcp_f32_e32 v47, v47
	s_nop 0
	v_pk_mul_f32 v[44:45], v[44:45], v[46:47]
	s_nop 0
	v_pk_mul_f32 v[42:43], v[42:43], v[44:45]
	v_mul_f32_e32 v44, 0xbfb8aa3b, v36
	v_mul_f32_e32 v45, 0xbfb8aa3b, v37
	v_exp_f32_e32 v44, v44
	v_exp_f32_e32 v45, v45
	v_add_f32_e32 v44, 1.0, v44
	v_add_f32_e32 v45, 1.0, v45
	v_rcp_f32_e32 v44, v44
	v_rcp_f32_e32 v45, v45
	s_nop 0
	v_pk_mul_f32 v[36:37], v[36:37], v[44:45]
	s_nop 0
	v_pk_mul_f32 v[36:37], v[32:33], v[36:37]
	v_pk_mul_f32 v[32:33], v[38:39], v[148:149] op_sel_hi:[1,0]
	v_lshl_add_u64 v[44:45], v[48:49], 0, v[112:113]
	v_mul_f32_e32 v38, 0xbfb8aa3b, v32
	v_mul_f32_e32 v39, 0xbfb8aa3b, v33
	v_exp_f32_e32 v38, v38
	v_exp_f32_e32 v39, v39
	v_add_f32_e32 v38, 1.0, v38
	v_add_f32_e32 v39, 1.0, v39
	v_rcp_f32_e32 v38, v38
	v_rcp_f32_e32 v39, v39
	s_nop 0
	v_pk_mul_f32 v[32:33], v[32:33], v[38:39]
	s_nop 0
	v_pk_mul_f32 v[38:39], v[34:35], v[32:33]
	v_cvt_pk_bf16_f32 v32, v40, v41
	v_cvt_pk_bf16_f32 v33, v42, v43
; DEV float siluf(float x) { return x * __builtin_amdgcn_rcpf(1.0f + __builtin_amdgcn_exp2f(x * -1.4426950408889634f)); }
; DEV bf16x8 pack8(f32x4 a, f32x4 b) { u32x4 w; w.x = cvt_pk_bf16(a[0], a[1]); w.y = cvt_pk_bf16(a[2], a[3]); w.z = cvt_pk_bf16(b[0], b[1]); w.w = cvt_pk_bf16(b[2], b[3]); return __builtin_bit_cast(bf16x8, w); }
; #define PG8_WAIT_V(n) asm volatile("s_waitcnt vmcnt(" #n ")" ::: "memory")
; #define PG8_BAR __builtin_amdgcn_s_barrier()
; template <class Epi>
; DEV void gemm_phase(LAS unsigned char* lds, const Gemm g, const StaticOrder& S, const Epi& E) {
;     ...
;     PG8_WAIT_V(0);
;     if (wr == 0) PG8_BAR;
;     PG8_BAR;
;     DEV void operator()(AccRef acc, const pg8::Unit& u, int wr, int wc, int fr, int fq) const {
;     ...
;             for (int m = 0; m < 4; ++m) { u16* rowp = O + (size_t)(row0 + ai * 128 + m * 16) * 5632 + col0; const float rs = rsv[ai][m]; f32x4 r[2];
; #pragma unroll
;                 for (int n = 0; n < 2; ++n) { const f32x4 g = acc[ai][0][m][n] * rs, uu = acc[ai][1][m][n] * rs;
; #pragma unroll
;                     for (int e = 0; e < 4; ++e) r[n][e] = siluf(g[e]) * uu[e]; }
;                 *(u32x4*)rowp = __builtin_bit_cast(u32x4, pack8(r[0], r[1])); }
	v_cvt_pk_bf16_f32 v34, v36, v37
	v_cvt_pk_bf16_f32 v35, v38, v39
	global_store_dwordx4 v[44:45], v[32:35], off
	s_nop 1
	v_mul_f32_e32 v34, 0xbfb8aa3b, v28
	v_mul_f32_e32 v35, 0xbfb8aa3b, v29
	v_exp_f32_e32 v34, v34
	v_exp_f32_e32 v35, v35
	v_mad_i64_i32 v[32:33], s[4:5], v150, s11, v[132:133]
	v_add_f32_e32 v34, 1.0, v34
	v_add_f32_e32 v35, 1.0, v35
	v_rcp_f32_e32 v34, v34
	v_rcp_f32_e32 v35, v35
	s_nop 0
	v_pk_mul_f32 v[28:29], v[28:29], v[34:35]
	s_nop 0
	v_pk_mul_f32 v[24:25], v[24:25], v[28:29]
	v_pk_mul_f32 v[28:29], v[30:31], v[130:131] op_sel_hi:[1,0]
	s_nop 0
	v_mul_f32_e32 v30, 0xbfb8aa3b, v28
	v_mul_f32_e32 v31, 0xbfb8aa3b, v29
	v_exp_f32_e32 v30, v30
	v_exp_f32_e32 v31, v31
	v_add_f32_e32 v30, 1.0, v30
	v_add_f32_e32 v31, 1.0, v31
	v_rcp_f32_e32 v30, v30
	v_rcp_f32_e32 v31, v31
	s_nop 0
	v_pk_mul_f32 v[28:29], v[28:29], v[30:31]
	s_nop 0
	v_pk_mul_f32 v[26:27], v[26:27], v[28:29]
	v_mul_f32_e32 v28, 0xbfb8aa3b, v20
	v_mul_f32_e32 v29, 0xbfb8aa3b, v21
	v_exp_f32_e32 v28, v28
	v_exp_f32_e32 v29, v29
	v_add_f32_e32 v28, 1.0, v28
	v_add_f32_e32 v29, 1.0, v29
	v_rcp_f32_e32 v28, v28
	v_rcp_f32_e32 v29, v29
	s_nop 0
	v_pk_mul_f32 v[20:21], v[20:21], v[28:29]
	s_nop 0
	v_pk_mul_f32 v[20:21], v[16:17], v[20:21]
	v_pk_mul_f32 v[16:17], v[22:23], v[130:131] op_sel_hi:[1,0]
	v_lshl_add_u64 v[28:29], v[32:33], 0, v[112:113]
	v_mul_f32_e32 v22, 0xbfb8aa3b, v16
	v_mul_f32_e32 v23, 0xbfb8aa3b, v17
	v_exp_f32_e32 v22, v22
	v_exp_f32_e32 v23, v23
	v_add_f32_e32 v22, 1.0, v22
	v_add_f32_e32 v23, 1.0, v23
	v_rcp_f32_e32 v22, v22
	v_rcp_f32_e32 v23, v23
	s_nop 0
	v_pk_mul_f32 v[16:17], v[16:17], v[22:23]
	s_nop 0
	v_pk_mul_f32 v[22:23], v[18:19], v[16:17]
	v_cvt_pk_bf16_f32 v16, v24, v25
	v_cvt_pk_bf16_f32 v17, v26, v27
	v_cvt_pk_bf16_f32 v18, v20, v21
	v_cvt_pk_bf16_f32 v19, v22, v23
	global_store_dwordx4 v[28:29], v[16:19], off
	s_nop 1
	v_mul_f32_e32 v18, 0xbfb8aa3b, v12
	v_mul_f32_e32 v19, 0xbfb8aa3b, v13
	v_exp_f32_e32 v18, v18
	v_exp_f32_e32 v19, v19
	v_mad_i64_i32 v[16:17], s[4:5], v146, s11, v[132:133]
	v_add_f32_e32 v18, 1.0, v18
	v_add_f32_e32 v19, 1.0, v19
	v_rcp_f32_e32 v18, v18
	v_rcp_f32_e32 v19, v19
	s_mov_b32 s4, s14
	v_pk_mul_f32 v[12:13], v[12:13], v[18:19]
	s_nop 0
	v_pk_mul_f32 v[8:9], v[8:9], v[12:13]
	v_pk_mul_f32 v[12:13], v[14:15], v[128:129] op_sel_hi:[1,0]
	s_nop 0
	v_mul_f32_e32 v14, 0xbfb8aa3b, v12
	v_mul_f32_e32 v15, 0xbfb8aa3b, v13
	v_exp_f32_e32 v14, v14
	v_exp_f32_e32 v15, v15
	v_add_f32_e32 v14, 1.0, v14
	v_add_f32_e32 v15, 1.0, v15
	v_rcp_f32_e32 v14, v14
	v_rcp_f32_e32 v15, v15
	s_nop 0
	v_pk_mul_f32 v[12:13], v[12:13], v[14:15]
	s_nop 0
	v_pk_mul_f32 v[10:11], v[10:11], v[12:13]
	v_mul_f32_e32 v12, 0xbfb8aa3b, v4
	v_mul_f32_e32 v13, 0xbfb8aa3b, v5
	v_exp_f32_e32 v12, v12
	v_exp_f32_e32 v13, v13
	v_add_f32_e32 v12, 1.0, v12
	v_add_f32_e32 v13, 1.0, v13
	v_rcp_f32_e32 v12, v12
	v_rcp_f32_e32 v13, v13
	s_nop 0
	v_pk_mul_f32 v[4:5], v[4:5], v[12:13]
	s_nop 0
	v_pk_mul_f32 v[4:5], v[0:1], v[4:5]
	v_pk_mul_f32 v[0:1], v[6:7], v[128:129] op_sel_hi:[1,0]
	v_lshl_add_u64 v[12:13], v[16:17], 0, v[112:113]
	v_mul_f32_e32 v6, 0xbfb8aa3b, v0
	v_mul_f32_e32 v7, 0xbfb8aa3b, v1
	v_exp_f32_e32 v6, v6
	v_exp_f32_e32 v7, v7
	v_add_f32_e32 v6, 1.0, v6
	v_add_f32_e32 v7, 1.0, v7
	v_rcp_f32_e32 v6, v6
	v_rcp_f32_e32 v7, v7
	s_nop 0
	v_pk_mul_f32 v[0:1], v[0:1], v[6:7]
	s_nop 0
	v_pk_mul_f32 v[6:7], v[2:3], v[0:1]
	v_cvt_pk_bf16_f32 v0, v8, v9
	v_cvt_pk_bf16_f32 v1, v10, v11
	v_cvt_pk_bf16_f32 v2, v4, v5
	v_cvt_pk_bf16_f32 v3, v6, v7
	global_store_dwordx4 v[12:13], v[0:3], off
	s_cbranch_vccz .LBB0_752
	s_waitcnt vmcnt(0)
	s_cmpk_gt_u32 s27, 0xff
	s_cbranch_scc1 .LBB0_759
	s_barrier
